# K-loops: DMA source addresses formed in the scalar unit (SGPR base + 32-bit lane offset, no per-DMA 64-bit VALU add) and the LDS read base registers kept resident instead of recomputed
# speedup vs baseline: 1.0210x; 1.0210x over previous
.LBB0_146:
	s_ashr_i32 s11, s10, 31
	v_cmp_lt_i64_e32 vcc, s[12:13], v[140:141]
	s_lshl_b64 s[12:13], s[10:11], 20
	s_add_u32 s12, s80, s12
	s_addc_u32 s13, s81, s13
	s_and_b64 s[14:15], vcc, exec
	s_cselect_b32 s11, s13, s17
	s_cselect_b32 s41, s12, s16
	s_ashr_i32 s9, s8, 31
	s_lshl_b64 s[14:15], s[8:9], 20
	s_add_u32 s14, s22, s14
	s_addc_u32 s15, s23, s15
	s_and_b64 s[20:21], vcc, exec
	s_cselect_b32 s9, s15, s19
	s_cselect_b32 s44, s14, s18
	s_add_u32 s16, s16, 0x80080
	s_addc_u32 s17, s17, 0
	s_add_u32 s45, s18, 0x100
	v_mov_b32_e32 v0, 0
	s_addc_u32 s46, s19, 0
	s_mov_b32 s47, -2
	v_mov_b32_e32 v1, v0
	v_mov_b32_e32 v2, v0
	v_mov_b32_e32 v3, v0
	v_mov_b32_e32 v4, v0
	v_mov_b32_e32 v5, v0
	v_mov_b32_e32 v6, v0
	v_mov_b32_e32 v7, v0
	v_mov_b32_e32 v16, v0
	v_mov_b32_e32 v17, v0
	s_waitcnt vmcnt(0)
	v_mov_b32_e32 v18, v0
	v_mov_b32_e32 v19, v0
	v_mov_b32_e32 v20, v0
	v_mov_b32_e32 v21, v0
	v_mov_b32_e32 v22, v0
	v_mov_b32_e32 v23, v0
	v_mov_b32_e32 v32, v0
	v_mov_b32_e32 v33, v0
	v_mov_b32_e32 v34, v0
	v_mov_b32_e32 v35, v0
	v_mov_b32_e32 v36, v0
	v_mov_b32_e32 v37, v0
	v_mov_b32_e32 v38, v0
	v_mov_b32_e32 v39, v0
	v_mov_b32_e32 v48, v0
	v_mov_b32_e32 v49, v0
	v_mov_b32_e32 v50, v0
	v_mov_b32_e32 v51, v0
	v_mov_b32_e32 v52, v0
	v_mov_b32_e32 v53, v0
	v_mov_b32_e32 v54, v0
	v_mov_b32_e32 v55, v0
	v_mov_b32_e32 v8, v0
	v_mov_b32_e32 v9, v0
	v_mov_b32_e32 v10, v0
	v_mov_b32_e32 v11, v0
	v_mov_b32_e32 v12, v0
	v_mov_b32_e32 v13, v0
	v_mov_b32_e32 v14, v0
	v_mov_b32_e32 v15, v0
	v_mov_b32_e32 v24, v0
	v_mov_b32_e32 v25, v0
	v_mov_b32_e32 v26, v0
	v_mov_b32_e32 v27, v0
	v_mov_b32_e32 v28, v0
	v_mov_b32_e32 v29, v0
	v_mov_b32_e32 v30, v0
	v_mov_b32_e32 v31, v0
	v_mov_b32_e32 v40, v0
	v_mov_b32_e32 v41, v0
	v_mov_b32_e32 v42, v0
	v_mov_b32_e32 v43, v0
	v_mov_b32_e32 v44, v0
	v_mov_b32_e32 v45, v0
	v_mov_b32_e32 v46, v0
	v_mov_b32_e32 v47, v0
	v_mov_b32_e32 v56, v0
	v_mov_b32_e32 v57, v0
	v_mov_b32_e32 v58, v0
	v_mov_b32_e32 v59, v0
	v_mov_b32_e32 v60, v0
	v_mov_b32_e32 v61, v0
	v_mov_b32_e32 v62, v0
	v_mov_b32_e32 v63, v0
	v_mov_b32_e32 v64, v0
	v_mov_b32_e32 v65, v0
	v_mov_b32_e32 v66, v0
	v_mov_b32_e32 v67, v0
	v_mov_b32_e32 v68, v0
	v_mov_b32_e32 v69, v0
	v_mov_b32_e32 v70, v0
	v_mov_b32_e32 v71, v0
	v_mov_b32_e32 v80, v0
	v_mov_b32_e32 v81, v0
	v_mov_b32_e32 v82, v0
	v_mov_b32_e32 v83, v0
	v_mov_b32_e32 v84, v0
	v_mov_b32_e32 v85, v0
	v_mov_b32_e32 v86, v0
	v_mov_b32_e32 v87, v0
	v_mov_b32_e32 v96, v0
	v_mov_b32_e32 v97, v0
	v_mov_b32_e32 v98, v0
	v_mov_b32_e32 v99, v0
	v_mov_b32_e32 v100, v0
	v_mov_b32_e32 v101, v0
	v_mov_b32_e32 v102, v0
	v_mov_b32_e32 v103, v0
	v_mov_b32_e32 v112, v0
	v_mov_b32_e32 v113, v0
	v_mov_b32_e32 v114, v0
	v_mov_b32_e32 v115, v0
	v_mov_b32_e32 v116, v0
	v_mov_b32_e32 v117, v0
	v_mov_b32_e32 v118, v0
	v_mov_b32_e32 v119, v0
	v_mov_b32_e32 v72, v0
	v_mov_b32_e32 v73, v0
	v_mov_b32_e32 v74, v0
	v_mov_b32_e32 v75, v0
	v_mov_b32_e32 v76, v0
	v_mov_b32_e32 v77, v0
	v_mov_b32_e32 v78, v0
	v_mov_b32_e32 v79, v0
	v_mov_b32_e32 v88, v0
	v_mov_b32_e32 v89, v0
	v_mov_b32_e32 v90, v0
	v_mov_b32_e32 v91, v0
	v_mov_b32_e32 v92, v0
	v_mov_b32_e32 v93, v0
	v_mov_b32_e32 v94, v0
	v_mov_b32_e32 v95, v0
	v_mov_b32_e32 v104, v0
	v_mov_b32_e32 v105, v0
	v_mov_b32_e32 v106, v0
	v_mov_b32_e32 v107, v0
	v_mov_b32_e32 v108, v0
	v_mov_b32_e32 v109, v0
	v_mov_b32_e32 v110, v0
	v_mov_b32_e32 v111, v0
	v_mov_b32_e32 v120, v0
	v_mov_b32_e32 v121, v0
	v_mov_b32_e32 v122, v0
	v_mov_b32_e32 v123, v0
	v_mov_b32_e32 v124, v0
	v_mov_b32_e32 v125, v0
	v_mov_b32_e32 v126, v0
	v_mov_b32_e32 v127, v0
	v_xor_b32_e32 v220, 64, v165
	v_xor_b32_e32 v221, 64, v166
	v_xor_b32_e32 v234, 64, v167
	v_add_u32_e32 v235, 0x18000, v161
	v_xor_b32_e32 v236, 64, v235
.LBB0_147:
	ds_read_b128 v[144:147], v165
	ds_read_b128 v[148:151], v220
	ds_read_b128 v[170:173], v165 offset:2048
	ds_read_b128 v[174:177], v220 offset:2048
	s_add_u32 s18, s16, 0xfff80080
	s_addc_u32 s19, s17, -1
	s_cmp_eq_u32 s47, 28
	s_cselect_b32 s21, s11, s19
	s_cselect_b32 s20, s41, s18
	s_cselect_b32 s19, s9, s46
	s_cselect_b32 s18, s44, s45
	s_add_i32 m0, s1, 0xc000
	ds_read_b128 v[178:181], v166
	ds_read_b128 v[182:185], v221
	ds_read_b128 v[186:189], v166 offset:2048
	ds_read_b128 v[190:193], v221 offset:2048
	ds_read_b128 v[194:197], v166 offset:4096
	ds_read_b128 v[198:201], v221 offset:4096
	ds_read_b128 v[202:205], v166 offset:6144
	ds_read_b128 v[206:209], v221 offset:6144
	global_load_lds_dwordx4 v136, s[16:17]
	s_add_i32 m0, s1, 0xe000
	s_nop 0
	global_load_lds_dwordx4 v138, s[16:17]
	s_waitcnt lgkmcnt(8)
	s_barrier
	s_waitcnt lgkmcnt(0)
	s_setprio 1
	s_waitcnt lgkmcnt(0)
	v_mfma_f32_16x16x32_bf16 v[124:127], v[144:147], v[178:181], v[124:127]
	v_mfma_f32_16x16x32_bf16 v[124:127], v[148:151], v[182:185], v[124:127]
	v_mfma_f32_16x16x32_bf16 v[120:123], v[174:177], v[182:185], v[120:123]
	v_mfma_f32_16x16x32_bf16 v[120:123], v[170:173], v[178:181], v[120:123]
	v_mfma_f32_16x16x32_bf16 v[104:107], v[170:173], v[186:189], v[104:107]
	v_mfma_f32_16x16x32_bf16 v[104:107], v[174:177], v[190:193], v[104:107]
	v_mfma_f32_16x16x32_bf16 v[108:111], v[148:151], v[190:193], v[108:111]
	v_mfma_f32_16x16x32_bf16 v[108:111], v[144:147], v[186:189], v[108:111]
	v_mfma_f32_16x16x32_bf16 v[92:95], v[144:147], v[194:197], v[92:95]
	v_mfma_f32_16x16x32_bf16 v[92:95], v[148:151], v[198:201], v[92:95]
	v_mfma_f32_16x16x32_bf16 v[88:91], v[174:177], v[198:201], v[88:91]
	v_mfma_f32_16x16x32_bf16 v[88:91], v[170:173], v[194:197], v[88:91]
	v_mfma_f32_16x16x32_bf16 v[72:75], v[170:173], v[202:205], v[72:75]
	v_mfma_f32_16x16x32_bf16 v[72:75], v[174:177], v[206:209], v[72:75]
	v_mfma_f32_16x16x32_bf16 v[76:79], v[148:151], v[206:209], v[76:79]
	v_mfma_f32_16x16x32_bf16 v[76:79], v[144:147], v[202:205], v[76:79]
	s_setprio 0
	s_barrier
	s_add_i32 s48, s35, s24
	s_add_u32 s98, s18, s6
	s_addc_u32 s99, s19, s7
	s_mov_b32 m0, s48
	ds_read_b128 v[210:213], v167
	ds_read_b128 v[214:217], v234
	ds_read_b128 v[226:229], v167 offset:2048
	ds_read_b128 v[230:233], v234 offset:2048
	global_load_lds_dwordx4 v132, s[18:19]
	s_add_i32 m0, s48, 0x2000
	s_nop 0
	global_load_lds_dwordx4 v128, s[18:19]
	s_barrier
	s_waitcnt lgkmcnt(0)
	s_setprio 1
	s_waitcnt lgkmcnt(0)
	v_mfma_f32_16x16x32_bf16 v[116:119], v[210:213], v[178:181], v[116:119]
	v_mfma_f32_16x16x32_bf16 v[116:119], v[214:217], v[182:185], v[116:119]
	v_mfma_f32_16x16x32_bf16 v[112:115], v[230:233], v[182:185], v[112:115]
	v_mfma_f32_16x16x32_bf16 v[112:115], v[226:229], v[178:181], v[112:115]
	v_mfma_f32_16x16x32_bf16 v[96:99], v[226:229], v[186:189], v[96:99]
	v_mfma_f32_16x16x32_bf16 v[96:99], v[230:233], v[190:193], v[96:99]
	v_mfma_f32_16x16x32_bf16 v[100:103], v[214:217], v[190:193], v[100:103]
	v_mfma_f32_16x16x32_bf16 v[100:103], v[210:213], v[186:189], v[100:103]
	v_mfma_f32_16x16x32_bf16 v[84:87], v[210:213], v[194:197], v[84:87]
	v_mfma_f32_16x16x32_bf16 v[84:87], v[214:217], v[198:201], v[84:87]
	v_mfma_f32_16x16x32_bf16 v[80:83], v[230:233], v[198:201], v[80:83]
	v_mfma_f32_16x16x32_bf16 v[80:83], v[226:229], v[194:197], v[80:83]
	v_mfma_f32_16x16x32_bf16 v[64:67], v[226:229], v[202:205], v[64:67]
	v_mfma_f32_16x16x32_bf16 v[64:67], v[230:233], v[206:209], v[64:67]
	v_mfma_f32_16x16x32_bf16 v[68:71], v[214:217], v[206:209], v[68:71]
	v_mfma_f32_16x16x32_bf16 v[68:71], v[210:213], v[202:205], v[68:71]
	s_setprio 0
	s_mov_b32 m0, s1
	s_add_u32 s100, s20, s6
	s_addc_u32 s101, s21, s7
	s_barrier
	ds_read_b128 v[178:181], v166 offset:16384
	ds_read_b128 v[182:185], v221 offset:16384
	ds_read_b128 v[186:189], v166 offset:18432
	ds_read_b128 v[190:193], v221 offset:18432
	ds_read_b128 v[194:197], v166 offset:20480
	ds_read_b128 v[198:201], v221 offset:20480
	ds_read_b128 v[202:205], v166 offset:22528
	ds_read_b128 v[206:209], v221 offset:22528
	global_load_lds_dwordx4 v134, s[20:21]
	s_mov_b32 m0, s26
	s_nop 0
	global_load_lds_dwordx4 v130, s[20:21]
	s_barrier
	s_waitcnt lgkmcnt(0)
	s_setprio 1
	s_waitcnt lgkmcnt(0)
	v_mfma_f32_16x16x32_bf16 v[60:63], v[144:147], v[178:181], v[60:63]
	v_mfma_f32_16x16x32_bf16 v[60:63], v[148:151], v[182:185], v[60:63]
	v_mfma_f32_16x16x32_bf16 v[56:59], v[174:177], v[182:185], v[56:59]
	v_mfma_f32_16x16x32_bf16 v[56:59], v[170:173], v[178:181], v[56:59]
	v_mfma_f32_16x16x32_bf16 v[40:43], v[170:173], v[186:189], v[40:43]
	v_mfma_f32_16x16x32_bf16 v[40:43], v[174:177], v[190:193], v[40:43]
	v_mfma_f32_16x16x32_bf16 v[44:47], v[148:151], v[190:193], v[44:47]
	v_mfma_f32_16x16x32_bf16 v[44:47], v[144:147], v[186:189], v[44:47]
	v_mfma_f32_16x16x32_bf16 v[28:31], v[144:147], v[194:197], v[28:31]
	v_mfma_f32_16x16x32_bf16 v[28:31], v[148:151], v[198:201], v[28:31]
	v_mfma_f32_16x16x32_bf16 v[24:27], v[174:177], v[198:201], v[24:27]
	v_mfma_f32_16x16x32_bf16 v[24:27], v[170:173], v[194:197], v[24:27]
	v_mfma_f32_16x16x32_bf16 v[8:11], v[170:173], v[202:205], v[8:11]
	v_mfma_f32_16x16x32_bf16 v[8:11], v[174:177], v[206:209], v[8:11]
	v_mfma_f32_16x16x32_bf16 v[12:15], v[148:151], v[206:209], v[12:15]
	v_mfma_f32_16x16x32_bf16 v[12:15], v[144:147], v[202:205], v[12:15]
	s_setprio 0
	s_barrier
	s_add_u32 s48, s18, 0x80000
	s_addc_u32 s49, s19, 0
	s_add_i32 s52, s38, s24
	s_mov_b32 m0, s52
	s_nop 0
	global_load_lds_dwordx4 v132, s[48:49]
	s_add_i32 m0, s52, 0x2000
	s_nop 0
	global_load_lds_dwordx4 v128, s[48:49]
	s_waitcnt vmcnt(6)
	s_barrier
	s_setprio 1
	v_mfma_f32_16x16x32_bf16 v[52:55], v[210:213], v[178:181], v[52:55]
	v_mfma_f32_16x16x32_bf16 v[52:55], v[214:217], v[182:185], v[52:55]
	v_mfma_f32_16x16x32_bf16 v[48:51], v[230:233], v[182:185], v[48:51]
	v_mfma_f32_16x16x32_bf16 v[48:51], v[226:229], v[178:181], v[48:51]
	v_mfma_f32_16x16x32_bf16 v[32:35], v[226:229], v[186:189], v[32:35]
	v_mfma_f32_16x16x32_bf16 v[32:35], v[230:233], v[190:193], v[32:35]
	v_mfma_f32_16x16x32_bf16 v[36:39], v[214:217], v[190:193], v[36:39]
	v_mfma_f32_16x16x32_bf16 v[36:39], v[210:213], v[186:189], v[36:39]
	v_mfma_f32_16x16x32_bf16 v[20:23], v[210:213], v[194:197], v[20:23]
	v_mfma_f32_16x16x32_bf16 v[20:23], v[214:217], v[198:201], v[20:23]
	v_mfma_f32_16x16x32_bf16 v[16:19], v[230:233], v[198:201], v[16:19]
	v_mfma_f32_16x16x32_bf16 v[16:19], v[226:229], v[194:197], v[16:19]
	v_mfma_f32_16x16x32_bf16 v[0:3], v[226:229], v[202:205], v[0:3]
	v_mfma_f32_16x16x32_bf16 v[0:3], v[230:233], v[206:209], v[0:3]
	v_mfma_f32_16x16x32_bf16 v[4:7], v[214:217], v[206:209], v[4:7]
	v_mfma_f32_16x16x32_bf16 v[4:7], v[210:213], v[202:205], v[4:7]
	s_setprio 0
	s_add_i32 s48, 0, 0x18000
	s_barrier
	ds_read_b128 v[144:147], v235
	ds_read_b128 v[148:151], v236
	ds_read_b128 v[170:173], v235 offset:2048
	ds_read_b128 v[174:177], v236 offset:2048
	s_add_u32 s20, s20, 0x80000
	s_addc_u32 s21, s21, 0
	s_mov_b32 m0, s27
	ds_read_b128 v[178:181], v166 offset:32768
	ds_read_b128 v[182:185], v221 offset:32768
	ds_read_b128 v[186:189], v166 offset:34816
	ds_read_b128 v[190:193], v221 offset:34816
	ds_read_b128 v[194:197], v166 offset:36864
	ds_read_b128 v[198:201], v221 offset:36864
	ds_read_b128 v[202:205], v166 offset:38912
	ds_read_b128 v[206:209], v221 offset:38912
	global_load_lds_dwordx4 v134, s[20:21]
	s_mov_b32 m0, s28
	s_nop 0
	global_load_lds_dwordx4 v130, s[20:21]
	s_waitcnt lgkmcnt(8)
	s_barrier
	s_waitcnt lgkmcnt(0)
	s_setprio 1
	s_waitcnt lgkmcnt(0)
	v_mfma_f32_16x16x32_bf16 v[124:127], v[144:147], v[178:181], v[124:127]
	v_mfma_f32_16x16x32_bf16 v[124:127], v[148:151], v[182:185], v[124:127]
	v_mfma_f32_16x16x32_bf16 v[120:123], v[174:177], v[182:185], v[120:123]
	v_mfma_f32_16x16x32_bf16 v[120:123], v[170:173], v[178:181], v[120:123]
	v_mfma_f32_16x16x32_bf16 v[104:107], v[170:173], v[186:189], v[104:107]
	v_mfma_f32_16x16x32_bf16 v[104:107], v[174:177], v[190:193], v[104:107]
	v_mfma_f32_16x16x32_bf16 v[108:111], v[148:151], v[190:193], v[108:111]
	v_mfma_f32_16x16x32_bf16 v[108:111], v[144:147], v[186:189], v[108:111]
	v_mfma_f32_16x16x32_bf16 v[92:95], v[144:147], v[194:197], v[92:95]
	v_mfma_f32_16x16x32_bf16 v[92:95], v[148:151], v[198:201], v[92:95]
	v_mfma_f32_16x16x32_bf16 v[88:91], v[174:177], v[198:201], v[88:91]
	v_mfma_f32_16x16x32_bf16 v[88:91], v[170:173], v[194:197], v[88:91]
	v_mfma_f32_16x16x32_bf16 v[72:75], v[170:173], v[202:205], v[72:75]
	v_mfma_f32_16x16x32_bf16 v[72:75], v[174:177], v[206:209], v[72:75]
	v_mfma_f32_16x16x32_bf16 v[76:79], v[148:151], v[206:209], v[76:79]
	v_mfma_f32_16x16x32_bf16 v[76:79], v[144:147], v[202:205], v[76:79]
	s_setprio 0
	s_barrier
	s_add_i32 s20, 0, 0x1c000
	s_add_i32 s21, s48, s24
	v_add_u32_e32 v169, s20, v161
	s_mov_b32 m0, s21
	ds_read_b128 v[210:213], v169
	v_xor_b32_e32 v233, 64, v169
	ds_read_b128 v[214:217], v233
	ds_read_b128 v[226:229], v169 offset:2048
	ds_read_b128 v[230:233], v233 offset:2048
	global_load_lds_dwordx4 v132, s[98:99]
	s_add_i32 m0, s21, 0x2000
	s_nop 0
	global_load_lds_dwordx4 v128, s[98:99]
	s_barrier
	s_waitcnt lgkmcnt(0)
	s_setprio 1
	s_waitcnt lgkmcnt(0)
	v_mfma_f32_16x16x32_bf16 v[116:119], v[210:213], v[178:181], v[116:119]
	v_mfma_f32_16x16x32_bf16 v[116:119], v[214:217], v[182:185], v[116:119]
	v_mfma_f32_16x16x32_bf16 v[112:115], v[230:233], v[182:185], v[112:115]
	v_mfma_f32_16x16x32_bf16 v[112:115], v[226:229], v[178:181], v[112:115]
	v_mfma_f32_16x16x32_bf16 v[96:99], v[226:229], v[186:189], v[96:99]
	v_mfma_f32_16x16x32_bf16 v[96:99], v[230:233], v[190:193], v[96:99]
	v_mfma_f32_16x16x32_bf16 v[100:103], v[214:217], v[190:193], v[100:103]
	v_mfma_f32_16x16x32_bf16 v[100:103], v[210:213], v[186:189], v[100:103]
	v_mfma_f32_16x16x32_bf16 v[84:87], v[210:213], v[194:197], v[84:87]
	v_mfma_f32_16x16x32_bf16 v[84:87], v[214:217], v[198:201], v[84:87]
	v_mfma_f32_16x16x32_bf16 v[80:83], v[230:233], v[198:201], v[80:83]
	v_mfma_f32_16x16x32_bf16 v[80:83], v[226:229], v[194:197], v[80:83]
	v_mfma_f32_16x16x32_bf16 v[64:67], v[226:229], v[202:205], v[64:67]
	v_mfma_f32_16x16x32_bf16 v[64:67], v[230:233], v[206:209], v[64:67]
	v_mfma_f32_16x16x32_bf16 v[68:71], v[214:217], v[206:209], v[68:71]
	v_mfma_f32_16x16x32_bf16 v[68:71], v[210:213], v[202:205], v[68:71]
	s_setprio 0
	s_mov_b32 m0, s30
	s_barrier
	ds_read_b128 v[178:181], v166 offset:49152
	ds_read_b128 v[182:185], v221 offset:49152
	ds_read_b128 v[186:189], v166 offset:51200
	ds_read_b128 v[190:193], v221 offset:51200
	ds_read_b128 v[194:197], v166 offset:53248
	ds_read_b128 v[198:201], v221 offset:53248
	ds_read_b128 v[202:205], v166 offset:55296
	ds_read_b128 v[206:209], v221 offset:55296
	global_load_lds_dwordx4 v134, s[100:101]
	s_mov_b32 m0, s31
	s_nop 0
	global_load_lds_dwordx4 v130, s[100:101]
	s_barrier
	s_waitcnt lgkmcnt(0)
	s_setprio 1
	s_waitcnt lgkmcnt(0)
	v_mfma_f32_16x16x32_bf16 v[60:63], v[144:147], v[178:181], v[60:63]
	v_mfma_f32_16x16x32_bf16 v[60:63], v[148:151], v[182:185], v[60:63]
	v_mfma_f32_16x16x32_bf16 v[56:59], v[174:177], v[182:185], v[56:59]
	v_mfma_f32_16x16x32_bf16 v[56:59], v[170:173], v[178:181], v[56:59]
	v_mfma_f32_16x16x32_bf16 v[40:43], v[170:173], v[186:189], v[40:43]
	v_mfma_f32_16x16x32_bf16 v[40:43], v[174:177], v[190:193], v[40:43]
	v_mfma_f32_16x16x32_bf16 v[44:47], v[148:151], v[190:193], v[44:47]
	v_mfma_f32_16x16x32_bf16 v[44:47], v[144:147], v[186:189], v[44:47]
	v_mfma_f32_16x16x32_bf16 v[28:31], v[144:147], v[194:197], v[28:31]
	v_mfma_f32_16x16x32_bf16 v[28:31], v[148:151], v[198:201], v[28:31]
	v_mfma_f32_16x16x32_bf16 v[24:27], v[174:177], v[198:201], v[24:27]
	v_mfma_f32_16x16x32_bf16 v[24:27], v[170:173], v[194:197], v[24:27]
	v_mfma_f32_16x16x32_bf16 v[8:11], v[170:173], v[202:205], v[8:11]
	v_mfma_f32_16x16x32_bf16 v[8:11], v[174:177], v[206:209], v[8:11]
	v_mfma_f32_16x16x32_bf16 v[12:15], v[148:151], v[206:209], v[12:15]
	v_mfma_f32_16x16x32_bf16 v[12:15], v[144:147], v[202:205], v[12:15]
	s_setprio 0
	s_barrier
	s_add_u32 s18, s18, 0x80080
	s_addc_u32 s19, s19, 0
	s_add_i32 s20, s20, s24
	s_mov_b32 m0, s20
	s_nop 0
	global_load_lds_dwordx4 v132, s[18:19]
	s_add_i32 m0, s20, 0x2000
	s_nop 0
	global_load_lds_dwordx4 v128, s[18:19]
	s_waitcnt vmcnt(6)
	s_barrier
	s_setprio 1
	v_mfma_f32_16x16x32_bf16 v[52:55], v[210:213], v[178:181], v[52:55]
	v_mfma_f32_16x16x32_bf16 v[52:55], v[214:217], v[182:185], v[52:55]
	v_mfma_f32_16x16x32_bf16 v[48:51], v[230:233], v[182:185], v[48:51]
	v_mfma_f32_16x16x32_bf16 v[48:51], v[226:229], v[178:181], v[48:51]
	v_mfma_f32_16x16x32_bf16 v[32:35], v[226:229], v[186:189], v[32:35]
	v_mfma_f32_16x16x32_bf16 v[32:35], v[230:233], v[190:193], v[32:35]
	v_mfma_f32_16x16x32_bf16 v[36:39], v[214:217], v[190:193], v[36:39]
	v_mfma_f32_16x16x32_bf16 v[36:39], v[210:213], v[186:189], v[36:39]
	v_mfma_f32_16x16x32_bf16 v[20:23], v[210:213], v[194:197], v[20:23]
	v_mfma_f32_16x16x32_bf16 v[20:23], v[214:217], v[198:201], v[20:23]
	v_mfma_f32_16x16x32_bf16 v[16:19], v[230:233], v[198:201], v[16:19]
	v_mfma_f32_16x16x32_bf16 v[16:19], v[226:229], v[194:197], v[16:19]
	v_mfma_f32_16x16x32_bf16 v[0:3], v[226:229], v[202:205], v[0:3]
	v_mfma_f32_16x16x32_bf16 v[0:3], v[230:233], v[206:209], v[0:3]
	v_mfma_f32_16x16x32_bf16 v[4:7], v[214:217], v[206:209], v[4:7]
	v_mfma_f32_16x16x32_bf16 v[4:7], v[210:213], v[202:205], v[4:7]
	s_setprio 0
	s_add_i32 s47, s47, 2
	s_add_u32 s16, s16, 0x100
	s_addc_u32 s17, s17, 0
	s_add_u32 s45, s45, 0x100
	s_addc_u32 s46, s46, 0
	s_cmp_gt_u32 s47, 29
	s_barrier
	s_cbranch_scc0 .LBB0_147
	v_lshl_add_u32 v144, s0, 8, v160
	v_ashrrev_i32_e32 v145, 31, v144
	v_lshl_add_u64 v[150:151], v[144:145], 2, s[92:93]
	global_load_dword v176, v[150:151], off
	global_load_dword v177, v[150:151], off offset:64
	global_load_dword v178, v[150:151], off offset:128
	global_load_dword v179, v[150:151], off offset:192
	global_load_dword v180, v[150:151], off offset:512
	global_load_dword v181, v[150:151], off offset:576
	global_load_dword v182, v[150:151], off offset:640
	global_load_dword v183, v[150:151], off offset:704
	v_lshl_or_b32 v148, s40, 8, v164
	v_mov_b64_e32 v[146:147], s[96:97]
	v_ashrrev_i32_e32 v149, 31, v148
	v_mad_i64_i32 v[172:173], s[16:17], v144, s39, v[146:147]
	v_lshlrev_b64 v[148:149], 1, v[148:149]
	v_lshl_add_u64 v[172:173], v[172:173], 0, v[148:149]
	s_and_b64 vcc, exec, s[4:5]
	s_mov_b32 s40, s8
	s_mov_b32 s0, s10
	s_mov_b64 s[18:19], s[14:15]
	s_waitcnt vmcnt(0)
	v_fmamk_f32 v145, v176, 0x3a000000, v168
	v_rsq_f32_e32 v170, v145
	s_nop 0
	v_pk_mul_f32 v[126:127], v[126:127], v[170:171] op_sel_hi:[1,0]
	v_pk_mul_f32 v[124:125], v[124:125], v[170:171] op_sel_hi:[1,0]
	v_pk_mul_f32 v[122:123], v[122:123], v[170:171] op_sel_hi:[1,0]
	v_pk_mul_f32 v[120:121], v[120:121], v[170:171] op_sel_hi:[1,0]
	v_pk_mul_f32 v[118:119], v[118:119], v[170:171] op_sel_hi:[1,0]
	v_pk_mul_f32 v[116:117], v[116:117], v[170:171] op_sel_hi:[1,0]
	v_pk_mul_f32 v[174:175], v[114:115], v[170:171] op_sel_hi:[1,0]
	v_pk_mul_f32 v[170:171], v[112:113], v[170:171] op_sel_hi:[1,0]
	v_cvt_pk_bf16_f32 v112, v124, v125
	v_cvt_pk_bf16_f32 v113, v126, v127
	v_cvt_pk_bf16_f32 v114, v120, v121
	v_cvt_pk_bf16_f32 v115, v122, v123
	global_store_dwordx4 v[172:173], v[112:115], off
	s_nop 1
	v_cvt_pk_bf16_f32 v112, v116, v117
	v_cvt_pk_bf16_f32 v113, v118, v119
	v_cvt_pk_bf16_f32 v114, v170, v171
	v_cvt_pk_bf16_f32 v115, v174, v175
	global_store_dwordx4 v[172:173], v[112:115], off offset:256
	s_nop 0
	s_nop 0
	v_or_b32_e32 v113, 16, v144
	v_mad_i64_i32 v[114:115], s[16:17], v113, s39, v[146:147]
	v_lshl_add_u64 v[114:115], v[114:115], 0, v[148:149]
	s_nop 0
	v_fmamk_f32 v112, v177, 0x3a000000, v168
	v_rsq_f32_e32 v112, v112
	s_nop 0
	v_pk_mul_f32 v[110:111], v[110:111], v[112:113] op_sel_hi:[1,0]
	v_pk_mul_f32 v[108:109], v[108:109], v[112:113] op_sel_hi:[1,0]
	v_pk_mul_f32 v[106:107], v[106:107], v[112:113] op_sel_hi:[1,0]
	v_pk_mul_f32 v[104:105], v[104:105], v[112:113] op_sel_hi:[1,0]
	v_pk_mul_f32 v[102:103], v[102:103], v[112:113] op_sel_hi:[1,0]
	v_pk_mul_f32 v[100:101], v[100:101], v[112:113] op_sel_hi:[1,0]
	v_pk_mul_f32 v[116:117], v[98:99], v[112:113] op_sel_hi:[1,0]
	v_pk_mul_f32 v[112:113], v[96:97], v[112:113] op_sel_hi:[1,0]
	v_cvt_pk_bf16_f32 v96, v108, v109
	v_cvt_pk_bf16_f32 v97, v110, v111
	v_cvt_pk_bf16_f32 v98, v104, v105
	v_cvt_pk_bf16_f32 v99, v106, v107
	global_store_dwordx4 v[114:115], v[96:99], off
	s_nop 1
	v_cvt_pk_bf16_f32 v96, v100, v101
	v_cvt_pk_bf16_f32 v97, v102, v103
	v_cvt_pk_bf16_f32 v98, v112, v113
	v_cvt_pk_bf16_f32 v99, v116, v117
	global_store_dwordx4 v[114:115], v[96:99], off offset:256
	s_nop 0
	s_nop 0
	v_or_b32_e32 v97, 32, v144
	v_mad_i64_i32 v[98:99], s[16:17], v97, s39, v[146:147]
	v_lshl_add_u64 v[98:99], v[98:99], 0, v[148:149]
	s_nop 0
	v_fmamk_f32 v96, v178, 0x3a000000, v168
	v_rsq_f32_e32 v96, v96
	s_nop 0
	v_pk_mul_f32 v[94:95], v[94:95], v[96:97] op_sel_hi:[1,0]
	v_pk_mul_f32 v[92:93], v[92:93], v[96:97] op_sel_hi:[1,0]
	v_pk_mul_f32 v[90:91], v[90:91], v[96:97] op_sel_hi:[1,0]
	v_pk_mul_f32 v[88:89], v[88:89], v[96:97] op_sel_hi:[1,0]
	v_pk_mul_f32 v[86:87], v[86:87], v[96:97] op_sel_hi:[1,0]
	v_pk_mul_f32 v[84:85], v[84:85], v[96:97] op_sel_hi:[1,0]
	v_pk_mul_f32 v[100:101], v[82:83], v[96:97] op_sel_hi:[1,0]
	v_pk_mul_f32 v[96:97], v[80:81], v[96:97] op_sel_hi:[1,0]
	v_cvt_pk_bf16_f32 v80, v92, v93
	v_cvt_pk_bf16_f32 v81, v94, v95
	v_cvt_pk_bf16_f32 v82, v88, v89
	v_cvt_pk_bf16_f32 v83, v90, v91
	global_store_dwordx4 v[98:99], v[80:83], off
	s_nop 1
	v_cvt_pk_bf16_f32 v80, v84, v85
	v_cvt_pk_bf16_f32 v81, v86, v87
	v_cvt_pk_bf16_f32 v82, v96, v97
	v_cvt_pk_bf16_f32 v83, v100, v101
	global_store_dwordx4 v[98:99], v[80:83], off offset:256
	s_nop 0
	s_nop 0
	v_or_b32_e32 v81, 48, v144
	v_mad_i64_i32 v[82:83], s[16:17], v81, s39, v[146:147]
	v_lshl_add_u64 v[82:83], v[82:83], 0, v[148:149]
	s_nop 0
	v_fmamk_f32 v80, v179, 0x3a000000, v168
	v_rsq_f32_e32 v80, v80
	s_nop 0
	v_pk_mul_f32 v[78:79], v[78:79], v[80:81] op_sel_hi:[1,0]
	v_pk_mul_f32 v[76:77], v[76:77], v[80:81] op_sel_hi:[1,0]
	v_pk_mul_f32 v[74:75], v[74:75], v[80:81] op_sel_hi:[1,0]
	v_pk_mul_f32 v[72:73], v[72:73], v[80:81] op_sel_hi:[1,0]
	v_pk_mul_f32 v[70:71], v[70:71], v[80:81] op_sel_hi:[1,0]
	v_pk_mul_f32 v[68:69], v[68:69], v[80:81] op_sel_hi:[1,0]
	v_pk_mul_f32 v[84:85], v[66:67], v[80:81] op_sel_hi:[1,0]
	v_pk_mul_f32 v[80:81], v[64:65], v[80:81] op_sel_hi:[1,0]
	v_cvt_pk_bf16_f32 v64, v76, v77
	v_cvt_pk_bf16_f32 v65, v78, v79
	v_cvt_pk_bf16_f32 v66, v72, v73
	v_cvt_pk_bf16_f32 v67, v74, v75
	global_store_dwordx4 v[82:83], v[64:67], off
	s_nop 1
	v_cvt_pk_bf16_f32 v64, v68, v69
	v_cvt_pk_bf16_f32 v65, v70, v71
	v_cvt_pk_bf16_f32 v66, v80, v81
	v_cvt_pk_bf16_f32 v67, v84, v85
	global_store_dwordx4 v[82:83], v[64:67], off offset:256
	s_nop 0
	s_nop 0
	v_add_u32_e32 v65, 0x80, v144
	v_mad_i64_i32 v[66:67], s[16:17], v65, s39, v[146:147]
	v_lshl_add_u64 v[66:67], v[66:67], 0, v[148:149]
	s_nop 0
	v_fmamk_f32 v64, v180, 0x3a000000, v168
	v_rsq_f32_e32 v64, v64
	s_nop 0
	v_pk_mul_f32 v[62:63], v[62:63], v[64:65] op_sel_hi:[1,0]
	v_pk_mul_f32 v[60:61], v[60:61], v[64:65] op_sel_hi:[1,0]
	v_pk_mul_f32 v[58:59], v[58:59], v[64:65] op_sel_hi:[1,0]
	v_pk_mul_f32 v[56:57], v[56:57], v[64:65] op_sel_hi:[1,0]
	v_pk_mul_f32 v[54:55], v[54:55], v[64:65] op_sel_hi:[1,0]
	v_pk_mul_f32 v[52:53], v[52:53], v[64:65] op_sel_hi:[1,0]
	v_pk_mul_f32 v[68:69], v[50:51], v[64:65] op_sel_hi:[1,0]
	v_pk_mul_f32 v[64:65], v[48:49], v[64:65] op_sel_hi:[1,0]
	v_cvt_pk_bf16_f32 v48, v60, v61
	v_cvt_pk_bf16_f32 v49, v62, v63
	v_cvt_pk_bf16_f32 v50, v56, v57
	v_cvt_pk_bf16_f32 v51, v58, v59
	global_store_dwordx4 v[66:67], v[48:51], off
	s_nop 1
	v_cvt_pk_bf16_f32 v48, v52, v53
	v_cvt_pk_bf16_f32 v49, v54, v55
	v_cvt_pk_bf16_f32 v50, v64, v65
	v_cvt_pk_bf16_f32 v51, v68, v69
	global_store_dwordx4 v[66:67], v[48:51], off offset:256
	s_nop 0
	s_nop 0
	v_add_u32_e32 v49, 0x90, v144
	v_mad_i64_i32 v[50:51], s[16:17], v49, s39, v[146:147]
	v_lshl_add_u64 v[50:51], v[50:51], 0, v[148:149]
	s_nop 0
	v_fmamk_f32 v48, v181, 0x3a000000, v168
	v_rsq_f32_e32 v48, v48
	s_nop 0
	v_pk_mul_f32 v[46:47], v[46:47], v[48:49] op_sel_hi:[1,0]
	v_pk_mul_f32 v[44:45], v[44:45], v[48:49] op_sel_hi:[1,0]
	v_pk_mul_f32 v[42:43], v[42:43], v[48:49] op_sel_hi:[1,0]
	v_pk_mul_f32 v[40:41], v[40:41], v[48:49] op_sel_hi:[1,0]
	v_pk_mul_f32 v[38:39], v[38:39], v[48:49] op_sel_hi:[1,0]
	v_pk_mul_f32 v[36:37], v[36:37], v[48:49] op_sel_hi:[1,0]
	v_pk_mul_f32 v[52:53], v[34:35], v[48:49] op_sel_hi:[1,0]
	v_pk_mul_f32 v[48:49], v[32:33], v[48:49] op_sel_hi:[1,0]
	v_cvt_pk_bf16_f32 v32, v44, v45
	v_cvt_pk_bf16_f32 v33, v46, v47
	v_cvt_pk_bf16_f32 v34, v40, v41
	v_cvt_pk_bf16_f32 v35, v42, v43
	global_store_dwordx4 v[50:51], v[32:35], off
	s_nop 1
	v_cvt_pk_bf16_f32 v32, v36, v37
	v_cvt_pk_bf16_f32 v33, v38, v39
	v_cvt_pk_bf16_f32 v34, v48, v49
	v_cvt_pk_bf16_f32 v35, v52, v53
	global_store_dwordx4 v[50:51], v[32:35], off offset:256
	s_nop 0
	s_nop 0
	v_add_u32_e32 v33, 0xa0, v144
	v_mad_i64_i32 v[34:35], s[16:17], v33, s39, v[146:147]
	v_lshl_add_u64 v[34:35], v[34:35], 0, v[148:149]
	s_mov_b64 s[16:17], s[12:13]
	s_nop 0
	v_fmamk_f32 v32, v182, 0x3a000000, v168
	v_rsq_f32_e32 v32, v32
	s_nop 0
	v_pk_mul_f32 v[30:31], v[30:31], v[32:33] op_sel_hi:[1,0]
	v_pk_mul_f32 v[28:29], v[28:29], v[32:33] op_sel_hi:[1,0]
	v_pk_mul_f32 v[26:27], v[26:27], v[32:33] op_sel_hi:[1,0]
	v_pk_mul_f32 v[24:25], v[24:25], v[32:33] op_sel_hi:[1,0]
	v_pk_mul_f32 v[22:23], v[22:23], v[32:33] op_sel_hi:[1,0]
	v_pk_mul_f32 v[20:21], v[20:21], v[32:33] op_sel_hi:[1,0]
	v_pk_mul_f32 v[36:37], v[18:19], v[32:33] op_sel_hi:[1,0]
	v_pk_mul_f32 v[32:33], v[16:17], v[32:33] op_sel_hi:[1,0]
	v_cvt_pk_bf16_f32 v16, v28, v29
	v_cvt_pk_bf16_f32 v17, v30, v31
	v_cvt_pk_bf16_f32 v18, v24, v25
	v_cvt_pk_bf16_f32 v19, v26, v27
	global_store_dwordx4 v[34:35], v[16:19], off
	s_nop 1
	v_cvt_pk_bf16_f32 v16, v20, v21
	v_cvt_pk_bf16_f32 v17, v22, v23
	v_cvt_pk_bf16_f32 v18, v32, v33
	v_cvt_pk_bf16_f32 v19, v36, v37
	global_store_dwordx4 v[34:35], v[16:19], off offset:256
	s_nop 0
	s_nop 0
	v_add_u32_e32 v17, 0xb0, v144
	v_mad_i64_i32 v[18:19], s[4:5], v17, s39, v[146:147]
	v_lshl_add_u64 v[18:19], v[18:19], 0, v[148:149]
	s_nop 0
	v_fmamk_f32 v16, v183, 0x3a000000, v168
	v_rsq_f32_e32 v16, v16
	s_nop 0
	v_pk_mul_f32 v[14:15], v[14:15], v[16:17] op_sel_hi:[1,0]
	v_pk_mul_f32 v[12:13], v[12:13], v[16:17] op_sel_hi:[1,0]
	v_pk_mul_f32 v[10:11], v[10:11], v[16:17] op_sel_hi:[1,0]
	v_pk_mul_f32 v[8:9], v[8:9], v[16:17] op_sel_hi:[1,0]
	v_pk_mul_f32 v[6:7], v[6:7], v[16:17] op_sel_hi:[1,0]
	v_pk_mul_f32 v[4:5], v[4:5], v[16:17] op_sel_hi:[1,0]
	v_pk_mul_f32 v[20:21], v[2:3], v[16:17] op_sel_hi:[1,0]
	v_pk_mul_f32 v[16:17], v[0:1], v[16:17] op_sel_hi:[1,0]
	v_cvt_pk_bf16_f32 v0, v12, v13
	v_cvt_pk_bf16_f32 v1, v14, v15
	v_cvt_pk_bf16_f32 v2, v8, v9
	v_cvt_pk_bf16_f32 v3, v10, v11
	global_store_dwordx4 v[18:19], v[0:3], off
	s_nop 1
	v_cvt_pk_bf16_f32 v0, v4, v5
	v_cvt_pk_bf16_f32 v1, v6, v7
	v_cvt_pk_bf16_f32 v2, v16, v17
	v_cvt_pk_bf16_f32 v3, v20, v21
	global_store_dwordx4 v[18:19], v[0:3], off offset:256
	s_cbranch_vccz .LBB0_144
	s_waitcnt vmcnt(0)
	s_cmpk_gt_u32 s3, 0xff
	s_cbranch_scc1 .LBB0_151
	s_barrier

.LBB0_282:
	s_ashr_i32 s11, s10, 31
	s_lshl_b64 s[16:17], s[10:11], 20
	s_add_u32 s16, s22, s16
	s_addc_u32 s17, s23, s17
	s_and_b64 s[6:7], s[6:7], exec
	s_cselect_b32 s1, s17, s19
	s_cselect_b32 s11, s16, s18
	s_add_u32 s6, s20, 0x180080
	s_addc_u32 s7, s21, 0
	s_add_u32 s43, s18, 0x100
	v_mov_b32_e32 v0, 0
	s_addc_u32 s44, s19, 0
	s_mov_b32 s45, -2
	s_waitcnt lgkmcnt(0)
	v_mov_b32_e32 v1, v0
	v_mov_b32_e32 v2, v0
	v_mov_b32_e32 v3, v0
	v_mov_b32_e32 v4, v0
	v_mov_b32_e32 v5, v0
	v_mov_b32_e32 v6, v0
	v_mov_b32_e32 v7, v0
	s_waitcnt vmcnt(0)
	v_mov_b32_e32 v16, v0
	v_mov_b32_e32 v17, v0
	v_mov_b32_e32 v18, v0
	v_mov_b32_e32 v19, v0
	v_mov_b32_e32 v20, v0
	v_mov_b32_e32 v21, v0
	v_mov_b32_e32 v22, v0
	v_mov_b32_e32 v23, v0
	v_mov_b32_e32 v32, v0
	v_mov_b32_e32 v33, v0
	v_mov_b32_e32 v34, v0
	v_mov_b32_e32 v35, v0
	v_mov_b32_e32 v36, v0
	v_mov_b32_e32 v37, v0
	v_mov_b32_e32 v38, v0
	v_mov_b32_e32 v39, v0
	v_mov_b32_e32 v48, v0
	v_mov_b32_e32 v49, v0
	v_mov_b32_e32 v50, v0
	v_mov_b32_e32 v51, v0
	v_mov_b32_e32 v52, v0
	v_mov_b32_e32 v53, v0
	v_mov_b32_e32 v54, v0
	v_mov_b32_e32 v55, v0
	v_mov_b32_e32 v8, v0
	v_mov_b32_e32 v9, v0
	v_mov_b32_e32 v10, v0
	v_mov_b32_e32 v11, v0
	v_mov_b32_e32 v12, v0
	v_mov_b32_e32 v13, v0
	v_mov_b32_e32 v14, v0
	v_mov_b32_e32 v15, v0
	v_mov_b32_e32 v24, v0
	v_mov_b32_e32 v25, v0
	v_mov_b32_e32 v26, v0
	v_mov_b32_e32 v27, v0
	v_mov_b32_e32 v28, v0
	v_mov_b32_e32 v29, v0
	v_mov_b32_e32 v30, v0
	v_mov_b32_e32 v31, v0
	v_mov_b32_e32 v40, v0
	v_mov_b32_e32 v41, v0
	v_mov_b32_e32 v42, v0
	v_mov_b32_e32 v43, v0
	v_mov_b32_e32 v44, v0
	v_mov_b32_e32 v45, v0
	v_mov_b32_e32 v46, v0
	v_mov_b32_e32 v47, v0
	v_mov_b32_e32 v56, v0
	v_mov_b32_e32 v57, v0
	v_mov_b32_e32 v58, v0
	v_mov_b32_e32 v59, v0
	v_mov_b32_e32 v60, v0
	v_mov_b32_e32 v61, v0
	v_mov_b32_e32 v62, v0
	v_mov_b32_e32 v63, v0
	v_mov_b32_e32 v64, v0
	v_mov_b32_e32 v65, v0
	v_mov_b32_e32 v66, v0
	v_mov_b32_e32 v67, v0
	v_mov_b32_e32 v68, v0
	v_mov_b32_e32 v69, v0
	v_mov_b32_e32 v70, v0
	v_mov_b32_e32 v71, v0
	v_mov_b32_e32 v80, v0
	v_mov_b32_e32 v81, v0
	v_mov_b32_e32 v82, v0
	v_mov_b32_e32 v83, v0
	v_mov_b32_e32 v84, v0
	v_mov_b32_e32 v85, v0
	v_mov_b32_e32 v86, v0
	v_mov_b32_e32 v87, v0
	v_mov_b32_e32 v96, v0
	v_mov_b32_e32 v97, v0
	v_mov_b32_e32 v98, v0
	v_mov_b32_e32 v99, v0
	v_mov_b32_e32 v100, v0
	v_mov_b32_e32 v101, v0
	v_mov_b32_e32 v102, v0
	v_mov_b32_e32 v103, v0
	v_mov_b32_e32 v112, v0
	v_mov_b32_e32 v113, v0
	v_mov_b32_e32 v114, v0
	v_mov_b32_e32 v115, v0
	v_mov_b32_e32 v116, v0
	v_mov_b32_e32 v117, v0
	v_mov_b32_e32 v118, v0
	v_mov_b32_e32 v119, v0
	v_mov_b32_e32 v72, v0
	v_mov_b32_e32 v73, v0
	v_mov_b32_e32 v74, v0
	v_mov_b32_e32 v75, v0
	v_mov_b32_e32 v76, v0
	v_mov_b32_e32 v77, v0
	v_mov_b32_e32 v78, v0
	v_mov_b32_e32 v79, v0
	v_mov_b32_e32 v88, v0
	v_mov_b32_e32 v89, v0
	v_mov_b32_e32 v90, v0
	v_mov_b32_e32 v91, v0
	v_mov_b32_e32 v92, v0
	v_mov_b32_e32 v93, v0
	v_mov_b32_e32 v94, v0
	v_mov_b32_e32 v95, v0
	v_mov_b32_e32 v104, v0
	v_mov_b32_e32 v105, v0
	v_mov_b32_e32 v106, v0
	v_mov_b32_e32 v107, v0
	v_mov_b32_e32 v108, v0
	v_mov_b32_e32 v109, v0
	v_mov_b32_e32 v110, v0
	v_mov_b32_e32 v111, v0
	v_mov_b32_e32 v120, v0
	v_mov_b32_e32 v121, v0
	v_mov_b32_e32 v122, v0
	v_mov_b32_e32 v123, v0
	v_mov_b32_e32 v124, v0
	v_mov_b32_e32 v125, v0
	v_mov_b32_e32 v126, v0
	v_mov_b32_e32 v127, v0
	v_xor_b32_e32 v150, 64, v146
	v_xor_b32_e32 v151, 64, v147
	v_xor_b32_e32 v216, 64, v148
	v_add_u32_e32 v217, 0x18000, v145
	v_xor_b32_e32 v220, 64, v217
.LBB0_283:
	ds_read_b128 v[140:143], v146
	ds_read_b128 v[154:157], v150
	ds_read_b128 v[158:161], v146 offset:2048
	ds_read_b128 v[168:171], v150 offset:2048
	s_add_u32 s18, s6, 0xffe80080
	s_addc_u32 s19, s7, -1
	s_cmp_eq_u32 s45, 28
	s_cselect_b32 s21, s15, s19
	s_cselect_b32 s20, s14, s18
	s_cselect_b32 s19, s1, s44
	s_cselect_b32 s18, s11, s43
	s_add_i32 m0, s25, 0xc000
	ds_read_b128 v[172:175], v147
	ds_read_b128 v[176:179], v151
	ds_read_b128 v[180:183], v147 offset:2048
	ds_read_b128 v[184:187], v151 offset:2048
	ds_read_b128 v[188:191], v147 offset:4096
	ds_read_b128 v[192:195], v151 offset:4096
	ds_read_b128 v[196:199], v147 offset:6144
	ds_read_b128 v[200:203], v151 offset:6144
	global_load_lds_dwordx4 v132, s[6:7]
	s_add_i32 m0, s25, 0xe000
	s_nop 0
	global_load_lds_dwordx4 v134, s[6:7]
	s_waitcnt lgkmcnt(8)
	s_barrier
	s_waitcnt lgkmcnt(0)
	s_setprio 1
	s_waitcnt lgkmcnt(0)
	v_mfma_f32_16x16x32_bf16 v[124:127], v[140:143], v[172:175], v[124:127]
	v_mfma_f32_16x16x32_bf16 v[124:127], v[154:157], v[176:179], v[124:127]
	v_mfma_f32_16x16x32_bf16 v[120:123], v[168:171], v[176:179], v[120:123]
	v_mfma_f32_16x16x32_bf16 v[120:123], v[158:161], v[172:175], v[120:123]
	v_mfma_f32_16x16x32_bf16 v[104:107], v[158:161], v[180:183], v[104:107]
	v_mfma_f32_16x16x32_bf16 v[104:107], v[168:171], v[184:187], v[104:107]
	v_mfma_f32_16x16x32_bf16 v[108:111], v[154:157], v[184:187], v[108:111]
	v_mfma_f32_16x16x32_bf16 v[108:111], v[140:143], v[180:183], v[108:111]
	v_mfma_f32_16x16x32_bf16 v[92:95], v[140:143], v[188:191], v[92:95]
	v_mfma_f32_16x16x32_bf16 v[92:95], v[154:157], v[192:195], v[92:95]
	v_mfma_f32_16x16x32_bf16 v[88:91], v[168:171], v[192:195], v[88:91]
	v_mfma_f32_16x16x32_bf16 v[88:91], v[158:161], v[188:191], v[88:91]
	v_mfma_f32_16x16x32_bf16 v[72:75], v[158:161], v[196:199], v[72:75]
	v_mfma_f32_16x16x32_bf16 v[72:75], v[168:171], v[200:203], v[72:75]
	v_mfma_f32_16x16x32_bf16 v[76:79], v[154:157], v[200:203], v[76:79]
	v_mfma_f32_16x16x32_bf16 v[76:79], v[140:143], v[196:199], v[76:79]
	s_setprio 0
	s_barrier
	s_add_i32 s46, s39, s24
	s_add_u32 s98, s18, s8
	s_addc_u32 s99, s19, s9
	s_mov_b32 m0, s46
	ds_read_b128 v[204:207], v148
	ds_read_b128 v[208:211], v216
	ds_read_b128 v[212:215], v148 offset:2048
	ds_read_b128 v[242:245], v216 offset:2048
	global_load_lds_dwordx4 v164, s[18:19]
	s_add_i32 m0, s46, 0x2000
	s_nop 0
	global_load_lds_dwordx4 v166, s[18:19]
	s_barrier
	s_waitcnt lgkmcnt(0)
	s_setprio 1
	s_waitcnt lgkmcnt(0)
	v_mfma_f32_16x16x32_bf16 v[116:119], v[204:207], v[172:175], v[116:119]
	v_mfma_f32_16x16x32_bf16 v[116:119], v[208:211], v[176:179], v[116:119]
	v_mfma_f32_16x16x32_bf16 v[112:115], v[242:245], v[176:179], v[112:115]
	v_mfma_f32_16x16x32_bf16 v[112:115], v[212:215], v[172:175], v[112:115]
	v_mfma_f32_16x16x32_bf16 v[96:99], v[212:215], v[180:183], v[96:99]
	v_mfma_f32_16x16x32_bf16 v[96:99], v[242:245], v[184:187], v[96:99]
	v_mfma_f32_16x16x32_bf16 v[100:103], v[208:211], v[184:187], v[100:103]
	v_mfma_f32_16x16x32_bf16 v[100:103], v[204:207], v[180:183], v[100:103]
	v_mfma_f32_16x16x32_bf16 v[84:87], v[204:207], v[188:191], v[84:87]
	v_mfma_f32_16x16x32_bf16 v[84:87], v[208:211], v[192:195], v[84:87]
	v_mfma_f32_16x16x32_bf16 v[80:83], v[242:245], v[192:195], v[80:83]
	v_mfma_f32_16x16x32_bf16 v[80:83], v[212:215], v[188:191], v[80:83]
	v_mfma_f32_16x16x32_bf16 v[64:67], v[212:215], v[196:199], v[64:67]
	v_mfma_f32_16x16x32_bf16 v[64:67], v[242:245], v[200:203], v[64:67]
	v_mfma_f32_16x16x32_bf16 v[68:71], v[208:211], v[200:203], v[68:71]
	v_mfma_f32_16x16x32_bf16 v[68:71], v[204:207], v[196:199], v[68:71]
	s_setprio 0
	s_mov_b32 m0, s25
	s_add_u32 s100, s20, s8
	s_addc_u32 s101, s21, s9
	s_barrier
	ds_read_b128 v[172:175], v147 offset:16384
	ds_read_b128 v[176:179], v151 offset:16384
	ds_read_b128 v[180:183], v147 offset:18432
	ds_read_b128 v[184:187], v151 offset:18432
	ds_read_b128 v[188:191], v147 offset:20480
	ds_read_b128 v[192:195], v151 offset:20480
	ds_read_b128 v[196:199], v147 offset:22528
	ds_read_b128 v[200:203], v151 offset:22528
	global_load_lds_dwordx4 v128, s[20:21]
	s_mov_b32 m0, s26
	s_nop 0
	global_load_lds_dwordx4 v130, s[20:21]
	s_barrier
	s_waitcnt lgkmcnt(0)
	s_setprio 1
	s_waitcnt lgkmcnt(0)
	v_mfma_f32_16x16x32_bf16 v[60:63], v[140:143], v[172:175], v[60:63]
	v_mfma_f32_16x16x32_bf16 v[60:63], v[154:157], v[176:179], v[60:63]
	v_mfma_f32_16x16x32_bf16 v[56:59], v[168:171], v[176:179], v[56:59]
	v_mfma_f32_16x16x32_bf16 v[56:59], v[158:161], v[172:175], v[56:59]
	v_mfma_f32_16x16x32_bf16 v[40:43], v[158:161], v[180:183], v[40:43]
	v_mfma_f32_16x16x32_bf16 v[40:43], v[168:171], v[184:187], v[40:43]
	v_mfma_f32_16x16x32_bf16 v[44:47], v[154:157], v[184:187], v[44:47]
	v_mfma_f32_16x16x32_bf16 v[44:47], v[140:143], v[180:183], v[44:47]
	v_mfma_f32_16x16x32_bf16 v[28:31], v[140:143], v[188:191], v[28:31]
	v_mfma_f32_16x16x32_bf16 v[28:31], v[154:157], v[192:195], v[28:31]
	v_mfma_f32_16x16x32_bf16 v[24:27], v[168:171], v[192:195], v[24:27]
	v_mfma_f32_16x16x32_bf16 v[24:27], v[158:161], v[188:191], v[24:27]
	v_mfma_f32_16x16x32_bf16 v[8:11], v[158:161], v[196:199], v[8:11]
	v_mfma_f32_16x16x32_bf16 v[8:11], v[168:171], v[200:203], v[8:11]
	v_mfma_f32_16x16x32_bf16 v[12:15], v[154:157], v[200:203], v[12:15]
	v_mfma_f32_16x16x32_bf16 v[12:15], v[140:143], v[196:199], v[12:15]
	s_setprio 0
	s_barrier
	s_add_u32 s46, s18, 0x80000
	s_addc_u32 s47, s19, 0
	s_add_i32 s48, s40, s24
	s_mov_b32 m0, s48
	s_nop 0
	global_load_lds_dwordx4 v164, s[46:47]
	s_add_i32 m0, s48, 0x2000
	s_nop 0
	global_load_lds_dwordx4 v166, s[46:47]
	s_waitcnt vmcnt(6)
	s_barrier
	s_setprio 1
	v_mfma_f32_16x16x32_bf16 v[52:55], v[204:207], v[172:175], v[52:55]
	v_mfma_f32_16x16x32_bf16 v[52:55], v[208:211], v[176:179], v[52:55]
	v_mfma_f32_16x16x32_bf16 v[48:51], v[242:245], v[176:179], v[48:51]
	v_mfma_f32_16x16x32_bf16 v[48:51], v[212:215], v[172:175], v[48:51]
	v_mfma_f32_16x16x32_bf16 v[32:35], v[212:215], v[180:183], v[32:35]
	v_mfma_f32_16x16x32_bf16 v[32:35], v[242:245], v[184:187], v[32:35]
	v_mfma_f32_16x16x32_bf16 v[36:39], v[208:211], v[184:187], v[36:39]
	v_mfma_f32_16x16x32_bf16 v[36:39], v[204:207], v[180:183], v[36:39]
	v_mfma_f32_16x16x32_bf16 v[20:23], v[204:207], v[188:191], v[20:23]
	v_mfma_f32_16x16x32_bf16 v[20:23], v[208:211], v[192:195], v[20:23]
	v_mfma_f32_16x16x32_bf16 v[16:19], v[242:245], v[192:195], v[16:19]
	v_mfma_f32_16x16x32_bf16 v[16:19], v[212:215], v[188:191], v[16:19]
	v_mfma_f32_16x16x32_bf16 v[0:3], v[212:215], v[196:199], v[0:3]
	v_mfma_f32_16x16x32_bf16 v[0:3], v[242:245], v[200:203], v[0:3]
	v_mfma_f32_16x16x32_bf16 v[4:7], v[208:211], v[200:203], v[4:7]
	v_mfma_f32_16x16x32_bf16 v[4:7], v[204:207], v[196:199], v[4:7]
	s_setprio 0
	s_add_i32 s46, 0, 0x18000
	s_barrier
	ds_read_b128 v[140:143], v217
	ds_read_b128 v[154:157], v220
	ds_read_b128 v[158:161], v217 offset:2048
	ds_read_b128 v[168:171], v220 offset:2048
	s_add_u32 s20, s20, 0x180000
	s_addc_u32 s21, s21, 0
	s_mov_b32 m0, s27
	ds_read_b128 v[172:175], v147 offset:32768
	ds_read_b128 v[176:179], v151 offset:32768
	ds_read_b128 v[180:183], v147 offset:34816
	ds_read_b128 v[184:187], v151 offset:34816
	ds_read_b128 v[188:191], v147 offset:36864
	ds_read_b128 v[192:195], v151 offset:36864
	ds_read_b128 v[196:199], v147 offset:38912
	ds_read_b128 v[200:203], v151 offset:38912
	global_load_lds_dwordx4 v128, s[20:21]
	s_mov_b32 m0, s28
	s_nop 0
	global_load_lds_dwordx4 v130, s[20:21]
	s_waitcnt lgkmcnt(8)
	s_barrier
	s_waitcnt lgkmcnt(0)
	s_setprio 1
	s_waitcnt lgkmcnt(0)
	v_mfma_f32_16x16x32_bf16 v[124:127], v[140:143], v[172:175], v[124:127]
	v_mfma_f32_16x16x32_bf16 v[124:127], v[154:157], v[176:179], v[124:127]
	v_mfma_f32_16x16x32_bf16 v[120:123], v[168:171], v[176:179], v[120:123]
	v_mfma_f32_16x16x32_bf16 v[120:123], v[158:161], v[172:175], v[120:123]
	v_mfma_f32_16x16x32_bf16 v[104:107], v[158:161], v[180:183], v[104:107]
	v_mfma_f32_16x16x32_bf16 v[104:107], v[168:171], v[184:187], v[104:107]
	v_mfma_f32_16x16x32_bf16 v[108:111], v[154:157], v[184:187], v[108:111]
	v_mfma_f32_16x16x32_bf16 v[108:111], v[140:143], v[180:183], v[108:111]
	v_mfma_f32_16x16x32_bf16 v[92:95], v[140:143], v[188:191], v[92:95]
	v_mfma_f32_16x16x32_bf16 v[92:95], v[154:157], v[192:195], v[92:95]
	v_mfma_f32_16x16x32_bf16 v[88:91], v[168:171], v[192:195], v[88:91]
	v_mfma_f32_16x16x32_bf16 v[88:91], v[158:161], v[188:191], v[88:91]
	v_mfma_f32_16x16x32_bf16 v[72:75], v[158:161], v[196:199], v[72:75]
	v_mfma_f32_16x16x32_bf16 v[72:75], v[168:171], v[200:203], v[72:75]
	v_mfma_f32_16x16x32_bf16 v[76:79], v[154:157], v[200:203], v[76:79]
	v_mfma_f32_16x16x32_bf16 v[76:79], v[140:143], v[196:199], v[76:79]
	s_setprio 0
	s_barrier
	s_add_i32 s20, 0, 0x1c000
	s_add_i32 s21, s46, s24
	v_add_u32_e32 v223, s20, v145
	s_mov_b32 m0, s21
	ds_read_b128 v[204:207], v223
	v_xor_b32_e32 v245, 64, v223
	ds_read_b128 v[208:211], v245
	ds_read_b128 v[212:215], v223 offset:2048
	ds_read_b128 v[242:245], v245 offset:2048
	global_load_lds_dwordx4 v164, s[98:99]
	s_add_i32 m0, s21, 0x2000
	s_nop 0
	global_load_lds_dwordx4 v166, s[98:99]
	s_barrier
	s_waitcnt lgkmcnt(0)
	s_setprio 1
	s_waitcnt lgkmcnt(0)
	v_mfma_f32_16x16x32_bf16 v[116:119], v[204:207], v[172:175], v[116:119]
	v_mfma_f32_16x16x32_bf16 v[116:119], v[208:211], v[176:179], v[116:119]
	v_mfma_f32_16x16x32_bf16 v[112:115], v[242:245], v[176:179], v[112:115]
	v_mfma_f32_16x16x32_bf16 v[112:115], v[212:215], v[172:175], v[112:115]
	v_mfma_f32_16x16x32_bf16 v[96:99], v[212:215], v[180:183], v[96:99]
	v_mfma_f32_16x16x32_bf16 v[96:99], v[242:245], v[184:187], v[96:99]
	v_mfma_f32_16x16x32_bf16 v[100:103], v[208:211], v[184:187], v[100:103]
	v_mfma_f32_16x16x32_bf16 v[100:103], v[204:207], v[180:183], v[100:103]
	v_mfma_f32_16x16x32_bf16 v[84:87], v[204:207], v[188:191], v[84:87]
	v_mfma_f32_16x16x32_bf16 v[84:87], v[208:211], v[192:195], v[84:87]
	v_mfma_f32_16x16x32_bf16 v[80:83], v[242:245], v[192:195], v[80:83]
	v_mfma_f32_16x16x32_bf16 v[80:83], v[212:215], v[188:191], v[80:83]
	v_mfma_f32_16x16x32_bf16 v[64:67], v[212:215], v[196:199], v[64:67]
	v_mfma_f32_16x16x32_bf16 v[64:67], v[242:245], v[200:203], v[64:67]
	v_mfma_f32_16x16x32_bf16 v[68:71], v[208:211], v[200:203], v[68:71]
	v_mfma_f32_16x16x32_bf16 v[68:71], v[204:207], v[196:199], v[68:71]
	s_setprio 0
	s_mov_b32 m0, s33
	s_barrier
	ds_read_b128 v[172:175], v147 offset:49152
	ds_read_b128 v[176:179], v151 offset:49152
	ds_read_b128 v[180:183], v147 offset:51200
	ds_read_b128 v[184:187], v151 offset:51200
	ds_read_b128 v[188:191], v147 offset:53248
	ds_read_b128 v[192:195], v151 offset:53248
	ds_read_b128 v[196:199], v147 offset:55296
	ds_read_b128 v[200:203], v151 offset:55296
	global_load_lds_dwordx4 v128, s[100:101]
	s_mov_b32 m0, s34
	s_nop 0
	global_load_lds_dwordx4 v130, s[100:101]
	s_barrier
	s_waitcnt lgkmcnt(0)
	s_setprio 1
	s_waitcnt lgkmcnt(0)
	v_mfma_f32_16x16x32_bf16 v[60:63], v[140:143], v[172:175], v[60:63]
	v_mfma_f32_16x16x32_bf16 v[60:63], v[154:157], v[176:179], v[60:63]
	v_mfma_f32_16x16x32_bf16 v[56:59], v[168:171], v[176:179], v[56:59]
	v_mfma_f32_16x16x32_bf16 v[56:59], v[158:161], v[172:175], v[56:59]
	v_mfma_f32_16x16x32_bf16 v[40:43], v[158:161], v[180:183], v[40:43]
	v_mfma_f32_16x16x32_bf16 v[40:43], v[168:171], v[184:187], v[40:43]
	v_mfma_f32_16x16x32_bf16 v[44:47], v[154:157], v[184:187], v[44:47]
	v_mfma_f32_16x16x32_bf16 v[44:47], v[140:143], v[180:183], v[44:47]
	v_mfma_f32_16x16x32_bf16 v[28:31], v[140:143], v[188:191], v[28:31]
	v_mfma_f32_16x16x32_bf16 v[28:31], v[154:157], v[192:195], v[28:31]
	v_mfma_f32_16x16x32_bf16 v[24:27], v[168:171], v[192:195], v[24:27]
	v_mfma_f32_16x16x32_bf16 v[24:27], v[158:161], v[188:191], v[24:27]
	v_mfma_f32_16x16x32_bf16 v[8:11], v[158:161], v[196:199], v[8:11]
	v_mfma_f32_16x16x32_bf16 v[8:11], v[168:171], v[200:203], v[8:11]
	v_mfma_f32_16x16x32_bf16 v[12:15], v[154:157], v[200:203], v[12:15]
	v_mfma_f32_16x16x32_bf16 v[12:15], v[140:143], v[196:199], v[12:15]
	s_setprio 0
	s_barrier
	s_add_u32 s18, s18, 0x80080
	s_addc_u32 s19, s19, 0
	s_add_i32 s20, s20, s24
	s_mov_b32 m0, s20
	s_nop 0
	global_load_lds_dwordx4 v164, s[18:19]
	s_add_i32 m0, s20, 0x2000
	s_nop 0
	global_load_lds_dwordx4 v166, s[18:19]
	s_waitcnt vmcnt(6)
	s_barrier
	s_setprio 1
	v_mfma_f32_16x16x32_bf16 v[52:55], v[204:207], v[172:175], v[52:55]
	v_mfma_f32_16x16x32_bf16 v[52:55], v[208:211], v[176:179], v[52:55]
	v_mfma_f32_16x16x32_bf16 v[48:51], v[242:245], v[176:179], v[48:51]
	v_mfma_f32_16x16x32_bf16 v[48:51], v[212:215], v[172:175], v[48:51]
	v_mfma_f32_16x16x32_bf16 v[32:35], v[212:215], v[180:183], v[32:35]
	v_mfma_f32_16x16x32_bf16 v[32:35], v[242:245], v[184:187], v[32:35]
	v_mfma_f32_16x16x32_bf16 v[36:39], v[208:211], v[184:187], v[36:39]
	v_mfma_f32_16x16x32_bf16 v[36:39], v[204:207], v[180:183], v[36:39]
	v_mfma_f32_16x16x32_bf16 v[20:23], v[204:207], v[188:191], v[20:23]
	v_mfma_f32_16x16x32_bf16 v[20:23], v[208:211], v[192:195], v[20:23]
	v_mfma_f32_16x16x32_bf16 v[16:19], v[242:245], v[192:195], v[16:19]
	v_mfma_f32_16x16x32_bf16 v[16:19], v[212:215], v[188:191], v[16:19]
	v_mfma_f32_16x16x32_bf16 v[0:3], v[212:215], v[196:199], v[0:3]
	v_mfma_f32_16x16x32_bf16 v[0:3], v[242:245], v[200:203], v[0:3]
	v_mfma_f32_16x16x32_bf16 v[4:7], v[208:211], v[200:203], v[4:7]
	v_mfma_f32_16x16x32_bf16 v[4:7], v[204:207], v[196:199], v[4:7]
	s_setprio 0
	s_add_i32 s45, s45, 2
	s_add_u32 s6, s6, 0x100
	s_addc_u32 s7, s7, 0
	s_add_u32 s43, s43, 0x100
	s_addc_u32 s44, s44, 0
	s_cmp_gt_u32 s45, 29
	s_barrier
	s_cbranch_scc0 .LBB0_283
	v_lshl_add_u32 v217, s42, 8, v163
	v_add_u32_e32 v217, s30, v217
	v_lshlrev_b32_e32 v208, 2, v217
	v_lshl_add_u32 v214, v225, 3, s31
	v_lshl_add_u32 v214, s0, 8, v214
	v_lshl_add_u32 v209, v217, 11, v214
	v_lshlrev_b32_e32 v209, 1, v209
	v_lshlrev_b32_e32 v210, 1, v209
	v_lshl_add_u32 v217, v225, 4, v163
	v_xor_b32_e32 v215, 16, v217
	v_lshlrev_b32_e32 v215, 2, v215
	v_xor_b32_e32 v216, 32, v217
	v_lshlrev_b32_e32 v216, 2, v216
	v_add_u32_e32 v212, 0x0, v210
	global_load_dwordx4 v[176:179], v212, s[36:37]
	global_load_dwordx4 v[180:183], v212, s[36:37] offset:16
	global_load_dwordx4 v[184:187], v212, s[36:37] offset:512
	global_load_dwordx4 v[188:191], v212, s[36:37] offset:528
	v_add_u32_e32 v212, 0x20000, v210
	global_load_dwordx4 v[192:195], v212, s[36:37]
	global_load_dwordx4 v[196:199], v212, s[36:37] offset:16
	global_load_dwordx4 v[200:203], v212, s[36:37] offset:512
	global_load_dwordx4 v[204:207], v212, s[36:37] offset:528
	s_waitcnt vmcnt(4)
	v_pk_add_f32 v[124:125], v[124:125], v[176:177]
	v_pk_add_f32 v[126:127], v[126:127], v[178:179]
	v_pk_add_f32 v[120:121], v[120:121], v[180:181]
	v_pk_add_f32 v[122:123], v[122:123], v[182:183]
	v_mul_f32_e32 v213, v124, v124
	v_fmac_f32_e32 v213, v125, v125
	v_fmac_f32_e32 v213, v126, v126
	v_fmac_f32_e32 v213, v127, v127
	v_fmac_f32_e32 v213, v120, v120
	v_fmac_f32_e32 v213, v121, v121
	v_fmac_f32_e32 v213, v122, v122
	v_fmac_f32_e32 v213, v123, v123
	v_cvt_pk_bf16_f32 v176, v124, v125
	v_cvt_pk_bf16_f32 v177, v126, v127
	v_cvt_pk_bf16_f32 v178, v120, v121
	v_cvt_pk_bf16_f32 v179, v122, v123
	v_add_u32_e32 v217, 0x0, v209
	global_store_dwordx4 v217, v[176:179], s[80:81]
	v_pk_add_f32 v[116:117], v[116:117], v[184:185]
	v_pk_add_f32 v[118:119], v[118:119], v[186:187]
	v_pk_add_f32 v[112:113], v[112:113], v[188:189]
	v_pk_add_f32 v[114:115], v[114:115], v[190:191]
	v_fmac_f32_e32 v213, v116, v116
	v_fmac_f32_e32 v213, v117, v117
	v_fmac_f32_e32 v213, v118, v118
	v_fmac_f32_e32 v213, v119, v119
	v_fmac_f32_e32 v213, v112, v112
	v_fmac_f32_e32 v213, v113, v113
	v_fmac_f32_e32 v213, v114, v114
	v_fmac_f32_e32 v213, v115, v115
	v_cvt_pk_bf16_f32 v184, v116, v117
	v_cvt_pk_bf16_f32 v185, v118, v119
	v_cvt_pk_bf16_f32 v186, v112, v113
	v_cvt_pk_bf16_f32 v187, v114, v115
	global_store_dwordx4 v217, v[184:187], s[80:81] offset:256
	ds_bpermute_b32 v214, v215, v213
	s_waitcnt lgkmcnt(0)
	v_add_f32_e32 v213, v213, v214
	ds_bpermute_b32 v214, v216, v213
	s_waitcnt lgkmcnt(0)
	v_add_f32_e32 v213, v213, v214
	s_mov_b64 exec, 0xffff
	global_atomic_add_f32 v208, v213, s[12:13]
	s_mov_b64 exec, -1
	v_add_u32_e32 v212, 0x40000, v210
	global_load_dwordx4 v[176:179], v212, s[36:37]
	global_load_dwordx4 v[180:183], v212, s[36:37] offset:16
	global_load_dwordx4 v[184:187], v212, s[36:37] offset:512
	global_load_dwordx4 v[188:191], v212, s[36:37] offset:528
	s_waitcnt vmcnt(7)
	v_pk_add_f32 v[108:109], v[108:109], v[192:193]
	v_pk_add_f32 v[110:111], v[110:111], v[194:195]
	v_pk_add_f32 v[104:105], v[104:105], v[196:197]
	v_pk_add_f32 v[106:107], v[106:107], v[198:199]
	v_mul_f32_e32 v213, v108, v108
	v_fmac_f32_e32 v213, v109, v109
	v_fmac_f32_e32 v213, v110, v110
	v_fmac_f32_e32 v213, v111, v111
	v_fmac_f32_e32 v213, v104, v104
	v_fmac_f32_e32 v213, v105, v105
	v_fmac_f32_e32 v213, v106, v106
	v_fmac_f32_e32 v213, v107, v107
	v_cvt_pk_bf16_f32 v192, v108, v109
	v_cvt_pk_bf16_f32 v193, v110, v111
	v_cvt_pk_bf16_f32 v194, v104, v105
	v_cvt_pk_bf16_f32 v195, v106, v107
	v_add_u32_e32 v217, 0x10000, v209
	global_store_dwordx4 v217, v[192:195], s[80:81]
	v_pk_add_f32 v[100:101], v[100:101], v[200:201]
	v_pk_add_f32 v[102:103], v[102:103], v[202:203]
	v_pk_add_f32 v[96:97], v[96:97], v[204:205]
	v_pk_add_f32 v[98:99], v[98:99], v[206:207]
	v_fmac_f32_e32 v213, v100, v100
	v_fmac_f32_e32 v213, v101, v101
	v_fmac_f32_e32 v213, v102, v102
	v_fmac_f32_e32 v213, v103, v103
	v_fmac_f32_e32 v213, v96, v96
	v_fmac_f32_e32 v213, v97, v97
	v_fmac_f32_e32 v213, v98, v98
	v_fmac_f32_e32 v213, v99, v99
	v_cvt_pk_bf16_f32 v200, v100, v101
	v_cvt_pk_bf16_f32 v201, v102, v103
	v_cvt_pk_bf16_f32 v202, v96, v97
	v_cvt_pk_bf16_f32 v203, v98, v99
	global_store_dwordx4 v217, v[200:203], s[80:81] offset:256
	ds_bpermute_b32 v214, v215, v213
	s_waitcnt lgkmcnt(0)
	v_add_f32_e32 v213, v213, v214
	ds_bpermute_b32 v214, v216, v213
	s_waitcnt lgkmcnt(0)
	v_add_f32_e32 v213, v213, v214
	s_mov_b64 exec, 0xffff
	global_atomic_add_f32 v208, v213, s[12:13] offset:64
	s_mov_b64 exec, -1
	v_add_u32_e32 v212, 0x60000, v210
	global_load_dwordx4 v[192:195], v212, s[36:37]
	global_load_dwordx4 v[196:199], v212, s[36:37] offset:16
	global_load_dwordx4 v[200:203], v212, s[36:37] offset:512
	global_load_dwordx4 v[204:207], v212, s[36:37] offset:528
	s_waitcnt vmcnt(7)
	v_pk_add_f32 v[92:93], v[92:93], v[176:177]
	v_pk_add_f32 v[94:95], v[94:95], v[178:179]
	v_pk_add_f32 v[88:89], v[88:89], v[180:181]
	v_pk_add_f32 v[90:91], v[90:91], v[182:183]
	v_mul_f32_e32 v213, v92, v92
	v_fmac_f32_e32 v213, v93, v93
	v_fmac_f32_e32 v213, v94, v94
	v_fmac_f32_e32 v213, v95, v95
	v_fmac_f32_e32 v213, v88, v88
	v_fmac_f32_e32 v213, v89, v89
	v_fmac_f32_e32 v213, v90, v90
	v_fmac_f32_e32 v213, v91, v91
	v_cvt_pk_bf16_f32 v176, v92, v93
	v_cvt_pk_bf16_f32 v177, v94, v95
	v_cvt_pk_bf16_f32 v178, v88, v89
	v_cvt_pk_bf16_f32 v179, v90, v91
	v_add_u32_e32 v217, 0x20000, v209
	global_store_dwordx4 v217, v[176:179], s[80:81]
	v_pk_add_f32 v[84:85], v[84:85], v[184:185]
	v_pk_add_f32 v[86:87], v[86:87], v[186:187]
	v_pk_add_f32 v[80:81], v[80:81], v[188:189]
	v_pk_add_f32 v[82:83], v[82:83], v[190:191]
	v_fmac_f32_e32 v213, v84, v84
	v_fmac_f32_e32 v213, v85, v85
	v_fmac_f32_e32 v213, v86, v86
	v_fmac_f32_e32 v213, v87, v87
	v_fmac_f32_e32 v213, v80, v80
	v_fmac_f32_e32 v213, v81, v81
	v_fmac_f32_e32 v213, v82, v82
	v_fmac_f32_e32 v213, v83, v83
	v_cvt_pk_bf16_f32 v184, v84, v85
	v_cvt_pk_bf16_f32 v185, v86, v87
	v_cvt_pk_bf16_f32 v186, v80, v81
	v_cvt_pk_bf16_f32 v187, v82, v83
	global_store_dwordx4 v217, v[184:187], s[80:81] offset:256
	ds_bpermute_b32 v214, v215, v213
	s_waitcnt lgkmcnt(0)
	v_add_f32_e32 v213, v213, v214
	ds_bpermute_b32 v214, v216, v213
	s_waitcnt lgkmcnt(0)
	v_add_f32_e32 v213, v213, v214
	s_mov_b64 exec, 0xffff
	global_atomic_add_f32 v208, v213, s[12:13] offset:128
	s_mov_b64 exec, -1
	v_add_u32_e32 v212, 0x100000, v210
	global_load_dwordx4 v[176:179], v212, s[36:37]
	global_load_dwordx4 v[180:183], v212, s[36:37] offset:16
	global_load_dwordx4 v[184:187], v212, s[36:37] offset:512
	global_load_dwordx4 v[188:191], v212, s[36:37] offset:528
	s_waitcnt vmcnt(7)
	v_pk_add_f32 v[76:77], v[76:77], v[192:193]
	v_pk_add_f32 v[78:79], v[78:79], v[194:195]
	v_pk_add_f32 v[72:73], v[72:73], v[196:197]
	v_pk_add_f32 v[74:75], v[74:75], v[198:199]
	v_mul_f32_e32 v213, v76, v76
	v_fmac_f32_e32 v213, v77, v77
	v_fmac_f32_e32 v213, v78, v78
	v_fmac_f32_e32 v213, v79, v79
	v_fmac_f32_e32 v213, v72, v72
	v_fmac_f32_e32 v213, v73, v73
	v_fmac_f32_e32 v213, v74, v74
	v_fmac_f32_e32 v213, v75, v75
	v_cvt_pk_bf16_f32 v192, v76, v77
	v_cvt_pk_bf16_f32 v193, v78, v79
	v_cvt_pk_bf16_f32 v194, v72, v73
	v_cvt_pk_bf16_f32 v195, v74, v75
	v_add_u32_e32 v217, 0x30000, v209
	global_store_dwordx4 v217, v[192:195], s[80:81]
	v_pk_add_f32 v[68:69], v[68:69], v[200:201]
	v_pk_add_f32 v[70:71], v[70:71], v[202:203]
	v_pk_add_f32 v[64:65], v[64:65], v[204:205]
	v_pk_add_f32 v[66:67], v[66:67], v[206:207]
	v_fmac_f32_e32 v213, v68, v68
	v_fmac_f32_e32 v213, v69, v69
	v_fmac_f32_e32 v213, v70, v70
	v_fmac_f32_e32 v213, v71, v71
	v_fmac_f32_e32 v213, v64, v64
	v_fmac_f32_e32 v213, v65, v65
	v_fmac_f32_e32 v213, v66, v66
	v_fmac_f32_e32 v213, v67, v67
	v_cvt_pk_bf16_f32 v200, v68, v69
	v_cvt_pk_bf16_f32 v201, v70, v71
	v_cvt_pk_bf16_f32 v202, v64, v65
	v_cvt_pk_bf16_f32 v203, v66, v67
	global_store_dwordx4 v217, v[200:203], s[80:81] offset:256
	ds_bpermute_b32 v214, v215, v213
	s_waitcnt lgkmcnt(0)
	v_add_f32_e32 v213, v213, v214
	ds_bpermute_b32 v214, v216, v213
	s_waitcnt lgkmcnt(0)
	v_add_f32_e32 v213, v213, v214
	s_mov_b64 exec, 0xffff
	global_atomic_add_f32 v208, v213, s[12:13] offset:192
	s_mov_b64 exec, -1
	v_add_u32_e32 v212, 0x120000, v210
	global_load_dwordx4 v[192:195], v212, s[36:37]
	global_load_dwordx4 v[196:199], v212, s[36:37] offset:16
	global_load_dwordx4 v[200:203], v212, s[36:37] offset:512
	global_load_dwordx4 v[204:207], v212, s[36:37] offset:528
	s_waitcnt vmcnt(7)
	v_pk_add_f32 v[60:61], v[60:61], v[176:177]
	v_pk_add_f32 v[62:63], v[62:63], v[178:179]
	v_pk_add_f32 v[56:57], v[56:57], v[180:181]
	v_pk_add_f32 v[58:59], v[58:59], v[182:183]
	v_mul_f32_e32 v213, v60, v60
	v_fmac_f32_e32 v213, v61, v61
	v_fmac_f32_e32 v213, v62, v62
	v_fmac_f32_e32 v213, v63, v63
	v_fmac_f32_e32 v213, v56, v56
	v_fmac_f32_e32 v213, v57, v57
	v_fmac_f32_e32 v213, v58, v58
	v_fmac_f32_e32 v213, v59, v59
	v_cvt_pk_bf16_f32 v176, v60, v61
	v_cvt_pk_bf16_f32 v177, v62, v63
	v_cvt_pk_bf16_f32 v178, v56, v57
	v_cvt_pk_bf16_f32 v179, v58, v59
	v_add_u32_e32 v217, 0x80000, v209
	global_store_dwordx4 v217, v[176:179], s[80:81]
	v_pk_add_f32 v[52:53], v[52:53], v[184:185]
	v_pk_add_f32 v[54:55], v[54:55], v[186:187]
	v_pk_add_f32 v[48:49], v[48:49], v[188:189]
	v_pk_add_f32 v[50:51], v[50:51], v[190:191]
	v_fmac_f32_e32 v213, v52, v52
	v_fmac_f32_e32 v213, v53, v53
	v_fmac_f32_e32 v213, v54, v54
	v_fmac_f32_e32 v213, v55, v55
	v_fmac_f32_e32 v213, v48, v48
	v_fmac_f32_e32 v213, v49, v49
	v_fmac_f32_e32 v213, v50, v50
	v_fmac_f32_e32 v213, v51, v51
	v_cvt_pk_bf16_f32 v184, v52, v53
	v_cvt_pk_bf16_f32 v185, v54, v55
	v_cvt_pk_bf16_f32 v186, v48, v49
	v_cvt_pk_bf16_f32 v187, v50, v51
	global_store_dwordx4 v217, v[184:187], s[80:81] offset:256
	ds_bpermute_b32 v214, v215, v213
	s_waitcnt lgkmcnt(0)
	v_add_f32_e32 v213, v213, v214
	ds_bpermute_b32 v214, v216, v213
	s_waitcnt lgkmcnt(0)
	v_add_f32_e32 v213, v213, v214
	s_mov_b64 exec, 0xffff
	global_atomic_add_f32 v208, v213, s[12:13] offset:512
	s_mov_b64 exec, -1
	v_add_u32_e32 v212, 0x140000, v210
	global_load_dwordx4 v[176:179], v212, s[36:37]
	global_load_dwordx4 v[180:183], v212, s[36:37] offset:16
	global_load_dwordx4 v[184:187], v212, s[36:37] offset:512
	global_load_dwordx4 v[188:191], v212, s[36:37] offset:528
	s_waitcnt vmcnt(7)
	v_pk_add_f32 v[44:45], v[44:45], v[192:193]
	v_pk_add_f32 v[46:47], v[46:47], v[194:195]
	v_pk_add_f32 v[40:41], v[40:41], v[196:197]
	v_pk_add_f32 v[42:43], v[42:43], v[198:199]
	v_mul_f32_e32 v213, v44, v44
	v_fmac_f32_e32 v213, v45, v45
	v_fmac_f32_e32 v213, v46, v46
	v_fmac_f32_e32 v213, v47, v47
	v_fmac_f32_e32 v213, v40, v40
	v_fmac_f32_e32 v213, v41, v41
	v_fmac_f32_e32 v213, v42, v42
	v_fmac_f32_e32 v213, v43, v43
	v_cvt_pk_bf16_f32 v192, v44, v45
	v_cvt_pk_bf16_f32 v193, v46, v47
	v_cvt_pk_bf16_f32 v194, v40, v41
	v_cvt_pk_bf16_f32 v195, v42, v43
	v_add_u32_e32 v217, 0x90000, v209
	global_store_dwordx4 v217, v[192:195], s[80:81]
	v_pk_add_f32 v[36:37], v[36:37], v[200:201]
	v_pk_add_f32 v[38:39], v[38:39], v[202:203]
	v_pk_add_f32 v[32:33], v[32:33], v[204:205]
	v_pk_add_f32 v[34:35], v[34:35], v[206:207]
	v_fmac_f32_e32 v213, v36, v36
	v_fmac_f32_e32 v213, v37, v37
	v_fmac_f32_e32 v213, v38, v38
	v_fmac_f32_e32 v213, v39, v39
	v_fmac_f32_e32 v213, v32, v32
	v_fmac_f32_e32 v213, v33, v33
	v_fmac_f32_e32 v213, v34, v34
	v_fmac_f32_e32 v213, v35, v35
	v_cvt_pk_bf16_f32 v200, v36, v37
	v_cvt_pk_bf16_f32 v201, v38, v39
	v_cvt_pk_bf16_f32 v202, v32, v33
	v_cvt_pk_bf16_f32 v203, v34, v35
	global_store_dwordx4 v217, v[200:203], s[80:81] offset:256
	ds_bpermute_b32 v214, v215, v213
	s_waitcnt lgkmcnt(0)
	v_add_f32_e32 v213, v213, v214
	ds_bpermute_b32 v214, v216, v213
	s_waitcnt lgkmcnt(0)
	v_add_f32_e32 v213, v213, v214
	s_mov_b64 exec, 0xffff
	global_atomic_add_f32 v208, v213, s[12:13] offset:576
	s_mov_b64 exec, -1
	v_add_u32_e32 v212, 0x160000, v210
	global_load_dwordx4 v[192:195], v212, s[36:37]
	global_load_dwordx4 v[196:199], v212, s[36:37] offset:16
	global_load_dwordx4 v[200:203], v212, s[36:37] offset:512
	global_load_dwordx4 v[204:207], v212, s[36:37] offset:528
	s_waitcnt vmcnt(7)
	v_pk_add_f32 v[28:29], v[28:29], v[176:177]
	v_pk_add_f32 v[30:31], v[30:31], v[178:179]
	v_pk_add_f32 v[24:25], v[24:25], v[180:181]
	v_pk_add_f32 v[26:27], v[26:27], v[182:183]
	v_mul_f32_e32 v213, v28, v28
	v_fmac_f32_e32 v213, v29, v29
	v_fmac_f32_e32 v213, v30, v30
	v_fmac_f32_e32 v213, v31, v31
	v_fmac_f32_e32 v213, v24, v24
	v_fmac_f32_e32 v213, v25, v25
	v_fmac_f32_e32 v213, v26, v26
	v_fmac_f32_e32 v213, v27, v27
	v_cvt_pk_bf16_f32 v176, v28, v29
	v_cvt_pk_bf16_f32 v177, v30, v31
	v_cvt_pk_bf16_f32 v178, v24, v25
	v_cvt_pk_bf16_f32 v179, v26, v27
	v_add_u32_e32 v217, 0xa0000, v209
	global_store_dwordx4 v217, v[176:179], s[80:81]
	v_pk_add_f32 v[20:21], v[20:21], v[184:185]
	v_pk_add_f32 v[22:23], v[22:23], v[186:187]
	v_pk_add_f32 v[16:17], v[16:17], v[188:189]
	v_pk_add_f32 v[18:19], v[18:19], v[190:191]
	v_fmac_f32_e32 v213, v20, v20
	v_fmac_f32_e32 v213, v21, v21
	v_fmac_f32_e32 v213, v22, v22
	v_fmac_f32_e32 v213, v23, v23
	v_fmac_f32_e32 v213, v16, v16
	v_fmac_f32_e32 v213, v17, v17
	v_fmac_f32_e32 v213, v18, v18
	v_fmac_f32_e32 v213, v19, v19
	v_cvt_pk_bf16_f32 v184, v20, v21
	v_cvt_pk_bf16_f32 v185, v22, v23
	v_cvt_pk_bf16_f32 v186, v16, v17
	v_cvt_pk_bf16_f32 v187, v18, v19
	global_store_dwordx4 v217, v[184:187], s[80:81] offset:256
	ds_bpermute_b32 v214, v215, v213
	s_waitcnt lgkmcnt(0)
	v_add_f32_e32 v213, v213, v214
	ds_bpermute_b32 v214, v216, v213
	s_waitcnt lgkmcnt(0)
	v_add_f32_e32 v213, v213, v214
	s_mov_b64 exec, 0xffff
	global_atomic_add_f32 v208, v213, s[12:13] offset:640
	s_mov_b64 exec, -1
	s_waitcnt vmcnt(3)
	v_pk_add_f32 v[12:13], v[12:13], v[192:193]
	v_pk_add_f32 v[14:15], v[14:15], v[194:195]
	v_pk_add_f32 v[8:9], v[8:9], v[196:197]
	v_pk_add_f32 v[10:11], v[10:11], v[198:199]
	v_mul_f32_e32 v213, v12, v12
	v_fmac_f32_e32 v213, v13, v13
	v_fmac_f32_e32 v213, v14, v14
	v_fmac_f32_e32 v213, v15, v15
	v_fmac_f32_e32 v213, v8, v8
	v_fmac_f32_e32 v213, v9, v9
	v_fmac_f32_e32 v213, v10, v10
	v_fmac_f32_e32 v213, v11, v11
	v_cvt_pk_bf16_f32 v192, v12, v13
	v_cvt_pk_bf16_f32 v193, v14, v15
	v_cvt_pk_bf16_f32 v194, v8, v9
	v_cvt_pk_bf16_f32 v195, v10, v11
	v_add_u32_e32 v217, 0xb0000, v209
	global_store_dwordx4 v217, v[192:195], s[80:81]
	v_pk_add_f32 v[4:5], v[4:5], v[200:201]
	v_pk_add_f32 v[6:7], v[6:7], v[202:203]
	v_pk_add_f32 v[0:1], v[0:1], v[204:205]
	v_pk_add_f32 v[2:3], v[2:3], v[206:207]
	v_fmac_f32_e32 v213, v4, v4
	v_fmac_f32_e32 v213, v5, v5
	v_fmac_f32_e32 v213, v6, v6
	v_fmac_f32_e32 v213, v7, v7
	v_fmac_f32_e32 v213, v0, v0
	v_fmac_f32_e32 v213, v1, v1
	v_fmac_f32_e32 v213, v2, v2
	v_fmac_f32_e32 v213, v3, v3
	v_cvt_pk_bf16_f32 v200, v4, v5
	v_cvt_pk_bf16_f32 v201, v6, v7
	v_cvt_pk_bf16_f32 v202, v0, v1
	v_cvt_pk_bf16_f32 v203, v2, v3
	global_store_dwordx4 v217, v[200:203], s[80:81] offset:256
	ds_bpermute_b32 v214, v215, v213
	s_waitcnt lgkmcnt(0)
	v_add_f32_e32 v213, v213, v214
	ds_bpermute_b32 v214, v216, v213
	s_waitcnt lgkmcnt(0)
	v_add_f32_e32 v213, v213, v214
	s_mov_b64 exec, 0xffff
	global_atomic_add_f32 v208, v213, s[12:13] offset:704
	s_mov_b64 exec, -1
	s_branch .LBB0_273

.LBB0_362:
	s_ashr_i32 s31, s30, 31
	v_cmp_lt_i64_e32 vcc, s[10:11], v[176:177]
	s_lshl_b64 s[10:11], s[30:31], 20
	s_add_u32 s34, s80, s10
	s_addc_u32 s35, s81, s11
	s_and_b64 s[10:11], vcc, exec
	s_cselect_b32 s31, s35, s7
	s_cselect_b32 s33, s34, s6
	s_ashr_i32 s29, s28, 31
	s_lshl_b64 s[10:11], s[28:29], 19
	s_add_u32 s36, s40, s10
	s_addc_u32 s37, s41, s11
	s_and_b64 s[10:11], vcc, exec
	s_cselect_b32 s29, s37, s9
	s_cselect_b32 s62, s36, s8
	s_add_u32 s63, s8, 0x100
	v_mov_b32_e32 v0, 0
	s_addc_u32 s64, s9, 0
	s_mov_b32 s65, -2
	v_mov_b32_e32 v1, v0
	v_mov_b32_e32 v2, v0
	v_mov_b32_e32 v3, v0
	v_mov_b32_e32 v64, v0
	v_mov_b32_e32 v65, v0
	v_mov_b32_e32 v66, v0
	v_mov_b32_e32 v67, v0
	v_mov_b32_e32 v8, v0
	v_mov_b32_e32 v9, v0
	s_waitcnt vmcnt(0)
	v_mov_b32_e32 v10, v0
	v_mov_b32_e32 v11, v0
	v_mov_b32_e32 v68, v0
	v_mov_b32_e32 v69, v0
	v_mov_b32_e32 v70, v0
	v_mov_b32_e32 v71, v0
	v_mov_b32_e32 v12, v0
	v_mov_b32_e32 v13, v0
	v_mov_b32_e32 v14, v0
	v_mov_b32_e32 v15, v0
	v_mov_b32_e32 v110, v0
	v_mov_b32_e32 v111, v0
	v_mov_b32_e32 v112, v0
	v_mov_b32_e32 v113, v0
	v_mov_b32_e32 v16, v0
	v_mov_b32_e32 v17, v0
	v_mov_b32_e32 v18, v0
	v_mov_b32_e32 v19, v0
	v_mov_b32_e32 v118, v0
	v_mov_b32_e32 v119, v0
	v_mov_b32_e32 v120, v0
	v_mov_b32_e32 v121, v0
	v_mov_b32_e32 v4, v0
	v_mov_b32_e32 v5, v0
	v_mov_b32_e32 v6, v0
	v_mov_b32_e32 v7, v0
	v_mov_b32_e32 v72, v0
	v_mov_b32_e32 v73, v0
	v_mov_b32_e32 v74, v0
	v_mov_b32_e32 v75, v0
	v_mov_b32_e32 v20, v0
	v_mov_b32_e32 v21, v0
	v_mov_b32_e32 v22, v0
	v_mov_b32_e32 v23, v0
	v_mov_b32_e32 v114, v0
	v_mov_b32_e32 v115, v0
	v_mov_b32_e32 v116, v0
	v_mov_b32_e32 v117, v0
	v_mov_b32_e32 v24, v0
	v_mov_b32_e32 v25, v0
	v_mov_b32_e32 v26, v0
	v_mov_b32_e32 v27, v0
	v_mov_b32_e32 v122, v0
	v_mov_b32_e32 v123, v0
	v_mov_b32_e32 v124, v0
	v_mov_b32_e32 v125, v0
	v_mov_b32_e32 v28, v0
	v_mov_b32_e32 v29, v0
	v_mov_b32_e32 v30, v0
	v_mov_b32_e32 v31, v0
	v_mov_b32_e32 v126, v0
	v_mov_b32_e32 v127, v0
	v_mov_b32_e32 v128, v0
	v_mov_b32_e32 v129, v0
	v_mov_b32_e32 v32, v0
	v_mov_b32_e32 v33, v0
	v_mov_b32_e32 v34, v0
	v_mov_b32_e32 v35, v0
	v_mov_b32_e32 v130, v0
	v_mov_b32_e32 v131, v0
	v_mov_b32_e32 v132, v0
	v_mov_b32_e32 v133, v0
	v_mov_b32_e32 v36, v0
	v_mov_b32_e32 v37, v0
	v_mov_b32_e32 v38, v0
	v_mov_b32_e32 v39, v0
	v_mov_b32_e32 v134, v0
	v_mov_b32_e32 v135, v0
	v_mov_b32_e32 v136, v0
	v_mov_b32_e32 v137, v0
	v_mov_b32_e32 v44, v0
	v_mov_b32_e32 v45, v0
	v_mov_b32_e32 v46, v0
	v_mov_b32_e32 v47, v0
	v_mov_b32_e32 v142, v0
	v_mov_b32_e32 v143, v0
	v_mov_b32_e32 v144, v0
	v_mov_b32_e32 v145, v0
	v_mov_b32_e32 v56, v0
	v_mov_b32_e32 v57, v0
	v_mov_b32_e32 v58, v0
	v_mov_b32_e32 v59, v0
	v_mov_b32_e32 v154, v0
	v_mov_b32_e32 v155, v0
	v_mov_b32_e32 v156, v0
	v_mov_b32_e32 v157, v0
	v_mov_b32_e32 v40, v0
	v_mov_b32_e32 v41, v0
	v_mov_b32_e32 v42, v0
	v_mov_b32_e32 v43, v0
	v_mov_b32_e32 v138, v0
	v_mov_b32_e32 v139, v0
	v_mov_b32_e32 v140, v0
	v_mov_b32_e32 v141, v0
	v_mov_b32_e32 v48, v0
	v_mov_b32_e32 v49, v0
	v_mov_b32_e32 v50, v0
	v_mov_b32_e32 v51, v0
	v_mov_b32_e32 v146, v0
	v_mov_b32_e32 v147, v0
	v_mov_b32_e32 v148, v0
	v_mov_b32_e32 v149, v0
	v_mov_b32_e32 v52, v0
	v_mov_b32_e32 v53, v0
	v_mov_b32_e32 v54, v0
	v_mov_b32_e32 v55, v0
	v_mov_b32_e32 v150, v0
	v_mov_b32_e32 v151, v0
	v_mov_b32_e32 v152, v0
	v_mov_b32_e32 v153, v0
	v_mov_b32_e32 v60, v0
	v_mov_b32_e32 v61, v0
	v_mov_b32_e32 v62, v0
	v_mov_b32_e32 v63, v0
	v_mov_b32_e32 v158, v0
	v_mov_b32_e32 v159, v0
	v_mov_b32_e32 v160, v0
	v_mov_b32_e32 v161, v0
	v_xor_b32_e32 v216, 64, v231
	v_xor_b32_e32 v217, 64, v241
	v_xor_b32_e32 v244, 64, v242
	v_add_u32_e32 v245, 0x18000, v229
	v_xor_b32_e32 v246, 64, v245
	v_add_u32_e32 v247, 0x1c000, v229
	v_xor_b32_e32 v248, 64, v247
.LBB0_363:
	ds_read_b128 v[76:79], v231
	ds_read_b128 v[80:83], v216
	ds_read_b128 v[84:87], v231 offset:2048
	ds_read_b128 v[88:91], v216 offset:2048
	s_add_u32 s8, s6, 0x100
	s_addc_u32 s9, s7, 0
	s_cmp_eq_u32 s65, 28
	s_cselect_b32 s39, s31, s9
	s_cselect_b32 s38, s33, s8
	s_cselect_b32 s11, s29, s64
	s_cselect_b32 s10, s62, s63
	s_add_i32 m0, s44, 0xc000
	ds_read_b128 v[92:95], v241
	ds_read_b128 v[96:99], v217
	ds_read_b128 v[100:103], v241 offset:2048
	ds_read_b128 v[104:107], v217 offset:2048
	ds_read_b128 v[180:183], v241 offset:4096
	ds_read_b128 v[184:187], v217 offset:4096
	ds_read_b128 v[188:191], v241 offset:6144
	ds_read_b128 v[192:195], v217 offset:6144
	global_load_lds_dwordx4 v172, s[6:7]
	s_add_i32 m0, s44, 0xe000
	s_nop 0
	global_load_lds_dwordx4 v174, s[6:7]
	s_waitcnt lgkmcnt(8)
	s_barrier
	s_waitcnt lgkmcnt(0)
	s_setprio 1
	s_waitcnt lgkmcnt(0)
	v_mfma_f32_16x16x32_bf16 v[158:161], v[76:79], v[92:95], v[158:161]
	v_mfma_f32_16x16x32_bf16 v[158:161], v[80:83], v[96:99], v[158:161]
	v_mfma_f32_16x16x32_bf16 v[60:63], v[88:91], v[96:99], v[60:63]
	v_mfma_f32_16x16x32_bf16 v[60:63], v[84:87], v[92:95], v[60:63]
	v_mfma_f32_16x16x32_bf16 v[52:55], v[84:87], v[100:103], v[52:55]
	v_mfma_f32_16x16x32_bf16 v[52:55], v[88:91], v[104:107], v[52:55]
	v_mfma_f32_16x16x32_bf16 v[150:153], v[80:83], v[104:107], v[150:153]
	v_mfma_f32_16x16x32_bf16 v[150:153], v[76:79], v[100:103], v[150:153]
	v_mfma_f32_16x16x32_bf16 v[146:149], v[76:79], v[180:183], v[146:149]
	v_mfma_f32_16x16x32_bf16 v[146:149], v[80:83], v[184:187], v[146:149]
	v_mfma_f32_16x16x32_bf16 v[48:51], v[88:91], v[184:187], v[48:51]
	v_mfma_f32_16x16x32_bf16 v[48:51], v[84:87], v[180:183], v[48:51]
	v_mfma_f32_16x16x32_bf16 v[40:43], v[84:87], v[188:191], v[40:43]
	v_mfma_f32_16x16x32_bf16 v[40:43], v[88:91], v[192:195], v[40:43]
	v_mfma_f32_16x16x32_bf16 v[138:141], v[80:83], v[192:195], v[138:141]
	v_mfma_f32_16x16x32_bf16 v[138:141], v[76:79], v[188:191], v[138:141]
	s_setprio 0
	s_barrier
	s_add_i32 s6, s58, s42
	s_add_u32 s98, s10, s14
	s_addc_u32 s99, s11, s15
	s_mov_b32 m0, s6
	ds_read_b128 v[196:199], v242
	ds_read_b128 v[200:203], v244
	ds_read_b128 v[204:207], v242 offset:2048
	ds_read_b128 v[208:211], v244 offset:2048
	global_load_lds_dwordx4 v164, s[10:11]
	s_add_i32 m0, s6, 0x2000
	s_nop 0
	global_load_lds_dwordx4 v166, s[10:11]
	s_barrier
	s_waitcnt lgkmcnt(0)
	s_setprio 1
	s_waitcnt lgkmcnt(0)
	v_mfma_f32_16x16x32_bf16 v[154:157], v[196:199], v[92:95], v[154:157]
	v_mfma_f32_16x16x32_bf16 v[154:157], v[200:203], v[96:99], v[154:157]
	v_mfma_f32_16x16x32_bf16 v[56:59], v[208:211], v[96:99], v[56:59]
	v_mfma_f32_16x16x32_bf16 v[56:59], v[204:207], v[92:95], v[56:59]
	v_mfma_f32_16x16x32_bf16 v[44:47], v[204:207], v[100:103], v[44:47]
	v_mfma_f32_16x16x32_bf16 v[44:47], v[208:211], v[104:107], v[44:47]
	v_mfma_f32_16x16x32_bf16 v[36:39], v[208:211], v[184:187], v[36:39]
	v_mfma_f32_16x16x32_bf16 v[36:39], v[204:207], v[180:183], v[36:39]
	v_mfma_f32_16x16x32_bf16 v[32:35], v[204:207], v[188:191], v[32:35]
	v_mfma_f32_16x16x32_bf16 v[32:35], v[208:211], v[192:195], v[32:35]
	v_mfma_f32_16x16x32_bf16 v[92:95], v[196:199], v[100:103], v[142:145]
	v_mfma_f32_16x16x32_bf16 v[92:95], v[200:203], v[104:107], v[92:95]
	v_mfma_f32_16x16x32_bf16 v[96:99], v[200:203], v[184:187], v[134:137]
	v_mfma_f32_16x16x32_bf16 v[96:99], v[196:199], v[180:183], v[96:99]
	v_mfma_f32_16x16x32_bf16 v[100:103], v[196:199], v[188:191], v[130:133]
	v_mfma_f32_16x16x32_bf16 v[100:103], v[200:203], v[192:195], v[100:103]
	s_setprio 0
	s_mov_b32 m0, s44
	s_add_u32 s100, s38, s14
	s_addc_u32 s101, s39, s15
	s_barrier
	ds_read_b128 v[104:107], v241 offset:16384
	ds_read_b128 v[130:133], v217 offset:16384
	ds_read_b128 v[134:137], v241 offset:18432
	ds_read_b128 v[142:145], v217 offset:18432
	ds_read_b128 v[180:183], v241 offset:20480
	ds_read_b128 v[184:187], v217 offset:20480
	ds_read_b128 v[188:191], v241 offset:22528
	ds_read_b128 v[192:195], v217 offset:22528
	global_load_lds_dwordx4 v170, s[38:39]
	s_mov_b32 m0, s45
	s_nop 0
	global_load_lds_dwordx4 v168, s[38:39]
	s_barrier
	s_waitcnt lgkmcnt(0)
	s_setprio 1
	s_waitcnt lgkmcnt(0)
	v_mfma_f32_16x16x32_bf16 v[126:129], v[76:79], v[104:107], v[126:129]
	v_mfma_f32_16x16x32_bf16 v[126:129], v[80:83], v[130:133], v[126:129]
	v_mfma_f32_16x16x32_bf16 v[28:31], v[88:91], v[130:133], v[28:31]
	v_mfma_f32_16x16x32_bf16 v[28:31], v[84:87], v[104:107], v[28:31]
	v_mfma_f32_16x16x32_bf16 v[24:27], v[84:87], v[134:137], v[24:27]
	v_mfma_f32_16x16x32_bf16 v[24:27], v[88:91], v[142:145], v[24:27]
	v_mfma_f32_16x16x32_bf16 v[122:125], v[80:83], v[142:145], v[122:125]
	v_mfma_f32_16x16x32_bf16 v[122:125], v[76:79], v[134:137], v[122:125]
	v_mfma_f32_16x16x32_bf16 v[114:117], v[76:79], v[180:183], v[114:117]
	v_mfma_f32_16x16x32_bf16 v[114:117], v[80:83], v[184:187], v[114:117]
	v_mfma_f32_16x16x32_bf16 v[20:23], v[88:91], v[184:187], v[20:23]
	v_mfma_f32_16x16x32_bf16 v[20:23], v[84:87], v[180:183], v[20:23]
	v_mfma_f32_16x16x32_bf16 v[4:7], v[84:87], v[188:191], v[4:7]
	v_mfma_f32_16x16x32_bf16 v[4:7], v[88:91], v[192:195], v[4:7]
	v_mfma_f32_16x16x32_bf16 v[72:75], v[80:83], v[192:195], v[72:75]
	v_mfma_f32_16x16x32_bf16 v[72:75], v[76:79], v[188:191], v[72:75]
	s_setprio 0
	s_barrier
	s_add_u32 s6, s10, 0x1600000
	s_addc_u32 s7, s11, 0
	s_add_i32 s66, s59, s42
	s_mov_b32 m0, s66
	s_nop 0
	global_load_lds_dwordx4 v164, s[6:7]
	s_add_i32 m0, s66, 0x2000
	s_nop 0
	global_load_lds_dwordx4 v166, s[6:7]
	s_waitcnt vmcnt(6)
	s_barrier
	s_setprio 1
	v_mfma_f32_16x16x32_bf16 v[16:19], v[204:207], v[104:107], v[16:19]
	v_mfma_f32_16x16x32_bf16 v[16:19], v[208:211], v[130:133], v[16:19]
	v_mfma_f32_16x16x32_bf16 v[12:15], v[208:211], v[142:145], v[12:15]
	v_mfma_f32_16x16x32_bf16 v[12:15], v[204:207], v[134:137], v[12:15]
	v_mfma_f32_16x16x32_bf16 v[8:11], v[204:207], v[180:183], v[8:11]
	v_mfma_f32_16x16x32_bf16 v[8:11], v[208:211], v[184:187], v[8:11]
	v_mfma_f32_16x16x32_bf16 v[68:71], v[200:203], v[184:187], v[68:71]
	v_mfma_f32_16x16x32_bf16 v[68:71], v[196:199], v[180:183], v[68:71]
	v_mfma_f32_16x16x32_bf16 v[64:67], v[196:199], v[188:191], v[64:67]
	v_mfma_f32_16x16x32_bf16 v[64:67], v[200:203], v[192:195], v[64:67]
	v_mfma_f32_16x16x32_bf16 v[0:3], v[208:211], v[192:195], v[0:3]
	v_mfma_f32_16x16x32_bf16 v[0:3], v[204:207], v[188:191], v[0:3]
	v_mfma_f32_16x16x32_bf16 v[76:79], v[196:199], v[104:107], v[118:121]
	v_mfma_f32_16x16x32_bf16 v[76:79], v[200:203], v[130:133], v[76:79]
	v_mfma_f32_16x16x32_bf16 v[80:83], v[200:203], v[142:145], v[110:113]
	v_mfma_f32_16x16x32_bf16 v[80:83], v[196:199], v[134:137], v[80:83]
	s_setprio 0
	s_add_i32 s66, 0, 0x18000
	s_barrier
	ds_read_b128 v[84:87], v245
	ds_read_b128 v[88:91], v246
	ds_read_b128 v[104:107], v245 offset:2048
	ds_read_b128 v[108:111], v246 offset:2048
	s_add_u32 s6, s38, 0x40000
	s_addc_u32 s7, s39, 0
	s_mov_b32 m0, s46
	ds_read_b128 v[118:121], v241 offset:32768
	ds_read_b128 v[130:133], v217 offset:32768
	ds_read_b128 v[134:137], v241 offset:34816
	ds_read_b128 v[180:183], v217 offset:34816
	ds_read_b128 v[184:187], v241 offset:36864
	ds_read_b128 v[188:191], v217 offset:36864
	ds_read_b128 v[192:195], v241 offset:38912
	ds_read_b128 v[196:199], v217 offset:38912
	global_load_lds_dwordx4 v170, s[6:7]
	s_mov_b32 m0, s47
	s_nop 0
	global_load_lds_dwordx4 v168, s[6:7]
	s_waitcnt lgkmcnt(8)
	s_barrier
	s_waitcnt lgkmcnt(0)
	s_setprio 1
	s_waitcnt lgkmcnt(0)
	v_mfma_f32_16x16x32_bf16 v[142:145], v[84:87], v[118:121], v[158:161]
	v_mfma_f32_16x16x32_bf16 v[158:161], v[88:91], v[130:133], v[142:145]
	v_mfma_f32_16x16x32_bf16 v[60:63], v[108:111], v[130:133], v[60:63]
	v_mfma_f32_16x16x32_bf16 v[60:63], v[104:107], v[118:121], v[60:63]
	v_mfma_f32_16x16x32_bf16 v[52:55], v[104:107], v[134:137], v[52:55]
	v_mfma_f32_16x16x32_bf16 v[52:55], v[108:111], v[180:183], v[52:55]
	v_mfma_f32_16x16x32_bf16 v[48:51], v[108:111], v[188:191], v[48:51]
	v_mfma_f32_16x16x32_bf16 v[48:51], v[104:107], v[184:187], v[48:51]
	v_mfma_f32_16x16x32_bf16 v[40:43], v[104:107], v[192:195], v[40:43]
	v_mfma_f32_16x16x32_bf16 v[40:43], v[108:111], v[196:199], v[40:43]
	v_mfma_f32_16x16x32_bf16 v[138:141], v[88:91], v[196:199], v[138:141]
	v_mfma_f32_16x16x32_bf16 v[138:141], v[84:87], v[192:195], v[138:141]
	v_mfma_f32_16x16x32_bf16 v[142:145], v[84:87], v[134:137], v[150:153]
	v_mfma_f32_16x16x32_bf16 v[150:153], v[88:91], v[180:183], v[142:145]
	v_mfma_f32_16x16x32_bf16 v[142:145], v[84:87], v[184:187], v[146:149]
	v_mfma_f32_16x16x32_bf16 v[146:149], v[88:91], v[188:191], v[142:145]
	s_setprio 0
	s_barrier
	s_add_i32 s38, 0, 0x1c000
	s_add_i32 s6, s66, s42
	ds_read_b128 v[200:203], v247
	ds_read_b128 v[204:207], v248
	ds_read_b128 v[208:211], v247 offset:2048
	ds_read_b128 v[212:215], v248 offset:2048
	s_mov_b32 m0, s6
	s_nop 0
	global_load_lds_dwordx4 v164, s[98:99]
	s_add_i32 m0, s6, 0x2000
	s_nop 0
	global_load_lds_dwordx4 v166, s[98:99]
	s_barrier
	s_waitcnt lgkmcnt(0)
	s_setprio 1
	s_waitcnt lgkmcnt(0)
	v_mfma_f32_16x16x32_bf16 v[142:145], v[200:203], v[118:121], v[154:157]
	v_mfma_f32_16x16x32_bf16 v[154:157], v[204:207], v[130:133], v[142:145]
	v_mfma_f32_16x16x32_bf16 v[56:59], v[212:215], v[130:133], v[56:59]
	v_mfma_f32_16x16x32_bf16 v[56:59], v[208:211], v[118:121], v[56:59]
	v_mfma_f32_16x16x32_bf16 v[44:47], v[208:211], v[134:137], v[44:47]
	v_mfma_f32_16x16x32_bf16 v[44:47], v[212:215], v[180:183], v[44:47]
	v_mfma_f32_16x16x32_bf16 v[36:39], v[212:215], v[188:191], v[36:39]
	v_mfma_f32_16x16x32_bf16 v[36:39], v[208:211], v[184:187], v[36:39]
	v_mfma_f32_16x16x32_bf16 v[32:35], v[208:211], v[192:195], v[32:35]
	v_mfma_f32_16x16x32_bf16 v[32:35], v[212:215], v[196:199], v[32:35]
	v_mfma_f32_16x16x32_bf16 v[92:95], v[200:203], v[134:137], v[92:95]
	v_mfma_f32_16x16x32_bf16 v[142:145], v[204:207], v[180:183], v[92:95]
	v_mfma_f32_16x16x32_bf16 v[92:95], v[200:203], v[184:187], v[96:99]
	v_mfma_f32_16x16x32_bf16 v[134:137], v[204:207], v[188:191], v[92:95]
	v_mfma_f32_16x16x32_bf16 v[92:95], v[200:203], v[192:195], v[100:103]
	v_mfma_f32_16x16x32_bf16 v[130:133], v[204:207], v[196:199], v[92:95]
	s_setprio 0
	s_mov_b32 m0, s52
	s_barrier
	ds_read_b128 v[92:95], v241 offset:49152
	ds_read_b128 v[96:99], v217 offset:49152
	ds_read_b128 v[100:103], v241 offset:51200
	ds_read_b128 v[180:183], v217 offset:51200
	ds_read_b128 v[184:187], v241 offset:53248
	ds_read_b128 v[188:191], v217 offset:53248
	ds_read_b128 v[192:195], v241 offset:55296
	ds_read_b128 v[196:199], v217 offset:55296
	global_load_lds_dwordx4 v170, s[100:101]
	s_mov_b32 m0, s53
	s_nop 0
	global_load_lds_dwordx4 v168, s[100:101]
	s_barrier
	s_waitcnt lgkmcnt(0)
	s_setprio 1
	s_waitcnt lgkmcnt(0)
	v_mfma_f32_16x16x32_bf16 v[118:121], v[84:87], v[92:95], v[126:129]
	v_mfma_f32_16x16x32_bf16 v[126:129], v[88:91], v[96:99], v[118:121]
	v_mfma_f32_16x16x32_bf16 v[28:31], v[108:111], v[96:99], v[28:31]
	v_mfma_f32_16x16x32_bf16 v[28:31], v[104:107], v[92:95], v[28:31]
	v_mfma_f32_16x16x32_bf16 v[24:27], v[104:107], v[100:103], v[24:27]
	v_mfma_f32_16x16x32_bf16 v[24:27], v[108:111], v[180:183], v[24:27]
	v_mfma_f32_16x16x32_bf16 v[20:23], v[108:111], v[188:191], v[20:23]
	v_mfma_f32_16x16x32_bf16 v[20:23], v[104:107], v[184:187], v[20:23]
	v_mfma_f32_16x16x32_bf16 v[112:115], v[84:87], v[184:187], v[114:117]
	v_mfma_f32_16x16x32_bf16 v[114:117], v[88:91], v[188:191], v[112:115]
	v_mfma_f32_16x16x32_bf16 v[72:75], v[88:91], v[196:199], v[72:75]
	v_mfma_f32_16x16x32_bf16 v[72:75], v[84:87], v[192:195], v[72:75]
	v_mfma_f32_16x16x32_bf16 v[118:121], v[84:87], v[100:103], v[122:125]
	v_mfma_f32_16x16x32_bf16 v[122:125], v[88:91], v[180:183], v[118:121]
	v_mfma_f32_16x16x32_bf16 v[4:7], v[104:107], v[192:195], v[4:7]
	v_mfma_f32_16x16x32_bf16 v[4:7], v[108:111], v[196:199], v[4:7]
	s_setprio 0
	s_barrier
	s_add_u32 s6, s10, 0x1600080
	s_addc_u32 s7, s11, 0
	s_add_i32 s10, s38, s42
	s_mov_b32 m0, s10
	s_nop 0
	global_load_lds_dwordx4 v164, s[6:7]
	s_add_i32 m0, s10, 0x2000
	s_nop 0
	global_load_lds_dwordx4 v166, s[6:7]
	s_waitcnt vmcnt(6)
	s_barrier
	s_setprio 1
	v_mfma_f32_16x16x32_bf16 v[76:79], v[200:203], v[92:95], v[76:79]
	v_mfma_f32_16x16x32_bf16 v[118:121], v[204:207], v[96:99], v[76:79]
	v_mfma_f32_16x16x32_bf16 v[16:19], v[212:215], v[96:99], v[16:19]
	v_mfma_f32_16x16x32_bf16 v[16:19], v[208:211], v[92:95], v[16:19]
	v_mfma_f32_16x16x32_bf16 v[12:15], v[208:211], v[100:103], v[12:15]
	v_mfma_f32_16x16x32_bf16 v[12:15], v[212:215], v[180:183], v[12:15]
	v_mfma_f32_16x16x32_bf16 v[8:11], v[212:215], v[188:191], v[8:11]
	v_mfma_f32_16x16x32_bf16 v[8:11], v[208:211], v[184:187], v[8:11]
	v_mfma_f32_16x16x32_bf16 v[68:71], v[200:203], v[184:187], v[68:71]
	v_mfma_f32_16x16x32_bf16 v[68:71], v[204:207], v[188:191], v[68:71]
	v_mfma_f32_16x16x32_bf16 v[64:67], v[204:207], v[196:199], v[64:67]
	v_mfma_f32_16x16x32_bf16 v[64:67], v[200:203], v[192:195], v[64:67]
	v_mfma_f32_16x16x32_bf16 v[76:79], v[200:203], v[100:103], v[80:83]
	v_mfma_f32_16x16x32_bf16 v[110:113], v[204:207], v[180:183], v[76:79]
	v_mfma_f32_16x16x32_bf16 v[0:3], v[208:211], v[192:195], v[0:3]
	v_mfma_f32_16x16x32_bf16 v[0:3], v[212:215], v[196:199], v[0:3]
	s_setprio 0
	s_add_i32 s65, s65, 2
	s_add_u32 s63, s63, 0x100
	s_addc_u32 s64, s64, 0
	s_cmp_gt_u32 s65, 29
	s_mov_b64 s[6:7], s[8:9]
	s_barrier
	s_cbranch_scc0 .LBB0_363
	s_lshl_b32 s8, s0, 8
	s_add_i32 s8, s8, s56
	s_lshl_b32 s9, s1, 7
	s_add_i32 s9, s9, s49
	s_lshl_b32 s10, s0, 3
	s_lshr_b32 s11, s56, 5
	s_add_i32 s10, s10, s11
	v_add_u32_e32 v200, s8, v163
	v_lshlrev_b32_e32 v213, 2, v200
	global_load_dword v188, v213, s[12:13]
	global_load_dword v189, v213, s[12:13] offset:64
	global_load_dword v190, v213, s[12:13] offset:128
	global_load_dword v191, v213, s[12:13] offset:192
	global_load_dword v192, v213, s[12:13] offset:256
	global_load_dword v193, v213, s[12:13] offset:320
	global_load_dword v194, v213, s[12:13] offset:384
	global_load_dword v195, v213, s[12:13] offset:448
	v_lshl_add_u32 v201, v225, 3, s9
	v_lshlrev_b32_e32 v212, 2, v201
	global_load_dwordx4 v[76:79], v212, s[82:83]
	v_add_u32_e32 v213, 0xb000, v212
	global_load_dwordx4 v[80:83], v213, s[82:83]
	v_add_u32_e32 v213, 0x16000, v212
	global_load_dwordx4 v[84:87], v213, s[82:83]
	global_load_dwordx4 v[88:91], v212, s[84:85]
	v_add_u32_e32 v213, 0x5800, v212
	global_load_dwordx4 v[92:95], v213, s[82:83]
	v_add_u32_e32 v213, 0x10800, v212
	global_load_dwordx4 v[96:99], v213, s[82:83]
	v_add_u32_e32 v213, 0x1b800, v212
	global_load_dwordx4 v[100:103], v213, s[82:83]
	v_add_u32_e32 v213, 0x5800, v212
	global_load_dwordx4 v[104:107], v213, s[84:85]
	v_mul_u32_u24_e32 v215, 0x2c00, v200
	v_lshl_add_u32 v215, v201, 1, v215
	v_add_u32_e32 v213, s10, v163
	v_mul_u32_u24_e32 v217, 0xb000, v213
	v_add_u32_e32 v217, v217, v212
	v_cmp_gt_u32_e64 s[8:9], 2, v163
	v_cmp_lt_u32_e64 s[10:11], 13, v163
	v_cmp_lt_u32_e32 vcc, 1, v163
	v_mov_b32_e32 v214, 1.0
	v_mov_b32_e32 v216, 0xbfb8aa3b
	v_mov_b32_e32 v108, 0x3727c5ac
	s_waitcnt vmcnt(8)
	v_fmamk_f32 v188, v188, 0x3a000000, v108
	v_fmamk_f32 v189, v189, 0x3a000000, v108
	v_fmamk_f32 v190, v190, 0x3a000000, v108
	v_fmamk_f32 v191, v191, 0x3a000000, v108
	v_fmamk_f32 v192, v192, 0x3a000000, v108
	v_fmamk_f32 v193, v193, 0x3a000000, v108
	v_fmamk_f32 v194, v194, 0x3a000000, v108
	v_fmamk_f32 v195, v195, 0x3a000000, v108
	v_rsq_f32_e32 v188, v188
	v_rsq_f32_e32 v189, v189
	v_rsq_f32_e32 v190, v190
	v_rsq_f32_e32 v191, v191
	v_rsq_f32_e32 v192, v192
	v_rsq_f32_e32 v193, v193
	v_rsq_f32_e32 v194, v194
	v_rsq_f32_e32 v195, v195
	v_pk_mul_f32 v[158:159], v[158:159], v[188:189] op_sel_hi:[1,0]
	v_pk_mul_f32 v[160:161], v[160:161], v[188:189] op_sel_hi:[1,0]
	v_pk_mul_f32 v[60:61], v[60:61], v[188:189] op_sel_hi:[1,0]
	v_pk_mul_f32 v[62:63], v[62:63], v[188:189] op_sel_hi:[1,0]
	v_pk_mul_f32 v[154:155], v[154:155], v[188:189] op_sel_hi:[1,0]
	v_pk_mul_f32 v[156:157], v[156:157], v[188:189] op_sel_hi:[1,0]
	v_pk_mul_f32 v[56:57], v[56:57], v[188:189] op_sel_hi:[1,0]
	v_pk_mul_f32 v[58:59], v[58:59], v[188:189] op_sel_hi:[1,0]
	v_pk_mul_f32 v[150:151], v[150:151], v[188:189] op_sel:[0,1] op_sel_hi:[1,1]
	v_pk_mul_f32 v[152:153], v[152:153], v[188:189] op_sel:[0,1] op_sel_hi:[1,1]
	v_pk_mul_f32 v[52:53], v[52:53], v[188:189] op_sel:[0,1] op_sel_hi:[1,1]
	v_pk_mul_f32 v[54:55], v[54:55], v[188:189] op_sel:[0,1] op_sel_hi:[1,1]
	v_pk_mul_f32 v[142:143], v[142:143], v[188:189] op_sel:[0,1] op_sel_hi:[1,1]
	v_pk_mul_f32 v[144:145], v[144:145], v[188:189] op_sel:[0,1] op_sel_hi:[1,1]
	v_pk_mul_f32 v[44:45], v[44:45], v[188:189] op_sel:[0,1] op_sel_hi:[1,1]
	v_pk_mul_f32 v[46:47], v[46:47], v[188:189] op_sel:[0,1] op_sel_hi:[1,1]
	v_pk_mul_f32 v[146:147], v[146:147], v[190:191] op_sel_hi:[1,0]
	v_pk_mul_f32 v[148:149], v[148:149], v[190:191] op_sel_hi:[1,0]
	v_pk_mul_f32 v[48:49], v[48:49], v[190:191] op_sel_hi:[1,0]
	v_pk_mul_f32 v[50:51], v[50:51], v[190:191] op_sel_hi:[1,0]
	v_pk_mul_f32 v[134:135], v[134:135], v[190:191] op_sel_hi:[1,0]
	v_pk_mul_f32 v[136:137], v[136:137], v[190:191] op_sel_hi:[1,0]
	v_pk_mul_f32 v[36:37], v[36:37], v[190:191] op_sel_hi:[1,0]
	v_pk_mul_f32 v[38:39], v[38:39], v[190:191] op_sel_hi:[1,0]
	v_pk_mul_f32 v[138:139], v[138:139], v[190:191] op_sel:[0,1] op_sel_hi:[1,1]
	v_pk_mul_f32 v[140:141], v[140:141], v[190:191] op_sel:[0,1] op_sel_hi:[1,1]
	v_pk_mul_f32 v[40:41], v[40:41], v[190:191] op_sel:[0,1] op_sel_hi:[1,1]
	v_pk_mul_f32 v[42:43], v[42:43], v[190:191] op_sel:[0,1] op_sel_hi:[1,1]
	v_pk_mul_f32 v[130:131], v[130:131], v[190:191] op_sel:[0,1] op_sel_hi:[1,1]
	v_pk_mul_f32 v[132:133], v[132:133], v[190:191] op_sel:[0,1] op_sel_hi:[1,1]
	v_pk_mul_f32 v[32:33], v[32:33], v[190:191] op_sel:[0,1] op_sel_hi:[1,1]
	v_pk_mul_f32 v[34:35], v[34:35], v[190:191] op_sel:[0,1] op_sel_hi:[1,1]
	v_pk_mul_f32 v[126:127], v[126:127], v[192:193] op_sel_hi:[1,0]
	v_pk_mul_f32 v[128:129], v[128:129], v[192:193] op_sel_hi:[1,0]
	v_pk_mul_f32 v[28:29], v[28:29], v[192:193] op_sel_hi:[1,0]
	v_pk_mul_f32 v[30:31], v[30:31], v[192:193] op_sel_hi:[1,0]
	v_pk_mul_f32 v[118:119], v[118:119], v[192:193] op_sel_hi:[1,0]
	v_pk_mul_f32 v[120:121], v[120:121], v[192:193] op_sel_hi:[1,0]
	v_pk_mul_f32 v[16:17], v[16:17], v[192:193] op_sel_hi:[1,0]
	v_pk_mul_f32 v[18:19], v[18:19], v[192:193] op_sel_hi:[1,0]
	v_pk_mul_f32 v[122:123], v[122:123], v[192:193] op_sel:[0,1] op_sel_hi:[1,1]
	v_pk_mul_f32 v[124:125], v[124:125], v[192:193] op_sel:[0,1] op_sel_hi:[1,1]
	v_pk_mul_f32 v[24:25], v[24:25], v[192:193] op_sel:[0,1] op_sel_hi:[1,1]
	v_pk_mul_f32 v[26:27], v[26:27], v[192:193] op_sel:[0,1] op_sel_hi:[1,1]
	v_pk_mul_f32 v[110:111], v[110:111], v[192:193] op_sel:[0,1] op_sel_hi:[1,1]
	v_pk_mul_f32 v[112:113], v[112:113], v[192:193] op_sel:[0,1] op_sel_hi:[1,1]
	v_pk_mul_f32 v[12:13], v[12:13], v[192:193] op_sel:[0,1] op_sel_hi:[1,1]
	v_pk_mul_f32 v[14:15], v[14:15], v[192:193] op_sel:[0,1] op_sel_hi:[1,1]
	v_pk_mul_f32 v[114:115], v[114:115], v[194:195] op_sel_hi:[1,0]
	v_pk_mul_f32 v[116:117], v[116:117], v[194:195] op_sel_hi:[1,0]
	v_pk_mul_f32 v[20:21], v[20:21], v[194:195] op_sel_hi:[1,0]
	v_pk_mul_f32 v[22:23], v[22:23], v[194:195] op_sel_hi:[1,0]
	v_pk_mul_f32 v[68:69], v[68:69], v[194:195] op_sel_hi:[1,0]
	v_pk_mul_f32 v[70:71], v[70:71], v[194:195] op_sel_hi:[1,0]
	v_pk_mul_f32 v[8:9], v[8:9], v[194:195] op_sel_hi:[1,0]
	v_pk_mul_f32 v[10:11], v[10:11], v[194:195] op_sel_hi:[1,0]
	v_pk_mul_f32 v[72:73], v[72:73], v[194:195] op_sel:[0,1] op_sel_hi:[1,1]
	v_pk_mul_f32 v[74:75], v[74:75], v[194:195] op_sel:[0,1] op_sel_hi:[1,1]
	v_pk_mul_f32 v[4:5], v[4:5], v[194:195] op_sel:[0,1] op_sel_hi:[1,1]
	v_pk_mul_f32 v[6:7], v[6:7], v[194:195] op_sel:[0,1] op_sel_hi:[1,1]
	v_pk_mul_f32 v[64:65], v[64:65], v[194:195] op_sel:[0,1] op_sel_hi:[1,1]
	v_pk_mul_f32 v[66:67], v[66:67], v[194:195] op_sel:[0,1] op_sel_hi:[1,1]
	v_pk_mul_f32 v[0:1], v[0:1], v[194:195] op_sel:[0,1] op_sel_hi:[1,1]
	v_pk_mul_f32 v[2:3], v[2:3], v[194:195] op_sel:[0,1] op_sel_hi:[1,1]
	s_nop 1
	s_mov_b64 exec, s[8:9]
	v_add_u32_e32 v213, 0x5800, v217
	global_store_dwordx4 v217, v[158:161], s[70:71]
	global_store_dwordx4 v213, v[154:157], s[70:71]
	global_store_dwordx4 v217, v[60:63], s[70:71] offset:16
	global_store_dwordx4 v213, v[56:59], s[70:71] offset:16
	s_mov_b64 exec, s[10:11]
	v_add_u32_e32 v213, 0xfff7c000, v217
	global_store_dwordx4 v213, v[72:75], s[70:71]
	global_store_dwordx4 v213, v[4:7], s[70:71] offset:16
	v_add_u32_e32 v213, 0xfff81800, v217
	global_store_dwordx4 v213, v[64:67], s[70:71]
	global_store_dwordx4 v213, v[0:3], s[70:71] offset:16
	s_mov_b64 exec, -1
	v_add_u32_e32 v213, 0x1b800, v212
	global_load_dwordx4 v[204:207], v213, s[82:83] offset:16
	v_add_u32_e32 v213, 0x5800, v212
	global_load_dwordx4 v[208:211], v213, s[84:85] offset:16
	s_waitcnt vmcnt(10)
	v_pk_fma_f32 v[188:189], v[158:159], v[84:85], v[88:89]
	v_pk_fma_f32 v[190:191], v[160:161], v[86:87], v[90:91]
	v_pk_fma_f32 v[192:193], v[154:155], v[100:101], v[104:105]
	v_pk_fma_f32 v[194:195], v[156:157], v[102:103], v[106:107]
	v_fmac_f32_dpp v188, v158, v80 row_shr:1 row_mask:0xf bank_mask:0xf
	v_fmac_f32_dpp v189, v159, v81 row_shr:1 row_mask:0xf bank_mask:0xf
	v_fmac_f32_dpp v190, v160, v82 row_shr:1 row_mask:0xf bank_mask:0xf
	v_fmac_f32_dpp v191, v161, v83 row_shr:1 row_mask:0xf bank_mask:0xf
	v_fmac_f32_dpp v192, v154, v96 row_shr:1 row_mask:0xf bank_mask:0xf
	v_fmac_f32_dpp v193, v155, v97 row_shr:1 row_mask:0xf bank_mask:0xf
	v_fmac_f32_dpp v194, v156, v98 row_shr:1 row_mask:0xf bank_mask:0xf
	v_fmac_f32_dpp v195, v157, v99 row_shr:1 row_mask:0xf bank_mask:0xf
	v_fmac_f32_dpp v188, v158, v76 row_shr:2 row_mask:0xf bank_mask:0xf
	v_fmac_f32_dpp v189, v159, v77 row_shr:2 row_mask:0xf bank_mask:0xf
	v_fmac_f32_dpp v190, v160, v78 row_shr:2 row_mask:0xf bank_mask:0xf
	v_fmac_f32_dpp v191, v161, v79 row_shr:2 row_mask:0xf bank_mask:0xf
	v_fmac_f32_dpp v192, v154, v92 row_shr:2 row_mask:0xf bank_mask:0xf
	v_fmac_f32_dpp v193, v155, v93 row_shr:2 row_mask:0xf bank_mask:0xf
	v_fmac_f32_dpp v194, v156, v94 row_shr:2 row_mask:0xf bank_mask:0xf
	v_fmac_f32_dpp v195, v157, v95 row_shr:2 row_mask:0xf bank_mask:0xf
	v_pk_mul_f32 v[196:197], v[188:189], v[216:217] op_sel_hi:[1,0]
	v_pk_mul_f32 v[198:199], v[190:191], v[216:217] op_sel_hi:[1,0]
	v_exp_f32_e32 v196, v196
	v_exp_f32_e32 v197, v197
	v_exp_f32_e32 v198, v198
	v_exp_f32_e32 v199, v199
	v_pk_add_f32 v[196:197], v[196:197], v[214:215] op_sel_hi:[1,0]
	v_pk_add_f32 v[198:199], v[198:199], v[214:215] op_sel_hi:[1,0]
	v_rcp_f32_e32 v196, v196
	v_rcp_f32_e32 v197, v197
	v_rcp_f32_e32 v198, v198
	v_rcp_f32_e32 v199, v199
	v_pk_mul_f32 v[188:189], v[188:189], v[196:197]
	v_pk_mul_f32 v[190:191], v[190:191], v[198:199]
	v_pk_mul_f32 v[188:189], v[188:189], v[192:193]
	v_pk_mul_f32 v[190:191], v[190:191], v[194:195]
	v_cvt_pk_bf16_f32 v200, v188, v189
	v_cvt_pk_bf16_f32 v201, v190, v191
	v_pk_fma_f32 v[188:189], v[150:151], v[84:85], v[88:89]
	v_pk_fma_f32 v[190:191], v[152:153], v[86:87], v[90:91]
	v_pk_fma_f32 v[192:193], v[142:143], v[100:101], v[104:105]
	v_pk_fma_f32 v[194:195], v[144:145], v[102:103], v[106:107]
	v_fmac_f32_dpp v188, v150, v80 row_shr:1 row_mask:0xf bank_mask:0xf
	v_fmac_f32_dpp v189, v151, v81 row_shr:1 row_mask:0xf bank_mask:0xf
	v_fmac_f32_dpp v190, v152, v82 row_shr:1 row_mask:0xf bank_mask:0xf
	v_fmac_f32_dpp v191, v153, v83 row_shr:1 row_mask:0xf bank_mask:0xf
	v_fmac_f32_dpp v192, v142, v96 row_shr:1 row_mask:0xf bank_mask:0xf
	v_fmac_f32_dpp v193, v143, v97 row_shr:1 row_mask:0xf bank_mask:0xf
	v_fmac_f32_dpp v194, v144, v98 row_shr:1 row_mask:0xf bank_mask:0xf
	v_fmac_f32_dpp v195, v145, v99 row_shr:1 row_mask:0xf bank_mask:0xf
	v_fmac_f32_dpp v188, v150, v76 row_shr:2 row_mask:0xf bank_mask:0xf
	v_fmac_f32_dpp v189, v151, v77 row_shr:2 row_mask:0xf bank_mask:0xf
	v_fmac_f32_dpp v190, v152, v78 row_shr:2 row_mask:0xf bank_mask:0xf
	v_fmac_f32_dpp v191, v153, v79 row_shr:2 row_mask:0xf bank_mask:0xf
	v_fmac_f32_dpp v192, v142, v92 row_shr:2 row_mask:0xf bank_mask:0xf
	v_fmac_f32_dpp v193, v143, v93 row_shr:2 row_mask:0xf bank_mask:0xf
	v_fmac_f32_dpp v194, v144, v94 row_shr:2 row_mask:0xf bank_mask:0xf
	v_fmac_f32_dpp v195, v145, v95 row_shr:2 row_mask:0xf bank_mask:0xf
	v_fmac_f32_dpp v188, v158, v80 row_shl:15 row_mask:0xf bank_mask:0xf
	v_fmac_f32_dpp v189, v159, v81 row_shl:15 row_mask:0xf bank_mask:0xf
	v_fmac_f32_dpp v190, v160, v82 row_shl:15 row_mask:0xf bank_mask:0xf
	v_fmac_f32_dpp v191, v161, v83 row_shl:15 row_mask:0xf bank_mask:0xf
	v_fmac_f32_dpp v192, v154, v96 row_shl:15 row_mask:0xf bank_mask:0xf
	v_fmac_f32_dpp v193, v155, v97 row_shl:15 row_mask:0xf bank_mask:0xf
	v_fmac_f32_dpp v194, v156, v98 row_shl:15 row_mask:0xf bank_mask:0xf
	v_fmac_f32_dpp v195, v157, v99 row_shl:15 row_mask:0xf bank_mask:0xf
	v_fmac_f32_dpp v188, v158, v76 row_shl:14 row_mask:0xf bank_mask:0xf
	v_fmac_f32_dpp v189, v159, v77 row_shl:14 row_mask:0xf bank_mask:0xf
	v_fmac_f32_dpp v190, v160, v78 row_shl:14 row_mask:0xf bank_mask:0xf
	v_fmac_f32_dpp v191, v161, v79 row_shl:14 row_mask:0xf bank_mask:0xf
	v_fmac_f32_dpp v192, v154, v92 row_shl:14 row_mask:0xf bank_mask:0xf
	v_fmac_f32_dpp v193, v155, v93 row_shl:14 row_mask:0xf bank_mask:0xf
	v_fmac_f32_dpp v194, v156, v94 row_shl:14 row_mask:0xf bank_mask:0xf
	v_fmac_f32_dpp v195, v157, v95 row_shl:14 row_mask:0xf bank_mask:0xf
	v_pk_mul_f32 v[196:197], v[188:189], v[216:217] op_sel_hi:[1,0]
	v_pk_mul_f32 v[198:199], v[190:191], v[216:217] op_sel_hi:[1,0]
	v_exp_f32_e32 v196, v196
	v_exp_f32_e32 v197, v197
	v_exp_f32_e32 v198, v198
	v_exp_f32_e32 v199, v199
	v_pk_add_f32 v[196:197], v[196:197], v[214:215] op_sel_hi:[1,0]
	v_pk_add_f32 v[198:199], v[198:199], v[214:215] op_sel_hi:[1,0]
	v_rcp_f32_e32 v196, v196
	v_rcp_f32_e32 v197, v197
	v_rcp_f32_e32 v198, v198
	v_rcp_f32_e32 v199, v199
	v_pk_mul_f32 v[188:189], v[188:189], v[196:197]
	v_pk_mul_f32 v[190:191], v[190:191], v[198:199]
	v_pk_mul_f32 v[188:189], v[188:189], v[192:193]
	v_pk_mul_f32 v[190:191], v[190:191], v[194:195]
	v_cvt_pk_bf16_f32 v158, v188, v189
	v_cvt_pk_bf16_f32 v159, v190, v191
	global_load_dwordx4 v[154:157], v212, s[82:83] offset:16
	v_pk_fma_f32 v[188:189], v[146:147], v[84:85], v[88:89]
	v_pk_fma_f32 v[190:191], v[148:149], v[86:87], v[90:91]
	v_pk_fma_f32 v[192:193], v[134:135], v[100:101], v[104:105]
	v_pk_fma_f32 v[194:195], v[136:137], v[102:103], v[106:107]
	v_fmac_f32_dpp v188, v146, v80 row_shr:1 row_mask:0xf bank_mask:0xf
	v_fmac_f32_dpp v189, v147, v81 row_shr:1 row_mask:0xf bank_mask:0xf
	v_fmac_f32_dpp v190, v148, v82 row_shr:1 row_mask:0xf bank_mask:0xf
	v_fmac_f32_dpp v191, v149, v83 row_shr:1 row_mask:0xf bank_mask:0xf
	v_fmac_f32_dpp v192, v134, v96 row_shr:1 row_mask:0xf bank_mask:0xf
	v_fmac_f32_dpp v193, v135, v97 row_shr:1 row_mask:0xf bank_mask:0xf
	v_fmac_f32_dpp v194, v136, v98 row_shr:1 row_mask:0xf bank_mask:0xf
	v_fmac_f32_dpp v195, v137, v99 row_shr:1 row_mask:0xf bank_mask:0xf
	v_fmac_f32_dpp v188, v146, v76 row_shr:2 row_mask:0xf bank_mask:0xf
	v_fmac_f32_dpp v189, v147, v77 row_shr:2 row_mask:0xf bank_mask:0xf
	v_fmac_f32_dpp v190, v148, v78 row_shr:2 row_mask:0xf bank_mask:0xf
	v_fmac_f32_dpp v191, v149, v79 row_shr:2 row_mask:0xf bank_mask:0xf
	v_fmac_f32_dpp v192, v134, v92 row_shr:2 row_mask:0xf bank_mask:0xf
	v_fmac_f32_dpp v193, v135, v93 row_shr:2 row_mask:0xf bank_mask:0xf
	v_fmac_f32_dpp v194, v136, v94 row_shr:2 row_mask:0xf bank_mask:0xf
	v_fmac_f32_dpp v195, v137, v95 row_shr:2 row_mask:0xf bank_mask:0xf
	v_fmac_f32_dpp v188, v150, v80 row_shl:15 row_mask:0xf bank_mask:0xf
	v_fmac_f32_dpp v189, v151, v81 row_shl:15 row_mask:0xf bank_mask:0xf
	v_fmac_f32_dpp v190, v152, v82 row_shl:15 row_mask:0xf bank_mask:0xf
	v_fmac_f32_dpp v191, v153, v83 row_shl:15 row_mask:0xf bank_mask:0xf
	v_fmac_f32_dpp v192, v142, v96 row_shl:15 row_mask:0xf bank_mask:0xf
	v_fmac_f32_dpp v193, v143, v97 row_shl:15 row_mask:0xf bank_mask:0xf
	v_fmac_f32_dpp v194, v144, v98 row_shl:15 row_mask:0xf bank_mask:0xf
	v_fmac_f32_dpp v195, v145, v99 row_shl:15 row_mask:0xf bank_mask:0xf
	v_fmac_f32_dpp v188, v150, v76 row_shl:14 row_mask:0xf bank_mask:0xf
	v_fmac_f32_dpp v189, v151, v77 row_shl:14 row_mask:0xf bank_mask:0xf
	v_fmac_f32_dpp v190, v152, v78 row_shl:14 row_mask:0xf bank_mask:0xf
	v_fmac_f32_dpp v191, v153, v79 row_shl:14 row_mask:0xf bank_mask:0xf
	v_fmac_f32_dpp v192, v142, v92 row_shl:14 row_mask:0xf bank_mask:0xf
	v_fmac_f32_dpp v193, v143, v93 row_shl:14 row_mask:0xf bank_mask:0xf
	v_fmac_f32_dpp v194, v144, v94 row_shl:14 row_mask:0xf bank_mask:0xf
	v_fmac_f32_dpp v195, v145, v95 row_shl:14 row_mask:0xf bank_mask:0xf
	v_pk_mul_f32 v[196:197], v[188:189], v[216:217] op_sel_hi:[1,0]
	v_pk_mul_f32 v[198:199], v[190:191], v[216:217] op_sel_hi:[1,0]
	v_exp_f32_e32 v196, v196
	v_exp_f32_e32 v197, v197
	v_exp_f32_e32 v198, v198
	v_exp_f32_e32 v199, v199
	v_pk_add_f32 v[196:197], v[196:197], v[214:215] op_sel_hi:[1,0]
	v_pk_add_f32 v[198:199], v[198:199], v[214:215] op_sel_hi:[1,0]
	v_rcp_f32_e32 v196, v196
	v_rcp_f32_e32 v197, v197
	v_rcp_f32_e32 v198, v198
	v_rcp_f32_e32 v199, v199
	v_pk_mul_f32 v[188:189], v[188:189], v[196:197]
	v_pk_mul_f32 v[190:191], v[190:191], v[198:199]
	v_pk_mul_f32 v[188:189], v[188:189], v[192:193]
	v_pk_mul_f32 v[190:191], v[190:191], v[194:195]
	v_cvt_pk_bf16_f32 v150, v188, v189
	v_cvt_pk_bf16_f32 v151, v190, v191
	v_add_u32_e32 v213, 0xb000, v212
	global_load_dwordx4 v[142:145], v213, s[82:83] offset:16
	v_pk_fma_f32 v[188:189], v[138:139], v[84:85], v[88:89]
	v_pk_fma_f32 v[190:191], v[140:141], v[86:87], v[90:91]
	v_pk_fma_f32 v[192:193], v[130:131], v[100:101], v[104:105]
	v_pk_fma_f32 v[194:195], v[132:133], v[102:103], v[106:107]
	v_fmac_f32_dpp v188, v138, v80 row_shr:1 row_mask:0xf bank_mask:0xf
	v_fmac_f32_dpp v189, v139, v81 row_shr:1 row_mask:0xf bank_mask:0xf
	v_fmac_f32_dpp v190, v140, v82 row_shr:1 row_mask:0xf bank_mask:0xf
	v_fmac_f32_dpp v191, v141, v83 row_shr:1 row_mask:0xf bank_mask:0xf
	v_fmac_f32_dpp v192, v130, v96 row_shr:1 row_mask:0xf bank_mask:0xf
	v_fmac_f32_dpp v193, v131, v97 row_shr:1 row_mask:0xf bank_mask:0xf
	v_fmac_f32_dpp v194, v132, v98 row_shr:1 row_mask:0xf bank_mask:0xf
	v_fmac_f32_dpp v195, v133, v99 row_shr:1 row_mask:0xf bank_mask:0xf
	v_fmac_f32_dpp v188, v138, v76 row_shr:2 row_mask:0xf bank_mask:0xf
	v_fmac_f32_dpp v189, v139, v77 row_shr:2 row_mask:0xf bank_mask:0xf
	v_fmac_f32_dpp v190, v140, v78 row_shr:2 row_mask:0xf bank_mask:0xf
	v_fmac_f32_dpp v191, v141, v79 row_shr:2 row_mask:0xf bank_mask:0xf
	v_fmac_f32_dpp v192, v130, v92 row_shr:2 row_mask:0xf bank_mask:0xf
	v_fmac_f32_dpp v193, v131, v93 row_shr:2 row_mask:0xf bank_mask:0xf
	v_fmac_f32_dpp v194, v132, v94 row_shr:2 row_mask:0xf bank_mask:0xf
	v_fmac_f32_dpp v195, v133, v95 row_shr:2 row_mask:0xf bank_mask:0xf
	v_fmac_f32_dpp v188, v146, v80 row_shl:15 row_mask:0xf bank_mask:0xf
	v_fmac_f32_dpp v189, v147, v81 row_shl:15 row_mask:0xf bank_mask:0xf
	v_fmac_f32_dpp v190, v148, v82 row_shl:15 row_mask:0xf bank_mask:0xf
	v_fmac_f32_dpp v191, v149, v83 row_shl:15 row_mask:0xf bank_mask:0xf
	v_fmac_f32_dpp v192, v134, v96 row_shl:15 row_mask:0xf bank_mask:0xf
	v_fmac_f32_dpp v193, v135, v97 row_shl:15 row_mask:0xf bank_mask:0xf
	v_fmac_f32_dpp v194, v136, v98 row_shl:15 row_mask:0xf bank_mask:0xf
	v_fmac_f32_dpp v195, v137, v99 row_shl:15 row_mask:0xf bank_mask:0xf
	v_fmac_f32_dpp v188, v146, v76 row_shl:14 row_mask:0xf bank_mask:0xf
	v_fmac_f32_dpp v189, v147, v77 row_shl:14 row_mask:0xf bank_mask:0xf
	v_fmac_f32_dpp v190, v148, v78 row_shl:14 row_mask:0xf bank_mask:0xf
	v_fmac_f32_dpp v191, v149, v79 row_shl:14 row_mask:0xf bank_mask:0xf
	v_fmac_f32_dpp v192, v134, v92 row_shl:14 row_mask:0xf bank_mask:0xf
	v_fmac_f32_dpp v193, v135, v93 row_shl:14 row_mask:0xf bank_mask:0xf
	v_fmac_f32_dpp v194, v136, v94 row_shl:14 row_mask:0xf bank_mask:0xf
	v_fmac_f32_dpp v195, v137, v95 row_shl:14 row_mask:0xf bank_mask:0xf
	v_pk_mul_f32 v[196:197], v[188:189], v[216:217] op_sel_hi:[1,0]
	v_pk_mul_f32 v[198:199], v[190:191], v[216:217] op_sel_hi:[1,0]
	v_exp_f32_e32 v196, v196
	v_exp_f32_e32 v197, v197
	v_exp_f32_e32 v198, v198
	v_exp_f32_e32 v199, v199
	v_pk_add_f32 v[196:197], v[196:197], v[214:215] op_sel_hi:[1,0]
	v_pk_add_f32 v[198:199], v[198:199], v[214:215] op_sel_hi:[1,0]
	v_rcp_f32_e32 v196, v196
	v_rcp_f32_e32 v197, v197
	v_rcp_f32_e32 v198, v198
	v_rcp_f32_e32 v199, v199
	v_pk_mul_f32 v[188:189], v[188:189], v[196:197]
	v_pk_mul_f32 v[190:191], v[190:191], v[198:199]
	v_pk_mul_f32 v[188:189], v[188:189], v[192:193]
	v_pk_mul_f32 v[190:191], v[190:191], v[194:195]
	v_cvt_pk_bf16_f32 v146, v188, v189
	v_cvt_pk_bf16_f32 v147, v190, v191
	v_add_u32_e32 v213, 0x16000, v212
	global_load_dwordx4 v[134:137], v213, s[82:83] offset:16
	v_pk_fma_f32 v[188:189], v[126:127], v[84:85], v[88:89]
	v_pk_fma_f32 v[190:191], v[128:129], v[86:87], v[90:91]
	v_pk_fma_f32 v[192:193], v[118:119], v[100:101], v[104:105]
	v_pk_fma_f32 v[194:195], v[120:121], v[102:103], v[106:107]
	v_fmac_f32_dpp v188, v126, v80 row_shr:1 row_mask:0xf bank_mask:0xf
	v_fmac_f32_dpp v189, v127, v81 row_shr:1 row_mask:0xf bank_mask:0xf
	v_fmac_f32_dpp v190, v128, v82 row_shr:1 row_mask:0xf bank_mask:0xf
	v_fmac_f32_dpp v191, v129, v83 row_shr:1 row_mask:0xf bank_mask:0xf
	v_fmac_f32_dpp v192, v118, v96 row_shr:1 row_mask:0xf bank_mask:0xf
	v_fmac_f32_dpp v193, v119, v97 row_shr:1 row_mask:0xf bank_mask:0xf
	v_fmac_f32_dpp v194, v120, v98 row_shr:1 row_mask:0xf bank_mask:0xf
	v_fmac_f32_dpp v195, v121, v99 row_shr:1 row_mask:0xf bank_mask:0xf
	v_fmac_f32_dpp v188, v126, v76 row_shr:2 row_mask:0xf bank_mask:0xf
	v_fmac_f32_dpp v189, v127, v77 row_shr:2 row_mask:0xf bank_mask:0xf
	v_fmac_f32_dpp v190, v128, v78 row_shr:2 row_mask:0xf bank_mask:0xf
	v_fmac_f32_dpp v191, v129, v79 row_shr:2 row_mask:0xf bank_mask:0xf
	v_fmac_f32_dpp v192, v118, v92 row_shr:2 row_mask:0xf bank_mask:0xf
	v_fmac_f32_dpp v193, v119, v93 row_shr:2 row_mask:0xf bank_mask:0xf
	v_fmac_f32_dpp v194, v120, v94 row_shr:2 row_mask:0xf bank_mask:0xf
	v_fmac_f32_dpp v195, v121, v95 row_shr:2 row_mask:0xf bank_mask:0xf
	v_fmac_f32_dpp v188, v138, v80 row_shl:15 row_mask:0xf bank_mask:0xf
	v_fmac_f32_dpp v189, v139, v81 row_shl:15 row_mask:0xf bank_mask:0xf
	v_fmac_f32_dpp v190, v140, v82 row_shl:15 row_mask:0xf bank_mask:0xf
	v_fmac_f32_dpp v191, v141, v83 row_shl:15 row_mask:0xf bank_mask:0xf
	v_fmac_f32_dpp v192, v130, v96 row_shl:15 row_mask:0xf bank_mask:0xf
	v_fmac_f32_dpp v193, v131, v97 row_shl:15 row_mask:0xf bank_mask:0xf
	v_fmac_f32_dpp v194, v132, v98 row_shl:15 row_mask:0xf bank_mask:0xf
	v_fmac_f32_dpp v195, v133, v99 row_shl:15 row_mask:0xf bank_mask:0xf
	v_fmac_f32_dpp v188, v138, v76 row_shl:14 row_mask:0xf bank_mask:0xf
	v_fmac_f32_dpp v189, v139, v77 row_shl:14 row_mask:0xf bank_mask:0xf
	v_fmac_f32_dpp v190, v140, v78 row_shl:14 row_mask:0xf bank_mask:0xf
	v_fmac_f32_dpp v191, v141, v79 row_shl:14 row_mask:0xf bank_mask:0xf
	v_fmac_f32_dpp v192, v130, v92 row_shl:14 row_mask:0xf bank_mask:0xf
	v_fmac_f32_dpp v193, v131, v93 row_shl:14 row_mask:0xf bank_mask:0xf
	v_fmac_f32_dpp v194, v132, v94 row_shl:14 row_mask:0xf bank_mask:0xf
	v_fmac_f32_dpp v195, v133, v95 row_shl:14 row_mask:0xf bank_mask:0xf
	v_pk_mul_f32 v[196:197], v[188:189], v[216:217] op_sel_hi:[1,0]
	v_pk_mul_f32 v[198:199], v[190:191], v[216:217] op_sel_hi:[1,0]
	v_exp_f32_e32 v196, v196
	v_exp_f32_e32 v197, v197
	v_exp_f32_e32 v198, v198
	v_exp_f32_e32 v199, v199
	v_pk_add_f32 v[196:197], v[196:197], v[214:215] op_sel_hi:[1,0]
	v_pk_add_f32 v[198:199], v[198:199], v[214:215] op_sel_hi:[1,0]
	v_rcp_f32_e32 v196, v196
	v_rcp_f32_e32 v197, v197
	v_rcp_f32_e32 v198, v198
	v_rcp_f32_e32 v199, v199
	v_pk_mul_f32 v[188:189], v[188:189], v[196:197]
	v_pk_mul_f32 v[190:191], v[190:191], v[198:199]
	v_pk_mul_f32 v[188:189], v[188:189], v[192:193]
	v_pk_mul_f32 v[190:191], v[190:191], v[194:195]
	v_cvt_pk_bf16_f32 v138, v188, v189
	v_cvt_pk_bf16_f32 v139, v190, v191
	global_load_dwordx4 v[130:133], v212, s[84:85] offset:16
	v_pk_fma_f32 v[188:189], v[122:123], v[84:85], v[88:89]
	v_pk_fma_f32 v[190:191], v[124:125], v[86:87], v[90:91]
	v_pk_fma_f32 v[192:193], v[110:111], v[100:101], v[104:105]
	v_pk_fma_f32 v[194:195], v[112:113], v[102:103], v[106:107]
	v_fmac_f32_dpp v188, v122, v80 row_shr:1 row_mask:0xf bank_mask:0xf
	v_fmac_f32_dpp v189, v123, v81 row_shr:1 row_mask:0xf bank_mask:0xf
	v_fmac_f32_dpp v190, v124, v82 row_shr:1 row_mask:0xf bank_mask:0xf
	v_fmac_f32_dpp v191, v125, v83 row_shr:1 row_mask:0xf bank_mask:0xf
	v_fmac_f32_dpp v192, v110, v96 row_shr:1 row_mask:0xf bank_mask:0xf
	v_fmac_f32_dpp v193, v111, v97 row_shr:1 row_mask:0xf bank_mask:0xf
	v_fmac_f32_dpp v194, v112, v98 row_shr:1 row_mask:0xf bank_mask:0xf
	v_fmac_f32_dpp v195, v113, v99 row_shr:1 row_mask:0xf bank_mask:0xf
	v_fmac_f32_dpp v188, v122, v76 row_shr:2 row_mask:0xf bank_mask:0xf
	v_fmac_f32_dpp v189, v123, v77 row_shr:2 row_mask:0xf bank_mask:0xf
	v_fmac_f32_dpp v190, v124, v78 row_shr:2 row_mask:0xf bank_mask:0xf
	v_fmac_f32_dpp v191, v125, v79 row_shr:2 row_mask:0xf bank_mask:0xf
	v_fmac_f32_dpp v192, v110, v92 row_shr:2 row_mask:0xf bank_mask:0xf
	v_fmac_f32_dpp v193, v111, v93 row_shr:2 row_mask:0xf bank_mask:0xf
	v_fmac_f32_dpp v194, v112, v94 row_shr:2 row_mask:0xf bank_mask:0xf
	v_fmac_f32_dpp v195, v113, v95 row_shr:2 row_mask:0xf bank_mask:0xf
	v_fmac_f32_dpp v188, v126, v80 row_shl:15 row_mask:0xf bank_mask:0xf
	v_fmac_f32_dpp v189, v127, v81 row_shl:15 row_mask:0xf bank_mask:0xf
	v_fmac_f32_dpp v190, v128, v82 row_shl:15 row_mask:0xf bank_mask:0xf
	v_fmac_f32_dpp v191, v129, v83 row_shl:15 row_mask:0xf bank_mask:0xf
	v_fmac_f32_dpp v192, v118, v96 row_shl:15 row_mask:0xf bank_mask:0xf
	v_fmac_f32_dpp v193, v119, v97 row_shl:15 row_mask:0xf bank_mask:0xf
	v_fmac_f32_dpp v194, v120, v98 row_shl:15 row_mask:0xf bank_mask:0xf
	v_fmac_f32_dpp v195, v121, v99 row_shl:15 row_mask:0xf bank_mask:0xf
	v_fmac_f32_dpp v188, v126, v76 row_shl:14 row_mask:0xf bank_mask:0xf
	v_fmac_f32_dpp v189, v127, v77 row_shl:14 row_mask:0xf bank_mask:0xf
	v_fmac_f32_dpp v190, v128, v78 row_shl:14 row_mask:0xf bank_mask:0xf
	v_fmac_f32_dpp v191, v129, v79 row_shl:14 row_mask:0xf bank_mask:0xf
	v_fmac_f32_dpp v192, v118, v92 row_shl:14 row_mask:0xf bank_mask:0xf
	v_fmac_f32_dpp v193, v119, v93 row_shl:14 row_mask:0xf bank_mask:0xf
	v_fmac_f32_dpp v194, v120, v94 row_shl:14 row_mask:0xf bank_mask:0xf
	v_fmac_f32_dpp v195, v121, v95 row_shl:14 row_mask:0xf bank_mask:0xf
	v_pk_mul_f32 v[196:197], v[188:189], v[216:217] op_sel_hi:[1,0]
	v_pk_mul_f32 v[198:199], v[190:191], v[216:217] op_sel_hi:[1,0]
	v_exp_f32_e32 v196, v196
	v_exp_f32_e32 v197, v197
	v_exp_f32_e32 v198, v198
	v_exp_f32_e32 v199, v199
	v_pk_add_f32 v[196:197], v[196:197], v[214:215] op_sel_hi:[1,0]
	v_pk_add_f32 v[198:199], v[198:199], v[214:215] op_sel_hi:[1,0]
	v_rcp_f32_e32 v196, v196
	v_rcp_f32_e32 v197, v197
	v_rcp_f32_e32 v198, v198
	v_rcp_f32_e32 v199, v199
	v_pk_mul_f32 v[188:189], v[188:189], v[196:197]
	v_pk_mul_f32 v[190:191], v[190:191], v[198:199]
	v_pk_mul_f32 v[188:189], v[188:189], v[192:193]
	v_pk_mul_f32 v[190:191], v[190:191], v[194:195]
	v_cvt_pk_bf16_f32 v126, v188, v189
	v_cvt_pk_bf16_f32 v127, v190, v191
	v_add_u32_e32 v213, 0x5800, v212
	global_load_dwordx4 v[118:121], v213, s[82:83] offset:16
	v_pk_fma_f32 v[188:189], v[114:115], v[84:85], v[88:89]
	v_pk_fma_f32 v[190:191], v[116:117], v[86:87], v[90:91]
	v_pk_fma_f32 v[192:193], v[68:69], v[100:101], v[104:105]
	v_pk_fma_f32 v[194:195], v[70:71], v[102:103], v[106:107]
	v_fmac_f32_dpp v188, v114, v80 row_shr:1 row_mask:0xf bank_mask:0xf
	v_fmac_f32_dpp v189, v115, v81 row_shr:1 row_mask:0xf bank_mask:0xf
	v_fmac_f32_dpp v190, v116, v82 row_shr:1 row_mask:0xf bank_mask:0xf
	v_fmac_f32_dpp v191, v117, v83 row_shr:1 row_mask:0xf bank_mask:0xf
	v_fmac_f32_dpp v192, v68, v96 row_shr:1 row_mask:0xf bank_mask:0xf
	v_fmac_f32_dpp v193, v69, v97 row_shr:1 row_mask:0xf bank_mask:0xf
	v_fmac_f32_dpp v194, v70, v98 row_shr:1 row_mask:0xf bank_mask:0xf
	v_fmac_f32_dpp v195, v71, v99 row_shr:1 row_mask:0xf bank_mask:0xf
	v_fmac_f32_dpp v188, v114, v76 row_shr:2 row_mask:0xf bank_mask:0xf
	v_fmac_f32_dpp v189, v115, v77 row_shr:2 row_mask:0xf bank_mask:0xf
	v_fmac_f32_dpp v190, v116, v78 row_shr:2 row_mask:0xf bank_mask:0xf
	v_fmac_f32_dpp v191, v117, v79 row_shr:2 row_mask:0xf bank_mask:0xf
	v_fmac_f32_dpp v192, v68, v92 row_shr:2 row_mask:0xf bank_mask:0xf
	v_fmac_f32_dpp v193, v69, v93 row_shr:2 row_mask:0xf bank_mask:0xf
	v_fmac_f32_dpp v194, v70, v94 row_shr:2 row_mask:0xf bank_mask:0xf
	v_fmac_f32_dpp v195, v71, v95 row_shr:2 row_mask:0xf bank_mask:0xf
	v_fmac_f32_dpp v188, v122, v80 row_shl:15 row_mask:0xf bank_mask:0xf
	v_fmac_f32_dpp v189, v123, v81 row_shl:15 row_mask:0xf bank_mask:0xf
	v_fmac_f32_dpp v190, v124, v82 row_shl:15 row_mask:0xf bank_mask:0xf
	v_fmac_f32_dpp v191, v125, v83 row_shl:15 row_mask:0xf bank_mask:0xf
	v_fmac_f32_dpp v192, v110, v96 row_shl:15 row_mask:0xf bank_mask:0xf
	v_fmac_f32_dpp v193, v111, v97 row_shl:15 row_mask:0xf bank_mask:0xf
	v_fmac_f32_dpp v194, v112, v98 row_shl:15 row_mask:0xf bank_mask:0xf
	v_fmac_f32_dpp v195, v113, v99 row_shl:15 row_mask:0xf bank_mask:0xf
	v_fmac_f32_dpp v188, v122, v76 row_shl:14 row_mask:0xf bank_mask:0xf
	v_fmac_f32_dpp v189, v123, v77 row_shl:14 row_mask:0xf bank_mask:0xf
	v_fmac_f32_dpp v190, v124, v78 row_shl:14 row_mask:0xf bank_mask:0xf
	v_fmac_f32_dpp v191, v125, v79 row_shl:14 row_mask:0xf bank_mask:0xf
	v_fmac_f32_dpp v192, v110, v92 row_shl:14 row_mask:0xf bank_mask:0xf
	v_fmac_f32_dpp v193, v111, v93 row_shl:14 row_mask:0xf bank_mask:0xf
	v_fmac_f32_dpp v194, v112, v94 row_shl:14 row_mask:0xf bank_mask:0xf
	v_fmac_f32_dpp v195, v113, v95 row_shl:14 row_mask:0xf bank_mask:0xf
	v_pk_mul_f32 v[196:197], v[188:189], v[216:217] op_sel_hi:[1,0]
	v_pk_mul_f32 v[198:199], v[190:191], v[216:217] op_sel_hi:[1,0]
	v_exp_f32_e32 v196, v196
	v_exp_f32_e32 v197, v197
	v_exp_f32_e32 v198, v198
	v_exp_f32_e32 v199, v199
	v_pk_add_f32 v[196:197], v[196:197], v[214:215] op_sel_hi:[1,0]
	v_pk_add_f32 v[198:199], v[198:199], v[214:215] op_sel_hi:[1,0]
	v_rcp_f32_e32 v196, v196
	v_rcp_f32_e32 v197, v197
	v_rcp_f32_e32 v198, v198
	v_rcp_f32_e32 v199, v199
	v_pk_mul_f32 v[188:189], v[188:189], v[196:197]
	v_pk_mul_f32 v[190:191], v[190:191], v[198:199]
	v_pk_mul_f32 v[188:189], v[188:189], v[192:193]
	v_pk_mul_f32 v[190:191], v[190:191], v[194:195]
	v_cvt_pk_bf16_f32 v122, v188, v189
	v_cvt_pk_bf16_f32 v123, v190, v191
	v_add_u32_e32 v213, 0x10800, v212
	global_load_dwordx4 v[110:113], v213, s[82:83] offset:16
	v_pk_fma_f32 v[188:189], v[72:73], v[84:85], v[88:89]
	v_pk_fma_f32 v[190:191], v[74:75], v[86:87], v[90:91]
	v_pk_fma_f32 v[192:193], v[64:65], v[100:101], v[104:105]
	v_pk_fma_f32 v[194:195], v[66:67], v[102:103], v[106:107]
	v_fmac_f32_dpp v188, v72, v80 row_shr:1 row_mask:0xf bank_mask:0xf
	v_fmac_f32_dpp v189, v73, v81 row_shr:1 row_mask:0xf bank_mask:0xf
	v_fmac_f32_dpp v190, v74, v82 row_shr:1 row_mask:0xf bank_mask:0xf
	v_fmac_f32_dpp v191, v75, v83 row_shr:1 row_mask:0xf bank_mask:0xf
	v_fmac_f32_dpp v192, v64, v96 row_shr:1 row_mask:0xf bank_mask:0xf
	v_fmac_f32_dpp v193, v65, v97 row_shr:1 row_mask:0xf bank_mask:0xf
	v_fmac_f32_dpp v194, v66, v98 row_shr:1 row_mask:0xf bank_mask:0xf
	v_fmac_f32_dpp v195, v67, v99 row_shr:1 row_mask:0xf bank_mask:0xf
	v_fmac_f32_dpp v188, v72, v76 row_shr:2 row_mask:0xf bank_mask:0xf
	v_fmac_f32_dpp v189, v73, v77 row_shr:2 row_mask:0xf bank_mask:0xf
	v_fmac_f32_dpp v190, v74, v78 row_shr:2 row_mask:0xf bank_mask:0xf
	v_fmac_f32_dpp v191, v75, v79 row_shr:2 row_mask:0xf bank_mask:0xf
	v_fmac_f32_dpp v192, v64, v92 row_shr:2 row_mask:0xf bank_mask:0xf
	v_fmac_f32_dpp v193, v65, v93 row_shr:2 row_mask:0xf bank_mask:0xf
	v_fmac_f32_dpp v194, v66, v94 row_shr:2 row_mask:0xf bank_mask:0xf
	v_fmac_f32_dpp v195, v67, v95 row_shr:2 row_mask:0xf bank_mask:0xf
	v_fmac_f32_dpp v188, v114, v80 row_shl:15 row_mask:0xf bank_mask:0xf
	v_fmac_f32_dpp v189, v115, v81 row_shl:15 row_mask:0xf bank_mask:0xf
	v_fmac_f32_dpp v190, v116, v82 row_shl:15 row_mask:0xf bank_mask:0xf
	v_fmac_f32_dpp v191, v117, v83 row_shl:15 row_mask:0xf bank_mask:0xf
	v_fmac_f32_dpp v192, v68, v96 row_shl:15 row_mask:0xf bank_mask:0xf
	v_fmac_f32_dpp v193, v69, v97 row_shl:15 row_mask:0xf bank_mask:0xf
	v_fmac_f32_dpp v194, v70, v98 row_shl:15 row_mask:0xf bank_mask:0xf
	v_fmac_f32_dpp v195, v71, v99 row_shl:15 row_mask:0xf bank_mask:0xf
	v_fmac_f32_dpp v188, v114, v76 row_shl:14 row_mask:0xf bank_mask:0xf
	v_fmac_f32_dpp v189, v115, v77 row_shl:14 row_mask:0xf bank_mask:0xf
	v_fmac_f32_dpp v190, v116, v78 row_shl:14 row_mask:0xf bank_mask:0xf
	v_fmac_f32_dpp v191, v117, v79 row_shl:14 row_mask:0xf bank_mask:0xf
	v_fmac_f32_dpp v192, v68, v92 row_shl:14 row_mask:0xf bank_mask:0xf
	v_fmac_f32_dpp v193, v69, v93 row_shl:14 row_mask:0xf bank_mask:0xf
	v_fmac_f32_dpp v194, v70, v94 row_shl:14 row_mask:0xf bank_mask:0xf
	v_fmac_f32_dpp v195, v71, v95 row_shl:14 row_mask:0xf bank_mask:0xf
	v_pk_mul_f32 v[196:197], v[188:189], v[216:217] op_sel_hi:[1,0]
	v_pk_mul_f32 v[198:199], v[190:191], v[216:217] op_sel_hi:[1,0]
	v_exp_f32_e32 v196, v196
	v_exp_f32_e32 v197, v197
	v_exp_f32_e32 v198, v198
	v_exp_f32_e32 v199, v199
	v_pk_add_f32 v[196:197], v[196:197], v[214:215] op_sel_hi:[1,0]
	v_pk_add_f32 v[198:199], v[198:199], v[214:215] op_sel_hi:[1,0]
	v_rcp_f32_e32 v196, v196
	v_rcp_f32_e32 v197, v197
	v_rcp_f32_e32 v198, v198
	v_rcp_f32_e32 v199, v199
	v_pk_mul_f32 v[188:189], v[188:189], v[196:197]
	v_pk_mul_f32 v[190:191], v[190:191], v[198:199]
	v_pk_mul_f32 v[188:189], v[188:189], v[192:193]
	v_pk_mul_f32 v[190:191], v[190:191], v[194:195]
	v_cvt_pk_bf16_f32 v114, v188, v189
	v_cvt_pk_bf16_f32 v115, v190, v191
	s_waitcnt vmcnt(0)
	v_pk_fma_f32 v[188:189], v[60:61], v[134:135], v[130:131]
	v_pk_fma_f32 v[190:191], v[62:63], v[136:137], v[132:133]
	v_pk_fma_f32 v[192:193], v[56:57], v[204:205], v[208:209]
	v_pk_fma_f32 v[194:195], v[58:59], v[206:207], v[210:211]
	v_fmac_f32_dpp v188, v60, v142 row_shr:1 row_mask:0xf bank_mask:0xf
	v_fmac_f32_dpp v189, v61, v143 row_shr:1 row_mask:0xf bank_mask:0xf
	v_fmac_f32_dpp v190, v62, v144 row_shr:1 row_mask:0xf bank_mask:0xf
	v_fmac_f32_dpp v191, v63, v145 row_shr:1 row_mask:0xf bank_mask:0xf
	v_fmac_f32_dpp v192, v56, v110 row_shr:1 row_mask:0xf bank_mask:0xf
	v_fmac_f32_dpp v193, v57, v111 row_shr:1 row_mask:0xf bank_mask:0xf
	v_fmac_f32_dpp v194, v58, v112 row_shr:1 row_mask:0xf bank_mask:0xf
	v_fmac_f32_dpp v195, v59, v113 row_shr:1 row_mask:0xf bank_mask:0xf
	v_fmac_f32_dpp v188, v60, v154 row_shr:2 row_mask:0xf bank_mask:0xf
	v_fmac_f32_dpp v189, v61, v155 row_shr:2 row_mask:0xf bank_mask:0xf
	v_fmac_f32_dpp v190, v62, v156 row_shr:2 row_mask:0xf bank_mask:0xf
	v_fmac_f32_dpp v191, v63, v157 row_shr:2 row_mask:0xf bank_mask:0xf
	v_fmac_f32_dpp v192, v56, v118 row_shr:2 row_mask:0xf bank_mask:0xf
	v_fmac_f32_dpp v193, v57, v119 row_shr:2 row_mask:0xf bank_mask:0xf
	v_fmac_f32_dpp v194, v58, v120 row_shr:2 row_mask:0xf bank_mask:0xf
	v_fmac_f32_dpp v195, v59, v121 row_shr:2 row_mask:0xf bank_mask:0xf
	v_pk_mul_f32 v[196:197], v[188:189], v[216:217] op_sel_hi:[1,0]
	v_pk_mul_f32 v[198:199], v[190:191], v[216:217] op_sel_hi:[1,0]
	v_exp_f32_e32 v196, v196
	v_exp_f32_e32 v197, v197
	v_exp_f32_e32 v198, v198
	v_exp_f32_e32 v199, v199
	v_pk_add_f32 v[196:197], v[196:197], v[214:215] op_sel_hi:[1,0]
	v_pk_add_f32 v[198:199], v[198:199], v[214:215] op_sel_hi:[1,0]
	v_rcp_f32_e32 v196, v196
	v_rcp_f32_e32 v197, v197
	v_rcp_f32_e32 v198, v198
	v_rcp_f32_e32 v199, v199
	v_pk_mul_f32 v[188:189], v[188:189], v[196:197]
	v_pk_mul_f32 v[190:191], v[190:191], v[198:199]
	v_pk_mul_f32 v[188:189], v[188:189], v[192:193]
	v_pk_mul_f32 v[190:191], v[190:191], v[194:195]
	v_cvt_pk_bf16_f32 v202, v188, v189
	v_cvt_pk_bf16_f32 v203, v190, v191
	s_mov_b64 exec, vcc
	global_store_dwordx4 v215, v[200:203], s[96:97]
	s_mov_b64 exec, -1
	v_pk_fma_f32 v[188:189], v[52:53], v[134:135], v[130:131]
	v_pk_fma_f32 v[190:191], v[54:55], v[136:137], v[132:133]
	v_pk_fma_f32 v[192:193], v[44:45], v[204:205], v[208:209]
	v_pk_fma_f32 v[194:195], v[46:47], v[206:207], v[210:211]
	v_fmac_f32_dpp v188, v52, v142 row_shr:1 row_mask:0xf bank_mask:0xf
	v_fmac_f32_dpp v189, v53, v143 row_shr:1 row_mask:0xf bank_mask:0xf
	v_fmac_f32_dpp v190, v54, v144 row_shr:1 row_mask:0xf bank_mask:0xf
	v_fmac_f32_dpp v191, v55, v145 row_shr:1 row_mask:0xf bank_mask:0xf
	v_fmac_f32_dpp v192, v44, v110 row_shr:1 row_mask:0xf bank_mask:0xf
	v_fmac_f32_dpp v193, v45, v111 row_shr:1 row_mask:0xf bank_mask:0xf
	v_fmac_f32_dpp v194, v46, v112 row_shr:1 row_mask:0xf bank_mask:0xf
	v_fmac_f32_dpp v195, v47, v113 row_shr:1 row_mask:0xf bank_mask:0xf
	v_fmac_f32_dpp v188, v52, v154 row_shr:2 row_mask:0xf bank_mask:0xf
	v_fmac_f32_dpp v189, v53, v155 row_shr:2 row_mask:0xf bank_mask:0xf
	v_fmac_f32_dpp v190, v54, v156 row_shr:2 row_mask:0xf bank_mask:0xf
	v_fmac_f32_dpp v191, v55, v157 row_shr:2 row_mask:0xf bank_mask:0xf
	v_fmac_f32_dpp v192, v44, v118 row_shr:2 row_mask:0xf bank_mask:0xf
	v_fmac_f32_dpp v193, v45, v119 row_shr:2 row_mask:0xf bank_mask:0xf
	v_fmac_f32_dpp v194, v46, v120 row_shr:2 row_mask:0xf bank_mask:0xf
	v_fmac_f32_dpp v195, v47, v121 row_shr:2 row_mask:0xf bank_mask:0xf
	v_fmac_f32_dpp v188, v60, v142 row_shl:15 row_mask:0xf bank_mask:0xf
	v_fmac_f32_dpp v189, v61, v143 row_shl:15 row_mask:0xf bank_mask:0xf
	v_fmac_f32_dpp v190, v62, v144 row_shl:15 row_mask:0xf bank_mask:0xf
	v_fmac_f32_dpp v191, v63, v145 row_shl:15 row_mask:0xf bank_mask:0xf
	v_fmac_f32_dpp v192, v56, v110 row_shl:15 row_mask:0xf bank_mask:0xf
	v_fmac_f32_dpp v193, v57, v111 row_shl:15 row_mask:0xf bank_mask:0xf
	v_fmac_f32_dpp v194, v58, v112 row_shl:15 row_mask:0xf bank_mask:0xf
	v_fmac_f32_dpp v195, v59, v113 row_shl:15 row_mask:0xf bank_mask:0xf
	v_fmac_f32_dpp v188, v60, v154 row_shl:14 row_mask:0xf bank_mask:0xf
	v_fmac_f32_dpp v189, v61, v155 row_shl:14 row_mask:0xf bank_mask:0xf
	v_fmac_f32_dpp v190, v62, v156 row_shl:14 row_mask:0xf bank_mask:0xf
	v_fmac_f32_dpp v191, v63, v157 row_shl:14 row_mask:0xf bank_mask:0xf
	v_fmac_f32_dpp v192, v56, v118 row_shl:14 row_mask:0xf bank_mask:0xf
	v_fmac_f32_dpp v193, v57, v119 row_shl:14 row_mask:0xf bank_mask:0xf
	v_fmac_f32_dpp v194, v58, v120 row_shl:14 row_mask:0xf bank_mask:0xf
	v_fmac_f32_dpp v195, v59, v121 row_shl:14 row_mask:0xf bank_mask:0xf
	v_pk_mul_f32 v[196:197], v[188:189], v[216:217] op_sel_hi:[1,0]
	v_pk_mul_f32 v[198:199], v[190:191], v[216:217] op_sel_hi:[1,0]
	v_exp_f32_e32 v196, v196
	v_exp_f32_e32 v197, v197
	v_exp_f32_e32 v198, v198
	v_exp_f32_e32 v199, v199
	v_pk_add_f32 v[196:197], v[196:197], v[214:215] op_sel_hi:[1,0]
	v_pk_add_f32 v[198:199], v[198:199], v[214:215] op_sel_hi:[1,0]
	v_rcp_f32_e32 v196, v196
	v_rcp_f32_e32 v197, v197
	v_rcp_f32_e32 v198, v198
	v_rcp_f32_e32 v199, v199
	v_pk_mul_f32 v[188:189], v[188:189], v[196:197]
	v_pk_mul_f32 v[190:191], v[190:191], v[198:199]
	v_pk_mul_f32 v[188:189], v[188:189], v[192:193]
	v_pk_mul_f32 v[190:191], v[190:191], v[194:195]
	v_cvt_pk_bf16_f32 v160, v188, v189
	v_cvt_pk_bf16_f32 v161, v190, v191
	v_add_u32_e32 v213, 0x2c000, v215
	global_store_dwordx4 v213, v[158:161], s[96:97]
	v_pk_fma_f32 v[188:189], v[48:49], v[134:135], v[130:131]
	v_pk_fma_f32 v[190:191], v[50:51], v[136:137], v[132:133]
	v_pk_fma_f32 v[192:193], v[36:37], v[204:205], v[208:209]
	v_pk_fma_f32 v[194:195], v[38:39], v[206:207], v[210:211]
	v_fmac_f32_dpp v188, v48, v142 row_shr:1 row_mask:0xf bank_mask:0xf
	v_fmac_f32_dpp v189, v49, v143 row_shr:1 row_mask:0xf bank_mask:0xf
	v_fmac_f32_dpp v190, v50, v144 row_shr:1 row_mask:0xf bank_mask:0xf
	v_fmac_f32_dpp v191, v51, v145 row_shr:1 row_mask:0xf bank_mask:0xf
	v_fmac_f32_dpp v192, v36, v110 row_shr:1 row_mask:0xf bank_mask:0xf
	v_fmac_f32_dpp v193, v37, v111 row_shr:1 row_mask:0xf bank_mask:0xf
	v_fmac_f32_dpp v194, v38, v112 row_shr:1 row_mask:0xf bank_mask:0xf
	v_fmac_f32_dpp v195, v39, v113 row_shr:1 row_mask:0xf bank_mask:0xf
	v_fmac_f32_dpp v188, v48, v154 row_shr:2 row_mask:0xf bank_mask:0xf
	v_fmac_f32_dpp v189, v49, v155 row_shr:2 row_mask:0xf bank_mask:0xf
	v_fmac_f32_dpp v190, v50, v156 row_shr:2 row_mask:0xf bank_mask:0xf
	v_fmac_f32_dpp v191, v51, v157 row_shr:2 row_mask:0xf bank_mask:0xf
	v_fmac_f32_dpp v192, v36, v118 row_shr:2 row_mask:0xf bank_mask:0xf
	v_fmac_f32_dpp v193, v37, v119 row_shr:2 row_mask:0xf bank_mask:0xf
	v_fmac_f32_dpp v194, v38, v120 row_shr:2 row_mask:0xf bank_mask:0xf
	v_fmac_f32_dpp v195, v39, v121 row_shr:2 row_mask:0xf bank_mask:0xf
	v_fmac_f32_dpp v188, v52, v142 row_shl:15 row_mask:0xf bank_mask:0xf
	v_fmac_f32_dpp v189, v53, v143 row_shl:15 row_mask:0xf bank_mask:0xf
	v_fmac_f32_dpp v190, v54, v144 row_shl:15 row_mask:0xf bank_mask:0xf
	v_fmac_f32_dpp v191, v55, v145 row_shl:15 row_mask:0xf bank_mask:0xf
	v_fmac_f32_dpp v192, v44, v110 row_shl:15 row_mask:0xf bank_mask:0xf
	v_fmac_f32_dpp v193, v45, v111 row_shl:15 row_mask:0xf bank_mask:0xf
	v_fmac_f32_dpp v194, v46, v112 row_shl:15 row_mask:0xf bank_mask:0xf
	v_fmac_f32_dpp v195, v47, v113 row_shl:15 row_mask:0xf bank_mask:0xf
	v_fmac_f32_dpp v188, v52, v154 row_shl:14 row_mask:0xf bank_mask:0xf
	v_fmac_f32_dpp v189, v53, v155 row_shl:14 row_mask:0xf bank_mask:0xf
	v_fmac_f32_dpp v190, v54, v156 row_shl:14 row_mask:0xf bank_mask:0xf
	v_fmac_f32_dpp v191, v55, v157 row_shl:14 row_mask:0xf bank_mask:0xf
	v_fmac_f32_dpp v192, v44, v118 row_shl:14 row_mask:0xf bank_mask:0xf
	v_fmac_f32_dpp v193, v45, v119 row_shl:14 row_mask:0xf bank_mask:0xf
	v_fmac_f32_dpp v194, v46, v120 row_shl:14 row_mask:0xf bank_mask:0xf
	v_fmac_f32_dpp v195, v47, v121 row_shl:14 row_mask:0xf bank_mask:0xf
	v_pk_mul_f32 v[196:197], v[188:189], v[216:217] op_sel_hi:[1,0]
	v_pk_mul_f32 v[198:199], v[190:191], v[216:217] op_sel_hi:[1,0]
	v_exp_f32_e32 v196, v196
	v_exp_f32_e32 v197, v197
	v_exp_f32_e32 v198, v198
	v_exp_f32_e32 v199, v199
	v_pk_add_f32 v[196:197], v[196:197], v[214:215] op_sel_hi:[1,0]
	v_pk_add_f32 v[198:199], v[198:199], v[214:215] op_sel_hi:[1,0]
	v_rcp_f32_e32 v196, v196
	v_rcp_f32_e32 v197, v197
	v_rcp_f32_e32 v198, v198
	v_rcp_f32_e32 v199, v199
	v_pk_mul_f32 v[188:189], v[188:189], v[196:197]
	v_pk_mul_f32 v[190:191], v[190:191], v[198:199]
	v_pk_mul_f32 v[188:189], v[188:189], v[192:193]
	v_pk_mul_f32 v[190:191], v[190:191], v[194:195]
	v_cvt_pk_bf16_f32 v152, v188, v189
	v_cvt_pk_bf16_f32 v153, v190, v191
	v_add_u32_e32 v213, 0x58000, v215
	global_store_dwordx4 v213, v[150:153], s[96:97]
	v_pk_fma_f32 v[188:189], v[40:41], v[134:135], v[130:131]
	v_pk_fma_f32 v[190:191], v[42:43], v[136:137], v[132:133]
	v_pk_fma_f32 v[192:193], v[32:33], v[204:205], v[208:209]
	v_pk_fma_f32 v[194:195], v[34:35], v[206:207], v[210:211]
	v_fmac_f32_dpp v188, v40, v142 row_shr:1 row_mask:0xf bank_mask:0xf
	v_fmac_f32_dpp v189, v41, v143 row_shr:1 row_mask:0xf bank_mask:0xf
	v_fmac_f32_dpp v190, v42, v144 row_shr:1 row_mask:0xf bank_mask:0xf
	v_fmac_f32_dpp v191, v43, v145 row_shr:1 row_mask:0xf bank_mask:0xf
	v_fmac_f32_dpp v192, v32, v110 row_shr:1 row_mask:0xf bank_mask:0xf
	v_fmac_f32_dpp v193, v33, v111 row_shr:1 row_mask:0xf bank_mask:0xf
	v_fmac_f32_dpp v194, v34, v112 row_shr:1 row_mask:0xf bank_mask:0xf
	v_fmac_f32_dpp v195, v35, v113 row_shr:1 row_mask:0xf bank_mask:0xf
	v_fmac_f32_dpp v188, v40, v154 row_shr:2 row_mask:0xf bank_mask:0xf
	v_fmac_f32_dpp v189, v41, v155 row_shr:2 row_mask:0xf bank_mask:0xf
	v_fmac_f32_dpp v190, v42, v156 row_shr:2 row_mask:0xf bank_mask:0xf
	v_fmac_f32_dpp v191, v43, v157 row_shr:2 row_mask:0xf bank_mask:0xf
	v_fmac_f32_dpp v192, v32, v118 row_shr:2 row_mask:0xf bank_mask:0xf
	v_fmac_f32_dpp v193, v33, v119 row_shr:2 row_mask:0xf bank_mask:0xf
	v_fmac_f32_dpp v194, v34, v120 row_shr:2 row_mask:0xf bank_mask:0xf
	v_fmac_f32_dpp v195, v35, v121 row_shr:2 row_mask:0xf bank_mask:0xf
	v_fmac_f32_dpp v188, v48, v142 row_shl:15 row_mask:0xf bank_mask:0xf
	v_fmac_f32_dpp v189, v49, v143 row_shl:15 row_mask:0xf bank_mask:0xf
	v_fmac_f32_dpp v190, v50, v144 row_shl:15 row_mask:0xf bank_mask:0xf
	v_fmac_f32_dpp v191, v51, v145 row_shl:15 row_mask:0xf bank_mask:0xf
	v_fmac_f32_dpp v192, v36, v110 row_shl:15 row_mask:0xf bank_mask:0xf
	v_fmac_f32_dpp v193, v37, v111 row_shl:15 row_mask:0xf bank_mask:0xf
	v_fmac_f32_dpp v194, v38, v112 row_shl:15 row_mask:0xf bank_mask:0xf
	v_fmac_f32_dpp v195, v39, v113 row_shl:15 row_mask:0xf bank_mask:0xf
	v_fmac_f32_dpp v188, v48, v154 row_shl:14 row_mask:0xf bank_mask:0xf
	v_fmac_f32_dpp v189, v49, v155 row_shl:14 row_mask:0xf bank_mask:0xf
	v_fmac_f32_dpp v190, v50, v156 row_shl:14 row_mask:0xf bank_mask:0xf
	v_fmac_f32_dpp v191, v51, v157 row_shl:14 row_mask:0xf bank_mask:0xf
	v_fmac_f32_dpp v192, v36, v118 row_shl:14 row_mask:0xf bank_mask:0xf
	v_fmac_f32_dpp v193, v37, v119 row_shl:14 row_mask:0xf bank_mask:0xf
	v_fmac_f32_dpp v194, v38, v120 row_shl:14 row_mask:0xf bank_mask:0xf
	v_fmac_f32_dpp v195, v39, v121 row_shl:14 row_mask:0xf bank_mask:0xf
	v_pk_mul_f32 v[196:197], v[188:189], v[216:217] op_sel_hi:[1,0]
	v_pk_mul_f32 v[198:199], v[190:191], v[216:217] op_sel_hi:[1,0]
	v_exp_f32_e32 v196, v196
	v_exp_f32_e32 v197, v197
	v_exp_f32_e32 v198, v198
	v_exp_f32_e32 v199, v199
	v_pk_add_f32 v[196:197], v[196:197], v[214:215] op_sel_hi:[1,0]
	v_pk_add_f32 v[198:199], v[198:199], v[214:215] op_sel_hi:[1,0]
	v_rcp_f32_e32 v196, v196
	v_rcp_f32_e32 v197, v197
	v_rcp_f32_e32 v198, v198
	v_rcp_f32_e32 v199, v199
	v_pk_mul_f32 v[188:189], v[188:189], v[196:197]
	v_pk_mul_f32 v[190:191], v[190:191], v[198:199]
	v_pk_mul_f32 v[188:189], v[188:189], v[192:193]
	v_pk_mul_f32 v[190:191], v[190:191], v[194:195]
	v_cvt_pk_bf16_f32 v148, v188, v189
	v_cvt_pk_bf16_f32 v149, v190, v191
	v_add_u32_e32 v213, 0x84000, v215
	global_store_dwordx4 v213, v[146:149], s[96:97]
	v_pk_fma_f32 v[188:189], v[28:29], v[134:135], v[130:131]
	v_pk_fma_f32 v[190:191], v[30:31], v[136:137], v[132:133]
	v_pk_fma_f32 v[192:193], v[16:17], v[204:205], v[208:209]
	v_pk_fma_f32 v[194:195], v[18:19], v[206:207], v[210:211]
	v_fmac_f32_dpp v188, v28, v142 row_shr:1 row_mask:0xf bank_mask:0xf
	v_fmac_f32_dpp v189, v29, v143 row_shr:1 row_mask:0xf bank_mask:0xf
	v_fmac_f32_dpp v190, v30, v144 row_shr:1 row_mask:0xf bank_mask:0xf
	v_fmac_f32_dpp v191, v31, v145 row_shr:1 row_mask:0xf bank_mask:0xf
	v_fmac_f32_dpp v192, v16, v110 row_shr:1 row_mask:0xf bank_mask:0xf
	v_fmac_f32_dpp v193, v17, v111 row_shr:1 row_mask:0xf bank_mask:0xf
	v_fmac_f32_dpp v194, v18, v112 row_shr:1 row_mask:0xf bank_mask:0xf
	v_fmac_f32_dpp v195, v19, v113 row_shr:1 row_mask:0xf bank_mask:0xf
	v_fmac_f32_dpp v188, v28, v154 row_shr:2 row_mask:0xf bank_mask:0xf
	v_fmac_f32_dpp v189, v29, v155 row_shr:2 row_mask:0xf bank_mask:0xf
	v_fmac_f32_dpp v190, v30, v156 row_shr:2 row_mask:0xf bank_mask:0xf
	v_fmac_f32_dpp v191, v31, v157 row_shr:2 row_mask:0xf bank_mask:0xf
	v_fmac_f32_dpp v192, v16, v118 row_shr:2 row_mask:0xf bank_mask:0xf
	v_fmac_f32_dpp v193, v17, v119 row_shr:2 row_mask:0xf bank_mask:0xf
	v_fmac_f32_dpp v194, v18, v120 row_shr:2 row_mask:0xf bank_mask:0xf
	v_fmac_f32_dpp v195, v19, v121 row_shr:2 row_mask:0xf bank_mask:0xf
	v_fmac_f32_dpp v188, v40, v142 row_shl:15 row_mask:0xf bank_mask:0xf
	v_fmac_f32_dpp v189, v41, v143 row_shl:15 row_mask:0xf bank_mask:0xf
	v_fmac_f32_dpp v190, v42, v144 row_shl:15 row_mask:0xf bank_mask:0xf
	v_fmac_f32_dpp v191, v43, v145 row_shl:15 row_mask:0xf bank_mask:0xf
	v_fmac_f32_dpp v192, v32, v110 row_shl:15 row_mask:0xf bank_mask:0xf
	v_fmac_f32_dpp v193, v33, v111 row_shl:15 row_mask:0xf bank_mask:0xf
	v_fmac_f32_dpp v194, v34, v112 row_shl:15 row_mask:0xf bank_mask:0xf
	v_fmac_f32_dpp v195, v35, v113 row_shl:15 row_mask:0xf bank_mask:0xf
	v_fmac_f32_dpp v188, v40, v154 row_shl:14 row_mask:0xf bank_mask:0xf
	v_fmac_f32_dpp v189, v41, v155 row_shl:14 row_mask:0xf bank_mask:0xf
	v_fmac_f32_dpp v190, v42, v156 row_shl:14 row_mask:0xf bank_mask:0xf
	v_fmac_f32_dpp v191, v43, v157 row_shl:14 row_mask:0xf bank_mask:0xf
	v_fmac_f32_dpp v192, v32, v118 row_shl:14 row_mask:0xf bank_mask:0xf
	v_fmac_f32_dpp v193, v33, v119 row_shl:14 row_mask:0xf bank_mask:0xf
	v_fmac_f32_dpp v194, v34, v120 row_shl:14 row_mask:0xf bank_mask:0xf
	v_fmac_f32_dpp v195, v35, v121 row_shl:14 row_mask:0xf bank_mask:0xf
	v_pk_mul_f32 v[196:197], v[188:189], v[216:217] op_sel_hi:[1,0]
	v_pk_mul_f32 v[198:199], v[190:191], v[216:217] op_sel_hi:[1,0]
	v_exp_f32_e32 v196, v196
	v_exp_f32_e32 v197, v197
	v_exp_f32_e32 v198, v198
	v_exp_f32_e32 v199, v199
	v_pk_add_f32 v[196:197], v[196:197], v[214:215] op_sel_hi:[1,0]
	v_pk_add_f32 v[198:199], v[198:199], v[214:215] op_sel_hi:[1,0]
	v_rcp_f32_e32 v196, v196
	v_rcp_f32_e32 v197, v197
	v_rcp_f32_e32 v198, v198
	v_rcp_f32_e32 v199, v199
	v_pk_mul_f32 v[188:189], v[188:189], v[196:197]
	v_pk_mul_f32 v[190:191], v[190:191], v[198:199]
	v_pk_mul_f32 v[188:189], v[188:189], v[192:193]
	v_pk_mul_f32 v[190:191], v[190:191], v[194:195]
	v_cvt_pk_bf16_f32 v140, v188, v189
	v_cvt_pk_bf16_f32 v141, v190, v191
	v_add_u32_e32 v213, 0xb0000, v215
	global_store_dwordx4 v213, v[138:141], s[96:97]
	v_pk_fma_f32 v[188:189], v[24:25], v[134:135], v[130:131]
	v_pk_fma_f32 v[190:191], v[26:27], v[136:137], v[132:133]
	v_pk_fma_f32 v[192:193], v[12:13], v[204:205], v[208:209]
	v_pk_fma_f32 v[194:195], v[14:15], v[206:207], v[210:211]
	v_fmac_f32_dpp v188, v24, v142 row_shr:1 row_mask:0xf bank_mask:0xf
	v_fmac_f32_dpp v189, v25, v143 row_shr:1 row_mask:0xf bank_mask:0xf
	v_fmac_f32_dpp v190, v26, v144 row_shr:1 row_mask:0xf bank_mask:0xf
	v_fmac_f32_dpp v191, v27, v145 row_shr:1 row_mask:0xf bank_mask:0xf
	v_fmac_f32_dpp v192, v12, v110 row_shr:1 row_mask:0xf bank_mask:0xf
	v_fmac_f32_dpp v193, v13, v111 row_shr:1 row_mask:0xf bank_mask:0xf
	v_fmac_f32_dpp v194, v14, v112 row_shr:1 row_mask:0xf bank_mask:0xf
	v_fmac_f32_dpp v195, v15, v113 row_shr:1 row_mask:0xf bank_mask:0xf
	v_fmac_f32_dpp v188, v24, v154 row_shr:2 row_mask:0xf bank_mask:0xf
	v_fmac_f32_dpp v189, v25, v155 row_shr:2 row_mask:0xf bank_mask:0xf
	v_fmac_f32_dpp v190, v26, v156 row_shr:2 row_mask:0xf bank_mask:0xf
	v_fmac_f32_dpp v191, v27, v157 row_shr:2 row_mask:0xf bank_mask:0xf
	v_fmac_f32_dpp v192, v12, v118 row_shr:2 row_mask:0xf bank_mask:0xf
	v_fmac_f32_dpp v193, v13, v119 row_shr:2 row_mask:0xf bank_mask:0xf
	v_fmac_f32_dpp v194, v14, v120 row_shr:2 row_mask:0xf bank_mask:0xf
	v_fmac_f32_dpp v195, v15, v121 row_shr:2 row_mask:0xf bank_mask:0xf
	v_fmac_f32_dpp v188, v28, v142 row_shl:15 row_mask:0xf bank_mask:0xf
	v_fmac_f32_dpp v189, v29, v143 row_shl:15 row_mask:0xf bank_mask:0xf
	v_fmac_f32_dpp v190, v30, v144 row_shl:15 row_mask:0xf bank_mask:0xf
	v_fmac_f32_dpp v191, v31, v145 row_shl:15 row_mask:0xf bank_mask:0xf
	v_fmac_f32_dpp v192, v16, v110 row_shl:15 row_mask:0xf bank_mask:0xf
	v_fmac_f32_dpp v193, v17, v111 row_shl:15 row_mask:0xf bank_mask:0xf
	v_fmac_f32_dpp v194, v18, v112 row_shl:15 row_mask:0xf bank_mask:0xf
	v_fmac_f32_dpp v195, v19, v113 row_shl:15 row_mask:0xf bank_mask:0xf
	v_fmac_f32_dpp v188, v28, v154 row_shl:14 row_mask:0xf bank_mask:0xf
	v_fmac_f32_dpp v189, v29, v155 row_shl:14 row_mask:0xf bank_mask:0xf
	v_fmac_f32_dpp v190, v30, v156 row_shl:14 row_mask:0xf bank_mask:0xf
	v_fmac_f32_dpp v191, v31, v157 row_shl:14 row_mask:0xf bank_mask:0xf
	v_fmac_f32_dpp v192, v16, v118 row_shl:14 row_mask:0xf bank_mask:0xf
	v_fmac_f32_dpp v193, v17, v119 row_shl:14 row_mask:0xf bank_mask:0xf
	v_fmac_f32_dpp v194, v18, v120 row_shl:14 row_mask:0xf bank_mask:0xf
	v_fmac_f32_dpp v195, v19, v121 row_shl:14 row_mask:0xf bank_mask:0xf
	v_pk_mul_f32 v[196:197], v[188:189], v[216:217] op_sel_hi:[1,0]
	v_pk_mul_f32 v[198:199], v[190:191], v[216:217] op_sel_hi:[1,0]
	v_exp_f32_e32 v196, v196
	v_exp_f32_e32 v197, v197
	v_exp_f32_e32 v198, v198
	v_exp_f32_e32 v199, v199
	v_pk_add_f32 v[196:197], v[196:197], v[214:215] op_sel_hi:[1,0]
	v_pk_add_f32 v[198:199], v[198:199], v[214:215] op_sel_hi:[1,0]
	v_rcp_f32_e32 v196, v196
	v_rcp_f32_e32 v197, v197
	v_rcp_f32_e32 v198, v198
	v_rcp_f32_e32 v199, v199
	v_pk_mul_f32 v[188:189], v[188:189], v[196:197]
	v_pk_mul_f32 v[190:191], v[190:191], v[198:199]
	v_pk_mul_f32 v[188:189], v[188:189], v[192:193]
	v_pk_mul_f32 v[190:191], v[190:191], v[194:195]
	v_cvt_pk_bf16_f32 v128, v188, v189
	v_cvt_pk_bf16_f32 v129, v190, v191
	v_add_u32_e32 v213, 0xdc000, v215
	global_store_dwordx4 v213, v[126:129], s[96:97]
	v_pk_fma_f32 v[188:189], v[20:21], v[134:135], v[130:131]
	v_pk_fma_f32 v[190:191], v[22:23], v[136:137], v[132:133]
	v_pk_fma_f32 v[192:193], v[8:9], v[204:205], v[208:209]
	v_pk_fma_f32 v[194:195], v[10:11], v[206:207], v[210:211]
	v_fmac_f32_dpp v188, v20, v142 row_shr:1 row_mask:0xf bank_mask:0xf
	v_fmac_f32_dpp v189, v21, v143 row_shr:1 row_mask:0xf bank_mask:0xf
	v_fmac_f32_dpp v190, v22, v144 row_shr:1 row_mask:0xf bank_mask:0xf
	v_fmac_f32_dpp v191, v23, v145 row_shr:1 row_mask:0xf bank_mask:0xf
	v_fmac_f32_dpp v192, v8, v110 row_shr:1 row_mask:0xf bank_mask:0xf
	v_fmac_f32_dpp v193, v9, v111 row_shr:1 row_mask:0xf bank_mask:0xf
	v_fmac_f32_dpp v194, v10, v112 row_shr:1 row_mask:0xf bank_mask:0xf
	v_fmac_f32_dpp v195, v11, v113 row_shr:1 row_mask:0xf bank_mask:0xf
	v_fmac_f32_dpp v188, v20, v154 row_shr:2 row_mask:0xf bank_mask:0xf
	v_fmac_f32_dpp v189, v21, v155 row_shr:2 row_mask:0xf bank_mask:0xf
	v_fmac_f32_dpp v190, v22, v156 row_shr:2 row_mask:0xf bank_mask:0xf
	v_fmac_f32_dpp v191, v23, v157 row_shr:2 row_mask:0xf bank_mask:0xf
	v_fmac_f32_dpp v192, v8, v118 row_shr:2 row_mask:0xf bank_mask:0xf
	v_fmac_f32_dpp v193, v9, v119 row_shr:2 row_mask:0xf bank_mask:0xf
	v_fmac_f32_dpp v194, v10, v120 row_shr:2 row_mask:0xf bank_mask:0xf
	v_fmac_f32_dpp v195, v11, v121 row_shr:2 row_mask:0xf bank_mask:0xf
	v_fmac_f32_dpp v188, v24, v142 row_shl:15 row_mask:0xf bank_mask:0xf
	v_fmac_f32_dpp v189, v25, v143 row_shl:15 row_mask:0xf bank_mask:0xf
	v_fmac_f32_dpp v190, v26, v144 row_shl:15 row_mask:0xf bank_mask:0xf
	v_fmac_f32_dpp v191, v27, v145 row_shl:15 row_mask:0xf bank_mask:0xf
	v_fmac_f32_dpp v192, v12, v110 row_shl:15 row_mask:0xf bank_mask:0xf
	v_fmac_f32_dpp v193, v13, v111 row_shl:15 row_mask:0xf bank_mask:0xf
	v_fmac_f32_dpp v194, v14, v112 row_shl:15 row_mask:0xf bank_mask:0xf
	v_fmac_f32_dpp v195, v15, v113 row_shl:15 row_mask:0xf bank_mask:0xf
	v_fmac_f32_dpp v188, v24, v154 row_shl:14 row_mask:0xf bank_mask:0xf
	v_fmac_f32_dpp v189, v25, v155 row_shl:14 row_mask:0xf bank_mask:0xf
	v_fmac_f32_dpp v190, v26, v156 row_shl:14 row_mask:0xf bank_mask:0xf
	v_fmac_f32_dpp v191, v27, v157 row_shl:14 row_mask:0xf bank_mask:0xf
	v_fmac_f32_dpp v192, v12, v118 row_shl:14 row_mask:0xf bank_mask:0xf
	v_fmac_f32_dpp v193, v13, v119 row_shl:14 row_mask:0xf bank_mask:0xf
	v_fmac_f32_dpp v194, v14, v120 row_shl:14 row_mask:0xf bank_mask:0xf
	v_fmac_f32_dpp v195, v15, v121 row_shl:14 row_mask:0xf bank_mask:0xf
	v_pk_mul_f32 v[196:197], v[188:189], v[216:217] op_sel_hi:[1,0]
	v_pk_mul_f32 v[198:199], v[190:191], v[216:217] op_sel_hi:[1,0]
	v_exp_f32_e32 v196, v196
	v_exp_f32_e32 v197, v197
	v_exp_f32_e32 v198, v198
	v_exp_f32_e32 v199, v199
	v_pk_add_f32 v[196:197], v[196:197], v[214:215] op_sel_hi:[1,0]
	v_pk_add_f32 v[198:199], v[198:199], v[214:215] op_sel_hi:[1,0]
	v_rcp_f32_e32 v196, v196
	v_rcp_f32_e32 v197, v197
	v_rcp_f32_e32 v198, v198
	v_rcp_f32_e32 v199, v199
	v_pk_mul_f32 v[188:189], v[188:189], v[196:197]
	v_pk_mul_f32 v[190:191], v[190:191], v[198:199]
	v_pk_mul_f32 v[188:189], v[188:189], v[192:193]
	v_pk_mul_f32 v[190:191], v[190:191], v[194:195]
	v_cvt_pk_bf16_f32 v124, v188, v189
	v_cvt_pk_bf16_f32 v125, v190, v191
	v_add_u32_e32 v213, 0x108000, v215
	global_store_dwordx4 v213, v[122:125], s[96:97]
	v_pk_fma_f32 v[188:189], v[4:5], v[134:135], v[130:131]
	v_pk_fma_f32 v[190:191], v[6:7], v[136:137], v[132:133]
	v_pk_fma_f32 v[192:193], v[0:1], v[204:205], v[208:209]
	v_pk_fma_f32 v[194:195], v[2:3], v[206:207], v[210:211]
	v_fmac_f32_dpp v188, v4, v142 row_shr:1 row_mask:0xf bank_mask:0xf
	v_fmac_f32_dpp v189, v5, v143 row_shr:1 row_mask:0xf bank_mask:0xf
	v_fmac_f32_dpp v190, v6, v144 row_shr:1 row_mask:0xf bank_mask:0xf
	v_fmac_f32_dpp v191, v7, v145 row_shr:1 row_mask:0xf bank_mask:0xf
	v_fmac_f32_dpp v192, v0, v110 row_shr:1 row_mask:0xf bank_mask:0xf
	v_fmac_f32_dpp v193, v1, v111 row_shr:1 row_mask:0xf bank_mask:0xf
	v_fmac_f32_dpp v194, v2, v112 row_shr:1 row_mask:0xf bank_mask:0xf
	v_fmac_f32_dpp v195, v3, v113 row_shr:1 row_mask:0xf bank_mask:0xf
	v_fmac_f32_dpp v188, v4, v154 row_shr:2 row_mask:0xf bank_mask:0xf
	v_fmac_f32_dpp v189, v5, v155 row_shr:2 row_mask:0xf bank_mask:0xf
	v_fmac_f32_dpp v190, v6, v156 row_shr:2 row_mask:0xf bank_mask:0xf
	v_fmac_f32_dpp v191, v7, v157 row_shr:2 row_mask:0xf bank_mask:0xf
	v_fmac_f32_dpp v192, v0, v118 row_shr:2 row_mask:0xf bank_mask:0xf
	v_fmac_f32_dpp v193, v1, v119 row_shr:2 row_mask:0xf bank_mask:0xf
	v_fmac_f32_dpp v194, v2, v120 row_shr:2 row_mask:0xf bank_mask:0xf
	v_fmac_f32_dpp v195, v3, v121 row_shr:2 row_mask:0xf bank_mask:0xf
	v_fmac_f32_dpp v188, v20, v142 row_shl:15 row_mask:0xf bank_mask:0xf
	v_fmac_f32_dpp v189, v21, v143 row_shl:15 row_mask:0xf bank_mask:0xf
	v_fmac_f32_dpp v190, v22, v144 row_shl:15 row_mask:0xf bank_mask:0xf
	v_fmac_f32_dpp v191, v23, v145 row_shl:15 row_mask:0xf bank_mask:0xf
	v_fmac_f32_dpp v192, v8, v110 row_shl:15 row_mask:0xf bank_mask:0xf
	v_fmac_f32_dpp v193, v9, v111 row_shl:15 row_mask:0xf bank_mask:0xf
	v_fmac_f32_dpp v194, v10, v112 row_shl:15 row_mask:0xf bank_mask:0xf
	v_fmac_f32_dpp v195, v11, v113 row_shl:15 row_mask:0xf bank_mask:0xf
	v_fmac_f32_dpp v188, v20, v154 row_shl:14 row_mask:0xf bank_mask:0xf
	v_fmac_f32_dpp v189, v21, v155 row_shl:14 row_mask:0xf bank_mask:0xf
	v_fmac_f32_dpp v190, v22, v156 row_shl:14 row_mask:0xf bank_mask:0xf
	v_fmac_f32_dpp v191, v23, v157 row_shl:14 row_mask:0xf bank_mask:0xf
	v_fmac_f32_dpp v192, v8, v118 row_shl:14 row_mask:0xf bank_mask:0xf
	v_fmac_f32_dpp v193, v9, v119 row_shl:14 row_mask:0xf bank_mask:0xf
	v_fmac_f32_dpp v194, v10, v120 row_shl:14 row_mask:0xf bank_mask:0xf
	v_fmac_f32_dpp v195, v11, v121 row_shl:14 row_mask:0xf bank_mask:0xf
	v_pk_mul_f32 v[196:197], v[188:189], v[216:217] op_sel_hi:[1,0]
	v_pk_mul_f32 v[198:199], v[190:191], v[216:217] op_sel_hi:[1,0]
	v_exp_f32_e32 v196, v196
	v_exp_f32_e32 v197, v197
	v_exp_f32_e32 v198, v198
	v_exp_f32_e32 v199, v199
	v_pk_add_f32 v[196:197], v[196:197], v[214:215] op_sel_hi:[1,0]
	v_pk_add_f32 v[198:199], v[198:199], v[214:215] op_sel_hi:[1,0]
	v_rcp_f32_e32 v196, v196
	v_rcp_f32_e32 v197, v197
	v_rcp_f32_e32 v198, v198
	v_rcp_f32_e32 v199, v199
	v_pk_mul_f32 v[188:189], v[188:189], v[196:197]
	v_pk_mul_f32 v[190:191], v[190:191], v[198:199]
	v_pk_mul_f32 v[188:189], v[188:189], v[192:193]
	v_pk_mul_f32 v[190:191], v[190:191], v[194:195]
	v_cvt_pk_bf16_f32 v116, v188, v189
	v_cvt_pk_bf16_f32 v117, v190, v191
	v_add_u32_e32 v213, 0x134000, v215
	global_store_dwordx4 v213, v[114:117], s[96:97]
	s_branch .LBB0_359

.LBB0_507:
	s_add_u32 s0, s0, 0x160080
	s_addc_u32 s1, s1, 0
	s_add_u32 s39, s16, 0x100
	v_mov_b32_e32 v0, 0
	s_addc_u32 s40, s17, 0
	s_mov_b32 s41, -2
	s_waitcnt lgkmcnt(0)
	v_mov_b32_e32 v1, v0
	v_mov_b32_e32 v2, v0
	v_mov_b32_e32 v3, v0
	v_mov_b32_e32 v4, v0
	v_mov_b32_e32 v5, v0
	v_mov_b32_e32 v6, v0
	v_mov_b32_e32 v7, v0
	s_waitcnt vmcnt(0)
	v_mov_b32_e32 v16, v0
	v_mov_b32_e32 v17, v0
	v_mov_b32_e32 v18, v0
	v_mov_b32_e32 v19, v0
	v_mov_b32_e32 v20, v0
	v_mov_b32_e32 v21, v0
	v_mov_b32_e32 v22, v0
	v_mov_b32_e32 v23, v0
	v_mov_b32_e32 v32, v0
	v_mov_b32_e32 v33, v0
	v_mov_b32_e32 v34, v0
	v_mov_b32_e32 v35, v0
	v_mov_b32_e32 v36, v0
	v_mov_b32_e32 v37, v0
	v_mov_b32_e32 v38, v0
	v_mov_b32_e32 v39, v0
	v_mov_b32_e32 v48, v0
	v_mov_b32_e32 v49, v0
	v_mov_b32_e32 v50, v0
	v_mov_b32_e32 v51, v0
	v_mov_b32_e32 v52, v0
	v_mov_b32_e32 v53, v0
	v_mov_b32_e32 v54, v0
	v_mov_b32_e32 v55, v0
	v_mov_b32_e32 v8, v0
	v_mov_b32_e32 v9, v0
	v_mov_b32_e32 v10, v0
	v_mov_b32_e32 v11, v0
	v_mov_b32_e32 v12, v0
	v_mov_b32_e32 v13, v0
	v_mov_b32_e32 v14, v0
	v_mov_b32_e32 v15, v0
	v_mov_b32_e32 v24, v0
	v_mov_b32_e32 v25, v0
	v_mov_b32_e32 v26, v0
	v_mov_b32_e32 v27, v0
	v_mov_b32_e32 v28, v0
	v_mov_b32_e32 v29, v0
	v_mov_b32_e32 v30, v0
	v_mov_b32_e32 v31, v0
	v_mov_b32_e32 v40, v0
	v_mov_b32_e32 v41, v0
	v_mov_b32_e32 v42, v0
	v_mov_b32_e32 v43, v0
	v_mov_b32_e32 v44, v0
	v_mov_b32_e32 v45, v0
	v_mov_b32_e32 v46, v0
	v_mov_b32_e32 v47, v0
	v_mov_b32_e32 v56, v0
	v_mov_b32_e32 v57, v0
	v_mov_b32_e32 v58, v0
	v_mov_b32_e32 v59, v0
	v_mov_b32_e32 v60, v0
	v_mov_b32_e32 v61, v0
	v_mov_b32_e32 v62, v0
	v_mov_b32_e32 v63, v0
	v_mov_b32_e32 v64, v0
	v_mov_b32_e32 v65, v0
	v_mov_b32_e32 v66, v0
	v_mov_b32_e32 v67, v0
	v_mov_b32_e32 v68, v0
	v_mov_b32_e32 v69, v0
	v_mov_b32_e32 v70, v0
	v_mov_b32_e32 v71, v0
	v_mov_b32_e32 v80, v0
	v_mov_b32_e32 v81, v0
	v_mov_b32_e32 v82, v0
	v_mov_b32_e32 v83, v0
	v_mov_b32_e32 v84, v0
	v_mov_b32_e32 v85, v0
	v_mov_b32_e32 v86, v0
	v_mov_b32_e32 v87, v0
	v_mov_b32_e32 v96, v0
	v_mov_b32_e32 v97, v0
	v_mov_b32_e32 v98, v0
	v_mov_b32_e32 v99, v0
	v_mov_b32_e32 v100, v0
	v_mov_b32_e32 v101, v0
	v_mov_b32_e32 v102, v0
	v_mov_b32_e32 v103, v0
	v_mov_b32_e32 v112, v0
	v_mov_b32_e32 v113, v0
	v_mov_b32_e32 v114, v0
	v_mov_b32_e32 v115, v0
	v_mov_b32_e32 v116, v0
	v_mov_b32_e32 v117, v0
	v_mov_b32_e32 v118, v0
	v_mov_b32_e32 v119, v0
	v_mov_b32_e32 v72, v0
	v_mov_b32_e32 v73, v0
	v_mov_b32_e32 v74, v0
	v_mov_b32_e32 v75, v0
	v_mov_b32_e32 v76, v0
	v_mov_b32_e32 v77, v0
	v_mov_b32_e32 v78, v0
	v_mov_b32_e32 v79, v0
	v_mov_b32_e32 v88, v0
	v_mov_b32_e32 v89, v0
	v_mov_b32_e32 v90, v0
	v_mov_b32_e32 v91, v0
	v_mov_b32_e32 v92, v0
	v_mov_b32_e32 v93, v0
	v_mov_b32_e32 v94, v0
	v_mov_b32_e32 v95, v0
	v_mov_b32_e32 v104, v0
	v_mov_b32_e32 v105, v0
	v_mov_b32_e32 v106, v0
	v_mov_b32_e32 v107, v0
	v_mov_b32_e32 v108, v0
	v_mov_b32_e32 v109, v0
	v_mov_b32_e32 v110, v0
	v_mov_b32_e32 v111, v0
	v_mov_b32_e32 v120, v0
	v_mov_b32_e32 v121, v0
	v_mov_b32_e32 v122, v0
	v_mov_b32_e32 v123, v0
	v_mov_b32_e32 v124, v0
	v_mov_b32_e32 v125, v0
	v_mov_b32_e32 v126, v0
	v_mov_b32_e32 v127, v0
	v_xor_b32_e32 v216, 64, v141
	v_xor_b32_e32 v217, 64, v142
	v_xor_b32_e32 v244, 64, v143
	v_add_u32_e32 v245, 0x18000, v140
	v_xor_b32_e32 v246, 64, v245
.LBB0_508:
	ds_read_b128 v[136:139], v141
	ds_read_b128 v[146:149], v216
	ds_read_b128 v[150:153], v141 offset:2048
	ds_read_b128 v[154:157], v216 offset:2048
	s_add_u32 s8, s0, 0xffea0080
	s_addc_u32 s9, s1, -1
	s_cmpk_eq_i32 s41, 0x54
	s_cselect_b32 s17, s13, s9
	s_cselect_b32 s16, s12, s8
	s_cselect_b32 s9, s11, s40
	s_cselect_b32 s8, s10, s39
	s_add_i32 m0, s21, 0xc000
	ds_read_b128 v[158:161], v142
	ds_read_b128 v[176:179], v217
	ds_read_b128 v[180:183], v142 offset:2048
	ds_read_b128 v[184:187], v217 offset:2048
	ds_read_b128 v[188:191], v142 offset:4096
	ds_read_b128 v[192:195], v217 offset:4096
	ds_read_b128 v[196:199], v142 offset:6144
	ds_read_b128 v[200:203], v217 offset:6144
	global_load_lds_dwordx4 v128, s[0:1]
	s_add_i32 m0, s21, 0xe000
	s_nop 0
	global_load_lds_dwordx4 v130, s[0:1]
	s_waitcnt lgkmcnt(8)
	s_barrier
	s_waitcnt lgkmcnt(0)
	s_setprio 1
	s_waitcnt lgkmcnt(0)
	v_mfma_f32_16x16x32_bf16 v[124:127], v[136:139], v[158:161], v[124:127]
	v_mfma_f32_16x16x32_bf16 v[124:127], v[146:149], v[176:179], v[124:127]
	v_mfma_f32_16x16x32_bf16 v[120:123], v[154:157], v[176:179], v[120:123]
	v_mfma_f32_16x16x32_bf16 v[120:123], v[150:153], v[158:161], v[120:123]
	v_mfma_f32_16x16x32_bf16 v[104:107], v[150:153], v[180:183], v[104:107]
	v_mfma_f32_16x16x32_bf16 v[104:107], v[154:157], v[184:187], v[104:107]
	v_mfma_f32_16x16x32_bf16 v[108:111], v[146:149], v[184:187], v[108:111]
	v_mfma_f32_16x16x32_bf16 v[108:111], v[136:139], v[180:183], v[108:111]
	v_mfma_f32_16x16x32_bf16 v[92:95], v[136:139], v[188:191], v[92:95]
	v_mfma_f32_16x16x32_bf16 v[92:95], v[146:149], v[192:195], v[92:95]
	v_mfma_f32_16x16x32_bf16 v[88:91], v[154:157], v[192:195], v[88:91]
	v_mfma_f32_16x16x32_bf16 v[88:91], v[150:153], v[188:191], v[88:91]
	v_mfma_f32_16x16x32_bf16 v[72:75], v[150:153], v[196:199], v[72:75]
	v_mfma_f32_16x16x32_bf16 v[72:75], v[154:157], v[200:203], v[72:75]
	v_mfma_f32_16x16x32_bf16 v[76:79], v[146:149], v[200:203], v[76:79]
	v_mfma_f32_16x16x32_bf16 v[76:79], v[136:139], v[196:199], v[76:79]
	s_setprio 0
	s_barrier
	s_add_i32 s42, s33, s20
	s_add_u32 s98, s8, s4
	s_addc_u32 s99, s9, s5
	s_mov_b32 m0, s42
	ds_read_b128 v[204:207], v143
	ds_read_b128 v[208:211], v244
	ds_read_b128 v[212:215], v143 offset:2048
	ds_read_b128 v[240:243], v244 offset:2048
	global_load_lds_dwordx4 v170, s[8:9]
	s_add_i32 m0, s42, 0x2000
	s_nop 0
	global_load_lds_dwordx4 v174, s[8:9]
	s_barrier
	s_waitcnt lgkmcnt(0)
	s_setprio 1
	s_waitcnt lgkmcnt(0)
	v_mfma_f32_16x16x32_bf16 v[116:119], v[204:207], v[158:161], v[116:119]
	v_mfma_f32_16x16x32_bf16 v[116:119], v[208:211], v[176:179], v[116:119]
	v_mfma_f32_16x16x32_bf16 v[112:115], v[240:243], v[176:179], v[112:115]
	v_mfma_f32_16x16x32_bf16 v[112:115], v[212:215], v[158:161], v[112:115]
	v_mfma_f32_16x16x32_bf16 v[96:99], v[212:215], v[180:183], v[96:99]
	v_mfma_f32_16x16x32_bf16 v[96:99], v[240:243], v[184:187], v[96:99]
	v_mfma_f32_16x16x32_bf16 v[100:103], v[208:211], v[184:187], v[100:103]
	v_mfma_f32_16x16x32_bf16 v[100:103], v[204:207], v[180:183], v[100:103]
	v_mfma_f32_16x16x32_bf16 v[84:87], v[204:207], v[188:191], v[84:87]
	v_mfma_f32_16x16x32_bf16 v[84:87], v[208:211], v[192:195], v[84:87]
	v_mfma_f32_16x16x32_bf16 v[80:83], v[240:243], v[192:195], v[80:83]
	v_mfma_f32_16x16x32_bf16 v[80:83], v[212:215], v[188:191], v[80:83]
	v_mfma_f32_16x16x32_bf16 v[64:67], v[212:215], v[196:199], v[64:67]
	v_mfma_f32_16x16x32_bf16 v[64:67], v[240:243], v[200:203], v[64:67]
	v_mfma_f32_16x16x32_bf16 v[68:71], v[208:211], v[200:203], v[68:71]
	v_mfma_f32_16x16x32_bf16 v[68:71], v[204:207], v[196:199], v[68:71]
	s_setprio 0
	s_mov_b32 m0, s21
	s_add_u32 s100, s16, s4
	s_addc_u32 s101, s17, s5
	s_barrier
	ds_read_b128 v[158:161], v142 offset:16384
	ds_read_b128 v[176:179], v217 offset:16384
	ds_read_b128 v[180:183], v142 offset:18432
	ds_read_b128 v[184:187], v217 offset:18432
	ds_read_b128 v[188:191], v142 offset:20480
	ds_read_b128 v[192:195], v217 offset:20480
	ds_read_b128 v[196:199], v142 offset:22528
	ds_read_b128 v[200:203], v217 offset:22528
	global_load_lds_dwordx4 v168, s[16:17]
	s_mov_b32 m0, s22
	s_nop 0
	global_load_lds_dwordx4 v172, s[16:17]
	s_barrier
	s_waitcnt lgkmcnt(0)
	s_setprio 1
	s_waitcnt lgkmcnt(0)
	v_mfma_f32_16x16x32_bf16 v[60:63], v[136:139], v[158:161], v[60:63]
	v_mfma_f32_16x16x32_bf16 v[60:63], v[146:149], v[176:179], v[60:63]
	v_mfma_f32_16x16x32_bf16 v[56:59], v[154:157], v[176:179], v[56:59]
	v_mfma_f32_16x16x32_bf16 v[56:59], v[150:153], v[158:161], v[56:59]
	v_mfma_f32_16x16x32_bf16 v[40:43], v[150:153], v[180:183], v[40:43]
	v_mfma_f32_16x16x32_bf16 v[40:43], v[154:157], v[184:187], v[40:43]
	v_mfma_f32_16x16x32_bf16 v[44:47], v[146:149], v[184:187], v[44:47]
	v_mfma_f32_16x16x32_bf16 v[44:47], v[136:139], v[180:183], v[44:47]
	v_mfma_f32_16x16x32_bf16 v[28:31], v[136:139], v[188:191], v[28:31]
	v_mfma_f32_16x16x32_bf16 v[28:31], v[146:149], v[192:195], v[28:31]
	v_mfma_f32_16x16x32_bf16 v[24:27], v[154:157], v[192:195], v[24:27]
	v_mfma_f32_16x16x32_bf16 v[24:27], v[150:153], v[188:191], v[24:27]
	v_mfma_f32_16x16x32_bf16 v[8:11], v[150:153], v[196:199], v[8:11]
	v_mfma_f32_16x16x32_bf16 v[8:11], v[154:157], v[200:203], v[8:11]
	v_mfma_f32_16x16x32_bf16 v[12:15], v[146:149], v[200:203], v[12:15]
	v_mfma_f32_16x16x32_bf16 v[12:15], v[136:139], v[196:199], v[12:15]
	s_setprio 0
	s_barrier
	s_add_u32 s42, s8, 0x160000
	s_addc_u32 s43, s9, 0
	s_add_i32 s44, s34, s20
	s_mov_b32 m0, s44
	s_nop 0
	global_load_lds_dwordx4 v170, s[42:43]
	s_add_i32 m0, s44, 0x2000
	s_nop 0
	global_load_lds_dwordx4 v174, s[42:43]
	s_waitcnt vmcnt(6)
	s_barrier
	s_setprio 1
	v_mfma_f32_16x16x32_bf16 v[52:55], v[204:207], v[158:161], v[52:55]
	v_mfma_f32_16x16x32_bf16 v[52:55], v[208:211], v[176:179], v[52:55]
	v_mfma_f32_16x16x32_bf16 v[48:51], v[240:243], v[176:179], v[48:51]
	v_mfma_f32_16x16x32_bf16 v[48:51], v[212:215], v[158:161], v[48:51]
	v_mfma_f32_16x16x32_bf16 v[32:35], v[212:215], v[180:183], v[32:35]
	v_mfma_f32_16x16x32_bf16 v[32:35], v[240:243], v[184:187], v[32:35]
	v_mfma_f32_16x16x32_bf16 v[36:39], v[208:211], v[184:187], v[36:39]
	v_mfma_f32_16x16x32_bf16 v[36:39], v[204:207], v[180:183], v[36:39]
	v_mfma_f32_16x16x32_bf16 v[20:23], v[204:207], v[188:191], v[20:23]
	v_mfma_f32_16x16x32_bf16 v[20:23], v[208:211], v[192:195], v[20:23]
	v_mfma_f32_16x16x32_bf16 v[16:19], v[240:243], v[192:195], v[16:19]
	v_mfma_f32_16x16x32_bf16 v[16:19], v[212:215], v[188:191], v[16:19]
	v_mfma_f32_16x16x32_bf16 v[0:3], v[212:215], v[196:199], v[0:3]
	v_mfma_f32_16x16x32_bf16 v[0:3], v[240:243], v[200:203], v[0:3]
	v_mfma_f32_16x16x32_bf16 v[4:7], v[208:211], v[200:203], v[4:7]
	v_mfma_f32_16x16x32_bf16 v[4:7], v[204:207], v[196:199], v[4:7]
	s_setprio 0
	s_add_i32 s42, 0, 0x18000
	s_barrier
	ds_read_b128 v[136:139], v245
	ds_read_b128 v[146:149], v246
	ds_read_b128 v[150:153], v245 offset:2048
	ds_read_b128 v[154:157], v246 offset:2048
	s_add_u32 s16, s16, 0x160000
	s_addc_u32 s17, s17, 0
	s_mov_b32 m0, s23
	ds_read_b128 v[158:161], v142 offset:32768
	ds_read_b128 v[176:179], v217 offset:32768
	ds_read_b128 v[180:183], v142 offset:34816
	ds_read_b128 v[184:187], v217 offset:34816
	ds_read_b128 v[188:191], v142 offset:36864
	ds_read_b128 v[192:195], v217 offset:36864
	ds_read_b128 v[196:199], v142 offset:38912
	ds_read_b128 v[200:203], v217 offset:38912
	global_load_lds_dwordx4 v168, s[16:17]
	s_mov_b32 m0, s24
	s_nop 0
	global_load_lds_dwordx4 v172, s[16:17]
	s_waitcnt lgkmcnt(8)
	s_barrier
	s_waitcnt lgkmcnt(0)
	s_setprio 1
	s_waitcnt lgkmcnt(0)
	v_mfma_f32_16x16x32_bf16 v[124:127], v[136:139], v[158:161], v[124:127]
	v_mfma_f32_16x16x32_bf16 v[124:127], v[146:149], v[176:179], v[124:127]
	v_mfma_f32_16x16x32_bf16 v[120:123], v[154:157], v[176:179], v[120:123]
	v_mfma_f32_16x16x32_bf16 v[120:123], v[150:153], v[158:161], v[120:123]
	v_mfma_f32_16x16x32_bf16 v[104:107], v[150:153], v[180:183], v[104:107]
	v_mfma_f32_16x16x32_bf16 v[104:107], v[154:157], v[184:187], v[104:107]
	v_mfma_f32_16x16x32_bf16 v[108:111], v[146:149], v[184:187], v[108:111]
	v_mfma_f32_16x16x32_bf16 v[108:111], v[136:139], v[180:183], v[108:111]
	v_mfma_f32_16x16x32_bf16 v[92:95], v[136:139], v[188:191], v[92:95]
	v_mfma_f32_16x16x32_bf16 v[92:95], v[146:149], v[192:195], v[92:95]
	v_mfma_f32_16x16x32_bf16 v[88:91], v[154:157], v[192:195], v[88:91]
	v_mfma_f32_16x16x32_bf16 v[88:91], v[150:153], v[188:191], v[88:91]
	v_mfma_f32_16x16x32_bf16 v[72:75], v[150:153], v[196:199], v[72:75]
	v_mfma_f32_16x16x32_bf16 v[72:75], v[154:157], v[200:203], v[72:75]
	v_mfma_f32_16x16x32_bf16 v[76:79], v[146:149], v[200:203], v[76:79]
	v_mfma_f32_16x16x32_bf16 v[76:79], v[136:139], v[196:199], v[76:79]
	s_setprio 0
	s_barrier
	s_add_i32 s16, 0, 0x1c000
	s_add_i32 s17, s42, s20
	v_add_u32_e32 v145, s16, v140
	s_mov_b32 m0, s17
	ds_read_b128 v[204:207], v145
	v_xor_b32_e32 v243, 64, v145
	ds_read_b128 v[208:211], v243
	ds_read_b128 v[212:215], v145 offset:2048
	ds_read_b128 v[240:243], v243 offset:2048
	global_load_lds_dwordx4 v170, s[98:99]
	s_add_i32 m0, s17, 0x2000
	s_nop 0
	global_load_lds_dwordx4 v174, s[98:99]
	s_barrier
	s_waitcnt lgkmcnt(0)
	s_setprio 1
	s_waitcnt lgkmcnt(0)
	v_mfma_f32_16x16x32_bf16 v[116:119], v[204:207], v[158:161], v[116:119]
	v_mfma_f32_16x16x32_bf16 v[116:119], v[208:211], v[176:179], v[116:119]
	v_mfma_f32_16x16x32_bf16 v[112:115], v[240:243], v[176:179], v[112:115]
	v_mfma_f32_16x16x32_bf16 v[112:115], v[212:215], v[158:161], v[112:115]
	v_mfma_f32_16x16x32_bf16 v[96:99], v[212:215], v[180:183], v[96:99]
	v_mfma_f32_16x16x32_bf16 v[96:99], v[240:243], v[184:187], v[96:99]
	v_mfma_f32_16x16x32_bf16 v[100:103], v[208:211], v[184:187], v[100:103]
	v_mfma_f32_16x16x32_bf16 v[100:103], v[204:207], v[180:183], v[100:103]
	v_mfma_f32_16x16x32_bf16 v[84:87], v[204:207], v[188:191], v[84:87]
	v_mfma_f32_16x16x32_bf16 v[84:87], v[208:211], v[192:195], v[84:87]
	v_mfma_f32_16x16x32_bf16 v[80:83], v[240:243], v[192:195], v[80:83]
	v_mfma_f32_16x16x32_bf16 v[80:83], v[212:215], v[188:191], v[80:83]
	v_mfma_f32_16x16x32_bf16 v[64:67], v[212:215], v[196:199], v[64:67]
	v_mfma_f32_16x16x32_bf16 v[64:67], v[240:243], v[200:203], v[64:67]
	v_mfma_f32_16x16x32_bf16 v[68:71], v[208:211], v[200:203], v[68:71]
	v_mfma_f32_16x16x32_bf16 v[68:71], v[204:207], v[196:199], v[68:71]
	s_setprio 0
	s_mov_b32 m0, s28
	s_barrier
	ds_read_b128 v[158:161], v142 offset:49152
	ds_read_b128 v[176:179], v217 offset:49152
	ds_read_b128 v[180:183], v142 offset:51200
	ds_read_b128 v[184:187], v217 offset:51200
	ds_read_b128 v[188:191], v142 offset:53248
	ds_read_b128 v[192:195], v217 offset:53248
	ds_read_b128 v[196:199], v142 offset:55296
	ds_read_b128 v[200:203], v217 offset:55296
	global_load_lds_dwordx4 v168, s[100:101]
	s_mov_b32 m0, s29
	s_nop 0
	global_load_lds_dwordx4 v172, s[100:101]
	s_barrier
	s_waitcnt lgkmcnt(0)
	s_setprio 1
	s_waitcnt lgkmcnt(0)
	v_mfma_f32_16x16x32_bf16 v[60:63], v[136:139], v[158:161], v[60:63]
	v_mfma_f32_16x16x32_bf16 v[60:63], v[146:149], v[176:179], v[60:63]
	v_mfma_f32_16x16x32_bf16 v[56:59], v[154:157], v[176:179], v[56:59]
	v_mfma_f32_16x16x32_bf16 v[56:59], v[150:153], v[158:161], v[56:59]
	v_mfma_f32_16x16x32_bf16 v[40:43], v[150:153], v[180:183], v[40:43]
	v_mfma_f32_16x16x32_bf16 v[40:43], v[154:157], v[184:187], v[40:43]
	v_mfma_f32_16x16x32_bf16 v[44:47], v[146:149], v[184:187], v[44:47]
	v_mfma_f32_16x16x32_bf16 v[44:47], v[136:139], v[180:183], v[44:47]
	v_mfma_f32_16x16x32_bf16 v[28:31], v[136:139], v[188:191], v[28:31]
	v_mfma_f32_16x16x32_bf16 v[28:31], v[146:149], v[192:195], v[28:31]
	v_mfma_f32_16x16x32_bf16 v[24:27], v[154:157], v[192:195], v[24:27]
	v_mfma_f32_16x16x32_bf16 v[24:27], v[150:153], v[188:191], v[24:27]
	v_mfma_f32_16x16x32_bf16 v[8:11], v[150:153], v[196:199], v[8:11]
	v_mfma_f32_16x16x32_bf16 v[8:11], v[154:157], v[200:203], v[8:11]
	v_mfma_f32_16x16x32_bf16 v[12:15], v[146:149], v[200:203], v[12:15]
	v_mfma_f32_16x16x32_bf16 v[12:15], v[136:139], v[196:199], v[12:15]
	s_setprio 0
	s_barrier
	s_add_u32 s8, s8, 0x160080
	s_addc_u32 s9, s9, 0
	s_add_i32 s16, s16, s20
	s_mov_b32 m0, s16
	s_nop 0
	global_load_lds_dwordx4 v170, s[8:9]
	s_add_i32 m0, s16, 0x2000
	s_nop 0
	global_load_lds_dwordx4 v174, s[8:9]
	s_waitcnt vmcnt(6)
	s_barrier
	s_setprio 1
	v_mfma_f32_16x16x32_bf16 v[52:55], v[204:207], v[158:161], v[52:55]
	v_mfma_f32_16x16x32_bf16 v[52:55], v[208:211], v[176:179], v[52:55]
	v_mfma_f32_16x16x32_bf16 v[48:51], v[240:243], v[176:179], v[48:51]
	v_mfma_f32_16x16x32_bf16 v[48:51], v[212:215], v[158:161], v[48:51]
	v_mfma_f32_16x16x32_bf16 v[32:35], v[212:215], v[180:183], v[32:35]
	v_mfma_f32_16x16x32_bf16 v[32:35], v[240:243], v[184:187], v[32:35]
	v_mfma_f32_16x16x32_bf16 v[36:39], v[208:211], v[184:187], v[36:39]
	v_mfma_f32_16x16x32_bf16 v[36:39], v[204:207], v[180:183], v[36:39]
	v_mfma_f32_16x16x32_bf16 v[20:23], v[204:207], v[188:191], v[20:23]
	v_mfma_f32_16x16x32_bf16 v[20:23], v[208:211], v[192:195], v[20:23]
	v_mfma_f32_16x16x32_bf16 v[16:19], v[240:243], v[192:195], v[16:19]
	v_mfma_f32_16x16x32_bf16 v[16:19], v[212:215], v[188:191], v[16:19]
	v_mfma_f32_16x16x32_bf16 v[0:3], v[212:215], v[196:199], v[0:3]
	v_mfma_f32_16x16x32_bf16 v[0:3], v[240:243], v[200:203], v[0:3]
	v_mfma_f32_16x16x32_bf16 v[4:7], v[208:211], v[200:203], v[4:7]
	v_mfma_f32_16x16x32_bf16 v[4:7], v[204:207], v[196:199], v[4:7]
	s_setprio 0
	s_add_i32 s41, s41, 2
	s_add_u32 s0, s0, 0x100
	s_addc_u32 s1, s1, 0
	s_add_u32 s39, s39, 0x100
	s_addc_u32 s40, s40, 0
	s_cmpk_gt_u32 s41, 0x55
	s_barrier
	s_cbranch_scc0 .LBB0_508
	v_lshl_add_u32 v217, s38, 8, v163
	v_add_u32_e32 v217, s26, v217
	v_lshlrev_b32_e32 v208, 2, v217
	v_lshl_add_u32 v214, v225, 3, s27
	v_lshl_add_u32 v214, s37, 8, v214
	v_lshl_add_u32 v209, v217, 11, v214
	v_lshlrev_b32_e32 v209, 1, v209
	v_lshlrev_b32_e32 v210, 1, v209
	v_lshl_add_u32 v217, v225, 4, v163
	v_xor_b32_e32 v215, 16, v217
	v_lshlrev_b32_e32 v215, 2, v215
	v_xor_b32_e32 v216, 32, v217
	v_lshlrev_b32_e32 v216, 2, v216
	v_add_u32_e32 v211, 0x0, v209
	global_load_dwordx4 v[176:179], v211, s[80:81]
	global_load_dwordx4 v[180:183], v211, s[80:81] offset:256
	v_add_u32_e32 v211, 0x10000, v209
	global_load_dwordx4 v[192:195], v211, s[80:81]
	global_load_dwordx4 v[196:199], v211, s[80:81] offset:256
	s_waitcnt vmcnt(2)
	v_lshlrev_b32_e32 v184, 16, v176
	v_and_b32_e32 v185, 0xffff0000, v176
	v_lshlrev_b32_e32 v186, 16, v177
	v_and_b32_e32 v187, 0xffff0000, v177
	v_lshlrev_b32_e32 v188, 16, v178
	v_and_b32_e32 v189, 0xffff0000, v178
	v_lshlrev_b32_e32 v190, 16, v179
	v_and_b32_e32 v191, 0xffff0000, v179
	v_pk_add_f32 v[124:125], v[124:125], v[184:185]
	v_pk_add_f32 v[126:127], v[126:127], v[186:187]
	v_pk_add_f32 v[120:121], v[120:121], v[188:189]
	v_pk_add_f32 v[122:123], v[122:123], v[190:191]
	v_mul_f32_e32 v213, v124, v124
	v_fmac_f32_e32 v213, v125, v125
	v_fmac_f32_e32 v213, v126, v126
	v_fmac_f32_e32 v213, v127, v127
	v_fmac_f32_e32 v213, v120, v120
	v_fmac_f32_e32 v213, v121, v121
	v_fmac_f32_e32 v213, v122, v122
	v_fmac_f32_e32 v213, v123, v123
	v_cvt_pk_bf16_f32 v176, v124, v125
	v_cvt_pk_bf16_f32 v177, v126, v127
	v_cvt_pk_bf16_f32 v178, v120, v121
	v_cvt_pk_bf16_f32 v179, v122, v123
	v_add_u32_e32 v217, 0x0, v209
	global_store_dwordx4 v217, v[176:179], s[80:81]
	v_lshlrev_b32_e32 v184, 16, v180
	v_and_b32_e32 v185, 0xffff0000, v180
	v_lshlrev_b32_e32 v186, 16, v181
	v_and_b32_e32 v187, 0xffff0000, v181
	v_lshlrev_b32_e32 v188, 16, v182
	v_and_b32_e32 v189, 0xffff0000, v182
	v_lshlrev_b32_e32 v190, 16, v183
	v_and_b32_e32 v191, 0xffff0000, v183
	v_pk_add_f32 v[116:117], v[116:117], v[184:185]
	v_pk_add_f32 v[118:119], v[118:119], v[186:187]
	v_pk_add_f32 v[112:113], v[112:113], v[188:189]
	v_pk_add_f32 v[114:115], v[114:115], v[190:191]
	v_fmac_f32_e32 v213, v116, v116
	v_fmac_f32_e32 v213, v117, v117
	v_fmac_f32_e32 v213, v118, v118
	v_fmac_f32_e32 v213, v119, v119
	v_fmac_f32_e32 v213, v112, v112
	v_fmac_f32_e32 v213, v113, v113
	v_fmac_f32_e32 v213, v114, v114
	v_fmac_f32_e32 v213, v115, v115
	v_cvt_pk_bf16_f32 v180, v116, v117
	v_cvt_pk_bf16_f32 v181, v118, v119
	v_cvt_pk_bf16_f32 v182, v112, v113
	v_cvt_pk_bf16_f32 v183, v114, v115
	global_store_dwordx4 v217, v[180:183], s[80:81] offset:256
	ds_bpermute_b32 v214, v215, v213
	s_waitcnt lgkmcnt(0)
	v_add_f32_e32 v213, v213, v214
	ds_bpermute_b32 v214, v216, v213
	s_waitcnt lgkmcnt(0)
	v_add_f32_e32 v213, v213, v214
	s_mov_b64 exec, 0xffff
	global_atomic_add_f32 v208, v213, s[14:15]
	s_mov_b64 exec, -1
	v_add_u32_e32 v211, 0x20000, v209
	global_load_dwordx4 v[176:179], v211, s[80:81]
	global_load_dwordx4 v[180:183], v211, s[80:81] offset:256
	s_waitcnt vmcnt(5)
	v_lshlrev_b32_e32 v200, 16, v192
	v_and_b32_e32 v201, 0xffff0000, v192
	v_lshlrev_b32_e32 v202, 16, v193
	v_and_b32_e32 v203, 0xffff0000, v193
	v_lshlrev_b32_e32 v204, 16, v194
	v_and_b32_e32 v205, 0xffff0000, v194
	v_lshlrev_b32_e32 v206, 16, v195
	v_and_b32_e32 v207, 0xffff0000, v195
	v_pk_add_f32 v[108:109], v[108:109], v[200:201]
	v_pk_add_f32 v[110:111], v[110:111], v[202:203]
	v_pk_add_f32 v[104:105], v[104:105], v[204:205]
	v_pk_add_f32 v[106:107], v[106:107], v[206:207]
	v_mul_f32_e32 v213, v108, v108
	v_fmac_f32_e32 v213, v109, v109
	v_fmac_f32_e32 v213, v110, v110
	v_fmac_f32_e32 v213, v111, v111
	v_fmac_f32_e32 v213, v104, v104
	v_fmac_f32_e32 v213, v105, v105
	v_fmac_f32_e32 v213, v106, v106
	v_fmac_f32_e32 v213, v107, v107
	v_cvt_pk_bf16_f32 v192, v108, v109
	v_cvt_pk_bf16_f32 v193, v110, v111
	v_cvt_pk_bf16_f32 v194, v104, v105
	v_cvt_pk_bf16_f32 v195, v106, v107
	v_add_u32_e32 v217, 0x10000, v209
	global_store_dwordx4 v217, v[192:195], s[80:81]
	v_lshlrev_b32_e32 v200, 16, v196
	v_and_b32_e32 v201, 0xffff0000, v196
	v_lshlrev_b32_e32 v202, 16, v197
	v_and_b32_e32 v203, 0xffff0000, v197
	v_lshlrev_b32_e32 v204, 16, v198
	v_and_b32_e32 v205, 0xffff0000, v198
	v_lshlrev_b32_e32 v206, 16, v199
	v_and_b32_e32 v207, 0xffff0000, v199
	v_pk_add_f32 v[100:101], v[100:101], v[200:201]
	v_pk_add_f32 v[102:103], v[102:103], v[202:203]
	v_pk_add_f32 v[96:97], v[96:97], v[204:205]
	v_pk_add_f32 v[98:99], v[98:99], v[206:207]
	v_fmac_f32_e32 v213, v100, v100
	v_fmac_f32_e32 v213, v101, v101
	v_fmac_f32_e32 v213, v102, v102
	v_fmac_f32_e32 v213, v103, v103
	v_fmac_f32_e32 v213, v96, v96
	v_fmac_f32_e32 v213, v97, v97
	v_fmac_f32_e32 v213, v98, v98
	v_fmac_f32_e32 v213, v99, v99
	v_cvt_pk_bf16_f32 v196, v100, v101
	v_cvt_pk_bf16_f32 v197, v102, v103
	v_cvt_pk_bf16_f32 v198, v96, v97
	v_cvt_pk_bf16_f32 v199, v98, v99
	global_store_dwordx4 v217, v[196:199], s[80:81] offset:256
	ds_bpermute_b32 v214, v215, v213
	s_waitcnt lgkmcnt(0)
	v_add_f32_e32 v213, v213, v214
	ds_bpermute_b32 v214, v216, v213
	s_waitcnt lgkmcnt(0)
	v_add_f32_e32 v213, v213, v214
	s_mov_b64 exec, 0xffff
	global_atomic_add_f32 v208, v213, s[14:15] offset:64
	s_mov_b64 exec, -1
	v_add_u32_e32 v211, 0x30000, v209
	global_load_dwordx4 v[192:195], v211, s[80:81]
	global_load_dwordx4 v[196:199], v211, s[80:81] offset:256
	s_waitcnt vmcnt(5)
	v_lshlrev_b32_e32 v184, 16, v176
	v_and_b32_e32 v185, 0xffff0000, v176
	v_lshlrev_b32_e32 v186, 16, v177
	v_and_b32_e32 v187, 0xffff0000, v177
	v_lshlrev_b32_e32 v188, 16, v178
	v_and_b32_e32 v189, 0xffff0000, v178
	v_lshlrev_b32_e32 v190, 16, v179
	v_and_b32_e32 v191, 0xffff0000, v179
	v_pk_add_f32 v[92:93], v[92:93], v[184:185]
	v_pk_add_f32 v[94:95], v[94:95], v[186:187]
	v_pk_add_f32 v[88:89], v[88:89], v[188:189]
	v_pk_add_f32 v[90:91], v[90:91], v[190:191]
	v_mul_f32_e32 v213, v92, v92
	v_fmac_f32_e32 v213, v93, v93
	v_fmac_f32_e32 v213, v94, v94
	v_fmac_f32_e32 v213, v95, v95
	v_fmac_f32_e32 v213, v88, v88
	v_fmac_f32_e32 v213, v89, v89
	v_fmac_f32_e32 v213, v90, v90
	v_fmac_f32_e32 v213, v91, v91
	v_cvt_pk_bf16_f32 v176, v92, v93
	v_cvt_pk_bf16_f32 v177, v94, v95
	v_cvt_pk_bf16_f32 v178, v88, v89
	v_cvt_pk_bf16_f32 v179, v90, v91
	v_add_u32_e32 v217, 0x20000, v209
	global_store_dwordx4 v217, v[176:179], s[80:81]
	v_lshlrev_b32_e32 v184, 16, v180
	v_and_b32_e32 v185, 0xffff0000, v180
	v_lshlrev_b32_e32 v186, 16, v181
	v_and_b32_e32 v187, 0xffff0000, v181
	v_lshlrev_b32_e32 v188, 16, v182
	v_and_b32_e32 v189, 0xffff0000, v182
	v_lshlrev_b32_e32 v190, 16, v183
	v_and_b32_e32 v191, 0xffff0000, v183
	v_pk_add_f32 v[84:85], v[84:85], v[184:185]
	v_pk_add_f32 v[86:87], v[86:87], v[186:187]
	v_pk_add_f32 v[80:81], v[80:81], v[188:189]
	v_pk_add_f32 v[82:83], v[82:83], v[190:191]
	v_fmac_f32_e32 v213, v84, v84
	v_fmac_f32_e32 v213, v85, v85
	v_fmac_f32_e32 v213, v86, v86
	v_fmac_f32_e32 v213, v87, v87
	v_fmac_f32_e32 v213, v80, v80
	v_fmac_f32_e32 v213, v81, v81
	v_fmac_f32_e32 v213, v82, v82
	v_fmac_f32_e32 v213, v83, v83
	v_cvt_pk_bf16_f32 v180, v84, v85
	v_cvt_pk_bf16_f32 v181, v86, v87
	v_cvt_pk_bf16_f32 v182, v80, v81
	v_cvt_pk_bf16_f32 v183, v82, v83
	global_store_dwordx4 v217, v[180:183], s[80:81] offset:256
	ds_bpermute_b32 v214, v215, v213
	s_waitcnt lgkmcnt(0)
	v_add_f32_e32 v213, v213, v214
	ds_bpermute_b32 v214, v216, v213
	s_waitcnt lgkmcnt(0)
	v_add_f32_e32 v213, v213, v214
	s_mov_b64 exec, 0xffff
	global_atomic_add_f32 v208, v213, s[14:15] offset:128
	s_mov_b64 exec, -1
	v_add_u32_e32 v211, 0x80000, v209
	global_load_dwordx4 v[176:179], v211, s[80:81]
	global_load_dwordx4 v[180:183], v211, s[80:81] offset:256
	s_waitcnt vmcnt(5)
	v_lshlrev_b32_e32 v200, 16, v192
	v_and_b32_e32 v201, 0xffff0000, v192
	v_lshlrev_b32_e32 v202, 16, v193
	v_and_b32_e32 v203, 0xffff0000, v193
	v_lshlrev_b32_e32 v204, 16, v194
	v_and_b32_e32 v205, 0xffff0000, v194
	v_lshlrev_b32_e32 v206, 16, v195
	v_and_b32_e32 v207, 0xffff0000, v195
	v_pk_add_f32 v[76:77], v[76:77], v[200:201]
	v_pk_add_f32 v[78:79], v[78:79], v[202:203]
	v_pk_add_f32 v[72:73], v[72:73], v[204:205]
	v_pk_add_f32 v[74:75], v[74:75], v[206:207]
	v_mul_f32_e32 v213, v76, v76
	v_fmac_f32_e32 v213, v77, v77
	v_fmac_f32_e32 v213, v78, v78
	v_fmac_f32_e32 v213, v79, v79
	v_fmac_f32_e32 v213, v72, v72
	v_fmac_f32_e32 v213, v73, v73
	v_fmac_f32_e32 v213, v74, v74
	v_fmac_f32_e32 v213, v75, v75
	v_cvt_pk_bf16_f32 v192, v76, v77
	v_cvt_pk_bf16_f32 v193, v78, v79
	v_cvt_pk_bf16_f32 v194, v72, v73
	v_cvt_pk_bf16_f32 v195, v74, v75
	v_add_u32_e32 v217, 0x30000, v209
	global_store_dwordx4 v217, v[192:195], s[80:81]
	v_lshlrev_b32_e32 v200, 16, v196
	v_and_b32_e32 v201, 0xffff0000, v196
	v_lshlrev_b32_e32 v202, 16, v197
	v_and_b32_e32 v203, 0xffff0000, v197
	v_lshlrev_b32_e32 v204, 16, v198
	v_and_b32_e32 v205, 0xffff0000, v198
	v_lshlrev_b32_e32 v206, 16, v199
	v_and_b32_e32 v207, 0xffff0000, v199
	v_pk_add_f32 v[68:69], v[68:69], v[200:201]
	v_pk_add_f32 v[70:71], v[70:71], v[202:203]
	v_pk_add_f32 v[64:65], v[64:65], v[204:205]
	v_pk_add_f32 v[66:67], v[66:67], v[206:207]
	v_fmac_f32_e32 v213, v68, v68
	v_fmac_f32_e32 v213, v69, v69
	v_fmac_f32_e32 v213, v70, v70
	v_fmac_f32_e32 v213, v71, v71
	v_fmac_f32_e32 v213, v64, v64
	v_fmac_f32_e32 v213, v65, v65
	v_fmac_f32_e32 v213, v66, v66
	v_fmac_f32_e32 v213, v67, v67
	v_cvt_pk_bf16_f32 v196, v68, v69
	v_cvt_pk_bf16_f32 v197, v70, v71
	v_cvt_pk_bf16_f32 v198, v64, v65
	v_cvt_pk_bf16_f32 v199, v66, v67
	global_store_dwordx4 v217, v[196:199], s[80:81] offset:256
	ds_bpermute_b32 v214, v215, v213
	s_waitcnt lgkmcnt(0)
	v_add_f32_e32 v213, v213, v214
	ds_bpermute_b32 v214, v216, v213
	s_waitcnt lgkmcnt(0)
	v_add_f32_e32 v213, v213, v214
	s_mov_b64 exec, 0xffff
	global_atomic_add_f32 v208, v213, s[14:15] offset:192
	s_mov_b64 exec, -1
	v_add_u32_e32 v211, 0x90000, v209
	global_load_dwordx4 v[192:195], v211, s[80:81]
	global_load_dwordx4 v[196:199], v211, s[80:81] offset:256
	s_waitcnt vmcnt(5)
	v_lshlrev_b32_e32 v184, 16, v176
	v_and_b32_e32 v185, 0xffff0000, v176
	v_lshlrev_b32_e32 v186, 16, v177
	v_and_b32_e32 v187, 0xffff0000, v177
	v_lshlrev_b32_e32 v188, 16, v178
	v_and_b32_e32 v189, 0xffff0000, v178
	v_lshlrev_b32_e32 v190, 16, v179
	v_and_b32_e32 v191, 0xffff0000, v179
	v_pk_add_f32 v[60:61], v[60:61], v[184:185]
	v_pk_add_f32 v[62:63], v[62:63], v[186:187]
	v_pk_add_f32 v[56:57], v[56:57], v[188:189]
	v_pk_add_f32 v[58:59], v[58:59], v[190:191]
	v_mul_f32_e32 v213, v60, v60
	v_fmac_f32_e32 v213, v61, v61
	v_fmac_f32_e32 v213, v62, v62
	v_fmac_f32_e32 v213, v63, v63
	v_fmac_f32_e32 v213, v56, v56
	v_fmac_f32_e32 v213, v57, v57
	v_fmac_f32_e32 v213, v58, v58
	v_fmac_f32_e32 v213, v59, v59
	v_cvt_pk_bf16_f32 v176, v60, v61
	v_cvt_pk_bf16_f32 v177, v62, v63
	v_cvt_pk_bf16_f32 v178, v56, v57
	v_cvt_pk_bf16_f32 v179, v58, v59
	v_add_u32_e32 v217, 0x80000, v209
	global_store_dwordx4 v217, v[176:179], s[80:81]
	v_lshlrev_b32_e32 v184, 16, v180
	v_and_b32_e32 v185, 0xffff0000, v180
	v_lshlrev_b32_e32 v186, 16, v181
	v_and_b32_e32 v187, 0xffff0000, v181
	v_lshlrev_b32_e32 v188, 16, v182
	v_and_b32_e32 v189, 0xffff0000, v182
	v_lshlrev_b32_e32 v190, 16, v183
	v_and_b32_e32 v191, 0xffff0000, v183
	v_pk_add_f32 v[52:53], v[52:53], v[184:185]
	v_pk_add_f32 v[54:55], v[54:55], v[186:187]
	v_pk_add_f32 v[48:49], v[48:49], v[188:189]
	v_pk_add_f32 v[50:51], v[50:51], v[190:191]
	v_fmac_f32_e32 v213, v52, v52
	v_fmac_f32_e32 v213, v53, v53
	v_fmac_f32_e32 v213, v54, v54
	v_fmac_f32_e32 v213, v55, v55
	v_fmac_f32_e32 v213, v48, v48
	v_fmac_f32_e32 v213, v49, v49
	v_fmac_f32_e32 v213, v50, v50
	v_fmac_f32_e32 v213, v51, v51
	v_cvt_pk_bf16_f32 v180, v52, v53
	v_cvt_pk_bf16_f32 v181, v54, v55
	v_cvt_pk_bf16_f32 v182, v48, v49
	v_cvt_pk_bf16_f32 v183, v50, v51
	global_store_dwordx4 v217, v[180:183], s[80:81] offset:256
	ds_bpermute_b32 v214, v215, v213
	s_waitcnt lgkmcnt(0)
	v_add_f32_e32 v213, v213, v214
	ds_bpermute_b32 v214, v216, v213
	s_waitcnt lgkmcnt(0)
	v_add_f32_e32 v213, v213, v214
	s_mov_b64 exec, 0xffff
	global_atomic_add_f32 v208, v213, s[14:15] offset:512
	s_mov_b64 exec, -1
	v_add_u32_e32 v211, 0xa0000, v209
	global_load_dwordx4 v[176:179], v211, s[80:81]
	global_load_dwordx4 v[180:183], v211, s[80:81] offset:256
	s_waitcnt vmcnt(5)
	v_lshlrev_b32_e32 v200, 16, v192
	v_and_b32_e32 v201, 0xffff0000, v192
	v_lshlrev_b32_e32 v202, 16, v193
	v_and_b32_e32 v203, 0xffff0000, v193
	v_lshlrev_b32_e32 v204, 16, v194
	v_and_b32_e32 v205, 0xffff0000, v194
	v_lshlrev_b32_e32 v206, 16, v195
	v_and_b32_e32 v207, 0xffff0000, v195
	v_pk_add_f32 v[44:45], v[44:45], v[200:201]
	v_pk_add_f32 v[46:47], v[46:47], v[202:203]
	v_pk_add_f32 v[40:41], v[40:41], v[204:205]
	v_pk_add_f32 v[42:43], v[42:43], v[206:207]
	v_mul_f32_e32 v213, v44, v44
	v_fmac_f32_e32 v213, v45, v45
	v_fmac_f32_e32 v213, v46, v46
	v_fmac_f32_e32 v213, v47, v47
	v_fmac_f32_e32 v213, v40, v40
	v_fmac_f32_e32 v213, v41, v41
	v_fmac_f32_e32 v213, v42, v42
	v_fmac_f32_e32 v213, v43, v43
	v_cvt_pk_bf16_f32 v192, v44, v45
	v_cvt_pk_bf16_f32 v193, v46, v47
	v_cvt_pk_bf16_f32 v194, v40, v41
	v_cvt_pk_bf16_f32 v195, v42, v43
	v_add_u32_e32 v217, 0x90000, v209
	global_store_dwordx4 v217, v[192:195], s[80:81]
	v_lshlrev_b32_e32 v200, 16, v196
	v_and_b32_e32 v201, 0xffff0000, v196
	v_lshlrev_b32_e32 v202, 16, v197
	v_and_b32_e32 v203, 0xffff0000, v197
	v_lshlrev_b32_e32 v204, 16, v198
	v_and_b32_e32 v205, 0xffff0000, v198
	v_lshlrev_b32_e32 v206, 16, v199
	v_and_b32_e32 v207, 0xffff0000, v199
	v_pk_add_f32 v[36:37], v[36:37], v[200:201]
	v_pk_add_f32 v[38:39], v[38:39], v[202:203]
	v_pk_add_f32 v[32:33], v[32:33], v[204:205]
	v_pk_add_f32 v[34:35], v[34:35], v[206:207]
	v_fmac_f32_e32 v213, v36, v36
	v_fmac_f32_e32 v213, v37, v37
	v_fmac_f32_e32 v213, v38, v38
	v_fmac_f32_e32 v213, v39, v39
	v_fmac_f32_e32 v213, v32, v32
	v_fmac_f32_e32 v213, v33, v33
	v_fmac_f32_e32 v213, v34, v34
	v_fmac_f32_e32 v213, v35, v35
	v_cvt_pk_bf16_f32 v196, v36, v37
	v_cvt_pk_bf16_f32 v197, v38, v39
	v_cvt_pk_bf16_f32 v198, v32, v33
	v_cvt_pk_bf16_f32 v199, v34, v35
	global_store_dwordx4 v217, v[196:199], s[80:81] offset:256
	ds_bpermute_b32 v214, v215, v213
	s_waitcnt lgkmcnt(0)
	v_add_f32_e32 v213, v213, v214
	ds_bpermute_b32 v214, v216, v213
	s_waitcnt lgkmcnt(0)
	v_add_f32_e32 v213, v213, v214
	s_mov_b64 exec, 0xffff
	global_atomic_add_f32 v208, v213, s[14:15] offset:576
	s_mov_b64 exec, -1
	v_add_u32_e32 v211, 0xb0000, v209
	global_load_dwordx4 v[192:195], v211, s[80:81]
	global_load_dwordx4 v[196:199], v211, s[80:81] offset:256
	s_waitcnt vmcnt(5)
	v_lshlrev_b32_e32 v184, 16, v176
	v_and_b32_e32 v185, 0xffff0000, v176
	v_lshlrev_b32_e32 v186, 16, v177
	v_and_b32_e32 v187, 0xffff0000, v177
	v_lshlrev_b32_e32 v188, 16, v178
	v_and_b32_e32 v189, 0xffff0000, v178
	v_lshlrev_b32_e32 v190, 16, v179
	v_and_b32_e32 v191, 0xffff0000, v179
	v_pk_add_f32 v[28:29], v[28:29], v[184:185]
	v_pk_add_f32 v[30:31], v[30:31], v[186:187]
	v_pk_add_f32 v[24:25], v[24:25], v[188:189]
	v_pk_add_f32 v[26:27], v[26:27], v[190:191]
	v_mul_f32_e32 v213, v28, v28
	v_fmac_f32_e32 v213, v29, v29
	v_fmac_f32_e32 v213, v30, v30
	v_fmac_f32_e32 v213, v31, v31
	v_fmac_f32_e32 v213, v24, v24
	v_fmac_f32_e32 v213, v25, v25
	v_fmac_f32_e32 v213, v26, v26
	v_fmac_f32_e32 v213, v27, v27
	v_cvt_pk_bf16_f32 v176, v28, v29
	v_cvt_pk_bf16_f32 v177, v30, v31
	v_cvt_pk_bf16_f32 v178, v24, v25
	v_cvt_pk_bf16_f32 v179, v26, v27
	v_add_u32_e32 v217, 0xa0000, v209
	global_store_dwordx4 v217, v[176:179], s[80:81]
	v_lshlrev_b32_e32 v184, 16, v180
	v_and_b32_e32 v185, 0xffff0000, v180
	v_lshlrev_b32_e32 v186, 16, v181
	v_and_b32_e32 v187, 0xffff0000, v181
	v_lshlrev_b32_e32 v188, 16, v182
	v_and_b32_e32 v189, 0xffff0000, v182
	v_lshlrev_b32_e32 v190, 16, v183
	v_and_b32_e32 v191, 0xffff0000, v183
	v_pk_add_f32 v[20:21], v[20:21], v[184:185]
	v_pk_add_f32 v[22:23], v[22:23], v[186:187]
	v_pk_add_f32 v[16:17], v[16:17], v[188:189]
	v_pk_add_f32 v[18:19], v[18:19], v[190:191]
	v_fmac_f32_e32 v213, v20, v20
	v_fmac_f32_e32 v213, v21, v21
	v_fmac_f32_e32 v213, v22, v22
	v_fmac_f32_e32 v213, v23, v23
	v_fmac_f32_e32 v213, v16, v16
	v_fmac_f32_e32 v213, v17, v17
	v_fmac_f32_e32 v213, v18, v18
	v_fmac_f32_e32 v213, v19, v19
	v_cvt_pk_bf16_f32 v180, v20, v21
	v_cvt_pk_bf16_f32 v181, v22, v23
	v_cvt_pk_bf16_f32 v182, v16, v17
	v_cvt_pk_bf16_f32 v183, v18, v19
	global_store_dwordx4 v217, v[180:183], s[80:81] offset:256
	ds_bpermute_b32 v214, v215, v213
	s_waitcnt lgkmcnt(0)
	v_add_f32_e32 v213, v213, v214
	ds_bpermute_b32 v214, v216, v213
	s_waitcnt lgkmcnt(0)
	v_add_f32_e32 v213, v213, v214
	s_mov_b64 exec, 0xffff
	global_atomic_add_f32 v208, v213, s[14:15] offset:640
	s_mov_b64 exec, -1
	s_waitcnt vmcnt(3)
	v_lshlrev_b32_e32 v200, 16, v192
	v_and_b32_e32 v201, 0xffff0000, v192
	v_lshlrev_b32_e32 v202, 16, v193
	v_and_b32_e32 v203, 0xffff0000, v193
	v_lshlrev_b32_e32 v204, 16, v194
	v_and_b32_e32 v205, 0xffff0000, v194
	v_lshlrev_b32_e32 v206, 16, v195
	v_and_b32_e32 v207, 0xffff0000, v195
	v_pk_add_f32 v[12:13], v[12:13], v[200:201]
	v_pk_add_f32 v[14:15], v[14:15], v[202:203]
	v_pk_add_f32 v[8:9], v[8:9], v[204:205]
	v_pk_add_f32 v[10:11], v[10:11], v[206:207]
	v_mul_f32_e32 v213, v12, v12
	v_fmac_f32_e32 v213, v13, v13
	v_fmac_f32_e32 v213, v14, v14
	v_fmac_f32_e32 v213, v15, v15
	v_fmac_f32_e32 v213, v8, v8
	v_fmac_f32_e32 v213, v9, v9
	v_fmac_f32_e32 v213, v10, v10
	v_fmac_f32_e32 v213, v11, v11
	v_cvt_pk_bf16_f32 v192, v12, v13
	v_cvt_pk_bf16_f32 v193, v14, v15
	v_cvt_pk_bf16_f32 v194, v8, v9
	v_cvt_pk_bf16_f32 v195, v10, v11
	v_add_u32_e32 v217, 0xb0000, v209
	global_store_dwordx4 v217, v[192:195], s[80:81]
	v_lshlrev_b32_e32 v200, 16, v196
	v_and_b32_e32 v201, 0xffff0000, v196
	v_lshlrev_b32_e32 v202, 16, v197
	v_and_b32_e32 v203, 0xffff0000, v197
	v_lshlrev_b32_e32 v204, 16, v198
	v_and_b32_e32 v205, 0xffff0000, v198
	v_lshlrev_b32_e32 v206, 16, v199
	v_and_b32_e32 v207, 0xffff0000, v199
	v_pk_add_f32 v[4:5], v[4:5], v[200:201]
	v_pk_add_f32 v[6:7], v[6:7], v[202:203]
	v_pk_add_f32 v[0:1], v[0:1], v[204:205]
	v_pk_add_f32 v[2:3], v[2:3], v[206:207]
	v_fmac_f32_e32 v213, v4, v4
	v_fmac_f32_e32 v213, v5, v5
	v_fmac_f32_e32 v213, v6, v6
	v_fmac_f32_e32 v213, v7, v7
	v_fmac_f32_e32 v213, v0, v0
	v_fmac_f32_e32 v213, v1, v1
	v_fmac_f32_e32 v213, v2, v2
	v_fmac_f32_e32 v213, v3, v3
	v_cvt_pk_bf16_f32 v196, v4, v5
	v_cvt_pk_bf16_f32 v197, v6, v7
	v_cvt_pk_bf16_f32 v198, v0, v1
	v_cvt_pk_bf16_f32 v199, v2, v3
	global_store_dwordx4 v217, v[196:199], s[80:81] offset:256
	ds_bpermute_b32 v214, v215, v213
	s_waitcnt lgkmcnt(0)
	v_add_f32_e32 v213, v213, v214
	ds_bpermute_b32 v214, v216, v213
	s_waitcnt lgkmcnt(0)
	v_add_f32_e32 v213, v213, v214
	s_mov_b64 exec, 0xffff
	global_atomic_add_f32 v208, v213, s[14:15] offset:704
	s_mov_b64 exec, -1
	s_branch .LBB0_496

.LBB0_598:
	s_ashr_i32 s21, s20, 31
	v_cmp_lt_i64_e32 vcc, s[22:23], v[136:137]
	s_lshl_b64 s[22:23], s[20:21], 20
	s_add_u32 s22, s80, s22
	s_addc_u32 s23, s81, s23
	s_and_b64 s[24:25], vcc, exec
	s_cselect_b32 s1, s23, s27
	s_cselect_b32 s13, s22, s26
	s_ashr_i32 s19, s18, 31
	s_lshl_b64 s[24:25], s[18:19], 20
	s_add_u32 s24, s34, s24
	s_addc_u32 s25, s35, s25
	s_and_b64 s[30:31], vcc, exec
	s_cselect_b32 s19, s25, s29
	s_cselect_b32 s21, s24, s28
	s_add_u32 s26, s26, 0x80080
	s_addc_u32 s27, s27, 0
	s_add_u32 s33, s28, 0x100
	v_mov_b32_e32 v0, 0
	s_addc_u32 s48, s29, 0
	s_mov_b32 s49, -2
	s_waitcnt lgkmcnt(0)
	v_mov_b32_e32 v1, v0
	v_mov_b32_e32 v2, v0
	v_mov_b32_e32 v3, v0
	v_mov_b32_e32 v4, v0
	v_mov_b32_e32 v5, v0
	v_mov_b32_e32 v6, v0
	v_mov_b32_e32 v7, v0
	s_waitcnt vmcnt(0)
	v_mov_b32_e32 v16, v0
	v_mov_b32_e32 v17, v0
	v_mov_b32_e32 v18, v0
	v_mov_b32_e32 v19, v0
	v_mov_b32_e32 v20, v0
	v_mov_b32_e32 v21, v0
	v_mov_b32_e32 v22, v0
	v_mov_b32_e32 v23, v0
	v_mov_b32_e32 v32, v0
	v_mov_b32_e32 v33, v0
	v_mov_b32_e32 v34, v0
	v_mov_b32_e32 v35, v0
	v_mov_b32_e32 v36, v0
	v_mov_b32_e32 v37, v0
	v_mov_b32_e32 v38, v0
	v_mov_b32_e32 v39, v0
	v_mov_b32_e32 v48, v0
	v_mov_b32_e32 v49, v0
	v_mov_b32_e32 v50, v0
	v_mov_b32_e32 v51, v0
	v_mov_b32_e32 v52, v0
	v_mov_b32_e32 v53, v0
	v_mov_b32_e32 v54, v0
	v_mov_b32_e32 v55, v0
	v_mov_b32_e32 v8, v0
	v_mov_b32_e32 v9, v0
	v_mov_b32_e32 v10, v0
	v_mov_b32_e32 v11, v0
	v_mov_b32_e32 v12, v0
	v_mov_b32_e32 v13, v0
	v_mov_b32_e32 v14, v0
	v_mov_b32_e32 v15, v0
	v_mov_b32_e32 v24, v0
	v_mov_b32_e32 v25, v0
	v_mov_b32_e32 v26, v0
	v_mov_b32_e32 v27, v0
	v_mov_b32_e32 v28, v0
	v_mov_b32_e32 v29, v0
	v_mov_b32_e32 v30, v0
	v_mov_b32_e32 v31, v0
	v_mov_b32_e32 v40, v0
	v_mov_b32_e32 v41, v0
	v_mov_b32_e32 v42, v0
	v_mov_b32_e32 v43, v0
	v_mov_b32_e32 v44, v0
	v_mov_b32_e32 v45, v0
	v_mov_b32_e32 v46, v0
	v_mov_b32_e32 v47, v0
	v_mov_b32_e32 v56, v0
	v_mov_b32_e32 v57, v0
	v_mov_b32_e32 v58, v0
	v_mov_b32_e32 v59, v0
	v_mov_b32_e32 v60, v0
	v_mov_b32_e32 v61, v0
	v_mov_b32_e32 v62, v0
	v_mov_b32_e32 v63, v0
	v_mov_b32_e32 v64, v0
	v_mov_b32_e32 v65, v0
	v_mov_b32_e32 v66, v0
	v_mov_b32_e32 v67, v0
	v_mov_b32_e32 v68, v0
	v_mov_b32_e32 v69, v0
	v_mov_b32_e32 v70, v0
	v_mov_b32_e32 v71, v0
	v_mov_b32_e32 v80, v0
	v_mov_b32_e32 v81, v0
	v_mov_b32_e32 v82, v0
	v_mov_b32_e32 v83, v0
	v_mov_b32_e32 v84, v0
	v_mov_b32_e32 v85, v0
	v_mov_b32_e32 v86, v0
	v_mov_b32_e32 v87, v0
	v_mov_b32_e32 v96, v0
	v_mov_b32_e32 v97, v0
	v_mov_b32_e32 v98, v0
	v_mov_b32_e32 v99, v0
	v_mov_b32_e32 v100, v0
	v_mov_b32_e32 v101, v0
	v_mov_b32_e32 v102, v0
	v_mov_b32_e32 v103, v0
	v_mov_b32_e32 v112, v0
	v_mov_b32_e32 v113, v0
	v_mov_b32_e32 v114, v0
	v_mov_b32_e32 v115, v0
	v_mov_b32_e32 v116, v0
	v_mov_b32_e32 v117, v0
	v_mov_b32_e32 v118, v0
	v_mov_b32_e32 v119, v0
	v_mov_b32_e32 v72, v0
	v_mov_b32_e32 v73, v0
	v_mov_b32_e32 v74, v0
	v_mov_b32_e32 v75, v0
	v_mov_b32_e32 v76, v0
	v_mov_b32_e32 v77, v0
	v_mov_b32_e32 v78, v0
	v_mov_b32_e32 v79, v0
	v_mov_b32_e32 v88, v0
	v_mov_b32_e32 v89, v0
	v_mov_b32_e32 v90, v0
	v_mov_b32_e32 v91, v0
	v_mov_b32_e32 v92, v0
	v_mov_b32_e32 v93, v0
	v_mov_b32_e32 v94, v0
	v_mov_b32_e32 v95, v0
	v_mov_b32_e32 v104, v0
	v_mov_b32_e32 v105, v0
	v_mov_b32_e32 v106, v0
	v_mov_b32_e32 v107, v0
	v_mov_b32_e32 v108, v0
	v_mov_b32_e32 v109, v0
	v_mov_b32_e32 v110, v0
	v_mov_b32_e32 v111, v0
	v_mov_b32_e32 v120, v0
	v_mov_b32_e32 v121, v0
	v_mov_b32_e32 v122, v0
	v_mov_b32_e32 v123, v0
	v_mov_b32_e32 v124, v0
	v_mov_b32_e32 v125, v0
	v_mov_b32_e32 v126, v0
	v_mov_b32_e32 v127, v0
	v_xor_b32_e32 v144, 64, v149
	v_xor_b32_e32 v145, 64, v150
	v_xor_b32_e32 v216, 64, v151
	v_add_u32_e32 v217, 0x18000, v147
	v_xor_b32_e32 v234, 64, v217
	v_add_u32_e32 v235, 0x1c000, v147
	v_xor_b32_e32 v252, 64, v235
.LBB0_599:
	ds_read_b128 v[140:143], v149
	ds_read_b128 v[154:157], v144
	ds_read_b128 v[158:161], v149 offset:2048
	ds_read_b128 v[176:179], v144 offset:2048
	s_add_u32 s28, s26, 0xfff80080
	s_addc_u32 s29, s27, -1
	s_cmp_eq_u32 s49, 28
	s_cselect_b32 s31, s1, s29
	s_cselect_b32 s30, s13, s28
	s_cselect_b32 s29, s19, s48
	s_cselect_b32 s28, s21, s33
	s_add_i32 m0, s37, 0xc000
	ds_read_b128 v[180:183], v150
	ds_read_b128 v[184:187], v145
	ds_read_b128 v[188:191], v150 offset:2048
	ds_read_b128 v[192:195], v145 offset:2048
	ds_read_b128 v[196:199], v150 offset:4096
	ds_read_b128 v[200:203], v145 offset:4096
	ds_read_b128 v[204:207], v150 offset:6144
	ds_read_b128 v[208:211], v145 offset:6144
	global_load_lds_dwordx4 v132, s[26:27]
	s_add_i32 m0, s37, 0xe000
	s_nop 0
	global_load_lds_dwordx4 v134, s[26:27]
	s_waitcnt lgkmcnt(8)
	s_barrier
	s_waitcnt lgkmcnt(0)
	s_setprio 1
	s_waitcnt lgkmcnt(0)
	v_mfma_f32_16x16x32_bf16 v[124:127], v[140:143], v[180:183], v[124:127]
	v_mfma_f32_16x16x32_bf16 v[124:127], v[154:157], v[184:187], v[124:127]
	v_mfma_f32_16x16x32_bf16 v[120:123], v[176:179], v[184:187], v[120:123]
	v_mfma_f32_16x16x32_bf16 v[120:123], v[158:161], v[180:183], v[120:123]
	v_mfma_f32_16x16x32_bf16 v[104:107], v[158:161], v[188:191], v[104:107]
	v_mfma_f32_16x16x32_bf16 v[104:107], v[176:179], v[192:195], v[104:107]
	v_mfma_f32_16x16x32_bf16 v[108:111], v[154:157], v[192:195], v[108:111]
	v_mfma_f32_16x16x32_bf16 v[108:111], v[140:143], v[188:191], v[108:111]
	v_mfma_f32_16x16x32_bf16 v[92:95], v[140:143], v[196:199], v[92:95]
	v_mfma_f32_16x16x32_bf16 v[92:95], v[154:157], v[200:203], v[92:95]
	v_mfma_f32_16x16x32_bf16 v[88:91], v[176:179], v[200:203], v[88:91]
	v_mfma_f32_16x16x32_bf16 v[88:91], v[158:161], v[196:199], v[88:91]
	v_mfma_f32_16x16x32_bf16 v[72:75], v[158:161], v[204:207], v[72:75]
	v_mfma_f32_16x16x32_bf16 v[72:75], v[176:179], v[208:211], v[72:75]
	v_mfma_f32_16x16x32_bf16 v[76:79], v[154:157], v[208:211], v[76:79]
	v_mfma_f32_16x16x32_bf16 v[76:79], v[140:143], v[204:207], v[76:79]
	s_setprio 0
	s_barrier
	s_add_i32 s52, s46, s36
	s_add_u32 s98, s28, s16
	s_addc_u32 s99, s29, s17
	s_mov_b32 m0, s52
	ds_read_b128 v[212:215], v151
	ds_read_b128 v[240:243], v216
	ds_read_b128 v[244:247], v151 offset:2048
	ds_read_b128 v[248:251], v216 offset:2048
	global_load_lds_dwordx4 v164, s[28:29]
	s_add_i32 m0, s52, 0x2000
	s_nop 0
	global_load_lds_dwordx4 v166, s[28:29]
	s_barrier
	s_waitcnt lgkmcnt(0)
	s_setprio 1
	s_waitcnt lgkmcnt(0)
	v_mfma_f32_16x16x32_bf16 v[116:119], v[212:215], v[180:183], v[116:119]
	v_mfma_f32_16x16x32_bf16 v[116:119], v[240:243], v[184:187], v[116:119]
	v_mfma_f32_16x16x32_bf16 v[112:115], v[248:251], v[184:187], v[112:115]
	v_mfma_f32_16x16x32_bf16 v[112:115], v[244:247], v[180:183], v[112:115]
	v_mfma_f32_16x16x32_bf16 v[96:99], v[244:247], v[188:191], v[96:99]
	v_mfma_f32_16x16x32_bf16 v[96:99], v[248:251], v[192:195], v[96:99]
	v_mfma_f32_16x16x32_bf16 v[100:103], v[240:243], v[192:195], v[100:103]
	v_mfma_f32_16x16x32_bf16 v[100:103], v[212:215], v[188:191], v[100:103]
	v_mfma_f32_16x16x32_bf16 v[84:87], v[212:215], v[196:199], v[84:87]
	v_mfma_f32_16x16x32_bf16 v[84:87], v[240:243], v[200:203], v[84:87]
	v_mfma_f32_16x16x32_bf16 v[80:83], v[248:251], v[200:203], v[80:83]
	v_mfma_f32_16x16x32_bf16 v[80:83], v[244:247], v[196:199], v[80:83]
	v_mfma_f32_16x16x32_bf16 v[64:67], v[244:247], v[204:207], v[64:67]
	v_mfma_f32_16x16x32_bf16 v[64:67], v[248:251], v[208:211], v[64:67]
	v_mfma_f32_16x16x32_bf16 v[68:71], v[240:243], v[208:211], v[68:71]
	v_mfma_f32_16x16x32_bf16 v[68:71], v[212:215], v[204:207], v[68:71]
	s_setprio 0
	s_mov_b32 m0, s37
	s_add_u32 s100, s30, s16
	s_addc_u32 s101, s31, s17
	s_barrier
	ds_read_b128 v[180:183], v150 offset:16384
	ds_read_b128 v[184:187], v145 offset:16384
	ds_read_b128 v[188:191], v150 offset:18432
	ds_read_b128 v[192:195], v145 offset:18432
	ds_read_b128 v[196:199], v150 offset:20480
	ds_read_b128 v[200:203], v145 offset:20480
	ds_read_b128 v[204:207], v150 offset:22528
	ds_read_b128 v[208:211], v145 offset:22528
	global_load_lds_dwordx4 v128, s[30:31]
	s_mov_b32 m0, s38
	s_nop 0
	global_load_lds_dwordx4 v130, s[30:31]
	s_barrier
	s_waitcnt lgkmcnt(0)
	s_setprio 1
	s_waitcnt lgkmcnt(0)
	v_mfma_f32_16x16x32_bf16 v[60:63], v[140:143], v[180:183], v[60:63]
	v_mfma_f32_16x16x32_bf16 v[60:63], v[154:157], v[184:187], v[60:63]
	v_mfma_f32_16x16x32_bf16 v[56:59], v[176:179], v[184:187], v[56:59]
	v_mfma_f32_16x16x32_bf16 v[56:59], v[158:161], v[180:183], v[56:59]
	v_mfma_f32_16x16x32_bf16 v[40:43], v[158:161], v[188:191], v[40:43]
	v_mfma_f32_16x16x32_bf16 v[40:43], v[176:179], v[192:195], v[40:43]
	v_mfma_f32_16x16x32_bf16 v[44:47], v[154:157], v[192:195], v[44:47]
	v_mfma_f32_16x16x32_bf16 v[44:47], v[140:143], v[188:191], v[44:47]
	v_mfma_f32_16x16x32_bf16 v[28:31], v[140:143], v[196:199], v[28:31]
	v_mfma_f32_16x16x32_bf16 v[28:31], v[154:157], v[200:203], v[28:31]
	v_mfma_f32_16x16x32_bf16 v[24:27], v[176:179], v[200:203], v[24:27]
	v_mfma_f32_16x16x32_bf16 v[24:27], v[158:161], v[196:199], v[24:27]
	v_mfma_f32_16x16x32_bf16 v[8:11], v[158:161], v[204:207], v[8:11]
	v_mfma_f32_16x16x32_bf16 v[8:11], v[176:179], v[208:211], v[8:11]
	v_mfma_f32_16x16x32_bf16 v[12:15], v[154:157], v[208:211], v[12:15]
	v_mfma_f32_16x16x32_bf16 v[12:15], v[140:143], v[204:207], v[12:15]
	s_setprio 0
	s_barrier
	s_add_u32 s52, s28, 0x80000
	s_addc_u32 s53, s29, 0
	s_add_i32 s54, s47, s36
	s_mov_b32 m0, s54
	s_nop 0
	global_load_lds_dwordx4 v164, s[52:53]
	s_add_i32 m0, s54, 0x2000
	s_nop 0
	global_load_lds_dwordx4 v166, s[52:53]
	s_waitcnt vmcnt(6)
	s_barrier
	s_setprio 1
	v_mfma_f32_16x16x32_bf16 v[52:55], v[212:215], v[180:183], v[52:55]
	v_mfma_f32_16x16x32_bf16 v[52:55], v[240:243], v[184:187], v[52:55]
	v_mfma_f32_16x16x32_bf16 v[48:51], v[248:251], v[184:187], v[48:51]
	v_mfma_f32_16x16x32_bf16 v[48:51], v[244:247], v[180:183], v[48:51]
	v_mfma_f32_16x16x32_bf16 v[32:35], v[244:247], v[188:191], v[32:35]
	v_mfma_f32_16x16x32_bf16 v[32:35], v[248:251], v[192:195], v[32:35]
	v_mfma_f32_16x16x32_bf16 v[36:39], v[240:243], v[192:195], v[36:39]
	v_mfma_f32_16x16x32_bf16 v[36:39], v[212:215], v[188:191], v[36:39]
	v_mfma_f32_16x16x32_bf16 v[20:23], v[212:215], v[196:199], v[20:23]
	v_mfma_f32_16x16x32_bf16 v[20:23], v[240:243], v[200:203], v[20:23]
	v_mfma_f32_16x16x32_bf16 v[16:19], v[248:251], v[200:203], v[16:19]
	v_mfma_f32_16x16x32_bf16 v[16:19], v[244:247], v[196:199], v[16:19]
	v_mfma_f32_16x16x32_bf16 v[0:3], v[244:247], v[204:207], v[0:3]
	v_mfma_f32_16x16x32_bf16 v[0:3], v[248:251], v[208:211], v[0:3]
	v_mfma_f32_16x16x32_bf16 v[4:7], v[240:243], v[208:211], v[4:7]
	v_mfma_f32_16x16x32_bf16 v[4:7], v[212:215], v[204:207], v[4:7]
	s_setprio 0
	s_add_i32 s52, 0, 0x18000
	s_barrier
	ds_read_b128 v[140:143], v217
	ds_read_b128 v[154:157], v234
	ds_read_b128 v[158:161], v217 offset:2048
	ds_read_b128 v[176:179], v234 offset:2048
	s_add_u32 s30, s30, 0x80000
	s_addc_u32 s31, s31, 0
	s_mov_b32 m0, s39
	ds_read_b128 v[180:183], v150 offset:32768
	ds_read_b128 v[184:187], v145 offset:32768
	ds_read_b128 v[188:191], v150 offset:34816
	ds_read_b128 v[192:195], v145 offset:34816
	ds_read_b128 v[196:199], v150 offset:36864
	ds_read_b128 v[200:203], v145 offset:36864
	ds_read_b128 v[204:207], v150 offset:38912
	ds_read_b128 v[208:211], v145 offset:38912
	global_load_lds_dwordx4 v128, s[30:31]
	s_mov_b32 m0, s40
	s_nop 0
	global_load_lds_dwordx4 v130, s[30:31]
	s_waitcnt lgkmcnt(8)
	s_barrier
	s_waitcnt lgkmcnt(0)
	s_setprio 1
	s_waitcnt lgkmcnt(0)
	v_mfma_f32_16x16x32_bf16 v[124:127], v[140:143], v[180:183], v[124:127]
	v_mfma_f32_16x16x32_bf16 v[124:127], v[154:157], v[184:187], v[124:127]
	v_mfma_f32_16x16x32_bf16 v[120:123], v[176:179], v[184:187], v[120:123]
	v_mfma_f32_16x16x32_bf16 v[120:123], v[158:161], v[180:183], v[120:123]
	v_mfma_f32_16x16x32_bf16 v[104:107], v[158:161], v[188:191], v[104:107]
	v_mfma_f32_16x16x32_bf16 v[104:107], v[176:179], v[192:195], v[104:107]
	v_mfma_f32_16x16x32_bf16 v[108:111], v[154:157], v[192:195], v[108:111]
	v_mfma_f32_16x16x32_bf16 v[108:111], v[140:143], v[188:191], v[108:111]
	v_mfma_f32_16x16x32_bf16 v[92:95], v[140:143], v[196:199], v[92:95]
	v_mfma_f32_16x16x32_bf16 v[92:95], v[154:157], v[200:203], v[92:95]
	v_mfma_f32_16x16x32_bf16 v[88:91], v[176:179], v[200:203], v[88:91]
	v_mfma_f32_16x16x32_bf16 v[88:91], v[158:161], v[196:199], v[88:91]
	v_mfma_f32_16x16x32_bf16 v[72:75], v[158:161], v[204:207], v[72:75]
	v_mfma_f32_16x16x32_bf16 v[72:75], v[176:179], v[208:211], v[72:75]
	v_mfma_f32_16x16x32_bf16 v[76:79], v[154:157], v[208:211], v[76:79]
	v_mfma_f32_16x16x32_bf16 v[76:79], v[140:143], v[204:207], v[76:79]
	s_setprio 0
	s_barrier
	s_add_i32 s30, 0, 0x1c000
	s_add_i32 s31, s52, s36
	s_mov_b32 m0, s31
	ds_read_b128 v[212:215], v235
	ds_read_b128 v[240:243], v252
	ds_read_b128 v[244:247], v235 offset:2048
	ds_read_b128 v[248:251], v252 offset:2048
	global_load_lds_dwordx4 v164, s[98:99]
	s_add_i32 m0, s31, 0x2000
	s_nop 0
	global_load_lds_dwordx4 v166, s[98:99]
	s_barrier
	s_waitcnt lgkmcnt(0)
	s_setprio 1
	s_waitcnt lgkmcnt(0)
	v_mfma_f32_16x16x32_bf16 v[116:119], v[212:215], v[180:183], v[116:119]
	v_mfma_f32_16x16x32_bf16 v[116:119], v[240:243], v[184:187], v[116:119]
	v_mfma_f32_16x16x32_bf16 v[112:115], v[248:251], v[184:187], v[112:115]
	v_mfma_f32_16x16x32_bf16 v[112:115], v[244:247], v[180:183], v[112:115]
	v_mfma_f32_16x16x32_bf16 v[96:99], v[244:247], v[188:191], v[96:99]
	v_mfma_f32_16x16x32_bf16 v[96:99], v[248:251], v[192:195], v[96:99]
	v_mfma_f32_16x16x32_bf16 v[100:103], v[240:243], v[192:195], v[100:103]
	v_mfma_f32_16x16x32_bf16 v[100:103], v[212:215], v[188:191], v[100:103]
	v_mfma_f32_16x16x32_bf16 v[84:87], v[212:215], v[196:199], v[84:87]
	v_mfma_f32_16x16x32_bf16 v[84:87], v[240:243], v[200:203], v[84:87]
	v_mfma_f32_16x16x32_bf16 v[80:83], v[248:251], v[200:203], v[80:83]
	v_mfma_f32_16x16x32_bf16 v[80:83], v[244:247], v[196:199], v[80:83]
	v_mfma_f32_16x16x32_bf16 v[64:67], v[244:247], v[204:207], v[64:67]
	v_mfma_f32_16x16x32_bf16 v[64:67], v[248:251], v[208:211], v[64:67]
	v_mfma_f32_16x16x32_bf16 v[68:71], v[240:243], v[208:211], v[68:71]
	v_mfma_f32_16x16x32_bf16 v[68:71], v[212:215], v[204:207], v[68:71]
	s_setprio 0
	s_mov_b32 m0, s42
	s_barrier
	ds_read_b128 v[180:183], v150 offset:49152
	ds_read_b128 v[184:187], v145 offset:49152
	ds_read_b128 v[188:191], v150 offset:51200
	ds_read_b128 v[192:195], v145 offset:51200
	ds_read_b128 v[196:199], v150 offset:53248
	ds_read_b128 v[200:203], v145 offset:53248
	ds_read_b128 v[204:207], v150 offset:55296
	ds_read_b128 v[208:211], v145 offset:55296
	global_load_lds_dwordx4 v128, s[100:101]
	s_mov_b32 m0, s43
	s_nop 0
	global_load_lds_dwordx4 v130, s[100:101]
	s_barrier
	s_waitcnt lgkmcnt(0)
	s_setprio 1
	s_waitcnt lgkmcnt(0)
	v_mfma_f32_16x16x32_bf16 v[60:63], v[140:143], v[180:183], v[60:63]
	v_mfma_f32_16x16x32_bf16 v[60:63], v[154:157], v[184:187], v[60:63]
	v_mfma_f32_16x16x32_bf16 v[56:59], v[176:179], v[184:187], v[56:59]
	v_mfma_f32_16x16x32_bf16 v[56:59], v[158:161], v[180:183], v[56:59]
	v_mfma_f32_16x16x32_bf16 v[40:43], v[158:161], v[188:191], v[40:43]
	v_mfma_f32_16x16x32_bf16 v[40:43], v[176:179], v[192:195], v[40:43]
	v_mfma_f32_16x16x32_bf16 v[44:47], v[154:157], v[192:195], v[44:47]
	v_mfma_f32_16x16x32_bf16 v[44:47], v[140:143], v[188:191], v[44:47]
	v_mfma_f32_16x16x32_bf16 v[28:31], v[140:143], v[196:199], v[28:31]
	v_mfma_f32_16x16x32_bf16 v[28:31], v[154:157], v[200:203], v[28:31]
	v_mfma_f32_16x16x32_bf16 v[24:27], v[176:179], v[200:203], v[24:27]
	v_mfma_f32_16x16x32_bf16 v[24:27], v[158:161], v[196:199], v[24:27]
	v_mfma_f32_16x16x32_bf16 v[8:11], v[158:161], v[204:207], v[8:11]
	v_mfma_f32_16x16x32_bf16 v[8:11], v[176:179], v[208:211], v[8:11]
	v_mfma_f32_16x16x32_bf16 v[12:15], v[154:157], v[208:211], v[12:15]
	v_mfma_f32_16x16x32_bf16 v[12:15], v[140:143], v[204:207], v[12:15]
	s_setprio 0
	s_barrier
	s_add_u32 s28, s28, 0x80080
	s_addc_u32 s29, s29, 0
	s_add_i32 s30, s30, s36
	s_mov_b32 m0, s30
	s_nop 0
	global_load_lds_dwordx4 v164, s[28:29]
	s_add_i32 m0, s30, 0x2000
	s_nop 0
	global_load_lds_dwordx4 v166, s[28:29]
	s_waitcnt vmcnt(6)
	s_barrier
	s_setprio 1
	v_mfma_f32_16x16x32_bf16 v[52:55], v[212:215], v[180:183], v[52:55]
	v_mfma_f32_16x16x32_bf16 v[52:55], v[240:243], v[184:187], v[52:55]
	v_mfma_f32_16x16x32_bf16 v[48:51], v[248:251], v[184:187], v[48:51]
	v_mfma_f32_16x16x32_bf16 v[48:51], v[244:247], v[180:183], v[48:51]
	v_mfma_f32_16x16x32_bf16 v[32:35], v[244:247], v[188:191], v[32:35]
	v_mfma_f32_16x16x32_bf16 v[32:35], v[248:251], v[192:195], v[32:35]
	v_mfma_f32_16x16x32_bf16 v[36:39], v[240:243], v[192:195], v[36:39]
	v_mfma_f32_16x16x32_bf16 v[36:39], v[212:215], v[188:191], v[36:39]
	v_mfma_f32_16x16x32_bf16 v[20:23], v[212:215], v[196:199], v[20:23]
	v_mfma_f32_16x16x32_bf16 v[20:23], v[240:243], v[200:203], v[20:23]
	v_mfma_f32_16x16x32_bf16 v[16:19], v[248:251], v[200:203], v[16:19]
	v_mfma_f32_16x16x32_bf16 v[16:19], v[244:247], v[196:199], v[16:19]
	v_mfma_f32_16x16x32_bf16 v[0:3], v[244:247], v[204:207], v[0:3]
	v_mfma_f32_16x16x32_bf16 v[0:3], v[248:251], v[208:211], v[0:3]
	v_mfma_f32_16x16x32_bf16 v[4:7], v[240:243], v[208:211], v[4:7]
	v_mfma_f32_16x16x32_bf16 v[4:7], v[212:215], v[204:207], v[4:7]
	s_setprio 0
	s_add_i32 s49, s49, 2
	s_add_u32 s26, s26, 0x100
	s_addc_u32 s27, s27, 0
	s_add_u32 s33, s33, 0x100
	s_addc_u32 s48, s48, 0
	s_cmp_gt_u32 s49, 29
	s_barrier
	s_cbranch_scc0 .LBB0_599
	v_lshl_add_u32 v143, s12, 8, v146
	v_lshlrev_b32_e32 v145, 2, v143
	global_load_dword v154, v145, s[14:15]
	global_load_dword v155, v145, s[14:15] offset:64
	global_load_dword v156, v145, s[14:15] offset:128
	global_load_dword v157, v145, s[14:15] offset:192
	global_load_dword v158, v145, s[14:15] offset:512
	global_load_dword v159, v145, s[14:15] offset:576
	global_load_dword v160, v145, s[14:15] offset:640
	global_load_dword v161, v145, s[14:15] offset:704
	v_lshlrev_b32_e32 v141, 13, v143
	v_lshl_or_b32 v143, s0, 8, v148
	v_lshl_add_u32 v141, v143, 1, v141
	v_xor_b32_e32 v169, 16, v153
	v_lshlrev_b32_e32 v169, 2, v169
	v_xor_b32_e32 v171, 32, v153
	v_lshlrev_b32_e32 v171, 2, v171
	v_mov_b32_e32 v140, 0xbdd2d3e8
	v_mov_b32_e32 v142, 0xc0135761
	v_mov_b32_e32 v144, 1.0
	s_waitcnt vmcnt(0)
	v_fmamk_f32 v154, v154, 0x3a000000, v152
	v_fmamk_f32 v155, v155, 0x3a000000, v152
	v_fmamk_f32 v156, v156, 0x3a000000, v152
	v_fmamk_f32 v157, v157, 0x3a000000, v152
	v_fmamk_f32 v158, v158, 0x3a000000, v152
	v_fmamk_f32 v159, v159, 0x3a000000, v152
	v_fmamk_f32 v160, v160, 0x3a000000, v152
	v_fmamk_f32 v161, v161, 0x3a000000, v152
	v_rsq_f32_e32 v154, v154
	v_rsq_f32_e32 v155, v155
	v_rsq_f32_e32 v156, v156
	v_rsq_f32_e32 v157, v157
	v_rsq_f32_e32 v158, v158
	v_rsq_f32_e32 v159, v159
	v_rsq_f32_e32 v160, v160
	v_rsq_f32_e32 v161, v161
	v_pk_mul_f32 v[124:125], v[124:125], v[154:155] op_sel:[0,0] op_sel_hi:[1,0]
	v_pk_mul_f32 v[126:127], v[126:127], v[154:155] op_sel:[0,0] op_sel_hi:[1,0]
	v_pk_mul_f32 v[120:121], v[120:121], v[154:155] op_sel:[0,0] op_sel_hi:[1,0]
	v_pk_mul_f32 v[122:123], v[122:123], v[154:155] op_sel:[0,0] op_sel_hi:[1,0]
	v_pk_mul_f32 v[176:177], v[124:125], v[124:125]
	v_pk_mul_f32 v[178:179], v[126:127], v[126:127]
	v_pk_mul_f32 v[180:181], v[120:121], v[120:121]
	v_pk_mul_f32 v[182:183], v[122:123], v[122:123]
	v_pk_fma_f32 v[176:177], v[176:177], v[140:141], v[142:143] op_sel_hi:[1,0,0]
	v_pk_fma_f32 v[178:179], v[178:179], v[140:141], v[142:143] op_sel_hi:[1,0,0]
	v_pk_fma_f32 v[180:181], v[180:181], v[140:141], v[142:143] op_sel_hi:[1,0,0]
	v_pk_fma_f32 v[182:183], v[182:183], v[140:141], v[142:143] op_sel_hi:[1,0,0]
	v_pk_mul_f32 v[176:177], v[124:125], v[176:177]
	v_pk_mul_f32 v[178:179], v[126:127], v[178:179]
	v_pk_mul_f32 v[180:181], v[120:121], v[180:181]
	v_pk_mul_f32 v[182:183], v[122:123], v[182:183]
	v_exp_f32_e32 v176, v176
	v_exp_f32_e32 v177, v177
	v_exp_f32_e32 v178, v178
	v_exp_f32_e32 v179, v179
	v_exp_f32_e32 v180, v180
	v_exp_f32_e32 v181, v181
	v_exp_f32_e32 v182, v182
	v_exp_f32_e32 v183, v183
	v_pk_add_f32 v[176:177], v[176:177], v[144:145] op_sel_hi:[1,0]
	v_pk_add_f32 v[178:179], v[178:179], v[144:145] op_sel_hi:[1,0]
	v_pk_add_f32 v[180:181], v[180:181], v[144:145] op_sel_hi:[1,0]
	v_pk_add_f32 v[182:183], v[182:183], v[144:145] op_sel_hi:[1,0]
	v_rcp_f32_e32 v176, v176
	v_rcp_f32_e32 v177, v177
	v_rcp_f32_e32 v178, v178
	v_rcp_f32_e32 v179, v179
	v_rcp_f32_e32 v180, v180
	v_rcp_f32_e32 v181, v181
	v_rcp_f32_e32 v182, v182
	v_rcp_f32_e32 v183, v183
	v_pk_mul_f32 v[124:125], v[124:125], v[176:177]
	v_pk_mul_f32 v[126:127], v[126:127], v[178:179]
	v_pk_mul_f32 v[120:121], v[120:121], v[180:181]
	v_pk_mul_f32 v[122:123], v[122:123], v[182:183]
	v_pk_mul_f32 v[184:185], v[124:125], v[124:125]
	v_pk_fma_f32 v[184:185], v[126:127], v[126:127], v[184:185]
	v_pk_fma_f32 v[184:185], v[120:121], v[120:121], v[184:185]
	v_pk_fma_f32 v[184:185], v[122:123], v[122:123], v[184:185]
	v_cvt_pk_bf16_f32 v124, v124, v125
	v_cvt_pk_bf16_f32 v125, v126, v127
	v_cvt_pk_bf16_f32 v126, v120, v121
	v_cvt_pk_bf16_f32 v127, v122, v123
	global_store_dwordx4 v141, v[124:127], s[96:97]
	v_pk_mul_f32 v[116:117], v[116:117], v[154:155] op_sel:[0,0] op_sel_hi:[1,0]
	v_pk_mul_f32 v[118:119], v[118:119], v[154:155] op_sel:[0,0] op_sel_hi:[1,0]
	v_pk_mul_f32 v[112:113], v[112:113], v[154:155] op_sel:[0,0] op_sel_hi:[1,0]
	v_pk_mul_f32 v[114:115], v[114:115], v[154:155] op_sel:[0,0] op_sel_hi:[1,0]
	v_pk_mul_f32 v[176:177], v[116:117], v[116:117]
	v_pk_mul_f32 v[178:179], v[118:119], v[118:119]
	v_pk_mul_f32 v[180:181], v[112:113], v[112:113]
	v_pk_mul_f32 v[182:183], v[114:115], v[114:115]
	v_pk_fma_f32 v[176:177], v[176:177], v[140:141], v[142:143] op_sel_hi:[1,0,0]
	v_pk_fma_f32 v[178:179], v[178:179], v[140:141], v[142:143] op_sel_hi:[1,0,0]
	v_pk_fma_f32 v[180:181], v[180:181], v[140:141], v[142:143] op_sel_hi:[1,0,0]
	v_pk_fma_f32 v[182:183], v[182:183], v[140:141], v[142:143] op_sel_hi:[1,0,0]
	v_pk_mul_f32 v[176:177], v[116:117], v[176:177]
	v_pk_mul_f32 v[178:179], v[118:119], v[178:179]
	v_pk_mul_f32 v[180:181], v[112:113], v[180:181]
	v_pk_mul_f32 v[182:183], v[114:115], v[182:183]
	v_exp_f32_e32 v176, v176
	v_exp_f32_e32 v177, v177
	v_exp_f32_e32 v178, v178
	v_exp_f32_e32 v179, v179
	v_exp_f32_e32 v180, v180
	v_exp_f32_e32 v181, v181
	v_exp_f32_e32 v182, v182
	v_exp_f32_e32 v183, v183
	v_pk_add_f32 v[176:177], v[176:177], v[144:145] op_sel_hi:[1,0]
	v_pk_add_f32 v[178:179], v[178:179], v[144:145] op_sel_hi:[1,0]
	v_pk_add_f32 v[180:181], v[180:181], v[144:145] op_sel_hi:[1,0]
	v_pk_add_f32 v[182:183], v[182:183], v[144:145] op_sel_hi:[1,0]
	v_rcp_f32_e32 v176, v176
	v_rcp_f32_e32 v177, v177
	v_rcp_f32_e32 v178, v178
	v_rcp_f32_e32 v179, v179
	v_rcp_f32_e32 v180, v180
	v_rcp_f32_e32 v181, v181
	v_rcp_f32_e32 v182, v182
	v_rcp_f32_e32 v183, v183
	v_pk_mul_f32 v[116:117], v[116:117], v[176:177]
	v_pk_mul_f32 v[118:119], v[118:119], v[178:179]
	v_pk_mul_f32 v[112:113], v[112:113], v[180:181]
	v_pk_mul_f32 v[114:115], v[114:115], v[182:183]
	v_pk_fma_f32 v[184:185], v[116:117], v[116:117], v[184:185]
	v_pk_fma_f32 v[184:185], v[118:119], v[118:119], v[184:185]
	v_pk_fma_f32 v[184:185], v[112:113], v[112:113], v[184:185]
	v_pk_fma_f32 v[184:185], v[114:115], v[114:115], v[184:185]
	v_cvt_pk_bf16_f32 v116, v116, v117
	v_cvt_pk_bf16_f32 v117, v118, v119
	v_cvt_pk_bf16_f32 v118, v112, v113
	v_cvt_pk_bf16_f32 v119, v114, v115
	global_store_dwordx4 v141, v[116:119], s[96:97] offset:256
	s_cmp_lt_i32 s0, 8
	s_cbranch_scc1 .Le2_skip0
	v_add_f32_e32 v184, v184, v185
	ds_bpermute_b32 v173, v169, v184
	s_waitcnt lgkmcnt(0)
	v_add_f32_e32 v184, v184, v173
	ds_bpermute_b32 v173, v171, v184
	s_waitcnt lgkmcnt(0)
	v_add_f32_e32 v184, v184, v173
	s_mov_b64 exec, s[8:9]
	global_atomic_add_f32 v145, v184, s[4:5]
	s_mov_b64 exec, -1

.LBB0_759:
	s_ashr_i32 s15, s14, 31
	v_cmp_lt_i64_e32 vcc, s[16:17], v[136:137]
	s_lshl_b64 s[16:17], s[14:15], 21
	s_add_u32 s16, s96, s16
	s_addc_u32 s17, s97, s17
	s_and_b64 s[18:19], vcc, exec
	s_cselect_b32 s1, s17, s21
	s_cselect_b32 s9, s16, s20
	s_ashr_i32 s13, s12, 31
	s_lshl_b64 s[18:19], s[12:13], 20
	s_add_u32 s18, s26, s18
	s_addc_u32 s19, s27, s19
	s_and_b64 s[24:25], vcc, exec
	s_cselect_b32 s13, s19, s23
	s_cselect_b32 s15, s18, s22
	s_add_u32 s20, s20, 0x100080
	s_addc_u32 s21, s21, 0
	s_add_u32 s43, s22, 0x100
	v_mov_b32_e32 v0, 0
	s_addc_u32 s44, s23, 0
	s_mov_b32 s45, -2
	s_waitcnt lgkmcnt(0)
	v_mov_b32_e32 v1, v0
	v_mov_b32_e32 v2, v0
	v_mov_b32_e32 v3, v0
	v_mov_b32_e32 v4, v0
	v_mov_b32_e32 v5, v0
	v_mov_b32_e32 v6, v0
	v_mov_b32_e32 v7, v0
	s_waitcnt vmcnt(0)
	v_mov_b32_e32 v16, v0
	v_mov_b32_e32 v17, v0
	v_mov_b32_e32 v18, v0
	v_mov_b32_e32 v19, v0
	v_mov_b32_e32 v20, v0
	v_mov_b32_e32 v21, v0
	v_mov_b32_e32 v22, v0
	v_mov_b32_e32 v23, v0
	v_mov_b32_e32 v32, v0
	v_mov_b32_e32 v33, v0
	v_mov_b32_e32 v34, v0
	v_mov_b32_e32 v35, v0
	v_mov_b32_e32 v36, v0
	v_mov_b32_e32 v37, v0
	v_mov_b32_e32 v38, v0
	v_mov_b32_e32 v39, v0
	v_mov_b32_e32 v48, v0
	v_mov_b32_e32 v49, v0
	v_mov_b32_e32 v50, v0
	v_mov_b32_e32 v51, v0
	v_mov_b32_e32 v52, v0
	v_mov_b32_e32 v53, v0
	v_mov_b32_e32 v54, v0
	v_mov_b32_e32 v55, v0
	v_mov_b32_e32 v8, v0
	v_mov_b32_e32 v9, v0
	v_mov_b32_e32 v10, v0
	v_mov_b32_e32 v11, v0
	v_mov_b32_e32 v12, v0
	v_mov_b32_e32 v13, v0
	v_mov_b32_e32 v14, v0
	v_mov_b32_e32 v15, v0
	v_mov_b32_e32 v24, v0
	v_mov_b32_e32 v25, v0
	v_mov_b32_e32 v26, v0
	v_mov_b32_e32 v27, v0
	v_mov_b32_e32 v28, v0
	v_mov_b32_e32 v29, v0
	v_mov_b32_e32 v30, v0
	v_mov_b32_e32 v31, v0
	v_mov_b32_e32 v40, v0
	v_mov_b32_e32 v41, v0
	v_mov_b32_e32 v42, v0
	v_mov_b32_e32 v43, v0
	v_mov_b32_e32 v44, v0
	v_mov_b32_e32 v45, v0
	v_mov_b32_e32 v46, v0
	v_mov_b32_e32 v47, v0
	v_mov_b32_e32 v56, v0
	v_mov_b32_e32 v57, v0
	v_mov_b32_e32 v58, v0
	v_mov_b32_e32 v59, v0
	v_mov_b32_e32 v60, v0
	v_mov_b32_e32 v61, v0
	v_mov_b32_e32 v62, v0
	v_mov_b32_e32 v63, v0
	v_mov_b32_e32 v64, v0
	v_mov_b32_e32 v65, v0
	v_mov_b32_e32 v66, v0
	v_mov_b32_e32 v67, v0
	v_mov_b32_e32 v68, v0
	v_mov_b32_e32 v69, v0
	v_mov_b32_e32 v70, v0
	v_mov_b32_e32 v71, v0
	v_mov_b32_e32 v80, v0
	v_mov_b32_e32 v81, v0
	v_mov_b32_e32 v82, v0
	v_mov_b32_e32 v83, v0
	v_mov_b32_e32 v84, v0
	v_mov_b32_e32 v85, v0
	v_mov_b32_e32 v86, v0
	v_mov_b32_e32 v87, v0
	v_mov_b32_e32 v96, v0
	v_mov_b32_e32 v97, v0
	v_mov_b32_e32 v98, v0
	v_mov_b32_e32 v99, v0
	v_mov_b32_e32 v100, v0
	v_mov_b32_e32 v101, v0
	v_mov_b32_e32 v102, v0
	v_mov_b32_e32 v103, v0
	v_mov_b32_e32 v112, v0
	v_mov_b32_e32 v113, v0
	v_mov_b32_e32 v114, v0
	v_mov_b32_e32 v115, v0
	v_mov_b32_e32 v116, v0
	v_mov_b32_e32 v117, v0
	v_mov_b32_e32 v118, v0
	v_mov_b32_e32 v119, v0
	v_mov_b32_e32 v72, v0
	v_mov_b32_e32 v73, v0
	v_mov_b32_e32 v74, v0
	v_mov_b32_e32 v75, v0
	v_mov_b32_e32 v76, v0
	v_mov_b32_e32 v77, v0
	v_mov_b32_e32 v78, v0
	v_mov_b32_e32 v79, v0
	v_mov_b32_e32 v88, v0
	v_mov_b32_e32 v89, v0
	v_mov_b32_e32 v90, v0
	v_mov_b32_e32 v91, v0
	v_mov_b32_e32 v92, v0
	v_mov_b32_e32 v93, v0
	v_mov_b32_e32 v94, v0
	v_mov_b32_e32 v95, v0
	v_mov_b32_e32 v104, v0
	v_mov_b32_e32 v105, v0
	v_mov_b32_e32 v106, v0
	v_mov_b32_e32 v107, v0
	v_mov_b32_e32 v108, v0
	v_mov_b32_e32 v109, v0
	v_mov_b32_e32 v110, v0
	v_mov_b32_e32 v111, v0
	v_mov_b32_e32 v120, v0
	v_mov_b32_e32 v121, v0
	v_mov_b32_e32 v122, v0
	v_mov_b32_e32 v123, v0
	v_mov_b32_e32 v124, v0
	v_mov_b32_e32 v125, v0
	v_mov_b32_e32 v126, v0
	v_mov_b32_e32 v127, v0
	v_xor_b32_e32 v216, 64, v145
	v_xor_b32_e32 v217, 64, v146
	v_xor_b32_e32 v234, 64, v147
	v_add_u32_e32 v235, 0x18000, v144
	v_xor_b32_e32 v244, 64, v235
.LBB0_760:
	ds_read_b128 v[140:143], v145
	ds_read_b128 v[150:153], v216
	ds_read_b128 v[154:157], v145 offset:2048
	ds_read_b128 v[158:161], v216 offset:2048
	s_add_u32 s22, s20, 0xfff00080
	s_addc_u32 s23, s21, -1
	s_cmp_eq_u32 s45, 28
	s_cselect_b32 s25, s1, s23
	s_cselect_b32 s24, s9, s22
	s_cselect_b32 s23, s13, s44
	s_cselect_b32 s22, s15, s43
	s_add_i32 m0, s29, 0xc000
	ds_read_b128 v[176:179], v146
	ds_read_b128 v[180:183], v217
	ds_read_b128 v[184:187], v146 offset:2048
	ds_read_b128 v[188:191], v217 offset:2048
	ds_read_b128 v[192:195], v146 offset:4096
	ds_read_b128 v[196:199], v217 offset:4096
	ds_read_b128 v[200:203], v146 offset:6144
	ds_read_b128 v[204:207], v217 offset:6144
	global_load_lds_dwordx4 v132, s[20:21]
	s_add_i32 m0, s29, 0xe000
	s_nop 0
	global_load_lds_dwordx4 v134, s[20:21]
	s_waitcnt lgkmcnt(8)
	s_barrier
	s_waitcnt lgkmcnt(0)
	s_setprio 1
	s_waitcnt lgkmcnt(0)
	v_mfma_f32_16x16x32_bf16 v[124:127], v[140:143], v[176:179], v[124:127]
	v_mfma_f32_16x16x32_bf16 v[124:127], v[150:153], v[180:183], v[124:127]
	v_mfma_f32_16x16x32_bf16 v[120:123], v[158:161], v[180:183], v[120:123]
	v_mfma_f32_16x16x32_bf16 v[120:123], v[154:157], v[176:179], v[120:123]
	v_mfma_f32_16x16x32_bf16 v[104:107], v[154:157], v[184:187], v[104:107]
	v_mfma_f32_16x16x32_bf16 v[104:107], v[158:161], v[188:191], v[104:107]
	v_mfma_f32_16x16x32_bf16 v[108:111], v[150:153], v[188:191], v[108:111]
	v_mfma_f32_16x16x32_bf16 v[108:111], v[140:143], v[184:187], v[108:111]
	v_mfma_f32_16x16x32_bf16 v[92:95], v[140:143], v[192:195], v[92:95]
	v_mfma_f32_16x16x32_bf16 v[92:95], v[150:153], v[196:199], v[92:95]
	v_mfma_f32_16x16x32_bf16 v[88:91], v[158:161], v[196:199], v[88:91]
	v_mfma_f32_16x16x32_bf16 v[88:91], v[154:157], v[192:195], v[88:91]
	v_mfma_f32_16x16x32_bf16 v[72:75], v[154:157], v[200:203], v[72:75]
	v_mfma_f32_16x16x32_bf16 v[72:75], v[158:161], v[204:207], v[72:75]
	v_mfma_f32_16x16x32_bf16 v[76:79], v[150:153], v[204:207], v[76:79]
	v_mfma_f32_16x16x32_bf16 v[76:79], v[140:143], v[200:203], v[76:79]
	s_setprio 0
	s_barrier
	s_add_i32 s46, s41, s28
	s_add_u32 s98, s22, s10
	s_addc_u32 s99, s23, s11
	s_mov_b32 m0, s46
	ds_read_b128 v[208:211], v147
	ds_read_b128 v[212:215], v234
	ds_read_b128 v[236:239], v147 offset:2048
	ds_read_b128 v[240:243], v234 offset:2048
	global_load_lds_dwordx4 v164, s[22:23]
	s_add_i32 m0, s46, 0x2000
	s_nop 0
	global_load_lds_dwordx4 v166, s[22:23]
	s_barrier
	s_waitcnt lgkmcnt(0)
	s_setprio 1
	s_waitcnt lgkmcnt(0)
	v_mfma_f32_16x16x32_bf16 v[116:119], v[208:211], v[176:179], v[116:119]
	v_mfma_f32_16x16x32_bf16 v[116:119], v[212:215], v[180:183], v[116:119]
	v_mfma_f32_16x16x32_bf16 v[112:115], v[240:243], v[180:183], v[112:115]
	v_mfma_f32_16x16x32_bf16 v[112:115], v[236:239], v[176:179], v[112:115]
	v_mfma_f32_16x16x32_bf16 v[96:99], v[236:239], v[184:187], v[96:99]
	v_mfma_f32_16x16x32_bf16 v[96:99], v[240:243], v[188:191], v[96:99]
	v_mfma_f32_16x16x32_bf16 v[100:103], v[212:215], v[188:191], v[100:103]
	v_mfma_f32_16x16x32_bf16 v[100:103], v[208:211], v[184:187], v[100:103]
	v_mfma_f32_16x16x32_bf16 v[84:87], v[208:211], v[192:195], v[84:87]
	v_mfma_f32_16x16x32_bf16 v[84:87], v[212:215], v[196:199], v[84:87]
	v_mfma_f32_16x16x32_bf16 v[80:83], v[240:243], v[196:199], v[80:83]
	v_mfma_f32_16x16x32_bf16 v[80:83], v[236:239], v[192:195], v[80:83]
	v_mfma_f32_16x16x32_bf16 v[64:67], v[236:239], v[200:203], v[64:67]
	v_mfma_f32_16x16x32_bf16 v[64:67], v[240:243], v[204:207], v[64:67]
	v_mfma_f32_16x16x32_bf16 v[68:71], v[212:215], v[204:207], v[68:71]
	v_mfma_f32_16x16x32_bf16 v[68:71], v[208:211], v[200:203], v[68:71]
	s_setprio 0
	s_mov_b32 m0, s29
	s_add_u32 s100, s24, s10
	s_addc_u32 s101, s25, s11
	s_barrier
	ds_read_b128 v[176:179], v146 offset:16384
	ds_read_b128 v[180:183], v217 offset:16384
	ds_read_b128 v[184:187], v146 offset:18432
	ds_read_b128 v[188:191], v217 offset:18432
	ds_read_b128 v[192:195], v146 offset:20480
	ds_read_b128 v[196:199], v217 offset:20480
	ds_read_b128 v[200:203], v146 offset:22528
	ds_read_b128 v[204:207], v217 offset:22528
	global_load_lds_dwordx4 v128, s[24:25]
	s_mov_b32 m0, s30
	s_nop 0
	global_load_lds_dwordx4 v130, s[24:25]
	s_barrier
	s_waitcnt lgkmcnt(0)
	s_setprio 1
	s_waitcnt lgkmcnt(0)
	v_mfma_f32_16x16x32_bf16 v[60:63], v[140:143], v[176:179], v[60:63]
	v_mfma_f32_16x16x32_bf16 v[60:63], v[150:153], v[180:183], v[60:63]
	v_mfma_f32_16x16x32_bf16 v[56:59], v[158:161], v[180:183], v[56:59]
	v_mfma_f32_16x16x32_bf16 v[56:59], v[154:157], v[176:179], v[56:59]
	v_mfma_f32_16x16x32_bf16 v[40:43], v[154:157], v[184:187], v[40:43]
	v_mfma_f32_16x16x32_bf16 v[40:43], v[158:161], v[188:191], v[40:43]
	v_mfma_f32_16x16x32_bf16 v[44:47], v[150:153], v[188:191], v[44:47]
	v_mfma_f32_16x16x32_bf16 v[44:47], v[140:143], v[184:187], v[44:47]
	v_mfma_f32_16x16x32_bf16 v[28:31], v[140:143], v[192:195], v[28:31]
	v_mfma_f32_16x16x32_bf16 v[28:31], v[150:153], v[196:199], v[28:31]
	v_mfma_f32_16x16x32_bf16 v[24:27], v[158:161], v[196:199], v[24:27]
	v_mfma_f32_16x16x32_bf16 v[24:27], v[154:157], v[192:195], v[24:27]
	v_mfma_f32_16x16x32_bf16 v[8:11], v[154:157], v[200:203], v[8:11]
	v_mfma_f32_16x16x32_bf16 v[8:11], v[158:161], v[204:207], v[8:11]
	v_mfma_f32_16x16x32_bf16 v[12:15], v[150:153], v[204:207], v[12:15]
	v_mfma_f32_16x16x32_bf16 v[12:15], v[140:143], v[200:203], v[12:15]
	s_setprio 0
	s_barrier
	s_add_u32 s46, s22, 0x80000
	s_addc_u32 s47, s23, 0
	s_add_i32 s48, s42, s28
	s_mov_b32 m0, s48
	s_nop 0
	global_load_lds_dwordx4 v164, s[46:47]
	s_add_i32 m0, s48, 0x2000
	s_nop 0
	global_load_lds_dwordx4 v166, s[46:47]
	s_waitcnt vmcnt(6)
	s_barrier
	s_setprio 1
	v_mfma_f32_16x16x32_bf16 v[52:55], v[208:211], v[176:179], v[52:55]
	v_mfma_f32_16x16x32_bf16 v[52:55], v[212:215], v[180:183], v[52:55]
	v_mfma_f32_16x16x32_bf16 v[48:51], v[240:243], v[180:183], v[48:51]
	v_mfma_f32_16x16x32_bf16 v[48:51], v[236:239], v[176:179], v[48:51]
	v_mfma_f32_16x16x32_bf16 v[32:35], v[236:239], v[184:187], v[32:35]
	v_mfma_f32_16x16x32_bf16 v[32:35], v[240:243], v[188:191], v[32:35]
	v_mfma_f32_16x16x32_bf16 v[36:39], v[212:215], v[188:191], v[36:39]
	v_mfma_f32_16x16x32_bf16 v[36:39], v[208:211], v[184:187], v[36:39]
	v_mfma_f32_16x16x32_bf16 v[20:23], v[208:211], v[192:195], v[20:23]
	v_mfma_f32_16x16x32_bf16 v[20:23], v[212:215], v[196:199], v[20:23]
	v_mfma_f32_16x16x32_bf16 v[16:19], v[240:243], v[196:199], v[16:19]
	v_mfma_f32_16x16x32_bf16 v[16:19], v[236:239], v[192:195], v[16:19]
	v_mfma_f32_16x16x32_bf16 v[0:3], v[236:239], v[200:203], v[0:3]
	v_mfma_f32_16x16x32_bf16 v[0:3], v[240:243], v[204:207], v[0:3]
	v_mfma_f32_16x16x32_bf16 v[4:7], v[212:215], v[204:207], v[4:7]
	v_mfma_f32_16x16x32_bf16 v[4:7], v[208:211], v[200:203], v[4:7]
	s_setprio 0
	s_add_i32 s46, 0, 0x18000
	s_barrier
	ds_read_b128 v[140:143], v235
	ds_read_b128 v[150:153], v244
	ds_read_b128 v[154:157], v235 offset:2048
	ds_read_b128 v[158:161], v244 offset:2048
	s_add_u32 s24, s24, 0x100000
	s_addc_u32 s25, s25, 0
	s_mov_b32 m0, s31
	ds_read_b128 v[176:179], v146 offset:32768
	ds_read_b128 v[180:183], v217 offset:32768
	ds_read_b128 v[184:187], v146 offset:34816
	ds_read_b128 v[188:191], v217 offset:34816
	ds_read_b128 v[192:195], v146 offset:36864
	ds_read_b128 v[196:199], v217 offset:36864
	ds_read_b128 v[200:203], v146 offset:38912
	ds_read_b128 v[204:207], v217 offset:38912
	global_load_lds_dwordx4 v128, s[24:25]
	s_mov_b32 m0, s33
	s_nop 0
	global_load_lds_dwordx4 v130, s[24:25]
	s_waitcnt lgkmcnt(8)
	s_barrier
	s_waitcnt lgkmcnt(0)
	s_setprio 1
	s_waitcnt lgkmcnt(0)
	v_mfma_f32_16x16x32_bf16 v[124:127], v[140:143], v[176:179], v[124:127]
	v_mfma_f32_16x16x32_bf16 v[124:127], v[150:153], v[180:183], v[124:127]
	v_mfma_f32_16x16x32_bf16 v[120:123], v[158:161], v[180:183], v[120:123]
	v_mfma_f32_16x16x32_bf16 v[120:123], v[154:157], v[176:179], v[120:123]
	v_mfma_f32_16x16x32_bf16 v[104:107], v[154:157], v[184:187], v[104:107]
	v_mfma_f32_16x16x32_bf16 v[104:107], v[158:161], v[188:191], v[104:107]
	v_mfma_f32_16x16x32_bf16 v[108:111], v[150:153], v[188:191], v[108:111]
	v_mfma_f32_16x16x32_bf16 v[108:111], v[140:143], v[184:187], v[108:111]
	v_mfma_f32_16x16x32_bf16 v[92:95], v[140:143], v[192:195], v[92:95]
	v_mfma_f32_16x16x32_bf16 v[92:95], v[150:153], v[196:199], v[92:95]
	v_mfma_f32_16x16x32_bf16 v[88:91], v[158:161], v[196:199], v[88:91]
	v_mfma_f32_16x16x32_bf16 v[88:91], v[154:157], v[192:195], v[88:91]
	v_mfma_f32_16x16x32_bf16 v[72:75], v[154:157], v[200:203], v[72:75]
	v_mfma_f32_16x16x32_bf16 v[72:75], v[158:161], v[204:207], v[72:75]
	v_mfma_f32_16x16x32_bf16 v[76:79], v[150:153], v[204:207], v[76:79]
	v_mfma_f32_16x16x32_bf16 v[76:79], v[140:143], v[200:203], v[76:79]
	s_setprio 0
	s_barrier
	s_add_i32 s24, 0, 0x1c000
	s_add_i32 s25, s46, s28
	v_add_u32_e32 v149, s24, v144
	s_mov_b32 m0, s25
	ds_read_b128 v[208:211], v149
	v_xor_b32_e32 v243, 64, v149
	ds_read_b128 v[212:215], v243
	ds_read_b128 v[236:239], v149 offset:2048
	ds_read_b128 v[240:243], v243 offset:2048
	global_load_lds_dwordx4 v164, s[98:99]
	s_add_i32 m0, s25, 0x2000
	s_nop 0
	global_load_lds_dwordx4 v166, s[98:99]
	s_barrier
	s_waitcnt lgkmcnt(0)
	s_setprio 1
	s_waitcnt lgkmcnt(0)
	v_mfma_f32_16x16x32_bf16 v[116:119], v[208:211], v[176:179], v[116:119]
	v_mfma_f32_16x16x32_bf16 v[116:119], v[212:215], v[180:183], v[116:119]
	v_mfma_f32_16x16x32_bf16 v[112:115], v[240:243], v[180:183], v[112:115]
	v_mfma_f32_16x16x32_bf16 v[112:115], v[236:239], v[176:179], v[112:115]
	v_mfma_f32_16x16x32_bf16 v[96:99], v[236:239], v[184:187], v[96:99]
	v_mfma_f32_16x16x32_bf16 v[96:99], v[240:243], v[188:191], v[96:99]
	v_mfma_f32_16x16x32_bf16 v[100:103], v[212:215], v[188:191], v[100:103]
	v_mfma_f32_16x16x32_bf16 v[100:103], v[208:211], v[184:187], v[100:103]
	v_mfma_f32_16x16x32_bf16 v[84:87], v[208:211], v[192:195], v[84:87]
	v_mfma_f32_16x16x32_bf16 v[84:87], v[212:215], v[196:199], v[84:87]
	v_mfma_f32_16x16x32_bf16 v[80:83], v[240:243], v[196:199], v[80:83]
	v_mfma_f32_16x16x32_bf16 v[80:83], v[236:239], v[192:195], v[80:83]
	v_mfma_f32_16x16x32_bf16 v[64:67], v[236:239], v[200:203], v[64:67]
	v_mfma_f32_16x16x32_bf16 v[64:67], v[240:243], v[204:207], v[64:67]
	v_mfma_f32_16x16x32_bf16 v[68:71], v[212:215], v[204:207], v[68:71]
	v_mfma_f32_16x16x32_bf16 v[68:71], v[208:211], v[200:203], v[68:71]
	s_setprio 0
	s_mov_b32 m0, s37
	s_barrier
	ds_read_b128 v[176:179], v146 offset:49152
	ds_read_b128 v[180:183], v217 offset:49152
	ds_read_b128 v[184:187], v146 offset:51200
	ds_read_b128 v[188:191], v217 offset:51200
	ds_read_b128 v[192:195], v146 offset:53248
	ds_read_b128 v[196:199], v217 offset:53248
	ds_read_b128 v[200:203], v146 offset:55296
	ds_read_b128 v[204:207], v217 offset:55296
	global_load_lds_dwordx4 v128, s[100:101]
	s_mov_b32 m0, s38
	s_nop 0
	global_load_lds_dwordx4 v130, s[100:101]
	s_barrier
	s_waitcnt lgkmcnt(0)
	s_setprio 1
	s_waitcnt lgkmcnt(0)
	v_mfma_f32_16x16x32_bf16 v[60:63], v[140:143], v[176:179], v[60:63]
	v_mfma_f32_16x16x32_bf16 v[60:63], v[150:153], v[180:183], v[60:63]
	v_mfma_f32_16x16x32_bf16 v[56:59], v[158:161], v[180:183], v[56:59]
	v_mfma_f32_16x16x32_bf16 v[56:59], v[154:157], v[176:179], v[56:59]
	v_mfma_f32_16x16x32_bf16 v[40:43], v[154:157], v[184:187], v[40:43]
	v_mfma_f32_16x16x32_bf16 v[40:43], v[158:161], v[188:191], v[40:43]
	v_mfma_f32_16x16x32_bf16 v[44:47], v[150:153], v[188:191], v[44:47]
	v_mfma_f32_16x16x32_bf16 v[44:47], v[140:143], v[184:187], v[44:47]
	v_mfma_f32_16x16x32_bf16 v[28:31], v[140:143], v[192:195], v[28:31]
	v_mfma_f32_16x16x32_bf16 v[28:31], v[150:153], v[196:199], v[28:31]
	v_mfma_f32_16x16x32_bf16 v[24:27], v[158:161], v[196:199], v[24:27]
	v_mfma_f32_16x16x32_bf16 v[24:27], v[154:157], v[192:195], v[24:27]
	v_mfma_f32_16x16x32_bf16 v[8:11], v[154:157], v[200:203], v[8:11]
	v_mfma_f32_16x16x32_bf16 v[8:11], v[158:161], v[204:207], v[8:11]
	v_mfma_f32_16x16x32_bf16 v[12:15], v[150:153], v[204:207], v[12:15]
	v_mfma_f32_16x16x32_bf16 v[12:15], v[140:143], v[200:203], v[12:15]
	s_setprio 0
	s_barrier
	s_add_u32 s22, s22, 0x80080
	s_addc_u32 s23, s23, 0
	s_add_i32 s24, s24, s28
	s_mov_b32 m0, s24
	s_nop 0
	global_load_lds_dwordx4 v164, s[22:23]
	s_add_i32 m0, s24, 0x2000
	s_nop 0
	global_load_lds_dwordx4 v166, s[22:23]
	s_waitcnt vmcnt(6)
	s_barrier
	s_setprio 1
	v_mfma_f32_16x16x32_bf16 v[52:55], v[208:211], v[176:179], v[52:55]
	v_mfma_f32_16x16x32_bf16 v[52:55], v[212:215], v[180:183], v[52:55]
	v_mfma_f32_16x16x32_bf16 v[48:51], v[240:243], v[180:183], v[48:51]
	v_mfma_f32_16x16x32_bf16 v[48:51], v[236:239], v[176:179], v[48:51]
	v_mfma_f32_16x16x32_bf16 v[32:35], v[236:239], v[184:187], v[32:35]
	v_mfma_f32_16x16x32_bf16 v[32:35], v[240:243], v[188:191], v[32:35]
	v_mfma_f32_16x16x32_bf16 v[36:39], v[212:215], v[188:191], v[36:39]
	v_mfma_f32_16x16x32_bf16 v[36:39], v[208:211], v[184:187], v[36:39]
	v_mfma_f32_16x16x32_bf16 v[20:23], v[208:211], v[192:195], v[20:23]
	v_mfma_f32_16x16x32_bf16 v[20:23], v[212:215], v[196:199], v[20:23]
	v_mfma_f32_16x16x32_bf16 v[16:19], v[240:243], v[196:199], v[16:19]
	v_mfma_f32_16x16x32_bf16 v[16:19], v[236:239], v[192:195], v[16:19]
	v_mfma_f32_16x16x32_bf16 v[0:3], v[236:239], v[200:203], v[0:3]
	v_mfma_f32_16x16x32_bf16 v[0:3], v[240:243], v[204:207], v[0:3]
	v_mfma_f32_16x16x32_bf16 v[4:7], v[212:215], v[204:207], v[4:7]
	v_mfma_f32_16x16x32_bf16 v[4:7], v[208:211], v[200:203], v[4:7]
	s_setprio 0
	s_add_i32 s45, s45, 2
	s_add_u32 s20, s20, 0x100
	s_addc_u32 s21, s21, 0
	s_add_u32 s43, s43, 0x100
	s_addc_u32 s44, s44, 0
	s_cmp_gt_u32 s45, 29
	s_barrier
	s_cbranch_scc0 .LBB0_760
	v_lshl_add_u32 v217, s8, 8, v163
	v_add_u32_e32 v217, s35, v217
	v_lshlrev_b32_e32 v208, 2, v217
	v_lshl_add_u32 v214, v225, 3, s36
	v_lshl_add_u32 v214, s0, 8, v214
	v_lshl_add_u32 v209, v217, 11, v214
	v_lshlrev_b32_e32 v209, 1, v209
	v_lshlrev_b32_e32 v210, 1, v209
	v_lshl_add_u32 v217, v225, 4, v163
	v_xor_b32_e32 v215, 16, v217
	v_lshlrev_b32_e32 v215, 2, v215
	v_xor_b32_e32 v216, 32, v217
	v_lshlrev_b32_e32 v216, 2, v216
	v_add_u32_e32 v211, 0x0, v209
	global_load_dwordx4 v[176:179], v211, s[80:81]
	global_load_dwordx4 v[180:183], v211, s[80:81] offset:256
	v_add_u32_e32 v211, 0x10000, v209
	global_load_dwordx4 v[192:195], v211, s[80:81]
	global_load_dwordx4 v[196:199], v211, s[80:81] offset:256
	s_waitcnt vmcnt(2)
	v_lshlrev_b32_e32 v184, 16, v176
	v_and_b32_e32 v185, 0xffff0000, v176
	v_lshlrev_b32_e32 v186, 16, v177
	v_and_b32_e32 v187, 0xffff0000, v177
	v_lshlrev_b32_e32 v188, 16, v178
	v_and_b32_e32 v189, 0xffff0000, v178
	v_lshlrev_b32_e32 v190, 16, v179
	v_and_b32_e32 v191, 0xffff0000, v179
	v_pk_add_f32 v[124:125], v[124:125], v[184:185]
	v_pk_add_f32 v[126:127], v[126:127], v[186:187]
	v_pk_add_f32 v[120:121], v[120:121], v[188:189]
	v_pk_add_f32 v[122:123], v[122:123], v[190:191]
	v_mul_f32_e32 v213, v124, v124
	v_fmac_f32_e32 v213, v125, v125
	v_fmac_f32_e32 v213, v126, v126
	v_fmac_f32_e32 v213, v127, v127
	v_fmac_f32_e32 v213, v120, v120
	v_fmac_f32_e32 v213, v121, v121
	v_fmac_f32_e32 v213, v122, v122
	v_fmac_f32_e32 v213, v123, v123
	v_cvt_pk_bf16_f32 v176, v124, v125
	v_cvt_pk_bf16_f32 v177, v126, v127
	v_cvt_pk_bf16_f32 v178, v120, v121
	v_cvt_pk_bf16_f32 v179, v122, v123
	v_add_u32_e32 v217, 0x0, v209
	global_store_dwordx4 v217, v[176:179], s[80:81]
	v_lshlrev_b32_e32 v184, 16, v180
	v_and_b32_e32 v185, 0xffff0000, v180
	v_lshlrev_b32_e32 v186, 16, v181
	v_and_b32_e32 v187, 0xffff0000, v181
	v_lshlrev_b32_e32 v188, 16, v182
	v_and_b32_e32 v189, 0xffff0000, v182
	v_lshlrev_b32_e32 v190, 16, v183
	v_and_b32_e32 v191, 0xffff0000, v183
	v_pk_add_f32 v[116:117], v[116:117], v[184:185]
	v_pk_add_f32 v[118:119], v[118:119], v[186:187]
	v_pk_add_f32 v[112:113], v[112:113], v[188:189]
	v_pk_add_f32 v[114:115], v[114:115], v[190:191]
	v_fmac_f32_e32 v213, v116, v116
	v_fmac_f32_e32 v213, v117, v117
	v_fmac_f32_e32 v213, v118, v118
	v_fmac_f32_e32 v213, v119, v119
	v_fmac_f32_e32 v213, v112, v112
	v_fmac_f32_e32 v213, v113, v113
	v_fmac_f32_e32 v213, v114, v114
	v_fmac_f32_e32 v213, v115, v115
	v_cvt_pk_bf16_f32 v180, v116, v117
	v_cvt_pk_bf16_f32 v181, v118, v119
	v_cvt_pk_bf16_f32 v182, v112, v113
	v_cvt_pk_bf16_f32 v183, v114, v115
	global_store_dwordx4 v217, v[180:183], s[80:81] offset:256
	ds_bpermute_b32 v214, v215, v213
	s_waitcnt lgkmcnt(0)
	v_add_f32_e32 v213, v213, v214
	ds_bpermute_b32 v214, v216, v213
	s_waitcnt lgkmcnt(0)
	v_add_f32_e32 v213, v213, v214
	s_mov_b64 exec, 0xffff
	global_atomic_add_f32 v208, v213, s[4:5]
	s_mov_b64 exec, -1
	v_add_u32_e32 v211, 0x20000, v209
	global_load_dwordx4 v[176:179], v211, s[80:81]
	global_load_dwordx4 v[180:183], v211, s[80:81] offset:256
	s_waitcnt vmcnt(5)
	v_lshlrev_b32_e32 v200, 16, v192
	v_and_b32_e32 v201, 0xffff0000, v192
	v_lshlrev_b32_e32 v202, 16, v193
	v_and_b32_e32 v203, 0xffff0000, v193
	v_lshlrev_b32_e32 v204, 16, v194
	v_and_b32_e32 v205, 0xffff0000, v194
	v_lshlrev_b32_e32 v206, 16, v195
	v_and_b32_e32 v207, 0xffff0000, v195
	v_pk_add_f32 v[108:109], v[108:109], v[200:201]
	v_pk_add_f32 v[110:111], v[110:111], v[202:203]
	v_pk_add_f32 v[104:105], v[104:105], v[204:205]
	v_pk_add_f32 v[106:107], v[106:107], v[206:207]
	v_mul_f32_e32 v213, v108, v108
	v_fmac_f32_e32 v213, v109, v109
	v_fmac_f32_e32 v213, v110, v110
	v_fmac_f32_e32 v213, v111, v111
	v_fmac_f32_e32 v213, v104, v104
	v_fmac_f32_e32 v213, v105, v105
	v_fmac_f32_e32 v213, v106, v106
	v_fmac_f32_e32 v213, v107, v107
	v_cvt_pk_bf16_f32 v192, v108, v109
	v_cvt_pk_bf16_f32 v193, v110, v111
	v_cvt_pk_bf16_f32 v194, v104, v105
	v_cvt_pk_bf16_f32 v195, v106, v107
	v_add_u32_e32 v217, 0x10000, v209
	global_store_dwordx4 v217, v[192:195], s[80:81]
	v_lshlrev_b32_e32 v200, 16, v196
	v_and_b32_e32 v201, 0xffff0000, v196
	v_lshlrev_b32_e32 v202, 16, v197
	v_and_b32_e32 v203, 0xffff0000, v197
	v_lshlrev_b32_e32 v204, 16, v198
	v_and_b32_e32 v205, 0xffff0000, v198
	v_lshlrev_b32_e32 v206, 16, v199
	v_and_b32_e32 v207, 0xffff0000, v199
	v_pk_add_f32 v[100:101], v[100:101], v[200:201]
	v_pk_add_f32 v[102:103], v[102:103], v[202:203]
	v_pk_add_f32 v[96:97], v[96:97], v[204:205]
	v_pk_add_f32 v[98:99], v[98:99], v[206:207]
	v_fmac_f32_e32 v213, v100, v100
	v_fmac_f32_e32 v213, v101, v101
	v_fmac_f32_e32 v213, v102, v102
	v_fmac_f32_e32 v213, v103, v103
	v_fmac_f32_e32 v213, v96, v96
	v_fmac_f32_e32 v213, v97, v97
	v_fmac_f32_e32 v213, v98, v98
	v_fmac_f32_e32 v213, v99, v99
	v_cvt_pk_bf16_f32 v196, v100, v101
	v_cvt_pk_bf16_f32 v197, v102, v103
	v_cvt_pk_bf16_f32 v198, v96, v97
	v_cvt_pk_bf16_f32 v199, v98, v99
	global_store_dwordx4 v217, v[196:199], s[80:81] offset:256
	ds_bpermute_b32 v214, v215, v213
	s_waitcnt lgkmcnt(0)
	v_add_f32_e32 v213, v213, v214
	ds_bpermute_b32 v214, v216, v213
	s_waitcnt lgkmcnt(0)
	v_add_f32_e32 v213, v213, v214
	s_mov_b64 exec, 0xffff
	global_atomic_add_f32 v208, v213, s[4:5] offset:64
	s_mov_b64 exec, -1
	v_add_u32_e32 v211, 0x30000, v209
	global_load_dwordx4 v[192:195], v211, s[80:81]
	global_load_dwordx4 v[196:199], v211, s[80:81] offset:256
	s_waitcnt vmcnt(5)
	v_lshlrev_b32_e32 v184, 16, v176
	v_and_b32_e32 v185, 0xffff0000, v176
	v_lshlrev_b32_e32 v186, 16, v177
	v_and_b32_e32 v187, 0xffff0000, v177
	v_lshlrev_b32_e32 v188, 16, v178
	v_and_b32_e32 v189, 0xffff0000, v178
	v_lshlrev_b32_e32 v190, 16, v179
	v_and_b32_e32 v191, 0xffff0000, v179
	v_pk_add_f32 v[92:93], v[92:93], v[184:185]
	v_pk_add_f32 v[94:95], v[94:95], v[186:187]
	v_pk_add_f32 v[88:89], v[88:89], v[188:189]
	v_pk_add_f32 v[90:91], v[90:91], v[190:191]
	v_mul_f32_e32 v213, v92, v92
	v_fmac_f32_e32 v213, v93, v93
	v_fmac_f32_e32 v213, v94, v94
	v_fmac_f32_e32 v213, v95, v95
	v_fmac_f32_e32 v213, v88, v88
	v_fmac_f32_e32 v213, v89, v89
	v_fmac_f32_e32 v213, v90, v90
	v_fmac_f32_e32 v213, v91, v91
	v_cvt_pk_bf16_f32 v176, v92, v93
	v_cvt_pk_bf16_f32 v177, v94, v95
	v_cvt_pk_bf16_f32 v178, v88, v89
	v_cvt_pk_bf16_f32 v179, v90, v91
	v_add_u32_e32 v217, 0x20000, v209
	global_store_dwordx4 v217, v[176:179], s[80:81]
	v_lshlrev_b32_e32 v184, 16, v180
	v_and_b32_e32 v185, 0xffff0000, v180
	v_lshlrev_b32_e32 v186, 16, v181
	v_and_b32_e32 v187, 0xffff0000, v181
	v_lshlrev_b32_e32 v188, 16, v182
	v_and_b32_e32 v189, 0xffff0000, v182
	v_lshlrev_b32_e32 v190, 16, v183
	v_and_b32_e32 v191, 0xffff0000, v183
	v_pk_add_f32 v[84:85], v[84:85], v[184:185]
	v_pk_add_f32 v[86:87], v[86:87], v[186:187]
	v_pk_add_f32 v[80:81], v[80:81], v[188:189]
	v_pk_add_f32 v[82:83], v[82:83], v[190:191]
	v_fmac_f32_e32 v213, v84, v84
	v_fmac_f32_e32 v213, v85, v85
	v_fmac_f32_e32 v213, v86, v86
	v_fmac_f32_e32 v213, v87, v87
	v_fmac_f32_e32 v213, v80, v80
	v_fmac_f32_e32 v213, v81, v81
	v_fmac_f32_e32 v213, v82, v82
	v_fmac_f32_e32 v213, v83, v83
	v_cvt_pk_bf16_f32 v180, v84, v85
	v_cvt_pk_bf16_f32 v181, v86, v87
	v_cvt_pk_bf16_f32 v182, v80, v81
	v_cvt_pk_bf16_f32 v183, v82, v83
	global_store_dwordx4 v217, v[180:183], s[80:81] offset:256
	ds_bpermute_b32 v214, v215, v213
	s_waitcnt lgkmcnt(0)
	v_add_f32_e32 v213, v213, v214
	ds_bpermute_b32 v214, v216, v213
	s_waitcnt lgkmcnt(0)
	v_add_f32_e32 v213, v213, v214
	s_mov_b64 exec, 0xffff
	global_atomic_add_f32 v208, v213, s[4:5] offset:128
	s_mov_b64 exec, -1
	v_add_u32_e32 v211, 0x80000, v209
	global_load_dwordx4 v[176:179], v211, s[80:81]
	global_load_dwordx4 v[180:183], v211, s[80:81] offset:256
	s_waitcnt vmcnt(5)
	v_lshlrev_b32_e32 v200, 16, v192
	v_and_b32_e32 v201, 0xffff0000, v192
	v_lshlrev_b32_e32 v202, 16, v193
	v_and_b32_e32 v203, 0xffff0000, v193
	v_lshlrev_b32_e32 v204, 16, v194
	v_and_b32_e32 v205, 0xffff0000, v194
	v_lshlrev_b32_e32 v206, 16, v195
	v_and_b32_e32 v207, 0xffff0000, v195
	v_pk_add_f32 v[76:77], v[76:77], v[200:201]
	v_pk_add_f32 v[78:79], v[78:79], v[202:203]
	v_pk_add_f32 v[72:73], v[72:73], v[204:205]
	v_pk_add_f32 v[74:75], v[74:75], v[206:207]
	v_mul_f32_e32 v213, v76, v76
	v_fmac_f32_e32 v213, v77, v77
	v_fmac_f32_e32 v213, v78, v78
	v_fmac_f32_e32 v213, v79, v79
	v_fmac_f32_e32 v213, v72, v72
	v_fmac_f32_e32 v213, v73, v73
	v_fmac_f32_e32 v213, v74, v74
	v_fmac_f32_e32 v213, v75, v75
	v_cvt_pk_bf16_f32 v192, v76, v77
	v_cvt_pk_bf16_f32 v193, v78, v79
	v_cvt_pk_bf16_f32 v194, v72, v73
	v_cvt_pk_bf16_f32 v195, v74, v75
	v_add_u32_e32 v217, 0x30000, v209
	global_store_dwordx4 v217, v[192:195], s[80:81]
	v_lshlrev_b32_e32 v200, 16, v196
	v_and_b32_e32 v201, 0xffff0000, v196
	v_lshlrev_b32_e32 v202, 16, v197
	v_and_b32_e32 v203, 0xffff0000, v197
	v_lshlrev_b32_e32 v204, 16, v198
	v_and_b32_e32 v205, 0xffff0000, v198
	v_lshlrev_b32_e32 v206, 16, v199
	v_and_b32_e32 v207, 0xffff0000, v199
	v_pk_add_f32 v[68:69], v[68:69], v[200:201]
	v_pk_add_f32 v[70:71], v[70:71], v[202:203]
	v_pk_add_f32 v[64:65], v[64:65], v[204:205]
	v_pk_add_f32 v[66:67], v[66:67], v[206:207]
	v_fmac_f32_e32 v213, v68, v68
	v_fmac_f32_e32 v213, v69, v69
	v_fmac_f32_e32 v213, v70, v70
	v_fmac_f32_e32 v213, v71, v71
	v_fmac_f32_e32 v213, v64, v64
	v_fmac_f32_e32 v213, v65, v65
	v_fmac_f32_e32 v213, v66, v66
	v_fmac_f32_e32 v213, v67, v67
	v_cvt_pk_bf16_f32 v196, v68, v69
	v_cvt_pk_bf16_f32 v197, v70, v71
	v_cvt_pk_bf16_f32 v198, v64, v65
	v_cvt_pk_bf16_f32 v199, v66, v67
	global_store_dwordx4 v217, v[196:199], s[80:81] offset:256
	ds_bpermute_b32 v214, v215, v213
	s_waitcnt lgkmcnt(0)
	v_add_f32_e32 v213, v213, v214
	ds_bpermute_b32 v214, v216, v213
	s_waitcnt lgkmcnt(0)
	v_add_f32_e32 v213, v213, v214
	s_mov_b64 exec, 0xffff
	global_atomic_add_f32 v208, v213, s[4:5] offset:192
	s_mov_b64 exec, -1
	v_add_u32_e32 v211, 0x90000, v209
	global_load_dwordx4 v[192:195], v211, s[80:81]
	global_load_dwordx4 v[196:199], v211, s[80:81] offset:256
	s_waitcnt vmcnt(5)
	v_lshlrev_b32_e32 v184, 16, v176
	v_and_b32_e32 v185, 0xffff0000, v176
	v_lshlrev_b32_e32 v186, 16, v177
	v_and_b32_e32 v187, 0xffff0000, v177
	v_lshlrev_b32_e32 v188, 16, v178
	v_and_b32_e32 v189, 0xffff0000, v178
	v_lshlrev_b32_e32 v190, 16, v179
	v_and_b32_e32 v191, 0xffff0000, v179
	v_pk_add_f32 v[60:61], v[60:61], v[184:185]
	v_pk_add_f32 v[62:63], v[62:63], v[186:187]
	v_pk_add_f32 v[56:57], v[56:57], v[188:189]
	v_pk_add_f32 v[58:59], v[58:59], v[190:191]
	v_mul_f32_e32 v213, v60, v60
	v_fmac_f32_e32 v213, v61, v61
	v_fmac_f32_e32 v213, v62, v62
	v_fmac_f32_e32 v213, v63, v63
	v_fmac_f32_e32 v213, v56, v56
	v_fmac_f32_e32 v213, v57, v57
	v_fmac_f32_e32 v213, v58, v58
	v_fmac_f32_e32 v213, v59, v59
	v_cvt_pk_bf16_f32 v176, v60, v61
	v_cvt_pk_bf16_f32 v177, v62, v63
	v_cvt_pk_bf16_f32 v178, v56, v57
	v_cvt_pk_bf16_f32 v179, v58, v59
	v_add_u32_e32 v217, 0x80000, v209
	global_store_dwordx4 v217, v[176:179], s[80:81]
	v_lshlrev_b32_e32 v184, 16, v180
	v_and_b32_e32 v185, 0xffff0000, v180
	v_lshlrev_b32_e32 v186, 16, v181
	v_and_b32_e32 v187, 0xffff0000, v181
	v_lshlrev_b32_e32 v188, 16, v182
	v_and_b32_e32 v189, 0xffff0000, v182
	v_lshlrev_b32_e32 v190, 16, v183
	v_and_b32_e32 v191, 0xffff0000, v183
	v_pk_add_f32 v[52:53], v[52:53], v[184:185]
	v_pk_add_f32 v[54:55], v[54:55], v[186:187]
	v_pk_add_f32 v[48:49], v[48:49], v[188:189]
	v_pk_add_f32 v[50:51], v[50:51], v[190:191]
	v_fmac_f32_e32 v213, v52, v52
	v_fmac_f32_e32 v213, v53, v53
	v_fmac_f32_e32 v213, v54, v54
	v_fmac_f32_e32 v213, v55, v55
	v_fmac_f32_e32 v213, v48, v48
	v_fmac_f32_e32 v213, v49, v49
	v_fmac_f32_e32 v213, v50, v50
	v_fmac_f32_e32 v213, v51, v51
	v_cvt_pk_bf16_f32 v180, v52, v53
	v_cvt_pk_bf16_f32 v181, v54, v55
	v_cvt_pk_bf16_f32 v182, v48, v49
	v_cvt_pk_bf16_f32 v183, v50, v51
	global_store_dwordx4 v217, v[180:183], s[80:81] offset:256
	ds_bpermute_b32 v214, v215, v213
	s_waitcnt lgkmcnt(0)
	v_add_f32_e32 v213, v213, v214
	ds_bpermute_b32 v214, v216, v213
	s_waitcnt lgkmcnt(0)
	v_add_f32_e32 v213, v213, v214
	s_mov_b64 exec, 0xffff
	global_atomic_add_f32 v208, v213, s[4:5] offset:512
	s_mov_b64 exec, -1
	v_add_u32_e32 v211, 0xa0000, v209
	global_load_dwordx4 v[176:179], v211, s[80:81]
	global_load_dwordx4 v[180:183], v211, s[80:81] offset:256
	s_waitcnt vmcnt(5)
	v_lshlrev_b32_e32 v200, 16, v192
	v_and_b32_e32 v201, 0xffff0000, v192
	v_lshlrev_b32_e32 v202, 16, v193
	v_and_b32_e32 v203, 0xffff0000, v193
	v_lshlrev_b32_e32 v204, 16, v194
	v_and_b32_e32 v205, 0xffff0000, v194
	v_lshlrev_b32_e32 v206, 16, v195
	v_and_b32_e32 v207, 0xffff0000, v195
	v_pk_add_f32 v[44:45], v[44:45], v[200:201]
	v_pk_add_f32 v[46:47], v[46:47], v[202:203]
	v_pk_add_f32 v[40:41], v[40:41], v[204:205]
	v_pk_add_f32 v[42:43], v[42:43], v[206:207]
	v_mul_f32_e32 v213, v44, v44
	v_fmac_f32_e32 v213, v45, v45
	v_fmac_f32_e32 v213, v46, v46
	v_fmac_f32_e32 v213, v47, v47
	v_fmac_f32_e32 v213, v40, v40
	v_fmac_f32_e32 v213, v41, v41
	v_fmac_f32_e32 v213, v42, v42
	v_fmac_f32_e32 v213, v43, v43
	v_cvt_pk_bf16_f32 v192, v44, v45
	v_cvt_pk_bf16_f32 v193, v46, v47
	v_cvt_pk_bf16_f32 v194, v40, v41
	v_cvt_pk_bf16_f32 v195, v42, v43
	v_add_u32_e32 v217, 0x90000, v209
	global_store_dwordx4 v217, v[192:195], s[80:81]
	v_lshlrev_b32_e32 v200, 16, v196
	v_and_b32_e32 v201, 0xffff0000, v196
	v_lshlrev_b32_e32 v202, 16, v197
	v_and_b32_e32 v203, 0xffff0000, v197
	v_lshlrev_b32_e32 v204, 16, v198
	v_and_b32_e32 v205, 0xffff0000, v198
	v_lshlrev_b32_e32 v206, 16, v199
	v_and_b32_e32 v207, 0xffff0000, v199
	v_pk_add_f32 v[36:37], v[36:37], v[200:201]
	v_pk_add_f32 v[38:39], v[38:39], v[202:203]
	v_pk_add_f32 v[32:33], v[32:33], v[204:205]
	v_pk_add_f32 v[34:35], v[34:35], v[206:207]
	v_fmac_f32_e32 v213, v36, v36
	v_fmac_f32_e32 v213, v37, v37
	v_fmac_f32_e32 v213, v38, v38
	v_fmac_f32_e32 v213, v39, v39
	v_fmac_f32_e32 v213, v32, v32
	v_fmac_f32_e32 v213, v33, v33
	v_fmac_f32_e32 v213, v34, v34
	v_fmac_f32_e32 v213, v35, v35
	v_cvt_pk_bf16_f32 v196, v36, v37
	v_cvt_pk_bf16_f32 v197, v38, v39
	v_cvt_pk_bf16_f32 v198, v32, v33
	v_cvt_pk_bf16_f32 v199, v34, v35
	global_store_dwordx4 v217, v[196:199], s[80:81] offset:256
	ds_bpermute_b32 v214, v215, v213
	s_waitcnt lgkmcnt(0)
	v_add_f32_e32 v213, v213, v214
	ds_bpermute_b32 v214, v216, v213
	s_waitcnt lgkmcnt(0)
	v_add_f32_e32 v213, v213, v214
	s_mov_b64 exec, 0xffff
	global_atomic_add_f32 v208, v213, s[4:5] offset:576
	s_mov_b64 exec, -1
	v_add_u32_e32 v211, 0xb0000, v209
	global_load_dwordx4 v[192:195], v211, s[80:81]
	global_load_dwordx4 v[196:199], v211, s[80:81] offset:256
	s_waitcnt vmcnt(5)
	v_lshlrev_b32_e32 v184, 16, v176
	v_and_b32_e32 v185, 0xffff0000, v176
	v_lshlrev_b32_e32 v186, 16, v177
	v_and_b32_e32 v187, 0xffff0000, v177
	v_lshlrev_b32_e32 v188, 16, v178
	v_and_b32_e32 v189, 0xffff0000, v178
	v_lshlrev_b32_e32 v190, 16, v179
	v_and_b32_e32 v191, 0xffff0000, v179
	v_pk_add_f32 v[28:29], v[28:29], v[184:185]
	v_pk_add_f32 v[30:31], v[30:31], v[186:187]
	v_pk_add_f32 v[24:25], v[24:25], v[188:189]
	v_pk_add_f32 v[26:27], v[26:27], v[190:191]
	v_mul_f32_e32 v213, v28, v28
	v_fmac_f32_e32 v213, v29, v29
	v_fmac_f32_e32 v213, v30, v30
	v_fmac_f32_e32 v213, v31, v31
	v_fmac_f32_e32 v213, v24, v24
	v_fmac_f32_e32 v213, v25, v25
	v_fmac_f32_e32 v213, v26, v26
	v_fmac_f32_e32 v213, v27, v27
	v_cvt_pk_bf16_f32 v176, v28, v29
	v_cvt_pk_bf16_f32 v177, v30, v31
	v_cvt_pk_bf16_f32 v178, v24, v25
	v_cvt_pk_bf16_f32 v179, v26, v27
	v_add_u32_e32 v217, 0xa0000, v209
	global_store_dwordx4 v217, v[176:179], s[80:81]
	v_lshlrev_b32_e32 v184, 16, v180
	v_and_b32_e32 v185, 0xffff0000, v180
	v_lshlrev_b32_e32 v186, 16, v181
	v_and_b32_e32 v187, 0xffff0000, v181
	v_lshlrev_b32_e32 v188, 16, v182
	v_and_b32_e32 v189, 0xffff0000, v182
	v_lshlrev_b32_e32 v190, 16, v183
	v_and_b32_e32 v191, 0xffff0000, v183
	v_pk_add_f32 v[20:21], v[20:21], v[184:185]
	v_pk_add_f32 v[22:23], v[22:23], v[186:187]
	v_pk_add_f32 v[16:17], v[16:17], v[188:189]
	v_pk_add_f32 v[18:19], v[18:19], v[190:191]
	v_fmac_f32_e32 v213, v20, v20
	v_fmac_f32_e32 v213, v21, v21
	v_fmac_f32_e32 v213, v22, v22
	v_fmac_f32_e32 v213, v23, v23
	v_fmac_f32_e32 v213, v16, v16
	v_fmac_f32_e32 v213, v17, v17
	v_fmac_f32_e32 v213, v18, v18
	v_fmac_f32_e32 v213, v19, v19
	v_cvt_pk_bf16_f32 v180, v20, v21
	v_cvt_pk_bf16_f32 v181, v22, v23
	v_cvt_pk_bf16_f32 v182, v16, v17
	v_cvt_pk_bf16_f32 v183, v18, v19
	global_store_dwordx4 v217, v[180:183], s[80:81] offset:256
	ds_bpermute_b32 v214, v215, v213
	s_waitcnt lgkmcnt(0)
	v_add_f32_e32 v213, v213, v214
	ds_bpermute_b32 v214, v216, v213
	s_waitcnt lgkmcnt(0)
	v_add_f32_e32 v213, v213, v214
	s_mov_b64 exec, 0xffff
	global_atomic_add_f32 v208, v213, s[4:5] offset:640
	s_mov_b64 exec, -1
	s_waitcnt vmcnt(3)
	v_lshlrev_b32_e32 v200, 16, v192
	v_and_b32_e32 v201, 0xffff0000, v192
	v_lshlrev_b32_e32 v202, 16, v193
	v_and_b32_e32 v203, 0xffff0000, v193
	v_lshlrev_b32_e32 v204, 16, v194
	v_and_b32_e32 v205, 0xffff0000, v194
	v_lshlrev_b32_e32 v206, 16, v195
	v_and_b32_e32 v207, 0xffff0000, v195
	v_pk_add_f32 v[12:13], v[12:13], v[200:201]
	v_pk_add_f32 v[14:15], v[14:15], v[202:203]
	v_pk_add_f32 v[8:9], v[8:9], v[204:205]
	v_pk_add_f32 v[10:11], v[10:11], v[206:207]
	v_mul_f32_e32 v213, v12, v12
	v_fmac_f32_e32 v213, v13, v13
	v_fmac_f32_e32 v213, v14, v14
	v_fmac_f32_e32 v213, v15, v15
	v_fmac_f32_e32 v213, v8, v8
	v_fmac_f32_e32 v213, v9, v9
	v_fmac_f32_e32 v213, v10, v10
	v_fmac_f32_e32 v213, v11, v11
	v_cvt_pk_bf16_f32 v192, v12, v13
	v_cvt_pk_bf16_f32 v193, v14, v15
	v_cvt_pk_bf16_f32 v194, v8, v9
	v_cvt_pk_bf16_f32 v195, v10, v11
	v_add_u32_e32 v217, 0xb0000, v209
	global_store_dwordx4 v217, v[192:195], s[80:81]
	v_lshlrev_b32_e32 v200, 16, v196
	v_and_b32_e32 v201, 0xffff0000, v196
	v_lshlrev_b32_e32 v202, 16, v197
	v_and_b32_e32 v203, 0xffff0000, v197
	v_lshlrev_b32_e32 v204, 16, v198
	v_and_b32_e32 v205, 0xffff0000, v198
	v_lshlrev_b32_e32 v206, 16, v199
	v_and_b32_e32 v207, 0xffff0000, v199
	v_pk_add_f32 v[4:5], v[4:5], v[200:201]
	v_pk_add_f32 v[6:7], v[6:7], v[202:203]
	v_pk_add_f32 v[0:1], v[0:1], v[204:205]
	v_pk_add_f32 v[2:3], v[2:3], v[206:207]
	v_fmac_f32_e32 v213, v4, v4
	v_fmac_f32_e32 v213, v5, v5
	v_fmac_f32_e32 v213, v6, v6
	v_fmac_f32_e32 v213, v7, v7
	v_fmac_f32_e32 v213, v0, v0
	v_fmac_f32_e32 v213, v1, v1
	v_fmac_f32_e32 v213, v2, v2
	v_fmac_f32_e32 v213, v3, v3
	v_cvt_pk_bf16_f32 v196, v4, v5
	v_cvt_pk_bf16_f32 v197, v6, v7
	v_cvt_pk_bf16_f32 v198, v0, v1
	v_cvt_pk_bf16_f32 v199, v2, v3
	global_store_dwordx4 v217, v[196:199], s[80:81] offset:256
	ds_bpermute_b32 v214, v215, v213
	s_waitcnt lgkmcnt(0)
	v_add_f32_e32 v213, v213, v214
	ds_bpermute_b32 v214, v216, v213
	s_waitcnt lgkmcnt(0)
	v_add_f32_e32 v213, v213, v214
	s_mov_b64 exec, 0xffff
	global_atomic_add_f32 v208, v213, s[4:5] offset:704
	s_mov_b64 exec, -1
	s_branch .LBB0_752

.LBB0_839:
	s_ashr_i32 s37, s36, 31
	v_cmp_lt_i64_e32 vcc, s[12:13], v[184:185]
	s_lshl_b64 s[12:13], s[36:37], 20
	s_add_u32 s38, s80, s12
	s_addc_u32 s39, s81, s13
	s_and_b64 s[12:13], vcc, exec
	s_cselect_b32 s33, s39, s9
	s_cselect_b32 s37, s38, s8
	s_ashr_i32 s35, s34, 31
	s_lshl_b64 s[12:13], s[34:35], 19
	s_add_u32 s40, s44, s12
	s_addc_u32 s41, s45, s13
	s_and_b64 s[12:13], vcc, exec
	s_cselect_b32 s35, s41, s11
	s_cselect_b32 s64, s40, s10
	s_add_u32 s65, s10, 0x100
	v_mov_b32_e32 v0, 0
	s_addc_u32 s66, s11, 0
	s_mov_b32 s67, -2
	v_mov_b32_e32 v1, v0
	v_mov_b32_e32 v2, v0
	v_mov_b32_e32 v3, v0
	v_mov_b32_e32 v64, v0
	v_mov_b32_e32 v65, v0
	v_mov_b32_e32 v66, v0
	v_mov_b32_e32 v67, v0
	v_mov_b32_e32 v8, v0
	v_mov_b32_e32 v9, v0
	s_waitcnt vmcnt(0)
	v_mov_b32_e32 v10, v0
	v_mov_b32_e32 v11, v0
	v_mov_b32_e32 v68, v0
	v_mov_b32_e32 v69, v0
	v_mov_b32_e32 v70, v0
	v_mov_b32_e32 v71, v0
	v_mov_b32_e32 v12, v0
	v_mov_b32_e32 v13, v0
	v_mov_b32_e32 v14, v0
	v_mov_b32_e32 v15, v0
	v_mov_b32_e32 v110, v0
	v_mov_b32_e32 v111, v0
	v_mov_b32_e32 v112, v0
	v_mov_b32_e32 v113, v0
	v_mov_b32_e32 v16, v0
	v_mov_b32_e32 v17, v0
	v_mov_b32_e32 v18, v0
	v_mov_b32_e32 v19, v0
	v_mov_b32_e32 v118, v0
	v_mov_b32_e32 v119, v0
	v_mov_b32_e32 v120, v0
	v_mov_b32_e32 v121, v0
	v_mov_b32_e32 v4, v0
	v_mov_b32_e32 v5, v0
	v_mov_b32_e32 v6, v0
	v_mov_b32_e32 v7, v0
	v_mov_b32_e32 v72, v0
	v_mov_b32_e32 v73, v0
	v_mov_b32_e32 v74, v0
	v_mov_b32_e32 v75, v0
	v_mov_b32_e32 v20, v0
	v_mov_b32_e32 v21, v0
	v_mov_b32_e32 v22, v0
	v_mov_b32_e32 v23, v0
	v_mov_b32_e32 v114, v0
	v_mov_b32_e32 v115, v0
	v_mov_b32_e32 v116, v0
	v_mov_b32_e32 v117, v0
	v_mov_b32_e32 v24, v0
	v_mov_b32_e32 v25, v0
	v_mov_b32_e32 v26, v0
	v_mov_b32_e32 v27, v0
	v_mov_b32_e32 v122, v0
	v_mov_b32_e32 v123, v0
	v_mov_b32_e32 v124, v0
	v_mov_b32_e32 v125, v0
	v_mov_b32_e32 v28, v0
	v_mov_b32_e32 v29, v0
	v_mov_b32_e32 v30, v0
	v_mov_b32_e32 v31, v0
	v_mov_b32_e32 v126, v0
	v_mov_b32_e32 v127, v0
	v_mov_b32_e32 v128, v0
	v_mov_b32_e32 v129, v0
	v_mov_b32_e32 v32, v0
	v_mov_b32_e32 v33, v0
	v_mov_b32_e32 v34, v0
	v_mov_b32_e32 v35, v0
	v_mov_b32_e32 v130, v0
	v_mov_b32_e32 v131, v0
	v_mov_b32_e32 v132, v0
	v_mov_b32_e32 v133, v0
	v_mov_b32_e32 v36, v0
	v_mov_b32_e32 v37, v0
	v_mov_b32_e32 v38, v0
	v_mov_b32_e32 v39, v0
	v_mov_b32_e32 v134, v0
	v_mov_b32_e32 v135, v0
	v_mov_b32_e32 v136, v0
	v_mov_b32_e32 v137, v0
	v_mov_b32_e32 v44, v0
	v_mov_b32_e32 v45, v0
	v_mov_b32_e32 v46, v0
	v_mov_b32_e32 v47, v0
	v_mov_b32_e32 v142, v0
	v_mov_b32_e32 v143, v0
	v_mov_b32_e32 v144, v0
	v_mov_b32_e32 v145, v0
	v_mov_b32_e32 v56, v0
	v_mov_b32_e32 v57, v0
	v_mov_b32_e32 v58, v0
	v_mov_b32_e32 v59, v0
	v_mov_b32_e32 v154, v0
	v_mov_b32_e32 v155, v0
	v_mov_b32_e32 v156, v0
	v_mov_b32_e32 v157, v0
	v_mov_b32_e32 v40, v0
	v_mov_b32_e32 v41, v0
	v_mov_b32_e32 v42, v0
	v_mov_b32_e32 v43, v0
	v_mov_b32_e32 v138, v0
	v_mov_b32_e32 v139, v0
	v_mov_b32_e32 v140, v0
	v_mov_b32_e32 v141, v0
	v_mov_b32_e32 v48, v0
	v_mov_b32_e32 v49, v0
	v_mov_b32_e32 v50, v0
	v_mov_b32_e32 v51, v0
	v_mov_b32_e32 v146, v0
	v_mov_b32_e32 v147, v0
	v_mov_b32_e32 v148, v0
	v_mov_b32_e32 v149, v0
	v_mov_b32_e32 v52, v0
	v_mov_b32_e32 v53, v0
	v_mov_b32_e32 v54, v0
	v_mov_b32_e32 v55, v0
	v_mov_b32_e32 v150, v0
	v_mov_b32_e32 v151, v0
	v_mov_b32_e32 v152, v0
	v_mov_b32_e32 v153, v0
	v_mov_b32_e32 v60, v0
	v_mov_b32_e32 v61, v0
	v_mov_b32_e32 v62, v0
	v_mov_b32_e32 v63, v0
	v_mov_b32_e32 v158, v0
	v_mov_b32_e32 v159, v0
	v_mov_b32_e32 v160, v0
	v_mov_b32_e32 v161, v0
	v_xor_b32_e32 v220, 64, v171
	v_xor_b32_e32 v221, 64, v173
	v_xor_b32_e32 v238, 64, v175
	v_add_u32_e32 v239, 0x18000, v169
	v_xor_b32_e32 v240, 64, v239
	v_add_u32_e32 v241, 0x1c000, v169
	v_xor_b32_e32 v242, 64, v241
.LBB0_840:
	ds_read_b128 v[76:79], v171
	ds_read_b128 v[80:83], v220
	ds_read_b128 v[84:87], v171 offset:2048
	ds_read_b128 v[88:91], v220 offset:2048
	s_add_u32 s10, s8, 0x100
	s_addc_u32 s11, s9, 0
	s_cmp_eq_u32 s67, 28
	s_cselect_b32 s43, s33, s11
	s_cselect_b32 s42, s37, s10
	s_cselect_b32 s13, s35, s66
	s_cselect_b32 s12, s64, s65
	s_add_i32 m0, s48, 0xc000
	ds_read_b128 v[92:95], v173
	ds_read_b128 v[96:99], v221
	ds_read_b128 v[100:103], v173 offset:2048
	ds_read_b128 v[104:107], v221 offset:2048
	ds_read_b128 v[188:191], v173 offset:4096
	ds_read_b128 v[192:195], v221 offset:4096
	ds_read_b128 v[196:199], v173 offset:6144
	ds_read_b128 v[200:203], v221 offset:6144
	global_load_lds_dwordx4 v180, s[8:9]
	s_add_i32 m0, s48, 0xe000
	s_nop 0
	global_load_lds_dwordx4 v182, s[8:9]
	s_waitcnt lgkmcnt(8)
	s_barrier
	s_waitcnt lgkmcnt(0)
	s_setprio 1
	s_waitcnt lgkmcnt(0)
	v_mfma_f32_16x16x32_bf16 v[158:161], v[76:79], v[92:95], v[158:161]
	v_mfma_f32_16x16x32_bf16 v[158:161], v[80:83], v[96:99], v[158:161]
	v_mfma_f32_16x16x32_bf16 v[60:63], v[88:91], v[96:99], v[60:63]
	v_mfma_f32_16x16x32_bf16 v[60:63], v[84:87], v[92:95], v[60:63]
	v_mfma_f32_16x16x32_bf16 v[52:55], v[84:87], v[100:103], v[52:55]
	v_mfma_f32_16x16x32_bf16 v[52:55], v[88:91], v[104:107], v[52:55]
	v_mfma_f32_16x16x32_bf16 v[150:153], v[80:83], v[104:107], v[150:153]
	v_mfma_f32_16x16x32_bf16 v[150:153], v[76:79], v[100:103], v[150:153]
	v_mfma_f32_16x16x32_bf16 v[146:149], v[76:79], v[188:191], v[146:149]
	v_mfma_f32_16x16x32_bf16 v[146:149], v[80:83], v[192:195], v[146:149]
	v_mfma_f32_16x16x32_bf16 v[48:51], v[88:91], v[192:195], v[48:51]
	v_mfma_f32_16x16x32_bf16 v[48:51], v[84:87], v[188:191], v[48:51]
	v_mfma_f32_16x16x32_bf16 v[40:43], v[84:87], v[196:199], v[40:43]
	v_mfma_f32_16x16x32_bf16 v[40:43], v[88:91], v[200:203], v[40:43]
	v_mfma_f32_16x16x32_bf16 v[138:141], v[80:83], v[200:203], v[138:141]
	v_mfma_f32_16x16x32_bf16 v[138:141], v[76:79], v[196:199], v[138:141]
	s_setprio 0
	s_barrier
	s_add_i32 s8, s60, s46
	s_add_u32 s98, s12, s18
	s_addc_u32 s99, s13, s19
	s_mov_b32 m0, s8
	ds_read_b128 v[204:207], v175
	ds_read_b128 v[208:211], v238
	ds_read_b128 v[212:215], v175 offset:2048
	ds_read_b128 v[216:219], v238 offset:2048
	global_load_lds_dwordx4 v164, s[12:13]
	s_add_i32 m0, s8, 0x2000
	s_nop 0
	global_load_lds_dwordx4 v166, s[12:13]
	s_barrier
	s_waitcnt lgkmcnt(0)
	s_setprio 1
	s_waitcnt lgkmcnt(0)
	v_mfma_f32_16x16x32_bf16 v[154:157], v[204:207], v[92:95], v[154:157]
	v_mfma_f32_16x16x32_bf16 v[154:157], v[208:211], v[96:99], v[154:157]
	v_mfma_f32_16x16x32_bf16 v[56:59], v[216:219], v[96:99], v[56:59]
	v_mfma_f32_16x16x32_bf16 v[56:59], v[212:215], v[92:95], v[56:59]
	v_mfma_f32_16x16x32_bf16 v[44:47], v[212:215], v[100:103], v[44:47]
	v_mfma_f32_16x16x32_bf16 v[44:47], v[216:219], v[104:107], v[44:47]
	v_mfma_f32_16x16x32_bf16 v[36:39], v[216:219], v[192:195], v[36:39]
	v_mfma_f32_16x16x32_bf16 v[36:39], v[212:215], v[188:191], v[36:39]
	v_mfma_f32_16x16x32_bf16 v[32:35], v[212:215], v[196:199], v[32:35]
	v_mfma_f32_16x16x32_bf16 v[32:35], v[216:219], v[200:203], v[32:35]
	v_mfma_f32_16x16x32_bf16 v[92:95], v[204:207], v[100:103], v[142:145]
	v_mfma_f32_16x16x32_bf16 v[92:95], v[208:211], v[104:107], v[92:95]
	v_mfma_f32_16x16x32_bf16 v[96:99], v[208:211], v[192:195], v[134:137]
	v_mfma_f32_16x16x32_bf16 v[96:99], v[204:207], v[188:191], v[96:99]
	v_mfma_f32_16x16x32_bf16 v[100:103], v[204:207], v[196:199], v[130:133]
	v_mfma_f32_16x16x32_bf16 v[100:103], v[208:211], v[200:203], v[100:103]
	s_setprio 0
	s_mov_b32 m0, s48
	s_add_u32 s100, s42, s18
	s_addc_u32 s101, s43, s19
	s_barrier
	ds_read_b128 v[104:107], v173 offset:16384
	ds_read_b128 v[130:133], v221 offset:16384
	ds_read_b128 v[134:137], v173 offset:18432
	ds_read_b128 v[142:145], v221 offset:18432
	ds_read_b128 v[188:191], v173 offset:20480
	ds_read_b128 v[192:195], v221 offset:20480
	ds_read_b128 v[196:199], v173 offset:22528
	ds_read_b128 v[200:203], v221 offset:22528
	global_load_lds_dwordx4 v178, s[42:43]
	s_mov_b32 m0, s49
	s_nop 0
	global_load_lds_dwordx4 v176, s[42:43]
	s_barrier
	s_waitcnt lgkmcnt(0)
	s_setprio 1
	s_waitcnt lgkmcnt(0)
	v_mfma_f32_16x16x32_bf16 v[126:129], v[76:79], v[104:107], v[126:129]
	v_mfma_f32_16x16x32_bf16 v[126:129], v[80:83], v[130:133], v[126:129]
	v_mfma_f32_16x16x32_bf16 v[28:31], v[88:91], v[130:133], v[28:31]
	v_mfma_f32_16x16x32_bf16 v[28:31], v[84:87], v[104:107], v[28:31]
	v_mfma_f32_16x16x32_bf16 v[24:27], v[84:87], v[134:137], v[24:27]
	v_mfma_f32_16x16x32_bf16 v[24:27], v[88:91], v[142:145], v[24:27]
	v_mfma_f32_16x16x32_bf16 v[122:125], v[80:83], v[142:145], v[122:125]
	v_mfma_f32_16x16x32_bf16 v[122:125], v[76:79], v[134:137], v[122:125]
	v_mfma_f32_16x16x32_bf16 v[114:117], v[76:79], v[188:191], v[114:117]
	v_mfma_f32_16x16x32_bf16 v[114:117], v[80:83], v[192:195], v[114:117]
	v_mfma_f32_16x16x32_bf16 v[20:23], v[88:91], v[192:195], v[20:23]
	v_mfma_f32_16x16x32_bf16 v[20:23], v[84:87], v[188:191], v[20:23]
	v_mfma_f32_16x16x32_bf16 v[4:7], v[84:87], v[196:199], v[4:7]
	v_mfma_f32_16x16x32_bf16 v[4:7], v[88:91], v[200:203], v[4:7]
	v_mfma_f32_16x16x32_bf16 v[72:75], v[80:83], v[200:203], v[72:75]
	v_mfma_f32_16x16x32_bf16 v[72:75], v[76:79], v[196:199], v[72:75]
	s_setprio 0
	s_barrier
	s_add_u32 s8, s12, 0x1600000
	s_addc_u32 s9, s13, 0
	s_add_i32 s68, s61, s46
	s_mov_b32 m0, s68
	s_nop 0
	global_load_lds_dwordx4 v164, s[8:9]
	s_add_i32 m0, s68, 0x2000
	s_nop 0
	global_load_lds_dwordx4 v166, s[8:9]
	s_waitcnt vmcnt(6)
	s_barrier
	s_setprio 1
	v_mfma_f32_16x16x32_bf16 v[16:19], v[212:215], v[104:107], v[16:19]
	v_mfma_f32_16x16x32_bf16 v[16:19], v[216:219], v[130:133], v[16:19]
	v_mfma_f32_16x16x32_bf16 v[12:15], v[216:219], v[142:145], v[12:15]
	v_mfma_f32_16x16x32_bf16 v[12:15], v[212:215], v[134:137], v[12:15]
	v_mfma_f32_16x16x32_bf16 v[8:11], v[212:215], v[188:191], v[8:11]
	v_mfma_f32_16x16x32_bf16 v[8:11], v[216:219], v[192:195], v[8:11]
	v_mfma_f32_16x16x32_bf16 v[68:71], v[208:211], v[192:195], v[68:71]
	v_mfma_f32_16x16x32_bf16 v[68:71], v[204:207], v[188:191], v[68:71]
	v_mfma_f32_16x16x32_bf16 v[64:67], v[204:207], v[196:199], v[64:67]
	v_mfma_f32_16x16x32_bf16 v[64:67], v[208:211], v[200:203], v[64:67]
	v_mfma_f32_16x16x32_bf16 v[0:3], v[216:219], v[200:203], v[0:3]
	v_mfma_f32_16x16x32_bf16 v[0:3], v[212:215], v[196:199], v[0:3]
	v_mfma_f32_16x16x32_bf16 v[76:79], v[204:207], v[104:107], v[118:121]
	v_mfma_f32_16x16x32_bf16 v[76:79], v[208:211], v[130:133], v[76:79]
	v_mfma_f32_16x16x32_bf16 v[80:83], v[208:211], v[142:145], v[110:113]
	v_mfma_f32_16x16x32_bf16 v[80:83], v[204:207], v[134:137], v[80:83]
	s_setprio 0
	s_add_i32 s68, 0, 0x18000
	s_barrier
	ds_read_b128 v[84:87], v239
	ds_read_b128 v[88:91], v240
	ds_read_b128 v[104:107], v239 offset:2048
	ds_read_b128 v[108:111], v240 offset:2048
	s_add_u32 s8, s42, 0x40000
	s_addc_u32 s9, s43, 0
	s_mov_b32 m0, s50
	ds_read_b128 v[118:121], v173 offset:32768
	ds_read_b128 v[130:133], v221 offset:32768
	ds_read_b128 v[134:137], v173 offset:34816
	ds_read_b128 v[188:191], v221 offset:34816
	ds_read_b128 v[192:195], v173 offset:36864
	ds_read_b128 v[196:199], v221 offset:36864
	ds_read_b128 v[200:203], v173 offset:38912
	ds_read_b128 v[204:207], v221 offset:38912
	global_load_lds_dwordx4 v178, s[8:9]
	s_mov_b32 m0, s51
	s_nop 0
	global_load_lds_dwordx4 v176, s[8:9]
	s_waitcnt lgkmcnt(8)
	s_barrier
	s_waitcnt lgkmcnt(0)
	s_setprio 1
	s_waitcnt lgkmcnt(0)
	v_mfma_f32_16x16x32_bf16 v[142:145], v[84:87], v[118:121], v[158:161]
	v_mfma_f32_16x16x32_bf16 v[158:161], v[88:91], v[130:133], v[142:145]
	v_mfma_f32_16x16x32_bf16 v[60:63], v[108:111], v[130:133], v[60:63]
	v_mfma_f32_16x16x32_bf16 v[60:63], v[104:107], v[118:121], v[60:63]
	v_mfma_f32_16x16x32_bf16 v[52:55], v[104:107], v[134:137], v[52:55]
	v_mfma_f32_16x16x32_bf16 v[52:55], v[108:111], v[188:191], v[52:55]
	v_mfma_f32_16x16x32_bf16 v[48:51], v[108:111], v[196:199], v[48:51]
	v_mfma_f32_16x16x32_bf16 v[48:51], v[104:107], v[192:195], v[48:51]
	v_mfma_f32_16x16x32_bf16 v[40:43], v[104:107], v[200:203], v[40:43]
	v_mfma_f32_16x16x32_bf16 v[40:43], v[108:111], v[204:207], v[40:43]
	v_mfma_f32_16x16x32_bf16 v[138:141], v[88:91], v[204:207], v[138:141]
	v_mfma_f32_16x16x32_bf16 v[138:141], v[84:87], v[200:203], v[138:141]
	v_mfma_f32_16x16x32_bf16 v[142:145], v[84:87], v[134:137], v[150:153]
	v_mfma_f32_16x16x32_bf16 v[150:153], v[88:91], v[188:191], v[142:145]
	v_mfma_f32_16x16x32_bf16 v[142:145], v[84:87], v[192:195], v[146:149]
	v_mfma_f32_16x16x32_bf16 v[146:149], v[88:91], v[196:199], v[142:145]
	s_setprio 0
	s_barrier
	s_add_i32 s42, 0, 0x1c000
	s_add_i32 s8, s68, s46
	ds_read_b128 v[208:211], v241
	ds_read_b128 v[212:215], v242
	ds_read_b128 v[216:219], v241 offset:2048
	ds_read_b128 v[234:237], v242 offset:2048
	s_mov_b32 m0, s8
	s_nop 0
	global_load_lds_dwordx4 v164, s[98:99]
	s_add_i32 m0, s8, 0x2000
	s_nop 0
	global_load_lds_dwordx4 v166, s[98:99]
	s_barrier
	s_waitcnt lgkmcnt(0)
	s_setprio 1
	s_waitcnt lgkmcnt(0)
	v_mfma_f32_16x16x32_bf16 v[142:145], v[208:211], v[118:121], v[154:157]
	v_mfma_f32_16x16x32_bf16 v[154:157], v[212:215], v[130:133], v[142:145]
	v_mfma_f32_16x16x32_bf16 v[56:59], v[234:237], v[130:133], v[56:59]
	v_mfma_f32_16x16x32_bf16 v[56:59], v[216:219], v[118:121], v[56:59]
	v_mfma_f32_16x16x32_bf16 v[44:47], v[216:219], v[134:137], v[44:47]
	v_mfma_f32_16x16x32_bf16 v[44:47], v[234:237], v[188:191], v[44:47]
	v_mfma_f32_16x16x32_bf16 v[36:39], v[234:237], v[196:199], v[36:39]
	v_mfma_f32_16x16x32_bf16 v[36:39], v[216:219], v[192:195], v[36:39]
	v_mfma_f32_16x16x32_bf16 v[32:35], v[216:219], v[200:203], v[32:35]
	v_mfma_f32_16x16x32_bf16 v[32:35], v[234:237], v[204:207], v[32:35]
	v_mfma_f32_16x16x32_bf16 v[92:95], v[208:211], v[134:137], v[92:95]
	v_mfma_f32_16x16x32_bf16 v[142:145], v[212:215], v[188:191], v[92:95]
	v_mfma_f32_16x16x32_bf16 v[92:95], v[208:211], v[192:195], v[96:99]
	v_mfma_f32_16x16x32_bf16 v[134:137], v[212:215], v[196:199], v[92:95]
	v_mfma_f32_16x16x32_bf16 v[92:95], v[208:211], v[200:203], v[100:103]
	v_mfma_f32_16x16x32_bf16 v[130:133], v[212:215], v[204:207], v[92:95]
	s_setprio 0
	s_mov_b32 m0, s54
	s_barrier
	ds_read_b128 v[92:95], v173 offset:49152
	ds_read_b128 v[96:99], v221 offset:49152
	ds_read_b128 v[100:103], v173 offset:51200
	ds_read_b128 v[188:191], v221 offset:51200
	ds_read_b128 v[192:195], v173 offset:53248
	ds_read_b128 v[196:199], v221 offset:53248
	ds_read_b128 v[200:203], v173 offset:55296
	ds_read_b128 v[204:207], v221 offset:55296
	global_load_lds_dwordx4 v178, s[100:101]
	s_mov_b32 m0, s55
	s_nop 0
	global_load_lds_dwordx4 v176, s[100:101]
	s_barrier
	s_waitcnt lgkmcnt(0)
	s_setprio 1
	s_waitcnt lgkmcnt(0)
	v_mfma_f32_16x16x32_bf16 v[118:121], v[84:87], v[92:95], v[126:129]
	v_mfma_f32_16x16x32_bf16 v[126:129], v[88:91], v[96:99], v[118:121]
	v_mfma_f32_16x16x32_bf16 v[28:31], v[108:111], v[96:99], v[28:31]
	v_mfma_f32_16x16x32_bf16 v[28:31], v[104:107], v[92:95], v[28:31]
	v_mfma_f32_16x16x32_bf16 v[24:27], v[104:107], v[100:103], v[24:27]
	v_mfma_f32_16x16x32_bf16 v[24:27], v[108:111], v[188:191], v[24:27]
	v_mfma_f32_16x16x32_bf16 v[20:23], v[108:111], v[196:199], v[20:23]
	v_mfma_f32_16x16x32_bf16 v[20:23], v[104:107], v[192:195], v[20:23]
	v_mfma_f32_16x16x32_bf16 v[112:115], v[84:87], v[192:195], v[114:117]
	v_mfma_f32_16x16x32_bf16 v[114:117], v[88:91], v[196:199], v[112:115]
	v_mfma_f32_16x16x32_bf16 v[72:75], v[88:91], v[204:207], v[72:75]
	v_mfma_f32_16x16x32_bf16 v[72:75], v[84:87], v[200:203], v[72:75]
	v_mfma_f32_16x16x32_bf16 v[118:121], v[84:87], v[100:103], v[122:125]
	v_mfma_f32_16x16x32_bf16 v[122:125], v[88:91], v[188:191], v[118:121]
	v_mfma_f32_16x16x32_bf16 v[4:7], v[104:107], v[200:203], v[4:7]
	v_mfma_f32_16x16x32_bf16 v[4:7], v[108:111], v[204:207], v[4:7]
	s_setprio 0
	s_barrier
	s_add_u32 s8, s12, 0x1600080
	s_addc_u32 s9, s13, 0
	s_add_i32 s12, s42, s46
	s_mov_b32 m0, s12
	s_nop 0
	global_load_lds_dwordx4 v164, s[8:9]
	s_add_i32 m0, s12, 0x2000
	s_nop 0
	global_load_lds_dwordx4 v166, s[8:9]
	s_waitcnt vmcnt(6)
	s_barrier
	s_setprio 1
	v_mfma_f32_16x16x32_bf16 v[76:79], v[208:211], v[92:95], v[76:79]
	v_mfma_f32_16x16x32_bf16 v[118:121], v[212:215], v[96:99], v[76:79]
	v_mfma_f32_16x16x32_bf16 v[16:19], v[234:237], v[96:99], v[16:19]
	v_mfma_f32_16x16x32_bf16 v[16:19], v[216:219], v[92:95], v[16:19]
	v_mfma_f32_16x16x32_bf16 v[12:15], v[216:219], v[100:103], v[12:15]
	v_mfma_f32_16x16x32_bf16 v[12:15], v[234:237], v[188:191], v[12:15]
	v_mfma_f32_16x16x32_bf16 v[8:11], v[234:237], v[196:199], v[8:11]
	v_mfma_f32_16x16x32_bf16 v[8:11], v[216:219], v[192:195], v[8:11]
	v_mfma_f32_16x16x32_bf16 v[68:71], v[208:211], v[192:195], v[68:71]
	v_mfma_f32_16x16x32_bf16 v[68:71], v[212:215], v[196:199], v[68:71]
	v_mfma_f32_16x16x32_bf16 v[64:67], v[212:215], v[204:207], v[64:67]
	v_mfma_f32_16x16x32_bf16 v[64:67], v[208:211], v[200:203], v[64:67]
	v_mfma_f32_16x16x32_bf16 v[76:79], v[208:211], v[100:103], v[80:83]
	v_mfma_f32_16x16x32_bf16 v[110:113], v[212:215], v[188:191], v[76:79]
	v_mfma_f32_16x16x32_bf16 v[0:3], v[216:219], v[200:203], v[0:3]
	v_mfma_f32_16x16x32_bf16 v[0:3], v[234:237], v[204:207], v[0:3]
	s_setprio 0
	s_add_i32 s67, s67, 2
	s_add_u32 s65, s65, 0x100
	s_addc_u32 s66, s66, 0
	s_cmp_gt_u32 s67, 29
	s_mov_b64 s[8:9], s[10:11]
	s_barrier
	s_cbranch_scc0 .LBB0_840
	s_lshl_b32 s8, s0, 8
	s_add_i32 s8, s8, s58
	s_lshl_b32 s9, s1, 7
	s_add_i32 s9, s9, s53
	s_lshl_b32 s10, s0, 3
	s_lshr_b32 s11, s58, 5
	s_add_i32 s10, s10, s11
	v_add_u32_e32 v200, s8, v163
	v_lshlrev_b32_e32 v213, 2, v200
	global_load_dword v188, v213, s[4:5]
	global_load_dword v189, v213, s[4:5] offset:64
	global_load_dword v190, v213, s[4:5] offset:128
	global_load_dword v191, v213, s[4:5] offset:192
	global_load_dword v192, v213, s[4:5] offset:256
	global_load_dword v193, v213, s[4:5] offset:320
	global_load_dword v194, v213, s[4:5] offset:384
	global_load_dword v195, v213, s[4:5] offset:448
	v_lshl_add_u32 v201, v225, 3, s9
	v_lshlrev_b32_e32 v212, 2, v201
	v_add_u32_e32 v213, 0x21000, v212
	global_load_dwordx4 v[76:79], v213, s[82:83]
	v_add_u32_e32 v213, 0x2c000, v212
	global_load_dwordx4 v[80:83], v213, s[82:83]
	v_add_u32_e32 v213, 0x37000, v212
	global_load_dwordx4 v[84:87], v213, s[82:83]
	v_add_u32_e32 v213, 0xb000, v212
	global_load_dwordx4 v[88:91], v213, s[84:85]
	v_add_u32_e32 v213, 0x26800, v212
	global_load_dwordx4 v[92:95], v213, s[82:83]
	v_add_u32_e32 v213, 0x31800, v212
	global_load_dwordx4 v[96:99], v213, s[82:83]
	v_add_u32_e32 v213, 0x3c800, v212
	global_load_dwordx4 v[100:103], v213, s[82:83]
	v_add_u32_e32 v213, 0x10800, v212
	global_load_dwordx4 v[104:107], v213, s[84:85]
	v_mul_u32_u24_e32 v215, 0x2c00, v200
	v_lshl_add_u32 v215, v201, 1, v215
	v_add_u32_e32 v213, s10, v163
	v_mul_u32_u24_e32 v217, 0xb000, v213
	v_add_u32_e32 v217, v217, v212
	v_cmp_gt_u32_e64 s[8:9], 2, v163
	v_cmp_lt_u32_e64 s[10:11], 13, v163
	v_cmp_lt_u32_e32 vcc, 1, v163
	v_mov_b32_e32 v214, 1.0
	v_mov_b32_e32 v216, 0xbfb8aa3b
	v_mov_b32_e32 v108, 0x3727c5ac
	s_waitcnt vmcnt(8)
	v_fmamk_f32 v188, v188, 0x3a000000, v108
	v_fmamk_f32 v189, v189, 0x3a000000, v108
	v_fmamk_f32 v190, v190, 0x3a000000, v108
	v_fmamk_f32 v191, v191, 0x3a000000, v108
	v_fmamk_f32 v192, v192, 0x3a000000, v108
	v_fmamk_f32 v193, v193, 0x3a000000, v108
	v_fmamk_f32 v194, v194, 0x3a000000, v108
	v_fmamk_f32 v195, v195, 0x3a000000, v108
	v_rsq_f32_e32 v188, v188
	v_rsq_f32_e32 v189, v189
	v_rsq_f32_e32 v190, v190
	v_rsq_f32_e32 v191, v191
	v_rsq_f32_e32 v192, v192
	v_rsq_f32_e32 v193, v193
	v_rsq_f32_e32 v194, v194
	v_rsq_f32_e32 v195, v195
	v_pk_mul_f32 v[158:159], v[158:159], v[188:189] op_sel_hi:[1,0]
	v_pk_mul_f32 v[160:161], v[160:161], v[188:189] op_sel_hi:[1,0]
	v_pk_mul_f32 v[60:61], v[60:61], v[188:189] op_sel_hi:[1,0]
	v_pk_mul_f32 v[62:63], v[62:63], v[188:189] op_sel_hi:[1,0]
	v_pk_mul_f32 v[154:155], v[154:155], v[188:189] op_sel_hi:[1,0]
	v_pk_mul_f32 v[156:157], v[156:157], v[188:189] op_sel_hi:[1,0]
	v_pk_mul_f32 v[56:57], v[56:57], v[188:189] op_sel_hi:[1,0]
	v_pk_mul_f32 v[58:59], v[58:59], v[188:189] op_sel_hi:[1,0]
	v_pk_mul_f32 v[150:151], v[150:151], v[188:189] op_sel:[0,1] op_sel_hi:[1,1]
	v_pk_mul_f32 v[152:153], v[152:153], v[188:189] op_sel:[0,1] op_sel_hi:[1,1]
	v_pk_mul_f32 v[52:53], v[52:53], v[188:189] op_sel:[0,1] op_sel_hi:[1,1]
	v_pk_mul_f32 v[54:55], v[54:55], v[188:189] op_sel:[0,1] op_sel_hi:[1,1]
	v_pk_mul_f32 v[142:143], v[142:143], v[188:189] op_sel:[0,1] op_sel_hi:[1,1]
	v_pk_mul_f32 v[144:145], v[144:145], v[188:189] op_sel:[0,1] op_sel_hi:[1,1]
	v_pk_mul_f32 v[44:45], v[44:45], v[188:189] op_sel:[0,1] op_sel_hi:[1,1]
	v_pk_mul_f32 v[46:47], v[46:47], v[188:189] op_sel:[0,1] op_sel_hi:[1,1]
	v_pk_mul_f32 v[146:147], v[146:147], v[190:191] op_sel_hi:[1,0]
	v_pk_mul_f32 v[148:149], v[148:149], v[190:191] op_sel_hi:[1,0]
	v_pk_mul_f32 v[48:49], v[48:49], v[190:191] op_sel_hi:[1,0]
	v_pk_mul_f32 v[50:51], v[50:51], v[190:191] op_sel_hi:[1,0]
	v_pk_mul_f32 v[134:135], v[134:135], v[190:191] op_sel_hi:[1,0]
	v_pk_mul_f32 v[136:137], v[136:137], v[190:191] op_sel_hi:[1,0]
	v_pk_mul_f32 v[36:37], v[36:37], v[190:191] op_sel_hi:[1,0]
	v_pk_mul_f32 v[38:39], v[38:39], v[190:191] op_sel_hi:[1,0]
	v_pk_mul_f32 v[138:139], v[138:139], v[190:191] op_sel:[0,1] op_sel_hi:[1,1]
	v_pk_mul_f32 v[140:141], v[140:141], v[190:191] op_sel:[0,1] op_sel_hi:[1,1]
	v_pk_mul_f32 v[40:41], v[40:41], v[190:191] op_sel:[0,1] op_sel_hi:[1,1]
	v_pk_mul_f32 v[42:43], v[42:43], v[190:191] op_sel:[0,1] op_sel_hi:[1,1]
	v_pk_mul_f32 v[130:131], v[130:131], v[190:191] op_sel:[0,1] op_sel_hi:[1,1]
	v_pk_mul_f32 v[132:133], v[132:133], v[190:191] op_sel:[0,1] op_sel_hi:[1,1]
	v_pk_mul_f32 v[32:33], v[32:33], v[190:191] op_sel:[0,1] op_sel_hi:[1,1]
	v_pk_mul_f32 v[34:35], v[34:35], v[190:191] op_sel:[0,1] op_sel_hi:[1,1]
	v_pk_mul_f32 v[126:127], v[126:127], v[192:193] op_sel_hi:[1,0]
	v_pk_mul_f32 v[128:129], v[128:129], v[192:193] op_sel_hi:[1,0]
	v_pk_mul_f32 v[28:29], v[28:29], v[192:193] op_sel_hi:[1,0]
	v_pk_mul_f32 v[30:31], v[30:31], v[192:193] op_sel_hi:[1,0]
	v_pk_mul_f32 v[118:119], v[118:119], v[192:193] op_sel_hi:[1,0]
	v_pk_mul_f32 v[120:121], v[120:121], v[192:193] op_sel_hi:[1,0]
	v_pk_mul_f32 v[16:17], v[16:17], v[192:193] op_sel_hi:[1,0]
	v_pk_mul_f32 v[18:19], v[18:19], v[192:193] op_sel_hi:[1,0]
	v_pk_mul_f32 v[122:123], v[122:123], v[192:193] op_sel:[0,1] op_sel_hi:[1,1]
	v_pk_mul_f32 v[124:125], v[124:125], v[192:193] op_sel:[0,1] op_sel_hi:[1,1]
	v_pk_mul_f32 v[24:25], v[24:25], v[192:193] op_sel:[0,1] op_sel_hi:[1,1]
	v_pk_mul_f32 v[26:27], v[26:27], v[192:193] op_sel:[0,1] op_sel_hi:[1,1]
	v_pk_mul_f32 v[110:111], v[110:111], v[192:193] op_sel:[0,1] op_sel_hi:[1,1]
	v_pk_mul_f32 v[112:113], v[112:113], v[192:193] op_sel:[0,1] op_sel_hi:[1,1]
	v_pk_mul_f32 v[12:13], v[12:13], v[192:193] op_sel:[0,1] op_sel_hi:[1,1]
	v_pk_mul_f32 v[14:15], v[14:15], v[192:193] op_sel:[0,1] op_sel_hi:[1,1]
	v_pk_mul_f32 v[114:115], v[114:115], v[194:195] op_sel_hi:[1,0]
	v_pk_mul_f32 v[116:117], v[116:117], v[194:195] op_sel_hi:[1,0]
	v_pk_mul_f32 v[20:21], v[20:21], v[194:195] op_sel_hi:[1,0]
	v_pk_mul_f32 v[22:23], v[22:23], v[194:195] op_sel_hi:[1,0]
	v_pk_mul_f32 v[68:69], v[68:69], v[194:195] op_sel_hi:[1,0]
	v_pk_mul_f32 v[70:71], v[70:71], v[194:195] op_sel_hi:[1,0]
	v_pk_mul_f32 v[8:9], v[8:9], v[194:195] op_sel_hi:[1,0]
	v_pk_mul_f32 v[10:11], v[10:11], v[194:195] op_sel_hi:[1,0]
	v_pk_mul_f32 v[72:73], v[72:73], v[194:195] op_sel:[0,1] op_sel_hi:[1,1]
	v_pk_mul_f32 v[74:75], v[74:75], v[194:195] op_sel:[0,1] op_sel_hi:[1,1]
	v_pk_mul_f32 v[4:5], v[4:5], v[194:195] op_sel:[0,1] op_sel_hi:[1,1]
	v_pk_mul_f32 v[6:7], v[6:7], v[194:195] op_sel:[0,1] op_sel_hi:[1,1]
	v_pk_mul_f32 v[64:65], v[64:65], v[194:195] op_sel:[0,1] op_sel_hi:[1,1]
	v_pk_mul_f32 v[66:67], v[66:67], v[194:195] op_sel:[0,1] op_sel_hi:[1,1]
	v_pk_mul_f32 v[0:1], v[0:1], v[194:195] op_sel:[0,1] op_sel_hi:[1,1]
	v_pk_mul_f32 v[2:3], v[2:3], v[194:195] op_sel:[0,1] op_sel_hi:[1,1]
	s_nop 1
	s_mov_b64 exec, s[8:9]
	v_add_u32_e32 v213, 0x5800, v217
	global_store_dwordx4 v217, v[158:161], s[70:71]
	global_store_dwordx4 v213, v[154:157], s[70:71]
	global_store_dwordx4 v217, v[60:63], s[70:71] offset:16
	global_store_dwordx4 v213, v[56:59], s[70:71] offset:16
	s_mov_b64 exec, s[10:11]
	v_add_u32_e32 v213, 0xfff7c000, v217
	global_store_dwordx4 v213, v[72:75], s[70:71]
	global_store_dwordx4 v213, v[4:7], s[70:71] offset:16
	v_add_u32_e32 v213, 0xfff81800, v217
	global_store_dwordx4 v213, v[64:67], s[70:71]
	global_store_dwordx4 v213, v[0:3], s[70:71] offset:16
	s_mov_b64 exec, -1
	v_add_u32_e32 v213, 0x3c800, v212
	global_load_dwordx4 v[204:207], v213, s[82:83] offset:16
	v_add_u32_e32 v213, 0x10800, v212
	global_load_dwordx4 v[208:211], v213, s[84:85] offset:16
	s_waitcnt vmcnt(10)
	v_pk_fma_f32 v[188:189], v[158:159], v[84:85], v[88:89]
	v_pk_fma_f32 v[190:191], v[160:161], v[86:87], v[90:91]
	v_pk_fma_f32 v[192:193], v[154:155], v[100:101], v[104:105]
	v_pk_fma_f32 v[194:195], v[156:157], v[102:103], v[106:107]
	v_fmac_f32_dpp v188, v158, v80 row_shr:1 row_mask:0xf bank_mask:0xf
	v_fmac_f32_dpp v189, v159, v81 row_shr:1 row_mask:0xf bank_mask:0xf
	v_fmac_f32_dpp v190, v160, v82 row_shr:1 row_mask:0xf bank_mask:0xf
	v_fmac_f32_dpp v191, v161, v83 row_shr:1 row_mask:0xf bank_mask:0xf
	v_fmac_f32_dpp v192, v154, v96 row_shr:1 row_mask:0xf bank_mask:0xf
	v_fmac_f32_dpp v193, v155, v97 row_shr:1 row_mask:0xf bank_mask:0xf
	v_fmac_f32_dpp v194, v156, v98 row_shr:1 row_mask:0xf bank_mask:0xf
	v_fmac_f32_dpp v195, v157, v99 row_shr:1 row_mask:0xf bank_mask:0xf
	v_fmac_f32_dpp v188, v158, v76 row_shr:2 row_mask:0xf bank_mask:0xf
	v_fmac_f32_dpp v189, v159, v77 row_shr:2 row_mask:0xf bank_mask:0xf
	v_fmac_f32_dpp v190, v160, v78 row_shr:2 row_mask:0xf bank_mask:0xf
	v_fmac_f32_dpp v191, v161, v79 row_shr:2 row_mask:0xf bank_mask:0xf
	v_fmac_f32_dpp v192, v154, v92 row_shr:2 row_mask:0xf bank_mask:0xf
	v_fmac_f32_dpp v193, v155, v93 row_shr:2 row_mask:0xf bank_mask:0xf
	v_fmac_f32_dpp v194, v156, v94 row_shr:2 row_mask:0xf bank_mask:0xf
	v_fmac_f32_dpp v195, v157, v95 row_shr:2 row_mask:0xf bank_mask:0xf
	v_pk_mul_f32 v[196:197], v[188:189], v[216:217] op_sel_hi:[1,0]
	v_pk_mul_f32 v[198:199], v[190:191], v[216:217] op_sel_hi:[1,0]
	v_exp_f32_e32 v196, v196
	v_exp_f32_e32 v197, v197
	v_exp_f32_e32 v198, v198
	v_exp_f32_e32 v199, v199
	v_pk_add_f32 v[196:197], v[196:197], v[214:215] op_sel_hi:[1,0]
	v_pk_add_f32 v[198:199], v[198:199], v[214:215] op_sel_hi:[1,0]
	v_rcp_f32_e32 v196, v196
	v_rcp_f32_e32 v197, v197
	v_rcp_f32_e32 v198, v198
	v_rcp_f32_e32 v199, v199
	v_pk_mul_f32 v[188:189], v[188:189], v[196:197]
	v_pk_mul_f32 v[190:191], v[190:191], v[198:199]
	v_pk_mul_f32 v[188:189], v[188:189], v[192:193]
	v_pk_mul_f32 v[190:191], v[190:191], v[194:195]
	v_cvt_pk_bf16_f32 v200, v188, v189
	v_cvt_pk_bf16_f32 v201, v190, v191
	v_pk_fma_f32 v[188:189], v[150:151], v[84:85], v[88:89]
	v_pk_fma_f32 v[190:191], v[152:153], v[86:87], v[90:91]
	v_pk_fma_f32 v[192:193], v[142:143], v[100:101], v[104:105]
	v_pk_fma_f32 v[194:195], v[144:145], v[102:103], v[106:107]
	v_fmac_f32_dpp v188, v150, v80 row_shr:1 row_mask:0xf bank_mask:0xf
	v_fmac_f32_dpp v189, v151, v81 row_shr:1 row_mask:0xf bank_mask:0xf
	v_fmac_f32_dpp v190, v152, v82 row_shr:1 row_mask:0xf bank_mask:0xf
	v_fmac_f32_dpp v191, v153, v83 row_shr:1 row_mask:0xf bank_mask:0xf
	v_fmac_f32_dpp v192, v142, v96 row_shr:1 row_mask:0xf bank_mask:0xf
	v_fmac_f32_dpp v193, v143, v97 row_shr:1 row_mask:0xf bank_mask:0xf
	v_fmac_f32_dpp v194, v144, v98 row_shr:1 row_mask:0xf bank_mask:0xf
	v_fmac_f32_dpp v195, v145, v99 row_shr:1 row_mask:0xf bank_mask:0xf
	v_fmac_f32_dpp v188, v150, v76 row_shr:2 row_mask:0xf bank_mask:0xf
	v_fmac_f32_dpp v189, v151, v77 row_shr:2 row_mask:0xf bank_mask:0xf
	v_fmac_f32_dpp v190, v152, v78 row_shr:2 row_mask:0xf bank_mask:0xf
	v_fmac_f32_dpp v191, v153, v79 row_shr:2 row_mask:0xf bank_mask:0xf
	v_fmac_f32_dpp v192, v142, v92 row_shr:2 row_mask:0xf bank_mask:0xf
	v_fmac_f32_dpp v193, v143, v93 row_shr:2 row_mask:0xf bank_mask:0xf
	v_fmac_f32_dpp v194, v144, v94 row_shr:2 row_mask:0xf bank_mask:0xf
	v_fmac_f32_dpp v195, v145, v95 row_shr:2 row_mask:0xf bank_mask:0xf
	v_fmac_f32_dpp v188, v158, v80 row_shl:15 row_mask:0xf bank_mask:0xf
	v_fmac_f32_dpp v189, v159, v81 row_shl:15 row_mask:0xf bank_mask:0xf
	v_fmac_f32_dpp v190, v160, v82 row_shl:15 row_mask:0xf bank_mask:0xf
	v_fmac_f32_dpp v191, v161, v83 row_shl:15 row_mask:0xf bank_mask:0xf
	v_fmac_f32_dpp v192, v154, v96 row_shl:15 row_mask:0xf bank_mask:0xf
	v_fmac_f32_dpp v193, v155, v97 row_shl:15 row_mask:0xf bank_mask:0xf
	v_fmac_f32_dpp v194, v156, v98 row_shl:15 row_mask:0xf bank_mask:0xf
	v_fmac_f32_dpp v195, v157, v99 row_shl:15 row_mask:0xf bank_mask:0xf
	v_fmac_f32_dpp v188, v158, v76 row_shl:14 row_mask:0xf bank_mask:0xf
	v_fmac_f32_dpp v189, v159, v77 row_shl:14 row_mask:0xf bank_mask:0xf
	v_fmac_f32_dpp v190, v160, v78 row_shl:14 row_mask:0xf bank_mask:0xf
	v_fmac_f32_dpp v191, v161, v79 row_shl:14 row_mask:0xf bank_mask:0xf
	v_fmac_f32_dpp v192, v154, v92 row_shl:14 row_mask:0xf bank_mask:0xf
	v_fmac_f32_dpp v193, v155, v93 row_shl:14 row_mask:0xf bank_mask:0xf
	v_fmac_f32_dpp v194, v156, v94 row_shl:14 row_mask:0xf bank_mask:0xf
	v_fmac_f32_dpp v195, v157, v95 row_shl:14 row_mask:0xf bank_mask:0xf
	v_pk_mul_f32 v[196:197], v[188:189], v[216:217] op_sel_hi:[1,0]
	v_pk_mul_f32 v[198:199], v[190:191], v[216:217] op_sel_hi:[1,0]
	v_exp_f32_e32 v196, v196
	v_exp_f32_e32 v197, v197
	v_exp_f32_e32 v198, v198
	v_exp_f32_e32 v199, v199
	v_pk_add_f32 v[196:197], v[196:197], v[214:215] op_sel_hi:[1,0]
	v_pk_add_f32 v[198:199], v[198:199], v[214:215] op_sel_hi:[1,0]
	v_rcp_f32_e32 v196, v196
	v_rcp_f32_e32 v197, v197
	v_rcp_f32_e32 v198, v198
	v_rcp_f32_e32 v199, v199
	v_pk_mul_f32 v[188:189], v[188:189], v[196:197]
	v_pk_mul_f32 v[190:191], v[190:191], v[198:199]
	v_pk_mul_f32 v[188:189], v[188:189], v[192:193]
	v_pk_mul_f32 v[190:191], v[190:191], v[194:195]
	v_cvt_pk_bf16_f32 v158, v188, v189
	v_cvt_pk_bf16_f32 v159, v190, v191
	v_add_u32_e32 v213, 0x21000, v212
	global_load_dwordx4 v[154:157], v213, s[82:83] offset:16
	v_pk_fma_f32 v[188:189], v[146:147], v[84:85], v[88:89]
	v_pk_fma_f32 v[190:191], v[148:149], v[86:87], v[90:91]
	v_pk_fma_f32 v[192:193], v[134:135], v[100:101], v[104:105]
	v_pk_fma_f32 v[194:195], v[136:137], v[102:103], v[106:107]
	v_fmac_f32_dpp v188, v146, v80 row_shr:1 row_mask:0xf bank_mask:0xf
	v_fmac_f32_dpp v189, v147, v81 row_shr:1 row_mask:0xf bank_mask:0xf
	v_fmac_f32_dpp v190, v148, v82 row_shr:1 row_mask:0xf bank_mask:0xf
	v_fmac_f32_dpp v191, v149, v83 row_shr:1 row_mask:0xf bank_mask:0xf
	v_fmac_f32_dpp v192, v134, v96 row_shr:1 row_mask:0xf bank_mask:0xf
	v_fmac_f32_dpp v193, v135, v97 row_shr:1 row_mask:0xf bank_mask:0xf
	v_fmac_f32_dpp v194, v136, v98 row_shr:1 row_mask:0xf bank_mask:0xf
	v_fmac_f32_dpp v195, v137, v99 row_shr:1 row_mask:0xf bank_mask:0xf
	v_fmac_f32_dpp v188, v146, v76 row_shr:2 row_mask:0xf bank_mask:0xf
	v_fmac_f32_dpp v189, v147, v77 row_shr:2 row_mask:0xf bank_mask:0xf
	v_fmac_f32_dpp v190, v148, v78 row_shr:2 row_mask:0xf bank_mask:0xf
	v_fmac_f32_dpp v191, v149, v79 row_shr:2 row_mask:0xf bank_mask:0xf
	v_fmac_f32_dpp v192, v134, v92 row_shr:2 row_mask:0xf bank_mask:0xf
	v_fmac_f32_dpp v193, v135, v93 row_shr:2 row_mask:0xf bank_mask:0xf
	v_fmac_f32_dpp v194, v136, v94 row_shr:2 row_mask:0xf bank_mask:0xf
	v_fmac_f32_dpp v195, v137, v95 row_shr:2 row_mask:0xf bank_mask:0xf
	v_fmac_f32_dpp v188, v150, v80 row_shl:15 row_mask:0xf bank_mask:0xf
	v_fmac_f32_dpp v189, v151, v81 row_shl:15 row_mask:0xf bank_mask:0xf
	v_fmac_f32_dpp v190, v152, v82 row_shl:15 row_mask:0xf bank_mask:0xf
	v_fmac_f32_dpp v191, v153, v83 row_shl:15 row_mask:0xf bank_mask:0xf
	v_fmac_f32_dpp v192, v142, v96 row_shl:15 row_mask:0xf bank_mask:0xf
	v_fmac_f32_dpp v193, v143, v97 row_shl:15 row_mask:0xf bank_mask:0xf
	v_fmac_f32_dpp v194, v144, v98 row_shl:15 row_mask:0xf bank_mask:0xf
	v_fmac_f32_dpp v195, v145, v99 row_shl:15 row_mask:0xf bank_mask:0xf
	v_fmac_f32_dpp v188, v150, v76 row_shl:14 row_mask:0xf bank_mask:0xf
	v_fmac_f32_dpp v189, v151, v77 row_shl:14 row_mask:0xf bank_mask:0xf
	v_fmac_f32_dpp v190, v152, v78 row_shl:14 row_mask:0xf bank_mask:0xf
	v_fmac_f32_dpp v191, v153, v79 row_shl:14 row_mask:0xf bank_mask:0xf
	v_fmac_f32_dpp v192, v142, v92 row_shl:14 row_mask:0xf bank_mask:0xf
	v_fmac_f32_dpp v193, v143, v93 row_shl:14 row_mask:0xf bank_mask:0xf
	v_fmac_f32_dpp v194, v144, v94 row_shl:14 row_mask:0xf bank_mask:0xf
	v_fmac_f32_dpp v195, v145, v95 row_shl:14 row_mask:0xf bank_mask:0xf
	v_pk_mul_f32 v[196:197], v[188:189], v[216:217] op_sel_hi:[1,0]
	v_pk_mul_f32 v[198:199], v[190:191], v[216:217] op_sel_hi:[1,0]
	v_exp_f32_e32 v196, v196
	v_exp_f32_e32 v197, v197
	v_exp_f32_e32 v198, v198
	v_exp_f32_e32 v199, v199
	v_pk_add_f32 v[196:197], v[196:197], v[214:215] op_sel_hi:[1,0]
	v_pk_add_f32 v[198:199], v[198:199], v[214:215] op_sel_hi:[1,0]
	v_rcp_f32_e32 v196, v196
	v_rcp_f32_e32 v197, v197
	v_rcp_f32_e32 v198, v198
	v_rcp_f32_e32 v199, v199
	v_pk_mul_f32 v[188:189], v[188:189], v[196:197]
	v_pk_mul_f32 v[190:191], v[190:191], v[198:199]
	v_pk_mul_f32 v[188:189], v[188:189], v[192:193]
	v_pk_mul_f32 v[190:191], v[190:191], v[194:195]
	v_cvt_pk_bf16_f32 v150, v188, v189
	v_cvt_pk_bf16_f32 v151, v190, v191
	v_add_u32_e32 v213, 0x2c000, v212
	global_load_dwordx4 v[142:145], v213, s[82:83] offset:16
	v_pk_fma_f32 v[188:189], v[138:139], v[84:85], v[88:89]
	v_pk_fma_f32 v[190:191], v[140:141], v[86:87], v[90:91]
	v_pk_fma_f32 v[192:193], v[130:131], v[100:101], v[104:105]
	v_pk_fma_f32 v[194:195], v[132:133], v[102:103], v[106:107]
	v_fmac_f32_dpp v188, v138, v80 row_shr:1 row_mask:0xf bank_mask:0xf
	v_fmac_f32_dpp v189, v139, v81 row_shr:1 row_mask:0xf bank_mask:0xf
	v_fmac_f32_dpp v190, v140, v82 row_shr:1 row_mask:0xf bank_mask:0xf
	v_fmac_f32_dpp v191, v141, v83 row_shr:1 row_mask:0xf bank_mask:0xf
	v_fmac_f32_dpp v192, v130, v96 row_shr:1 row_mask:0xf bank_mask:0xf
	v_fmac_f32_dpp v193, v131, v97 row_shr:1 row_mask:0xf bank_mask:0xf
	v_fmac_f32_dpp v194, v132, v98 row_shr:1 row_mask:0xf bank_mask:0xf
	v_fmac_f32_dpp v195, v133, v99 row_shr:1 row_mask:0xf bank_mask:0xf
	v_fmac_f32_dpp v188, v138, v76 row_shr:2 row_mask:0xf bank_mask:0xf
	v_fmac_f32_dpp v189, v139, v77 row_shr:2 row_mask:0xf bank_mask:0xf
	v_fmac_f32_dpp v190, v140, v78 row_shr:2 row_mask:0xf bank_mask:0xf
	v_fmac_f32_dpp v191, v141, v79 row_shr:2 row_mask:0xf bank_mask:0xf
	v_fmac_f32_dpp v192, v130, v92 row_shr:2 row_mask:0xf bank_mask:0xf
	v_fmac_f32_dpp v193, v131, v93 row_shr:2 row_mask:0xf bank_mask:0xf
	v_fmac_f32_dpp v194, v132, v94 row_shr:2 row_mask:0xf bank_mask:0xf
	v_fmac_f32_dpp v195, v133, v95 row_shr:2 row_mask:0xf bank_mask:0xf
	v_fmac_f32_dpp v188, v146, v80 row_shl:15 row_mask:0xf bank_mask:0xf
	v_fmac_f32_dpp v189, v147, v81 row_shl:15 row_mask:0xf bank_mask:0xf
	v_fmac_f32_dpp v190, v148, v82 row_shl:15 row_mask:0xf bank_mask:0xf
	v_fmac_f32_dpp v191, v149, v83 row_shl:15 row_mask:0xf bank_mask:0xf
	v_fmac_f32_dpp v192, v134, v96 row_shl:15 row_mask:0xf bank_mask:0xf
	v_fmac_f32_dpp v193, v135, v97 row_shl:15 row_mask:0xf bank_mask:0xf
	v_fmac_f32_dpp v194, v136, v98 row_shl:15 row_mask:0xf bank_mask:0xf
	v_fmac_f32_dpp v195, v137, v99 row_shl:15 row_mask:0xf bank_mask:0xf
	v_fmac_f32_dpp v188, v146, v76 row_shl:14 row_mask:0xf bank_mask:0xf
	v_fmac_f32_dpp v189, v147, v77 row_shl:14 row_mask:0xf bank_mask:0xf
	v_fmac_f32_dpp v190, v148, v78 row_shl:14 row_mask:0xf bank_mask:0xf
	v_fmac_f32_dpp v191, v149, v79 row_shl:14 row_mask:0xf bank_mask:0xf
	v_fmac_f32_dpp v192, v134, v92 row_shl:14 row_mask:0xf bank_mask:0xf
	v_fmac_f32_dpp v193, v135, v93 row_shl:14 row_mask:0xf bank_mask:0xf
	v_fmac_f32_dpp v194, v136, v94 row_shl:14 row_mask:0xf bank_mask:0xf
	v_fmac_f32_dpp v195, v137, v95 row_shl:14 row_mask:0xf bank_mask:0xf
	v_pk_mul_f32 v[196:197], v[188:189], v[216:217] op_sel_hi:[1,0]
	v_pk_mul_f32 v[198:199], v[190:191], v[216:217] op_sel_hi:[1,0]
	v_exp_f32_e32 v196, v196
	v_exp_f32_e32 v197, v197
	v_exp_f32_e32 v198, v198
	v_exp_f32_e32 v199, v199
	v_pk_add_f32 v[196:197], v[196:197], v[214:215] op_sel_hi:[1,0]
	v_pk_add_f32 v[198:199], v[198:199], v[214:215] op_sel_hi:[1,0]
	v_rcp_f32_e32 v196, v196
	v_rcp_f32_e32 v197, v197
	v_rcp_f32_e32 v198, v198
	v_rcp_f32_e32 v199, v199
	v_pk_mul_f32 v[188:189], v[188:189], v[196:197]
	v_pk_mul_f32 v[190:191], v[190:191], v[198:199]
	v_pk_mul_f32 v[188:189], v[188:189], v[192:193]
	v_pk_mul_f32 v[190:191], v[190:191], v[194:195]
	v_cvt_pk_bf16_f32 v146, v188, v189
	v_cvt_pk_bf16_f32 v147, v190, v191
	v_add_u32_e32 v213, 0x37000, v212
	global_load_dwordx4 v[134:137], v213, s[82:83] offset:16
	v_pk_fma_f32 v[188:189], v[126:127], v[84:85], v[88:89]
	v_pk_fma_f32 v[190:191], v[128:129], v[86:87], v[90:91]
	v_pk_fma_f32 v[192:193], v[118:119], v[100:101], v[104:105]
	v_pk_fma_f32 v[194:195], v[120:121], v[102:103], v[106:107]
	v_fmac_f32_dpp v188, v126, v80 row_shr:1 row_mask:0xf bank_mask:0xf
	v_fmac_f32_dpp v189, v127, v81 row_shr:1 row_mask:0xf bank_mask:0xf
	v_fmac_f32_dpp v190, v128, v82 row_shr:1 row_mask:0xf bank_mask:0xf
	v_fmac_f32_dpp v191, v129, v83 row_shr:1 row_mask:0xf bank_mask:0xf
	v_fmac_f32_dpp v192, v118, v96 row_shr:1 row_mask:0xf bank_mask:0xf
	v_fmac_f32_dpp v193, v119, v97 row_shr:1 row_mask:0xf bank_mask:0xf
	v_fmac_f32_dpp v194, v120, v98 row_shr:1 row_mask:0xf bank_mask:0xf
	v_fmac_f32_dpp v195, v121, v99 row_shr:1 row_mask:0xf bank_mask:0xf
	v_fmac_f32_dpp v188, v126, v76 row_shr:2 row_mask:0xf bank_mask:0xf
	v_fmac_f32_dpp v189, v127, v77 row_shr:2 row_mask:0xf bank_mask:0xf
	v_fmac_f32_dpp v190, v128, v78 row_shr:2 row_mask:0xf bank_mask:0xf
	v_fmac_f32_dpp v191, v129, v79 row_shr:2 row_mask:0xf bank_mask:0xf
	v_fmac_f32_dpp v192, v118, v92 row_shr:2 row_mask:0xf bank_mask:0xf
	v_fmac_f32_dpp v193, v119, v93 row_shr:2 row_mask:0xf bank_mask:0xf
	v_fmac_f32_dpp v194, v120, v94 row_shr:2 row_mask:0xf bank_mask:0xf
	v_fmac_f32_dpp v195, v121, v95 row_shr:2 row_mask:0xf bank_mask:0xf
	v_fmac_f32_dpp v188, v138, v80 row_shl:15 row_mask:0xf bank_mask:0xf
	v_fmac_f32_dpp v189, v139, v81 row_shl:15 row_mask:0xf bank_mask:0xf
	v_fmac_f32_dpp v190, v140, v82 row_shl:15 row_mask:0xf bank_mask:0xf
	v_fmac_f32_dpp v191, v141, v83 row_shl:15 row_mask:0xf bank_mask:0xf
	v_fmac_f32_dpp v192, v130, v96 row_shl:15 row_mask:0xf bank_mask:0xf
	v_fmac_f32_dpp v193, v131, v97 row_shl:15 row_mask:0xf bank_mask:0xf
	v_fmac_f32_dpp v194, v132, v98 row_shl:15 row_mask:0xf bank_mask:0xf
	v_fmac_f32_dpp v195, v133, v99 row_shl:15 row_mask:0xf bank_mask:0xf
	v_fmac_f32_dpp v188, v138, v76 row_shl:14 row_mask:0xf bank_mask:0xf
	v_fmac_f32_dpp v189, v139, v77 row_shl:14 row_mask:0xf bank_mask:0xf
	v_fmac_f32_dpp v190, v140, v78 row_shl:14 row_mask:0xf bank_mask:0xf
	v_fmac_f32_dpp v191, v141, v79 row_shl:14 row_mask:0xf bank_mask:0xf
	v_fmac_f32_dpp v192, v130, v92 row_shl:14 row_mask:0xf bank_mask:0xf
	v_fmac_f32_dpp v193, v131, v93 row_shl:14 row_mask:0xf bank_mask:0xf
	v_fmac_f32_dpp v194, v132, v94 row_shl:14 row_mask:0xf bank_mask:0xf
	v_fmac_f32_dpp v195, v133, v95 row_shl:14 row_mask:0xf bank_mask:0xf
	v_pk_mul_f32 v[196:197], v[188:189], v[216:217] op_sel_hi:[1,0]
	v_pk_mul_f32 v[198:199], v[190:191], v[216:217] op_sel_hi:[1,0]
	v_exp_f32_e32 v196, v196
	v_exp_f32_e32 v197, v197
	v_exp_f32_e32 v198, v198
	v_exp_f32_e32 v199, v199
	v_pk_add_f32 v[196:197], v[196:197], v[214:215] op_sel_hi:[1,0]
	v_pk_add_f32 v[198:199], v[198:199], v[214:215] op_sel_hi:[1,0]
	v_rcp_f32_e32 v196, v196
	v_rcp_f32_e32 v197, v197
	v_rcp_f32_e32 v198, v198
	v_rcp_f32_e32 v199, v199
	v_pk_mul_f32 v[188:189], v[188:189], v[196:197]
	v_pk_mul_f32 v[190:191], v[190:191], v[198:199]
	v_pk_mul_f32 v[188:189], v[188:189], v[192:193]
	v_pk_mul_f32 v[190:191], v[190:191], v[194:195]
	v_cvt_pk_bf16_f32 v138, v188, v189
	v_cvt_pk_bf16_f32 v139, v190, v191
	v_add_u32_e32 v213, 0xb000, v212
	global_load_dwordx4 v[130:133], v213, s[84:85] offset:16
	v_pk_fma_f32 v[188:189], v[122:123], v[84:85], v[88:89]
	v_pk_fma_f32 v[190:191], v[124:125], v[86:87], v[90:91]
	v_pk_fma_f32 v[192:193], v[110:111], v[100:101], v[104:105]
	v_pk_fma_f32 v[194:195], v[112:113], v[102:103], v[106:107]
	v_fmac_f32_dpp v188, v122, v80 row_shr:1 row_mask:0xf bank_mask:0xf
	v_fmac_f32_dpp v189, v123, v81 row_shr:1 row_mask:0xf bank_mask:0xf
	v_fmac_f32_dpp v190, v124, v82 row_shr:1 row_mask:0xf bank_mask:0xf
	v_fmac_f32_dpp v191, v125, v83 row_shr:1 row_mask:0xf bank_mask:0xf
	v_fmac_f32_dpp v192, v110, v96 row_shr:1 row_mask:0xf bank_mask:0xf
	v_fmac_f32_dpp v193, v111, v97 row_shr:1 row_mask:0xf bank_mask:0xf
	v_fmac_f32_dpp v194, v112, v98 row_shr:1 row_mask:0xf bank_mask:0xf
	v_fmac_f32_dpp v195, v113, v99 row_shr:1 row_mask:0xf bank_mask:0xf
	v_fmac_f32_dpp v188, v122, v76 row_shr:2 row_mask:0xf bank_mask:0xf
	v_fmac_f32_dpp v189, v123, v77 row_shr:2 row_mask:0xf bank_mask:0xf
	v_fmac_f32_dpp v190, v124, v78 row_shr:2 row_mask:0xf bank_mask:0xf
	v_fmac_f32_dpp v191, v125, v79 row_shr:2 row_mask:0xf bank_mask:0xf
	v_fmac_f32_dpp v192, v110, v92 row_shr:2 row_mask:0xf bank_mask:0xf
	v_fmac_f32_dpp v193, v111, v93 row_shr:2 row_mask:0xf bank_mask:0xf
	v_fmac_f32_dpp v194, v112, v94 row_shr:2 row_mask:0xf bank_mask:0xf
	v_fmac_f32_dpp v195, v113, v95 row_shr:2 row_mask:0xf bank_mask:0xf
	v_fmac_f32_dpp v188, v126, v80 row_shl:15 row_mask:0xf bank_mask:0xf
	v_fmac_f32_dpp v189, v127, v81 row_shl:15 row_mask:0xf bank_mask:0xf
	v_fmac_f32_dpp v190, v128, v82 row_shl:15 row_mask:0xf bank_mask:0xf
	v_fmac_f32_dpp v191, v129, v83 row_shl:15 row_mask:0xf bank_mask:0xf
	v_fmac_f32_dpp v192, v118, v96 row_shl:15 row_mask:0xf bank_mask:0xf
	v_fmac_f32_dpp v193, v119, v97 row_shl:15 row_mask:0xf bank_mask:0xf
	v_fmac_f32_dpp v194, v120, v98 row_shl:15 row_mask:0xf bank_mask:0xf
	v_fmac_f32_dpp v195, v121, v99 row_shl:15 row_mask:0xf bank_mask:0xf
	v_fmac_f32_dpp v188, v126, v76 row_shl:14 row_mask:0xf bank_mask:0xf
	v_fmac_f32_dpp v189, v127, v77 row_shl:14 row_mask:0xf bank_mask:0xf
	v_fmac_f32_dpp v190, v128, v78 row_shl:14 row_mask:0xf bank_mask:0xf
	v_fmac_f32_dpp v191, v129, v79 row_shl:14 row_mask:0xf bank_mask:0xf
	v_fmac_f32_dpp v192, v118, v92 row_shl:14 row_mask:0xf bank_mask:0xf
	v_fmac_f32_dpp v193, v119, v93 row_shl:14 row_mask:0xf bank_mask:0xf
	v_fmac_f32_dpp v194, v120, v94 row_shl:14 row_mask:0xf bank_mask:0xf
	v_fmac_f32_dpp v195, v121, v95 row_shl:14 row_mask:0xf bank_mask:0xf
	v_pk_mul_f32 v[196:197], v[188:189], v[216:217] op_sel_hi:[1,0]
	v_pk_mul_f32 v[198:199], v[190:191], v[216:217] op_sel_hi:[1,0]
	v_exp_f32_e32 v196, v196
	v_exp_f32_e32 v197, v197
	v_exp_f32_e32 v198, v198
	v_exp_f32_e32 v199, v199
	v_pk_add_f32 v[196:197], v[196:197], v[214:215] op_sel_hi:[1,0]
	v_pk_add_f32 v[198:199], v[198:199], v[214:215] op_sel_hi:[1,0]
	v_rcp_f32_e32 v196, v196
	v_rcp_f32_e32 v197, v197
	v_rcp_f32_e32 v198, v198
	v_rcp_f32_e32 v199, v199
	v_pk_mul_f32 v[188:189], v[188:189], v[196:197]
	v_pk_mul_f32 v[190:191], v[190:191], v[198:199]
	v_pk_mul_f32 v[188:189], v[188:189], v[192:193]
	v_pk_mul_f32 v[190:191], v[190:191], v[194:195]
	v_cvt_pk_bf16_f32 v126, v188, v189
	v_cvt_pk_bf16_f32 v127, v190, v191
	v_add_u32_e32 v213, 0x26800, v212
	global_load_dwordx4 v[118:121], v213, s[82:83] offset:16
	v_pk_fma_f32 v[188:189], v[114:115], v[84:85], v[88:89]
	v_pk_fma_f32 v[190:191], v[116:117], v[86:87], v[90:91]
	v_pk_fma_f32 v[192:193], v[68:69], v[100:101], v[104:105]
	v_pk_fma_f32 v[194:195], v[70:71], v[102:103], v[106:107]
	v_fmac_f32_dpp v188, v114, v80 row_shr:1 row_mask:0xf bank_mask:0xf
	v_fmac_f32_dpp v189, v115, v81 row_shr:1 row_mask:0xf bank_mask:0xf
	v_fmac_f32_dpp v190, v116, v82 row_shr:1 row_mask:0xf bank_mask:0xf
	v_fmac_f32_dpp v191, v117, v83 row_shr:1 row_mask:0xf bank_mask:0xf
	v_fmac_f32_dpp v192, v68, v96 row_shr:1 row_mask:0xf bank_mask:0xf
	v_fmac_f32_dpp v193, v69, v97 row_shr:1 row_mask:0xf bank_mask:0xf
	v_fmac_f32_dpp v194, v70, v98 row_shr:1 row_mask:0xf bank_mask:0xf
	v_fmac_f32_dpp v195, v71, v99 row_shr:1 row_mask:0xf bank_mask:0xf
	v_fmac_f32_dpp v188, v114, v76 row_shr:2 row_mask:0xf bank_mask:0xf
	v_fmac_f32_dpp v189, v115, v77 row_shr:2 row_mask:0xf bank_mask:0xf
	v_fmac_f32_dpp v190, v116, v78 row_shr:2 row_mask:0xf bank_mask:0xf
	v_fmac_f32_dpp v191, v117, v79 row_shr:2 row_mask:0xf bank_mask:0xf
	v_fmac_f32_dpp v192, v68, v92 row_shr:2 row_mask:0xf bank_mask:0xf
	v_fmac_f32_dpp v193, v69, v93 row_shr:2 row_mask:0xf bank_mask:0xf
	v_fmac_f32_dpp v194, v70, v94 row_shr:2 row_mask:0xf bank_mask:0xf
	v_fmac_f32_dpp v195, v71, v95 row_shr:2 row_mask:0xf bank_mask:0xf
	v_fmac_f32_dpp v188, v122, v80 row_shl:15 row_mask:0xf bank_mask:0xf
	v_fmac_f32_dpp v189, v123, v81 row_shl:15 row_mask:0xf bank_mask:0xf
	v_fmac_f32_dpp v190, v124, v82 row_shl:15 row_mask:0xf bank_mask:0xf
	v_fmac_f32_dpp v191, v125, v83 row_shl:15 row_mask:0xf bank_mask:0xf
	v_fmac_f32_dpp v192, v110, v96 row_shl:15 row_mask:0xf bank_mask:0xf
	v_fmac_f32_dpp v193, v111, v97 row_shl:15 row_mask:0xf bank_mask:0xf
	v_fmac_f32_dpp v194, v112, v98 row_shl:15 row_mask:0xf bank_mask:0xf
	v_fmac_f32_dpp v195, v113, v99 row_shl:15 row_mask:0xf bank_mask:0xf
	v_fmac_f32_dpp v188, v122, v76 row_shl:14 row_mask:0xf bank_mask:0xf
	v_fmac_f32_dpp v189, v123, v77 row_shl:14 row_mask:0xf bank_mask:0xf
	v_fmac_f32_dpp v190, v124, v78 row_shl:14 row_mask:0xf bank_mask:0xf
	v_fmac_f32_dpp v191, v125, v79 row_shl:14 row_mask:0xf bank_mask:0xf
	v_fmac_f32_dpp v192, v110, v92 row_shl:14 row_mask:0xf bank_mask:0xf
	v_fmac_f32_dpp v193, v111, v93 row_shl:14 row_mask:0xf bank_mask:0xf
	v_fmac_f32_dpp v194, v112, v94 row_shl:14 row_mask:0xf bank_mask:0xf
	v_fmac_f32_dpp v195, v113, v95 row_shl:14 row_mask:0xf bank_mask:0xf
	v_pk_mul_f32 v[196:197], v[188:189], v[216:217] op_sel_hi:[1,0]
	v_pk_mul_f32 v[198:199], v[190:191], v[216:217] op_sel_hi:[1,0]
	v_exp_f32_e32 v196, v196
	v_exp_f32_e32 v197, v197
	v_exp_f32_e32 v198, v198
	v_exp_f32_e32 v199, v199
	v_pk_add_f32 v[196:197], v[196:197], v[214:215] op_sel_hi:[1,0]
	v_pk_add_f32 v[198:199], v[198:199], v[214:215] op_sel_hi:[1,0]
	v_rcp_f32_e32 v196, v196
	v_rcp_f32_e32 v197, v197
	v_rcp_f32_e32 v198, v198
	v_rcp_f32_e32 v199, v199
	v_pk_mul_f32 v[188:189], v[188:189], v[196:197]
	v_pk_mul_f32 v[190:191], v[190:191], v[198:199]
	v_pk_mul_f32 v[188:189], v[188:189], v[192:193]
	v_pk_mul_f32 v[190:191], v[190:191], v[194:195]
	v_cvt_pk_bf16_f32 v122, v188, v189
	v_cvt_pk_bf16_f32 v123, v190, v191
	v_add_u32_e32 v213, 0x31800, v212
	global_load_dwordx4 v[110:113], v213, s[82:83] offset:16
	v_pk_fma_f32 v[188:189], v[72:73], v[84:85], v[88:89]
	v_pk_fma_f32 v[190:191], v[74:75], v[86:87], v[90:91]
	v_pk_fma_f32 v[192:193], v[64:65], v[100:101], v[104:105]
	v_pk_fma_f32 v[194:195], v[66:67], v[102:103], v[106:107]
	v_fmac_f32_dpp v188, v72, v80 row_shr:1 row_mask:0xf bank_mask:0xf
	v_fmac_f32_dpp v189, v73, v81 row_shr:1 row_mask:0xf bank_mask:0xf
	v_fmac_f32_dpp v190, v74, v82 row_shr:1 row_mask:0xf bank_mask:0xf
	v_fmac_f32_dpp v191, v75, v83 row_shr:1 row_mask:0xf bank_mask:0xf
	v_fmac_f32_dpp v192, v64, v96 row_shr:1 row_mask:0xf bank_mask:0xf
	v_fmac_f32_dpp v193, v65, v97 row_shr:1 row_mask:0xf bank_mask:0xf
	v_fmac_f32_dpp v194, v66, v98 row_shr:1 row_mask:0xf bank_mask:0xf
	v_fmac_f32_dpp v195, v67, v99 row_shr:1 row_mask:0xf bank_mask:0xf
	v_fmac_f32_dpp v188, v72, v76 row_shr:2 row_mask:0xf bank_mask:0xf
	v_fmac_f32_dpp v189, v73, v77 row_shr:2 row_mask:0xf bank_mask:0xf
	v_fmac_f32_dpp v190, v74, v78 row_shr:2 row_mask:0xf bank_mask:0xf
	v_fmac_f32_dpp v191, v75, v79 row_shr:2 row_mask:0xf bank_mask:0xf
	v_fmac_f32_dpp v192, v64, v92 row_shr:2 row_mask:0xf bank_mask:0xf
	v_fmac_f32_dpp v193, v65, v93 row_shr:2 row_mask:0xf bank_mask:0xf
	v_fmac_f32_dpp v194, v66, v94 row_shr:2 row_mask:0xf bank_mask:0xf
	v_fmac_f32_dpp v195, v67, v95 row_shr:2 row_mask:0xf bank_mask:0xf
	v_fmac_f32_dpp v188, v114, v80 row_shl:15 row_mask:0xf bank_mask:0xf
	v_fmac_f32_dpp v189, v115, v81 row_shl:15 row_mask:0xf bank_mask:0xf
	v_fmac_f32_dpp v190, v116, v82 row_shl:15 row_mask:0xf bank_mask:0xf
	v_fmac_f32_dpp v191, v117, v83 row_shl:15 row_mask:0xf bank_mask:0xf
	v_fmac_f32_dpp v192, v68, v96 row_shl:15 row_mask:0xf bank_mask:0xf
	v_fmac_f32_dpp v193, v69, v97 row_shl:15 row_mask:0xf bank_mask:0xf
	v_fmac_f32_dpp v194, v70, v98 row_shl:15 row_mask:0xf bank_mask:0xf
	v_fmac_f32_dpp v195, v71, v99 row_shl:15 row_mask:0xf bank_mask:0xf
	v_fmac_f32_dpp v188, v114, v76 row_shl:14 row_mask:0xf bank_mask:0xf
	v_fmac_f32_dpp v189, v115, v77 row_shl:14 row_mask:0xf bank_mask:0xf
	v_fmac_f32_dpp v190, v116, v78 row_shl:14 row_mask:0xf bank_mask:0xf
	v_fmac_f32_dpp v191, v117, v79 row_shl:14 row_mask:0xf bank_mask:0xf
	v_fmac_f32_dpp v192, v68, v92 row_shl:14 row_mask:0xf bank_mask:0xf
	v_fmac_f32_dpp v193, v69, v93 row_shl:14 row_mask:0xf bank_mask:0xf
	v_fmac_f32_dpp v194, v70, v94 row_shl:14 row_mask:0xf bank_mask:0xf
	v_fmac_f32_dpp v195, v71, v95 row_shl:14 row_mask:0xf bank_mask:0xf
	v_pk_mul_f32 v[196:197], v[188:189], v[216:217] op_sel_hi:[1,0]
	v_pk_mul_f32 v[198:199], v[190:191], v[216:217] op_sel_hi:[1,0]
	v_exp_f32_e32 v196, v196
	v_exp_f32_e32 v197, v197
	v_exp_f32_e32 v198, v198
	v_exp_f32_e32 v199, v199
	v_pk_add_f32 v[196:197], v[196:197], v[214:215] op_sel_hi:[1,0]
	v_pk_add_f32 v[198:199], v[198:199], v[214:215] op_sel_hi:[1,0]
	v_rcp_f32_e32 v196, v196
	v_rcp_f32_e32 v197, v197
	v_rcp_f32_e32 v198, v198
	v_rcp_f32_e32 v199, v199
	v_pk_mul_f32 v[188:189], v[188:189], v[196:197]
	v_pk_mul_f32 v[190:191], v[190:191], v[198:199]
	v_pk_mul_f32 v[188:189], v[188:189], v[192:193]
	v_pk_mul_f32 v[190:191], v[190:191], v[194:195]
	v_cvt_pk_bf16_f32 v114, v188, v189
	v_cvt_pk_bf16_f32 v115, v190, v191
	s_waitcnt vmcnt(0)
	v_pk_fma_f32 v[188:189], v[60:61], v[134:135], v[130:131]
	v_pk_fma_f32 v[190:191], v[62:63], v[136:137], v[132:133]
	v_pk_fma_f32 v[192:193], v[56:57], v[204:205], v[208:209]
	v_pk_fma_f32 v[194:195], v[58:59], v[206:207], v[210:211]
	v_fmac_f32_dpp v188, v60, v142 row_shr:1 row_mask:0xf bank_mask:0xf
	v_fmac_f32_dpp v189, v61, v143 row_shr:1 row_mask:0xf bank_mask:0xf
	v_fmac_f32_dpp v190, v62, v144 row_shr:1 row_mask:0xf bank_mask:0xf
	v_fmac_f32_dpp v191, v63, v145 row_shr:1 row_mask:0xf bank_mask:0xf
	v_fmac_f32_dpp v192, v56, v110 row_shr:1 row_mask:0xf bank_mask:0xf
	v_fmac_f32_dpp v193, v57, v111 row_shr:1 row_mask:0xf bank_mask:0xf
	v_fmac_f32_dpp v194, v58, v112 row_shr:1 row_mask:0xf bank_mask:0xf
	v_fmac_f32_dpp v195, v59, v113 row_shr:1 row_mask:0xf bank_mask:0xf
	v_fmac_f32_dpp v188, v60, v154 row_shr:2 row_mask:0xf bank_mask:0xf
	v_fmac_f32_dpp v189, v61, v155 row_shr:2 row_mask:0xf bank_mask:0xf
	v_fmac_f32_dpp v190, v62, v156 row_shr:2 row_mask:0xf bank_mask:0xf
	v_fmac_f32_dpp v191, v63, v157 row_shr:2 row_mask:0xf bank_mask:0xf
	v_fmac_f32_dpp v192, v56, v118 row_shr:2 row_mask:0xf bank_mask:0xf
	v_fmac_f32_dpp v193, v57, v119 row_shr:2 row_mask:0xf bank_mask:0xf
	v_fmac_f32_dpp v194, v58, v120 row_shr:2 row_mask:0xf bank_mask:0xf
	v_fmac_f32_dpp v195, v59, v121 row_shr:2 row_mask:0xf bank_mask:0xf
	v_pk_mul_f32 v[196:197], v[188:189], v[216:217] op_sel_hi:[1,0]
	v_pk_mul_f32 v[198:199], v[190:191], v[216:217] op_sel_hi:[1,0]
	v_exp_f32_e32 v196, v196
	v_exp_f32_e32 v197, v197
	v_exp_f32_e32 v198, v198
	v_exp_f32_e32 v199, v199
	v_pk_add_f32 v[196:197], v[196:197], v[214:215] op_sel_hi:[1,0]
	v_pk_add_f32 v[198:199], v[198:199], v[214:215] op_sel_hi:[1,0]
	v_rcp_f32_e32 v196, v196
	v_rcp_f32_e32 v197, v197
	v_rcp_f32_e32 v198, v198
	v_rcp_f32_e32 v199, v199
	v_pk_mul_f32 v[188:189], v[188:189], v[196:197]
	v_pk_mul_f32 v[190:191], v[190:191], v[198:199]
	v_pk_mul_f32 v[188:189], v[188:189], v[192:193]
	v_pk_mul_f32 v[190:191], v[190:191], v[194:195]
	v_cvt_pk_bf16_f32 v202, v188, v189
	v_cvt_pk_bf16_f32 v203, v190, v191
	s_mov_b64 exec, vcc
	global_store_dwordx4 v215, v[200:203], s[96:97]
	s_mov_b64 exec, -1
	v_pk_fma_f32 v[188:189], v[52:53], v[134:135], v[130:131]
	v_pk_fma_f32 v[190:191], v[54:55], v[136:137], v[132:133]
	v_pk_fma_f32 v[192:193], v[44:45], v[204:205], v[208:209]
	v_pk_fma_f32 v[194:195], v[46:47], v[206:207], v[210:211]
	v_fmac_f32_dpp v188, v52, v142 row_shr:1 row_mask:0xf bank_mask:0xf
	v_fmac_f32_dpp v189, v53, v143 row_shr:1 row_mask:0xf bank_mask:0xf
	v_fmac_f32_dpp v190, v54, v144 row_shr:1 row_mask:0xf bank_mask:0xf
	v_fmac_f32_dpp v191, v55, v145 row_shr:1 row_mask:0xf bank_mask:0xf
	v_fmac_f32_dpp v192, v44, v110 row_shr:1 row_mask:0xf bank_mask:0xf
	v_fmac_f32_dpp v193, v45, v111 row_shr:1 row_mask:0xf bank_mask:0xf
	v_fmac_f32_dpp v194, v46, v112 row_shr:1 row_mask:0xf bank_mask:0xf
	v_fmac_f32_dpp v195, v47, v113 row_shr:1 row_mask:0xf bank_mask:0xf
	v_fmac_f32_dpp v188, v52, v154 row_shr:2 row_mask:0xf bank_mask:0xf
	v_fmac_f32_dpp v189, v53, v155 row_shr:2 row_mask:0xf bank_mask:0xf
	v_fmac_f32_dpp v190, v54, v156 row_shr:2 row_mask:0xf bank_mask:0xf
	v_fmac_f32_dpp v191, v55, v157 row_shr:2 row_mask:0xf bank_mask:0xf
	v_fmac_f32_dpp v192, v44, v118 row_shr:2 row_mask:0xf bank_mask:0xf
	v_fmac_f32_dpp v193, v45, v119 row_shr:2 row_mask:0xf bank_mask:0xf
	v_fmac_f32_dpp v194, v46, v120 row_shr:2 row_mask:0xf bank_mask:0xf
	v_fmac_f32_dpp v195, v47, v121 row_shr:2 row_mask:0xf bank_mask:0xf
	v_fmac_f32_dpp v188, v60, v142 row_shl:15 row_mask:0xf bank_mask:0xf
	v_fmac_f32_dpp v189, v61, v143 row_shl:15 row_mask:0xf bank_mask:0xf
	v_fmac_f32_dpp v190, v62, v144 row_shl:15 row_mask:0xf bank_mask:0xf
	v_fmac_f32_dpp v191, v63, v145 row_shl:15 row_mask:0xf bank_mask:0xf
	v_fmac_f32_dpp v192, v56, v110 row_shl:15 row_mask:0xf bank_mask:0xf
	v_fmac_f32_dpp v193, v57, v111 row_shl:15 row_mask:0xf bank_mask:0xf
	v_fmac_f32_dpp v194, v58, v112 row_shl:15 row_mask:0xf bank_mask:0xf
	v_fmac_f32_dpp v195, v59, v113 row_shl:15 row_mask:0xf bank_mask:0xf
	v_fmac_f32_dpp v188, v60, v154 row_shl:14 row_mask:0xf bank_mask:0xf
	v_fmac_f32_dpp v189, v61, v155 row_shl:14 row_mask:0xf bank_mask:0xf
	v_fmac_f32_dpp v190, v62, v156 row_shl:14 row_mask:0xf bank_mask:0xf
	v_fmac_f32_dpp v191, v63, v157 row_shl:14 row_mask:0xf bank_mask:0xf
	v_fmac_f32_dpp v192, v56, v118 row_shl:14 row_mask:0xf bank_mask:0xf
	v_fmac_f32_dpp v193, v57, v119 row_shl:14 row_mask:0xf bank_mask:0xf
	v_fmac_f32_dpp v194, v58, v120 row_shl:14 row_mask:0xf bank_mask:0xf
	v_fmac_f32_dpp v195, v59, v121 row_shl:14 row_mask:0xf bank_mask:0xf
	v_pk_mul_f32 v[196:197], v[188:189], v[216:217] op_sel_hi:[1,0]
	v_pk_mul_f32 v[198:199], v[190:191], v[216:217] op_sel_hi:[1,0]
	v_exp_f32_e32 v196, v196
	v_exp_f32_e32 v197, v197
	v_exp_f32_e32 v198, v198
	v_exp_f32_e32 v199, v199
	v_pk_add_f32 v[196:197], v[196:197], v[214:215] op_sel_hi:[1,0]
	v_pk_add_f32 v[198:199], v[198:199], v[214:215] op_sel_hi:[1,0]
	v_rcp_f32_e32 v196, v196
	v_rcp_f32_e32 v197, v197
	v_rcp_f32_e32 v198, v198
	v_rcp_f32_e32 v199, v199
	v_pk_mul_f32 v[188:189], v[188:189], v[196:197]
	v_pk_mul_f32 v[190:191], v[190:191], v[198:199]
	v_pk_mul_f32 v[188:189], v[188:189], v[192:193]
	v_pk_mul_f32 v[190:191], v[190:191], v[194:195]
	v_cvt_pk_bf16_f32 v160, v188, v189
	v_cvt_pk_bf16_f32 v161, v190, v191
	v_add_u32_e32 v213, 0x2c000, v215
	global_store_dwordx4 v213, v[158:161], s[96:97]
	v_pk_fma_f32 v[188:189], v[48:49], v[134:135], v[130:131]
	v_pk_fma_f32 v[190:191], v[50:51], v[136:137], v[132:133]
	v_pk_fma_f32 v[192:193], v[36:37], v[204:205], v[208:209]
	v_pk_fma_f32 v[194:195], v[38:39], v[206:207], v[210:211]
	v_fmac_f32_dpp v188, v48, v142 row_shr:1 row_mask:0xf bank_mask:0xf
	v_fmac_f32_dpp v189, v49, v143 row_shr:1 row_mask:0xf bank_mask:0xf
	v_fmac_f32_dpp v190, v50, v144 row_shr:1 row_mask:0xf bank_mask:0xf
	v_fmac_f32_dpp v191, v51, v145 row_shr:1 row_mask:0xf bank_mask:0xf
	v_fmac_f32_dpp v192, v36, v110 row_shr:1 row_mask:0xf bank_mask:0xf
	v_fmac_f32_dpp v193, v37, v111 row_shr:1 row_mask:0xf bank_mask:0xf
	v_fmac_f32_dpp v194, v38, v112 row_shr:1 row_mask:0xf bank_mask:0xf
	v_fmac_f32_dpp v195, v39, v113 row_shr:1 row_mask:0xf bank_mask:0xf
	v_fmac_f32_dpp v188, v48, v154 row_shr:2 row_mask:0xf bank_mask:0xf
	v_fmac_f32_dpp v189, v49, v155 row_shr:2 row_mask:0xf bank_mask:0xf
	v_fmac_f32_dpp v190, v50, v156 row_shr:2 row_mask:0xf bank_mask:0xf
	v_fmac_f32_dpp v191, v51, v157 row_shr:2 row_mask:0xf bank_mask:0xf
	v_fmac_f32_dpp v192, v36, v118 row_shr:2 row_mask:0xf bank_mask:0xf
	v_fmac_f32_dpp v193, v37, v119 row_shr:2 row_mask:0xf bank_mask:0xf
	v_fmac_f32_dpp v194, v38, v120 row_shr:2 row_mask:0xf bank_mask:0xf
	v_fmac_f32_dpp v195, v39, v121 row_shr:2 row_mask:0xf bank_mask:0xf
	v_fmac_f32_dpp v188, v52, v142 row_shl:15 row_mask:0xf bank_mask:0xf
	v_fmac_f32_dpp v189, v53, v143 row_shl:15 row_mask:0xf bank_mask:0xf
	v_fmac_f32_dpp v190, v54, v144 row_shl:15 row_mask:0xf bank_mask:0xf
	v_fmac_f32_dpp v191, v55, v145 row_shl:15 row_mask:0xf bank_mask:0xf
	v_fmac_f32_dpp v192, v44, v110 row_shl:15 row_mask:0xf bank_mask:0xf
	v_fmac_f32_dpp v193, v45, v111 row_shl:15 row_mask:0xf bank_mask:0xf
	v_fmac_f32_dpp v194, v46, v112 row_shl:15 row_mask:0xf bank_mask:0xf
	v_fmac_f32_dpp v195, v47, v113 row_shl:15 row_mask:0xf bank_mask:0xf
	v_fmac_f32_dpp v188, v52, v154 row_shl:14 row_mask:0xf bank_mask:0xf
	v_fmac_f32_dpp v189, v53, v155 row_shl:14 row_mask:0xf bank_mask:0xf
	v_fmac_f32_dpp v190, v54, v156 row_shl:14 row_mask:0xf bank_mask:0xf
	v_fmac_f32_dpp v191, v55, v157 row_shl:14 row_mask:0xf bank_mask:0xf
	v_fmac_f32_dpp v192, v44, v118 row_shl:14 row_mask:0xf bank_mask:0xf
	v_fmac_f32_dpp v193, v45, v119 row_shl:14 row_mask:0xf bank_mask:0xf
	v_fmac_f32_dpp v194, v46, v120 row_shl:14 row_mask:0xf bank_mask:0xf
	v_fmac_f32_dpp v195, v47, v121 row_shl:14 row_mask:0xf bank_mask:0xf
	v_pk_mul_f32 v[196:197], v[188:189], v[216:217] op_sel_hi:[1,0]
	v_pk_mul_f32 v[198:199], v[190:191], v[216:217] op_sel_hi:[1,0]
	v_exp_f32_e32 v196, v196
	v_exp_f32_e32 v197, v197
	v_exp_f32_e32 v198, v198
	v_exp_f32_e32 v199, v199
	v_pk_add_f32 v[196:197], v[196:197], v[214:215] op_sel_hi:[1,0]
	v_pk_add_f32 v[198:199], v[198:199], v[214:215] op_sel_hi:[1,0]
	v_rcp_f32_e32 v196, v196
	v_rcp_f32_e32 v197, v197
	v_rcp_f32_e32 v198, v198
	v_rcp_f32_e32 v199, v199
	v_pk_mul_f32 v[188:189], v[188:189], v[196:197]
	v_pk_mul_f32 v[190:191], v[190:191], v[198:199]
	v_pk_mul_f32 v[188:189], v[188:189], v[192:193]
	v_pk_mul_f32 v[190:191], v[190:191], v[194:195]
	v_cvt_pk_bf16_f32 v152, v188, v189
	v_cvt_pk_bf16_f32 v153, v190, v191
	v_add_u32_e32 v213, 0x58000, v215
	global_store_dwordx4 v213, v[150:153], s[96:97]
	v_pk_fma_f32 v[188:189], v[40:41], v[134:135], v[130:131]
	v_pk_fma_f32 v[190:191], v[42:43], v[136:137], v[132:133]
	v_pk_fma_f32 v[192:193], v[32:33], v[204:205], v[208:209]
	v_pk_fma_f32 v[194:195], v[34:35], v[206:207], v[210:211]
	v_fmac_f32_dpp v188, v40, v142 row_shr:1 row_mask:0xf bank_mask:0xf
	v_fmac_f32_dpp v189, v41, v143 row_shr:1 row_mask:0xf bank_mask:0xf
	v_fmac_f32_dpp v190, v42, v144 row_shr:1 row_mask:0xf bank_mask:0xf
	v_fmac_f32_dpp v191, v43, v145 row_shr:1 row_mask:0xf bank_mask:0xf
	v_fmac_f32_dpp v192, v32, v110 row_shr:1 row_mask:0xf bank_mask:0xf
	v_fmac_f32_dpp v193, v33, v111 row_shr:1 row_mask:0xf bank_mask:0xf
	v_fmac_f32_dpp v194, v34, v112 row_shr:1 row_mask:0xf bank_mask:0xf
	v_fmac_f32_dpp v195, v35, v113 row_shr:1 row_mask:0xf bank_mask:0xf
	v_fmac_f32_dpp v188, v40, v154 row_shr:2 row_mask:0xf bank_mask:0xf
	v_fmac_f32_dpp v189, v41, v155 row_shr:2 row_mask:0xf bank_mask:0xf
	v_fmac_f32_dpp v190, v42, v156 row_shr:2 row_mask:0xf bank_mask:0xf
	v_fmac_f32_dpp v191, v43, v157 row_shr:2 row_mask:0xf bank_mask:0xf
	v_fmac_f32_dpp v192, v32, v118 row_shr:2 row_mask:0xf bank_mask:0xf
	v_fmac_f32_dpp v193, v33, v119 row_shr:2 row_mask:0xf bank_mask:0xf
	v_fmac_f32_dpp v194, v34, v120 row_shr:2 row_mask:0xf bank_mask:0xf
	v_fmac_f32_dpp v195, v35, v121 row_shr:2 row_mask:0xf bank_mask:0xf
	v_fmac_f32_dpp v188, v48, v142 row_shl:15 row_mask:0xf bank_mask:0xf
	v_fmac_f32_dpp v189, v49, v143 row_shl:15 row_mask:0xf bank_mask:0xf
	v_fmac_f32_dpp v190, v50, v144 row_shl:15 row_mask:0xf bank_mask:0xf
	v_fmac_f32_dpp v191, v51, v145 row_shl:15 row_mask:0xf bank_mask:0xf
	v_fmac_f32_dpp v192, v36, v110 row_shl:15 row_mask:0xf bank_mask:0xf
	v_fmac_f32_dpp v193, v37, v111 row_shl:15 row_mask:0xf bank_mask:0xf
	v_fmac_f32_dpp v194, v38, v112 row_shl:15 row_mask:0xf bank_mask:0xf
	v_fmac_f32_dpp v195, v39, v113 row_shl:15 row_mask:0xf bank_mask:0xf
	v_fmac_f32_dpp v188, v48, v154 row_shl:14 row_mask:0xf bank_mask:0xf
	v_fmac_f32_dpp v189, v49, v155 row_shl:14 row_mask:0xf bank_mask:0xf
	v_fmac_f32_dpp v190, v50, v156 row_shl:14 row_mask:0xf bank_mask:0xf
	v_fmac_f32_dpp v191, v51, v157 row_shl:14 row_mask:0xf bank_mask:0xf
	v_fmac_f32_dpp v192, v36, v118 row_shl:14 row_mask:0xf bank_mask:0xf
	v_fmac_f32_dpp v193, v37, v119 row_shl:14 row_mask:0xf bank_mask:0xf
	v_fmac_f32_dpp v194, v38, v120 row_shl:14 row_mask:0xf bank_mask:0xf
	v_fmac_f32_dpp v195, v39, v121 row_shl:14 row_mask:0xf bank_mask:0xf
	v_pk_mul_f32 v[196:197], v[188:189], v[216:217] op_sel_hi:[1,0]
	v_pk_mul_f32 v[198:199], v[190:191], v[216:217] op_sel_hi:[1,0]
	v_exp_f32_e32 v196, v196
	v_exp_f32_e32 v197, v197
	v_exp_f32_e32 v198, v198
	v_exp_f32_e32 v199, v199
	v_pk_add_f32 v[196:197], v[196:197], v[214:215] op_sel_hi:[1,0]
	v_pk_add_f32 v[198:199], v[198:199], v[214:215] op_sel_hi:[1,0]
	v_rcp_f32_e32 v196, v196
	v_rcp_f32_e32 v197, v197
	v_rcp_f32_e32 v198, v198
	v_rcp_f32_e32 v199, v199
	v_pk_mul_f32 v[188:189], v[188:189], v[196:197]
	v_pk_mul_f32 v[190:191], v[190:191], v[198:199]
	v_pk_mul_f32 v[188:189], v[188:189], v[192:193]
	v_pk_mul_f32 v[190:191], v[190:191], v[194:195]
	v_cvt_pk_bf16_f32 v148, v188, v189
	v_cvt_pk_bf16_f32 v149, v190, v191
	v_add_u32_e32 v213, 0x84000, v215
	global_store_dwordx4 v213, v[146:149], s[96:97]
	v_pk_fma_f32 v[188:189], v[28:29], v[134:135], v[130:131]
	v_pk_fma_f32 v[190:191], v[30:31], v[136:137], v[132:133]
	v_pk_fma_f32 v[192:193], v[16:17], v[204:205], v[208:209]
	v_pk_fma_f32 v[194:195], v[18:19], v[206:207], v[210:211]
	v_fmac_f32_dpp v188, v28, v142 row_shr:1 row_mask:0xf bank_mask:0xf
	v_fmac_f32_dpp v189, v29, v143 row_shr:1 row_mask:0xf bank_mask:0xf
	v_fmac_f32_dpp v190, v30, v144 row_shr:1 row_mask:0xf bank_mask:0xf
	v_fmac_f32_dpp v191, v31, v145 row_shr:1 row_mask:0xf bank_mask:0xf
	v_fmac_f32_dpp v192, v16, v110 row_shr:1 row_mask:0xf bank_mask:0xf
	v_fmac_f32_dpp v193, v17, v111 row_shr:1 row_mask:0xf bank_mask:0xf
	v_fmac_f32_dpp v194, v18, v112 row_shr:1 row_mask:0xf bank_mask:0xf
	v_fmac_f32_dpp v195, v19, v113 row_shr:1 row_mask:0xf bank_mask:0xf
	v_fmac_f32_dpp v188, v28, v154 row_shr:2 row_mask:0xf bank_mask:0xf
	v_fmac_f32_dpp v189, v29, v155 row_shr:2 row_mask:0xf bank_mask:0xf
	v_fmac_f32_dpp v190, v30, v156 row_shr:2 row_mask:0xf bank_mask:0xf
	v_fmac_f32_dpp v191, v31, v157 row_shr:2 row_mask:0xf bank_mask:0xf
	v_fmac_f32_dpp v192, v16, v118 row_shr:2 row_mask:0xf bank_mask:0xf
	v_fmac_f32_dpp v193, v17, v119 row_shr:2 row_mask:0xf bank_mask:0xf
	v_fmac_f32_dpp v194, v18, v120 row_shr:2 row_mask:0xf bank_mask:0xf
	v_fmac_f32_dpp v195, v19, v121 row_shr:2 row_mask:0xf bank_mask:0xf
	v_fmac_f32_dpp v188, v40, v142 row_shl:15 row_mask:0xf bank_mask:0xf
	v_fmac_f32_dpp v189, v41, v143 row_shl:15 row_mask:0xf bank_mask:0xf
	v_fmac_f32_dpp v190, v42, v144 row_shl:15 row_mask:0xf bank_mask:0xf
	v_fmac_f32_dpp v191, v43, v145 row_shl:15 row_mask:0xf bank_mask:0xf
	v_fmac_f32_dpp v192, v32, v110 row_shl:15 row_mask:0xf bank_mask:0xf
	v_fmac_f32_dpp v193, v33, v111 row_shl:15 row_mask:0xf bank_mask:0xf
	v_fmac_f32_dpp v194, v34, v112 row_shl:15 row_mask:0xf bank_mask:0xf
	v_fmac_f32_dpp v195, v35, v113 row_shl:15 row_mask:0xf bank_mask:0xf
	v_fmac_f32_dpp v188, v40, v154 row_shl:14 row_mask:0xf bank_mask:0xf
	v_fmac_f32_dpp v189, v41, v155 row_shl:14 row_mask:0xf bank_mask:0xf
	v_fmac_f32_dpp v190, v42, v156 row_shl:14 row_mask:0xf bank_mask:0xf
	v_fmac_f32_dpp v191, v43, v157 row_shl:14 row_mask:0xf bank_mask:0xf
	v_fmac_f32_dpp v192, v32, v118 row_shl:14 row_mask:0xf bank_mask:0xf
	v_fmac_f32_dpp v193, v33, v119 row_shl:14 row_mask:0xf bank_mask:0xf
	v_fmac_f32_dpp v194, v34, v120 row_shl:14 row_mask:0xf bank_mask:0xf
	v_fmac_f32_dpp v195, v35, v121 row_shl:14 row_mask:0xf bank_mask:0xf
	v_pk_mul_f32 v[196:197], v[188:189], v[216:217] op_sel_hi:[1,0]
	v_pk_mul_f32 v[198:199], v[190:191], v[216:217] op_sel_hi:[1,0]
	v_exp_f32_e32 v196, v196
	v_exp_f32_e32 v197, v197
	v_exp_f32_e32 v198, v198
	v_exp_f32_e32 v199, v199
	v_pk_add_f32 v[196:197], v[196:197], v[214:215] op_sel_hi:[1,0]
	v_pk_add_f32 v[198:199], v[198:199], v[214:215] op_sel_hi:[1,0]
	v_rcp_f32_e32 v196, v196
	v_rcp_f32_e32 v197, v197
	v_rcp_f32_e32 v198, v198
	v_rcp_f32_e32 v199, v199
	v_pk_mul_f32 v[188:189], v[188:189], v[196:197]
	v_pk_mul_f32 v[190:191], v[190:191], v[198:199]
	v_pk_mul_f32 v[188:189], v[188:189], v[192:193]
	v_pk_mul_f32 v[190:191], v[190:191], v[194:195]
	v_cvt_pk_bf16_f32 v140, v188, v189
	v_cvt_pk_bf16_f32 v141, v190, v191
	v_add_u32_e32 v213, 0xb0000, v215
	global_store_dwordx4 v213, v[138:141], s[96:97]
	v_pk_fma_f32 v[188:189], v[24:25], v[134:135], v[130:131]
	v_pk_fma_f32 v[190:191], v[26:27], v[136:137], v[132:133]
	v_pk_fma_f32 v[192:193], v[12:13], v[204:205], v[208:209]
	v_pk_fma_f32 v[194:195], v[14:15], v[206:207], v[210:211]
	v_fmac_f32_dpp v188, v24, v142 row_shr:1 row_mask:0xf bank_mask:0xf
	v_fmac_f32_dpp v189, v25, v143 row_shr:1 row_mask:0xf bank_mask:0xf
	v_fmac_f32_dpp v190, v26, v144 row_shr:1 row_mask:0xf bank_mask:0xf
	v_fmac_f32_dpp v191, v27, v145 row_shr:1 row_mask:0xf bank_mask:0xf
	v_fmac_f32_dpp v192, v12, v110 row_shr:1 row_mask:0xf bank_mask:0xf
	v_fmac_f32_dpp v193, v13, v111 row_shr:1 row_mask:0xf bank_mask:0xf
	v_fmac_f32_dpp v194, v14, v112 row_shr:1 row_mask:0xf bank_mask:0xf
	v_fmac_f32_dpp v195, v15, v113 row_shr:1 row_mask:0xf bank_mask:0xf
	v_fmac_f32_dpp v188, v24, v154 row_shr:2 row_mask:0xf bank_mask:0xf
	v_fmac_f32_dpp v189, v25, v155 row_shr:2 row_mask:0xf bank_mask:0xf
	v_fmac_f32_dpp v190, v26, v156 row_shr:2 row_mask:0xf bank_mask:0xf
	v_fmac_f32_dpp v191, v27, v157 row_shr:2 row_mask:0xf bank_mask:0xf
	v_fmac_f32_dpp v192, v12, v118 row_shr:2 row_mask:0xf bank_mask:0xf
	v_fmac_f32_dpp v193, v13, v119 row_shr:2 row_mask:0xf bank_mask:0xf
	v_fmac_f32_dpp v194, v14, v120 row_shr:2 row_mask:0xf bank_mask:0xf
	v_fmac_f32_dpp v195, v15, v121 row_shr:2 row_mask:0xf bank_mask:0xf
	v_fmac_f32_dpp v188, v28, v142 row_shl:15 row_mask:0xf bank_mask:0xf
	v_fmac_f32_dpp v189, v29, v143 row_shl:15 row_mask:0xf bank_mask:0xf
	v_fmac_f32_dpp v190, v30, v144 row_shl:15 row_mask:0xf bank_mask:0xf
	v_fmac_f32_dpp v191, v31, v145 row_shl:15 row_mask:0xf bank_mask:0xf
	v_fmac_f32_dpp v192, v16, v110 row_shl:15 row_mask:0xf bank_mask:0xf
	v_fmac_f32_dpp v193, v17, v111 row_shl:15 row_mask:0xf bank_mask:0xf
	v_fmac_f32_dpp v194, v18, v112 row_shl:15 row_mask:0xf bank_mask:0xf
	v_fmac_f32_dpp v195, v19, v113 row_shl:15 row_mask:0xf bank_mask:0xf
	v_fmac_f32_dpp v188, v28, v154 row_shl:14 row_mask:0xf bank_mask:0xf
	v_fmac_f32_dpp v189, v29, v155 row_shl:14 row_mask:0xf bank_mask:0xf
	v_fmac_f32_dpp v190, v30, v156 row_shl:14 row_mask:0xf bank_mask:0xf
	v_fmac_f32_dpp v191, v31, v157 row_shl:14 row_mask:0xf bank_mask:0xf
	v_fmac_f32_dpp v192, v16, v118 row_shl:14 row_mask:0xf bank_mask:0xf
	v_fmac_f32_dpp v193, v17, v119 row_shl:14 row_mask:0xf bank_mask:0xf
	v_fmac_f32_dpp v194, v18, v120 row_shl:14 row_mask:0xf bank_mask:0xf
	v_fmac_f32_dpp v195, v19, v121 row_shl:14 row_mask:0xf bank_mask:0xf
	v_pk_mul_f32 v[196:197], v[188:189], v[216:217] op_sel_hi:[1,0]
	v_pk_mul_f32 v[198:199], v[190:191], v[216:217] op_sel_hi:[1,0]
	v_exp_f32_e32 v196, v196
	v_exp_f32_e32 v197, v197
	v_exp_f32_e32 v198, v198
	v_exp_f32_e32 v199, v199
	v_pk_add_f32 v[196:197], v[196:197], v[214:215] op_sel_hi:[1,0]
	v_pk_add_f32 v[198:199], v[198:199], v[214:215] op_sel_hi:[1,0]
	v_rcp_f32_e32 v196, v196
	v_rcp_f32_e32 v197, v197
	v_rcp_f32_e32 v198, v198
	v_rcp_f32_e32 v199, v199
	v_pk_mul_f32 v[188:189], v[188:189], v[196:197]
	v_pk_mul_f32 v[190:191], v[190:191], v[198:199]
	v_pk_mul_f32 v[188:189], v[188:189], v[192:193]
	v_pk_mul_f32 v[190:191], v[190:191], v[194:195]
	v_cvt_pk_bf16_f32 v128, v188, v189
	v_cvt_pk_bf16_f32 v129, v190, v191
	v_add_u32_e32 v213, 0xdc000, v215
	global_store_dwordx4 v213, v[126:129], s[96:97]
	v_pk_fma_f32 v[188:189], v[20:21], v[134:135], v[130:131]
	v_pk_fma_f32 v[190:191], v[22:23], v[136:137], v[132:133]
	v_pk_fma_f32 v[192:193], v[8:9], v[204:205], v[208:209]
	v_pk_fma_f32 v[194:195], v[10:11], v[206:207], v[210:211]
	v_fmac_f32_dpp v188, v20, v142 row_shr:1 row_mask:0xf bank_mask:0xf
	v_fmac_f32_dpp v189, v21, v143 row_shr:1 row_mask:0xf bank_mask:0xf
	v_fmac_f32_dpp v190, v22, v144 row_shr:1 row_mask:0xf bank_mask:0xf
	v_fmac_f32_dpp v191, v23, v145 row_shr:1 row_mask:0xf bank_mask:0xf
	v_fmac_f32_dpp v192, v8, v110 row_shr:1 row_mask:0xf bank_mask:0xf
	v_fmac_f32_dpp v193, v9, v111 row_shr:1 row_mask:0xf bank_mask:0xf
	v_fmac_f32_dpp v194, v10, v112 row_shr:1 row_mask:0xf bank_mask:0xf
	v_fmac_f32_dpp v195, v11, v113 row_shr:1 row_mask:0xf bank_mask:0xf
	v_fmac_f32_dpp v188, v20, v154 row_shr:2 row_mask:0xf bank_mask:0xf
	v_fmac_f32_dpp v189, v21, v155 row_shr:2 row_mask:0xf bank_mask:0xf
	v_fmac_f32_dpp v190, v22, v156 row_shr:2 row_mask:0xf bank_mask:0xf
	v_fmac_f32_dpp v191, v23, v157 row_shr:2 row_mask:0xf bank_mask:0xf
	v_fmac_f32_dpp v192, v8, v118 row_shr:2 row_mask:0xf bank_mask:0xf
	v_fmac_f32_dpp v193, v9, v119 row_shr:2 row_mask:0xf bank_mask:0xf
	v_fmac_f32_dpp v194, v10, v120 row_shr:2 row_mask:0xf bank_mask:0xf
	v_fmac_f32_dpp v195, v11, v121 row_shr:2 row_mask:0xf bank_mask:0xf
	v_fmac_f32_dpp v188, v24, v142 row_shl:15 row_mask:0xf bank_mask:0xf
	v_fmac_f32_dpp v189, v25, v143 row_shl:15 row_mask:0xf bank_mask:0xf
	v_fmac_f32_dpp v190, v26, v144 row_shl:15 row_mask:0xf bank_mask:0xf
	v_fmac_f32_dpp v191, v27, v145 row_shl:15 row_mask:0xf bank_mask:0xf
	v_fmac_f32_dpp v192, v12, v110 row_shl:15 row_mask:0xf bank_mask:0xf
	v_fmac_f32_dpp v193, v13, v111 row_shl:15 row_mask:0xf bank_mask:0xf
	v_fmac_f32_dpp v194, v14, v112 row_shl:15 row_mask:0xf bank_mask:0xf
	v_fmac_f32_dpp v195, v15, v113 row_shl:15 row_mask:0xf bank_mask:0xf
	v_fmac_f32_dpp v188, v24, v154 row_shl:14 row_mask:0xf bank_mask:0xf
	v_fmac_f32_dpp v189, v25, v155 row_shl:14 row_mask:0xf bank_mask:0xf
	v_fmac_f32_dpp v190, v26, v156 row_shl:14 row_mask:0xf bank_mask:0xf
	v_fmac_f32_dpp v191, v27, v157 row_shl:14 row_mask:0xf bank_mask:0xf
	v_fmac_f32_dpp v192, v12, v118 row_shl:14 row_mask:0xf bank_mask:0xf
	v_fmac_f32_dpp v193, v13, v119 row_shl:14 row_mask:0xf bank_mask:0xf
	v_fmac_f32_dpp v194, v14, v120 row_shl:14 row_mask:0xf bank_mask:0xf
	v_fmac_f32_dpp v195, v15, v121 row_shl:14 row_mask:0xf bank_mask:0xf
	v_pk_mul_f32 v[196:197], v[188:189], v[216:217] op_sel_hi:[1,0]
	v_pk_mul_f32 v[198:199], v[190:191], v[216:217] op_sel_hi:[1,0]
	v_exp_f32_e32 v196, v196
	v_exp_f32_e32 v197, v197
	v_exp_f32_e32 v198, v198
	v_exp_f32_e32 v199, v199
	v_pk_add_f32 v[196:197], v[196:197], v[214:215] op_sel_hi:[1,0]
	v_pk_add_f32 v[198:199], v[198:199], v[214:215] op_sel_hi:[1,0]
	v_rcp_f32_e32 v196, v196
	v_rcp_f32_e32 v197, v197
	v_rcp_f32_e32 v198, v198
	v_rcp_f32_e32 v199, v199
	v_pk_mul_f32 v[188:189], v[188:189], v[196:197]
	v_pk_mul_f32 v[190:191], v[190:191], v[198:199]
	v_pk_mul_f32 v[188:189], v[188:189], v[192:193]
	v_pk_mul_f32 v[190:191], v[190:191], v[194:195]
	v_cvt_pk_bf16_f32 v124, v188, v189
	v_cvt_pk_bf16_f32 v125, v190, v191
	v_add_u32_e32 v213, 0x108000, v215
	global_store_dwordx4 v213, v[122:125], s[96:97]
	v_pk_fma_f32 v[188:189], v[4:5], v[134:135], v[130:131]
	v_pk_fma_f32 v[190:191], v[6:7], v[136:137], v[132:133]
	v_pk_fma_f32 v[192:193], v[0:1], v[204:205], v[208:209]
	v_pk_fma_f32 v[194:195], v[2:3], v[206:207], v[210:211]
	v_fmac_f32_dpp v188, v4, v142 row_shr:1 row_mask:0xf bank_mask:0xf
	v_fmac_f32_dpp v189, v5, v143 row_shr:1 row_mask:0xf bank_mask:0xf
	v_fmac_f32_dpp v190, v6, v144 row_shr:1 row_mask:0xf bank_mask:0xf
	v_fmac_f32_dpp v191, v7, v145 row_shr:1 row_mask:0xf bank_mask:0xf
	v_fmac_f32_dpp v192, v0, v110 row_shr:1 row_mask:0xf bank_mask:0xf
	v_fmac_f32_dpp v193, v1, v111 row_shr:1 row_mask:0xf bank_mask:0xf
	v_fmac_f32_dpp v194, v2, v112 row_shr:1 row_mask:0xf bank_mask:0xf
	v_fmac_f32_dpp v195, v3, v113 row_shr:1 row_mask:0xf bank_mask:0xf
	v_fmac_f32_dpp v188, v4, v154 row_shr:2 row_mask:0xf bank_mask:0xf
	v_fmac_f32_dpp v189, v5, v155 row_shr:2 row_mask:0xf bank_mask:0xf
	v_fmac_f32_dpp v190, v6, v156 row_shr:2 row_mask:0xf bank_mask:0xf
	v_fmac_f32_dpp v191, v7, v157 row_shr:2 row_mask:0xf bank_mask:0xf
	v_fmac_f32_dpp v192, v0, v118 row_shr:2 row_mask:0xf bank_mask:0xf
	v_fmac_f32_dpp v193, v1, v119 row_shr:2 row_mask:0xf bank_mask:0xf
	v_fmac_f32_dpp v194, v2, v120 row_shr:2 row_mask:0xf bank_mask:0xf
	v_fmac_f32_dpp v195, v3, v121 row_shr:2 row_mask:0xf bank_mask:0xf
	v_fmac_f32_dpp v188, v20, v142 row_shl:15 row_mask:0xf bank_mask:0xf
	v_fmac_f32_dpp v189, v21, v143 row_shl:15 row_mask:0xf bank_mask:0xf
	v_fmac_f32_dpp v190, v22, v144 row_shl:15 row_mask:0xf bank_mask:0xf
	v_fmac_f32_dpp v191, v23, v145 row_shl:15 row_mask:0xf bank_mask:0xf
	v_fmac_f32_dpp v192, v8, v110 row_shl:15 row_mask:0xf bank_mask:0xf
	v_fmac_f32_dpp v193, v9, v111 row_shl:15 row_mask:0xf bank_mask:0xf
	v_fmac_f32_dpp v194, v10, v112 row_shl:15 row_mask:0xf bank_mask:0xf
	v_fmac_f32_dpp v195, v11, v113 row_shl:15 row_mask:0xf bank_mask:0xf
	v_fmac_f32_dpp v188, v20, v154 row_shl:14 row_mask:0xf bank_mask:0xf
	v_fmac_f32_dpp v189, v21, v155 row_shl:14 row_mask:0xf bank_mask:0xf
	v_fmac_f32_dpp v190, v22, v156 row_shl:14 row_mask:0xf bank_mask:0xf
	v_fmac_f32_dpp v191, v23, v157 row_shl:14 row_mask:0xf bank_mask:0xf
	v_fmac_f32_dpp v192, v8, v118 row_shl:14 row_mask:0xf bank_mask:0xf
	v_fmac_f32_dpp v193, v9, v119 row_shl:14 row_mask:0xf bank_mask:0xf
	v_fmac_f32_dpp v194, v10, v120 row_shl:14 row_mask:0xf bank_mask:0xf
	v_fmac_f32_dpp v195, v11, v121 row_shl:14 row_mask:0xf bank_mask:0xf
	v_pk_mul_f32 v[196:197], v[188:189], v[216:217] op_sel_hi:[1,0]
	v_pk_mul_f32 v[198:199], v[190:191], v[216:217] op_sel_hi:[1,0]
	v_exp_f32_e32 v196, v196
	v_exp_f32_e32 v197, v197
	v_exp_f32_e32 v198, v198
	v_exp_f32_e32 v199, v199
	v_pk_add_f32 v[196:197], v[196:197], v[214:215] op_sel_hi:[1,0]
	v_pk_add_f32 v[198:199], v[198:199], v[214:215] op_sel_hi:[1,0]
	v_rcp_f32_e32 v196, v196
	v_rcp_f32_e32 v197, v197
	v_rcp_f32_e32 v198, v198
	v_rcp_f32_e32 v199, v199
	v_pk_mul_f32 v[188:189], v[188:189], v[196:197]
	v_pk_mul_f32 v[190:191], v[190:191], v[198:199]
	v_pk_mul_f32 v[188:189], v[188:189], v[192:193]
	v_pk_mul_f32 v[190:191], v[190:191], v[194:195]
	v_cvt_pk_bf16_f32 v116, v188, v189
	v_cvt_pk_bf16_f32 v117, v190, v191
	v_add_u32_e32 v213, 0x134000, v215
	global_store_dwordx4 v213, v[114:117], s[96:97]
	s_branch .LBB0_836

.LBB0_984:
	s_add_u32 s0, s0, 0x160080
	s_addc_u32 s1, s1, 0
	s_add_u32 s39, s14, 0x100
	v_mov_b32_e32 v0, 0
	s_addc_u32 s40, s15, 0
	s_mov_b32 s41, -2
	s_waitcnt lgkmcnt(0)
	v_mov_b32_e32 v1, v0
	v_mov_b32_e32 v2, v0
	v_mov_b32_e32 v3, v0
	v_mov_b32_e32 v4, v0
	v_mov_b32_e32 v5, v0
	v_mov_b32_e32 v6, v0
	v_mov_b32_e32 v7, v0
	s_waitcnt vmcnt(0)
	v_mov_b32_e32 v16, v0
	v_mov_b32_e32 v17, v0
	v_mov_b32_e32 v18, v0
	v_mov_b32_e32 v19, v0
	v_mov_b32_e32 v20, v0
	v_mov_b32_e32 v21, v0
	v_mov_b32_e32 v22, v0
	v_mov_b32_e32 v23, v0
	v_mov_b32_e32 v32, v0
	v_mov_b32_e32 v33, v0
	v_mov_b32_e32 v34, v0
	v_mov_b32_e32 v35, v0
	v_mov_b32_e32 v36, v0
	v_mov_b32_e32 v37, v0
	v_mov_b32_e32 v38, v0
	v_mov_b32_e32 v39, v0
	v_mov_b32_e32 v48, v0
	v_mov_b32_e32 v49, v0
	v_mov_b32_e32 v50, v0
	v_mov_b32_e32 v51, v0
	v_mov_b32_e32 v52, v0
	v_mov_b32_e32 v53, v0
	v_mov_b32_e32 v54, v0
	v_mov_b32_e32 v55, v0
	v_mov_b32_e32 v8, v0
	v_mov_b32_e32 v9, v0
	v_mov_b32_e32 v10, v0
	v_mov_b32_e32 v11, v0
	v_mov_b32_e32 v12, v0
	v_mov_b32_e32 v13, v0
	v_mov_b32_e32 v14, v0
	v_mov_b32_e32 v15, v0
	v_mov_b32_e32 v24, v0
	v_mov_b32_e32 v25, v0
	v_mov_b32_e32 v26, v0
	v_mov_b32_e32 v27, v0
	v_mov_b32_e32 v28, v0
	v_mov_b32_e32 v29, v0
	v_mov_b32_e32 v30, v0
	v_mov_b32_e32 v31, v0
	v_mov_b32_e32 v40, v0
	v_mov_b32_e32 v41, v0
	v_mov_b32_e32 v42, v0
	v_mov_b32_e32 v43, v0
	v_mov_b32_e32 v44, v0
	v_mov_b32_e32 v45, v0
	v_mov_b32_e32 v46, v0
	v_mov_b32_e32 v47, v0
	v_mov_b32_e32 v56, v0
	v_mov_b32_e32 v57, v0
	v_mov_b32_e32 v58, v0
	v_mov_b32_e32 v59, v0
	v_mov_b32_e32 v60, v0
	v_mov_b32_e32 v61, v0
	v_mov_b32_e32 v62, v0
	v_mov_b32_e32 v63, v0
	v_mov_b32_e32 v64, v0
	v_mov_b32_e32 v65, v0
	v_mov_b32_e32 v66, v0
	v_mov_b32_e32 v67, v0
	v_mov_b32_e32 v68, v0
	v_mov_b32_e32 v69, v0
	v_mov_b32_e32 v70, v0
	v_mov_b32_e32 v71, v0
	v_mov_b32_e32 v80, v0
	v_mov_b32_e32 v81, v0
	v_mov_b32_e32 v82, v0
	v_mov_b32_e32 v83, v0
	v_mov_b32_e32 v84, v0
	v_mov_b32_e32 v85, v0
	v_mov_b32_e32 v86, v0
	v_mov_b32_e32 v87, v0
	v_mov_b32_e32 v96, v0
	v_mov_b32_e32 v97, v0
	v_mov_b32_e32 v98, v0
	v_mov_b32_e32 v99, v0
	v_mov_b32_e32 v100, v0
	v_mov_b32_e32 v101, v0
	v_mov_b32_e32 v102, v0
	v_mov_b32_e32 v103, v0
	v_mov_b32_e32 v112, v0
	v_mov_b32_e32 v113, v0
	v_mov_b32_e32 v114, v0
	v_mov_b32_e32 v115, v0
	v_mov_b32_e32 v116, v0
	v_mov_b32_e32 v117, v0
	v_mov_b32_e32 v118, v0
	v_mov_b32_e32 v119, v0
	v_mov_b32_e32 v72, v0
	v_mov_b32_e32 v73, v0
	v_mov_b32_e32 v74, v0
	v_mov_b32_e32 v75, v0
	v_mov_b32_e32 v76, v0
	v_mov_b32_e32 v77, v0
	v_mov_b32_e32 v78, v0
	v_mov_b32_e32 v79, v0
	v_mov_b32_e32 v88, v0
	v_mov_b32_e32 v89, v0
	v_mov_b32_e32 v90, v0
	v_mov_b32_e32 v91, v0
	v_mov_b32_e32 v92, v0
	v_mov_b32_e32 v93, v0
	v_mov_b32_e32 v94, v0
	v_mov_b32_e32 v95, v0
	v_mov_b32_e32 v104, v0
	v_mov_b32_e32 v105, v0
	v_mov_b32_e32 v106, v0
	v_mov_b32_e32 v107, v0
	v_mov_b32_e32 v108, v0
	v_mov_b32_e32 v109, v0
	v_mov_b32_e32 v110, v0
	v_mov_b32_e32 v111, v0
	v_mov_b32_e32 v120, v0
	v_mov_b32_e32 v121, v0
	v_mov_b32_e32 v122, v0
	v_mov_b32_e32 v123, v0
	v_mov_b32_e32 v124, v0
	v_mov_b32_e32 v125, v0
	v_mov_b32_e32 v126, v0
	v_mov_b32_e32 v127, v0
	v_xor_b32_e32 v216, 64, v141
	v_xor_b32_e32 v217, 64, v142
	v_xor_b32_e32 v218, 64, v143
	v_add_u32_e32 v219, 0x18000, v140
	v_xor_b32_e32 v220, 64, v219
.LBB0_985:
	ds_read_b128 v[136:139], v141
	ds_read_b128 v[146:149], v216
	ds_read_b128 v[150:153], v141 offset:2048
	ds_read_b128 v[154:157], v216 offset:2048
	s_add_u32 s14, s0, 0xffea0080
	s_addc_u32 s15, s1, -1
	s_cmpk_eq_i32 s41, 0x54
	s_cselect_b32 s17, s5, s15
	s_cselect_b32 s16, s4, s14
	s_cselect_b32 s15, s7, s40
	s_cselect_b32 s14, s6, s39
	s_add_i32 m0, s21, 0xc000
	ds_read_b128 v[158:161], v142
	ds_read_b128 v[164:167], v217
	ds_read_b128 v[176:179], v142 offset:2048
	ds_read_b128 v[180:183], v217 offset:2048
	ds_read_b128 v[184:187], v142 offset:4096
	ds_read_b128 v[188:191], v217 offset:4096
	ds_read_b128 v[192:195], v142 offset:6144
	ds_read_b128 v[196:199], v217 offset:6144
	global_load_lds_dwordx4 v128, s[0:1]
	s_add_i32 m0, s21, 0xe000
	s_nop 0
	global_load_lds_dwordx4 v130, s[0:1]
	s_waitcnt lgkmcnt(8)
	s_barrier
	s_waitcnt lgkmcnt(0)
	s_setprio 1
	s_waitcnt lgkmcnt(0)
	v_mfma_f32_16x16x32_bf16 v[124:127], v[136:139], v[158:161], v[124:127]
	v_mfma_f32_16x16x32_bf16 v[124:127], v[146:149], v[164:167], v[124:127]
	v_mfma_f32_16x16x32_bf16 v[120:123], v[154:157], v[164:167], v[120:123]
	v_mfma_f32_16x16x32_bf16 v[120:123], v[150:153], v[158:161], v[120:123]
	v_mfma_f32_16x16x32_bf16 v[104:107], v[150:153], v[176:179], v[104:107]
	v_mfma_f32_16x16x32_bf16 v[104:107], v[154:157], v[180:183], v[104:107]
	v_mfma_f32_16x16x32_bf16 v[108:111], v[146:149], v[180:183], v[108:111]
	v_mfma_f32_16x16x32_bf16 v[108:111], v[136:139], v[176:179], v[108:111]
	v_mfma_f32_16x16x32_bf16 v[92:95], v[136:139], v[184:187], v[92:95]
	v_mfma_f32_16x16x32_bf16 v[92:95], v[146:149], v[188:191], v[92:95]
	v_mfma_f32_16x16x32_bf16 v[88:91], v[154:157], v[188:191], v[88:91]
	v_mfma_f32_16x16x32_bf16 v[88:91], v[150:153], v[184:187], v[88:91]
	v_mfma_f32_16x16x32_bf16 v[72:75], v[150:153], v[192:195], v[72:75]
	v_mfma_f32_16x16x32_bf16 v[72:75], v[154:157], v[196:199], v[72:75]
	v_mfma_f32_16x16x32_bf16 v[76:79], v[146:149], v[196:199], v[76:79]
	v_mfma_f32_16x16x32_bf16 v[76:79], v[136:139], v[192:195], v[76:79]
	s_setprio 0
	s_barrier
	s_add_i32 s42, s33, s20
	s_add_u32 s98, s14, s12
	s_addc_u32 s99, s15, s13
	s_mov_b32 m0, s42
	ds_read_b128 v[200:203], v143
	ds_read_b128 v[204:207], v218
	ds_read_b128 v[208:211], v143 offset:2048
	ds_read_b128 v[212:215], v218 offset:2048
	global_load_lds_dwordx4 v170, s[14:15]
	s_add_i32 m0, s42, 0x2000
	s_nop 0
	global_load_lds_dwordx4 v174, s[14:15]
	s_barrier
	s_waitcnt lgkmcnt(0)
	s_setprio 1
	s_waitcnt lgkmcnt(0)
	v_mfma_f32_16x16x32_bf16 v[116:119], v[200:203], v[158:161], v[116:119]
	v_mfma_f32_16x16x32_bf16 v[116:119], v[204:207], v[164:167], v[116:119]
	v_mfma_f32_16x16x32_bf16 v[112:115], v[212:215], v[164:167], v[112:115]
	v_mfma_f32_16x16x32_bf16 v[112:115], v[208:211], v[158:161], v[112:115]
	v_mfma_f32_16x16x32_bf16 v[96:99], v[208:211], v[176:179], v[96:99]
	v_mfma_f32_16x16x32_bf16 v[96:99], v[212:215], v[180:183], v[96:99]
	v_mfma_f32_16x16x32_bf16 v[100:103], v[204:207], v[180:183], v[100:103]
	v_mfma_f32_16x16x32_bf16 v[100:103], v[200:203], v[176:179], v[100:103]
	v_mfma_f32_16x16x32_bf16 v[84:87], v[200:203], v[184:187], v[84:87]
	v_mfma_f32_16x16x32_bf16 v[84:87], v[204:207], v[188:191], v[84:87]
	v_mfma_f32_16x16x32_bf16 v[80:83], v[212:215], v[188:191], v[80:83]
	v_mfma_f32_16x16x32_bf16 v[80:83], v[208:211], v[184:187], v[80:83]
	v_mfma_f32_16x16x32_bf16 v[64:67], v[208:211], v[192:195], v[64:67]
	v_mfma_f32_16x16x32_bf16 v[64:67], v[212:215], v[196:199], v[64:67]
	v_mfma_f32_16x16x32_bf16 v[68:71], v[204:207], v[196:199], v[68:71]
	v_mfma_f32_16x16x32_bf16 v[68:71], v[200:203], v[192:195], v[68:71]
	s_setprio 0
	s_mov_b32 m0, s21
	s_add_u32 s100, s16, s12
	s_addc_u32 s101, s17, s13
	s_barrier
	ds_read_b128 v[158:161], v142 offset:16384
	ds_read_b128 v[164:167], v217 offset:16384
	ds_read_b128 v[176:179], v142 offset:18432
	ds_read_b128 v[180:183], v217 offset:18432
	ds_read_b128 v[184:187], v142 offset:20480
	ds_read_b128 v[188:191], v217 offset:20480
	ds_read_b128 v[192:195], v142 offset:22528
	ds_read_b128 v[196:199], v217 offset:22528
	global_load_lds_dwordx4 v168, s[16:17]
	s_mov_b32 m0, s22
	s_nop 0
	global_load_lds_dwordx4 v172, s[16:17]
	s_barrier
	s_waitcnt lgkmcnt(0)
	s_setprio 1
	s_waitcnt lgkmcnt(0)
	v_mfma_f32_16x16x32_bf16 v[60:63], v[136:139], v[158:161], v[60:63]
	v_mfma_f32_16x16x32_bf16 v[60:63], v[146:149], v[164:167], v[60:63]
	v_mfma_f32_16x16x32_bf16 v[56:59], v[154:157], v[164:167], v[56:59]
	v_mfma_f32_16x16x32_bf16 v[56:59], v[150:153], v[158:161], v[56:59]
	v_mfma_f32_16x16x32_bf16 v[40:43], v[150:153], v[176:179], v[40:43]
	v_mfma_f32_16x16x32_bf16 v[40:43], v[154:157], v[180:183], v[40:43]
	v_mfma_f32_16x16x32_bf16 v[44:47], v[146:149], v[180:183], v[44:47]
	v_mfma_f32_16x16x32_bf16 v[44:47], v[136:139], v[176:179], v[44:47]
	v_mfma_f32_16x16x32_bf16 v[28:31], v[136:139], v[184:187], v[28:31]
	v_mfma_f32_16x16x32_bf16 v[28:31], v[146:149], v[188:191], v[28:31]
	v_mfma_f32_16x16x32_bf16 v[24:27], v[154:157], v[188:191], v[24:27]
	v_mfma_f32_16x16x32_bf16 v[24:27], v[150:153], v[184:187], v[24:27]
	v_mfma_f32_16x16x32_bf16 v[8:11], v[150:153], v[192:195], v[8:11]
	v_mfma_f32_16x16x32_bf16 v[8:11], v[154:157], v[196:199], v[8:11]
	v_mfma_f32_16x16x32_bf16 v[12:15], v[146:149], v[196:199], v[12:15]
	v_mfma_f32_16x16x32_bf16 v[12:15], v[136:139], v[192:195], v[12:15]
	s_setprio 0
	s_barrier
	s_add_u32 s42, s14, 0x160000
	s_addc_u32 s43, s15, 0
	s_add_i32 s44, s34, s20
	s_mov_b32 m0, s44
	s_nop 0
	global_load_lds_dwordx4 v170, s[42:43]
	s_add_i32 m0, s44, 0x2000
	s_nop 0
	global_load_lds_dwordx4 v174, s[42:43]
	s_waitcnt vmcnt(6)
	s_barrier
	s_setprio 1
	v_mfma_f32_16x16x32_bf16 v[52:55], v[200:203], v[158:161], v[52:55]
	v_mfma_f32_16x16x32_bf16 v[52:55], v[204:207], v[164:167], v[52:55]
	v_mfma_f32_16x16x32_bf16 v[48:51], v[212:215], v[164:167], v[48:51]
	v_mfma_f32_16x16x32_bf16 v[48:51], v[208:211], v[158:161], v[48:51]
	v_mfma_f32_16x16x32_bf16 v[32:35], v[208:211], v[176:179], v[32:35]
	v_mfma_f32_16x16x32_bf16 v[32:35], v[212:215], v[180:183], v[32:35]
	v_mfma_f32_16x16x32_bf16 v[36:39], v[204:207], v[180:183], v[36:39]
	v_mfma_f32_16x16x32_bf16 v[36:39], v[200:203], v[176:179], v[36:39]
	v_mfma_f32_16x16x32_bf16 v[20:23], v[200:203], v[184:187], v[20:23]
	v_mfma_f32_16x16x32_bf16 v[20:23], v[204:207], v[188:191], v[20:23]
	v_mfma_f32_16x16x32_bf16 v[16:19], v[212:215], v[188:191], v[16:19]
	v_mfma_f32_16x16x32_bf16 v[16:19], v[208:211], v[184:187], v[16:19]
	v_mfma_f32_16x16x32_bf16 v[0:3], v[208:211], v[192:195], v[0:3]
	v_mfma_f32_16x16x32_bf16 v[0:3], v[212:215], v[196:199], v[0:3]
	v_mfma_f32_16x16x32_bf16 v[4:7], v[204:207], v[196:199], v[4:7]
	v_mfma_f32_16x16x32_bf16 v[4:7], v[200:203], v[192:195], v[4:7]
	s_setprio 0
	s_add_i32 s42, 0, 0x18000
	s_barrier
	ds_read_b128 v[136:139], v219
	ds_read_b128 v[146:149], v220
	ds_read_b128 v[150:153], v219 offset:2048
	ds_read_b128 v[154:157], v220 offset:2048
	s_add_u32 s16, s16, 0x160000
	s_addc_u32 s17, s17, 0
	s_mov_b32 m0, s23
	ds_read_b128 v[158:161], v142 offset:32768
	ds_read_b128 v[164:167], v217 offset:32768
	ds_read_b128 v[176:179], v142 offset:34816
	ds_read_b128 v[180:183], v217 offset:34816
	ds_read_b128 v[184:187], v142 offset:36864
	ds_read_b128 v[188:191], v217 offset:36864
	ds_read_b128 v[192:195], v142 offset:38912
	ds_read_b128 v[196:199], v217 offset:38912
	global_load_lds_dwordx4 v168, s[16:17]
	s_mov_b32 m0, s24
	s_nop 0
	global_load_lds_dwordx4 v172, s[16:17]
	s_waitcnt lgkmcnt(8)
	s_barrier
	s_waitcnt lgkmcnt(0)
	s_setprio 1
	s_waitcnt lgkmcnt(0)
	v_mfma_f32_16x16x32_bf16 v[124:127], v[136:139], v[158:161], v[124:127]
	v_mfma_f32_16x16x32_bf16 v[124:127], v[146:149], v[164:167], v[124:127]
	v_mfma_f32_16x16x32_bf16 v[120:123], v[154:157], v[164:167], v[120:123]
	v_mfma_f32_16x16x32_bf16 v[120:123], v[150:153], v[158:161], v[120:123]
	v_mfma_f32_16x16x32_bf16 v[104:107], v[150:153], v[176:179], v[104:107]
	v_mfma_f32_16x16x32_bf16 v[104:107], v[154:157], v[180:183], v[104:107]
	v_mfma_f32_16x16x32_bf16 v[108:111], v[146:149], v[180:183], v[108:111]
	v_mfma_f32_16x16x32_bf16 v[108:111], v[136:139], v[176:179], v[108:111]
	v_mfma_f32_16x16x32_bf16 v[92:95], v[136:139], v[184:187], v[92:95]
	v_mfma_f32_16x16x32_bf16 v[92:95], v[146:149], v[188:191], v[92:95]
	v_mfma_f32_16x16x32_bf16 v[88:91], v[154:157], v[188:191], v[88:91]
	v_mfma_f32_16x16x32_bf16 v[88:91], v[150:153], v[184:187], v[88:91]
	v_mfma_f32_16x16x32_bf16 v[72:75], v[150:153], v[192:195], v[72:75]
	v_mfma_f32_16x16x32_bf16 v[72:75], v[154:157], v[196:199], v[72:75]
	v_mfma_f32_16x16x32_bf16 v[76:79], v[146:149], v[196:199], v[76:79]
	v_mfma_f32_16x16x32_bf16 v[76:79], v[136:139], v[192:195], v[76:79]
	s_setprio 0
	s_barrier
	s_add_i32 s16, 0, 0x1c000
	s_add_i32 s17, s42, s20
	v_add_u32_e32 v145, s16, v140
	s_mov_b32 m0, s17
	ds_read_b128 v[200:203], v145
	v_xor_b32_e32 v215, 64, v145
	ds_read_b128 v[204:207], v215
	ds_read_b128 v[208:211], v145 offset:2048
	ds_read_b128 v[212:215], v215 offset:2048
	global_load_lds_dwordx4 v170, s[98:99]
	s_add_i32 m0, s17, 0x2000
	s_nop 0
	global_load_lds_dwordx4 v174, s[98:99]
	s_barrier
	s_waitcnt lgkmcnt(0)
	s_setprio 1
	s_waitcnt lgkmcnt(0)
	v_mfma_f32_16x16x32_bf16 v[116:119], v[200:203], v[158:161], v[116:119]
	v_mfma_f32_16x16x32_bf16 v[116:119], v[204:207], v[164:167], v[116:119]
	v_mfma_f32_16x16x32_bf16 v[112:115], v[212:215], v[164:167], v[112:115]
	v_mfma_f32_16x16x32_bf16 v[112:115], v[208:211], v[158:161], v[112:115]
	v_mfma_f32_16x16x32_bf16 v[96:99], v[208:211], v[176:179], v[96:99]
	v_mfma_f32_16x16x32_bf16 v[96:99], v[212:215], v[180:183], v[96:99]
	v_mfma_f32_16x16x32_bf16 v[100:103], v[204:207], v[180:183], v[100:103]
	v_mfma_f32_16x16x32_bf16 v[100:103], v[200:203], v[176:179], v[100:103]
	v_mfma_f32_16x16x32_bf16 v[84:87], v[200:203], v[184:187], v[84:87]
	v_mfma_f32_16x16x32_bf16 v[84:87], v[204:207], v[188:191], v[84:87]
	v_mfma_f32_16x16x32_bf16 v[80:83], v[212:215], v[188:191], v[80:83]
	v_mfma_f32_16x16x32_bf16 v[80:83], v[208:211], v[184:187], v[80:83]
	v_mfma_f32_16x16x32_bf16 v[64:67], v[208:211], v[192:195], v[64:67]
	v_mfma_f32_16x16x32_bf16 v[64:67], v[212:215], v[196:199], v[64:67]
	v_mfma_f32_16x16x32_bf16 v[68:71], v[204:207], v[196:199], v[68:71]
	v_mfma_f32_16x16x32_bf16 v[68:71], v[200:203], v[192:195], v[68:71]
	s_setprio 0
	s_mov_b32 m0, s28
	s_barrier
	ds_read_b128 v[158:161], v142 offset:49152
	ds_read_b128 v[164:167], v217 offset:49152
	ds_read_b128 v[176:179], v142 offset:51200
	ds_read_b128 v[180:183], v217 offset:51200
	ds_read_b128 v[184:187], v142 offset:53248
	ds_read_b128 v[188:191], v217 offset:53248
	ds_read_b128 v[192:195], v142 offset:55296
	ds_read_b128 v[196:199], v217 offset:55296
	global_load_lds_dwordx4 v168, s[100:101]
	s_mov_b32 m0, s29
	s_nop 0
	global_load_lds_dwordx4 v172, s[100:101]
	s_barrier
	s_waitcnt lgkmcnt(0)
	s_setprio 1
	s_waitcnt lgkmcnt(0)
	v_mfma_f32_16x16x32_bf16 v[60:63], v[136:139], v[158:161], v[60:63]
	v_mfma_f32_16x16x32_bf16 v[60:63], v[146:149], v[164:167], v[60:63]
	v_mfma_f32_16x16x32_bf16 v[56:59], v[154:157], v[164:167], v[56:59]
	v_mfma_f32_16x16x32_bf16 v[56:59], v[150:153], v[158:161], v[56:59]
	v_mfma_f32_16x16x32_bf16 v[40:43], v[150:153], v[176:179], v[40:43]
	v_mfma_f32_16x16x32_bf16 v[40:43], v[154:157], v[180:183], v[40:43]
	v_mfma_f32_16x16x32_bf16 v[44:47], v[146:149], v[180:183], v[44:47]
	v_mfma_f32_16x16x32_bf16 v[44:47], v[136:139], v[176:179], v[44:47]
	v_mfma_f32_16x16x32_bf16 v[28:31], v[136:139], v[184:187], v[28:31]
	v_mfma_f32_16x16x32_bf16 v[28:31], v[146:149], v[188:191], v[28:31]
	v_mfma_f32_16x16x32_bf16 v[24:27], v[154:157], v[188:191], v[24:27]
	v_mfma_f32_16x16x32_bf16 v[24:27], v[150:153], v[184:187], v[24:27]
	v_mfma_f32_16x16x32_bf16 v[8:11], v[150:153], v[192:195], v[8:11]
	v_mfma_f32_16x16x32_bf16 v[8:11], v[154:157], v[196:199], v[8:11]
	v_mfma_f32_16x16x32_bf16 v[12:15], v[146:149], v[196:199], v[12:15]
	v_mfma_f32_16x16x32_bf16 v[12:15], v[136:139], v[192:195], v[12:15]
	s_setprio 0
	s_barrier
	s_add_u32 s14, s14, 0x160080
	s_addc_u32 s15, s15, 0
	s_add_i32 s16, s16, s20
	s_mov_b32 m0, s16
	s_nop 0
	global_load_lds_dwordx4 v170, s[14:15]
	s_add_i32 m0, s16, 0x2000
	s_nop 0
	global_load_lds_dwordx4 v174, s[14:15]
	s_waitcnt vmcnt(6)
	s_barrier
	s_setprio 1
	v_mfma_f32_16x16x32_bf16 v[52:55], v[200:203], v[158:161], v[52:55]
	v_mfma_f32_16x16x32_bf16 v[52:55], v[204:207], v[164:167], v[52:55]
	v_mfma_f32_16x16x32_bf16 v[48:51], v[212:215], v[164:167], v[48:51]
	v_mfma_f32_16x16x32_bf16 v[48:51], v[208:211], v[158:161], v[48:51]
	v_mfma_f32_16x16x32_bf16 v[32:35], v[208:211], v[176:179], v[32:35]
	v_mfma_f32_16x16x32_bf16 v[32:35], v[212:215], v[180:183], v[32:35]
	v_mfma_f32_16x16x32_bf16 v[36:39], v[204:207], v[180:183], v[36:39]
	v_mfma_f32_16x16x32_bf16 v[36:39], v[200:203], v[176:179], v[36:39]
	v_mfma_f32_16x16x32_bf16 v[20:23], v[200:203], v[184:187], v[20:23]
	v_mfma_f32_16x16x32_bf16 v[20:23], v[204:207], v[188:191], v[20:23]
	v_mfma_f32_16x16x32_bf16 v[16:19], v[212:215], v[188:191], v[16:19]
	v_mfma_f32_16x16x32_bf16 v[16:19], v[208:211], v[184:187], v[16:19]
	v_mfma_f32_16x16x32_bf16 v[0:3], v[208:211], v[192:195], v[0:3]
	v_mfma_f32_16x16x32_bf16 v[0:3], v[212:215], v[196:199], v[0:3]
	v_mfma_f32_16x16x32_bf16 v[4:7], v[204:207], v[196:199], v[4:7]
	v_mfma_f32_16x16x32_bf16 v[4:7], v[200:203], v[192:195], v[4:7]
	s_setprio 0
	s_add_i32 s41, s41, 2
	s_add_u32 s0, s0, 0x100
	s_addc_u32 s1, s1, 0
	s_add_u32 s39, s39, 0x100
	s_addc_u32 s40, s40, 0
	s_cmpk_gt_u32 s41, 0x55
	s_barrier
	s_cbranch_scc0 .LBB0_985
	v_lshl_add_u32 v217, s38, 8, v163
	v_add_u32_e32 v217, s26, v217
	v_lshlrev_b32_e32 v208, 2, v217
	v_lshl_add_u32 v214, v225, 3, s27
	v_lshl_add_u32 v214, s37, 8, v214
	v_lshl_add_u32 v209, v217, 11, v214
	v_lshlrev_b32_e32 v209, 1, v209
	v_lshlrev_b32_e32 v210, 1, v209
	v_lshl_add_u32 v217, v225, 4, v163
	v_xor_b32_e32 v215, 16, v217
	v_lshlrev_b32_e32 v215, 2, v215
	v_xor_b32_e32 v216, 32, v217
	v_lshlrev_b32_e32 v216, 2, v216
	v_add_u32_e32 v211, 0x0, v209
	global_load_dwordx4 v[176:179], v211, s[80:81]
	global_load_dwordx4 v[180:183], v211, s[80:81] offset:256
	v_add_u32_e32 v211, 0x10000, v209
	global_load_dwordx4 v[192:195], v211, s[80:81]
	global_load_dwordx4 v[196:199], v211, s[80:81] offset:256
	s_waitcnt vmcnt(2)
	v_lshlrev_b32_e32 v184, 16, v176
	v_and_b32_e32 v185, 0xffff0000, v176
	v_lshlrev_b32_e32 v186, 16, v177
	v_and_b32_e32 v187, 0xffff0000, v177
	v_lshlrev_b32_e32 v188, 16, v178
	v_and_b32_e32 v189, 0xffff0000, v178
	v_lshlrev_b32_e32 v190, 16, v179
	v_and_b32_e32 v191, 0xffff0000, v179
	v_pk_add_f32 v[124:125], v[124:125], v[184:185]
	v_pk_add_f32 v[126:127], v[126:127], v[186:187]
	v_pk_add_f32 v[120:121], v[120:121], v[188:189]
	v_pk_add_f32 v[122:123], v[122:123], v[190:191]
	v_mul_f32_e32 v213, v124, v124
	v_fmac_f32_e32 v213, v125, v125
	v_fmac_f32_e32 v213, v126, v126
	v_fmac_f32_e32 v213, v127, v127
	v_fmac_f32_e32 v213, v120, v120
	v_fmac_f32_e32 v213, v121, v121
	v_fmac_f32_e32 v213, v122, v122
	v_fmac_f32_e32 v213, v123, v123
	v_add_u32_e32 v212, 0x0, v210
	global_store_dwordx4 v212, v[124:127], s[90:91]
	global_store_dwordx4 v212, v[120:123], s[90:91] offset:16
	v_lshlrev_b32_e32 v184, 16, v180
	v_and_b32_e32 v185, 0xffff0000, v180
	v_lshlrev_b32_e32 v186, 16, v181
	v_and_b32_e32 v187, 0xffff0000, v181
	v_lshlrev_b32_e32 v188, 16, v182
	v_and_b32_e32 v189, 0xffff0000, v182
	v_lshlrev_b32_e32 v190, 16, v183
	v_and_b32_e32 v191, 0xffff0000, v183
	v_pk_add_f32 v[116:117], v[116:117], v[184:185]
	v_pk_add_f32 v[118:119], v[118:119], v[186:187]
	v_pk_add_f32 v[112:113], v[112:113], v[188:189]
	v_pk_add_f32 v[114:115], v[114:115], v[190:191]
	v_fmac_f32_e32 v213, v116, v116
	v_fmac_f32_e32 v213, v117, v117
	v_fmac_f32_e32 v213, v118, v118
	v_fmac_f32_e32 v213, v119, v119
	v_fmac_f32_e32 v213, v112, v112
	v_fmac_f32_e32 v213, v113, v113
	v_fmac_f32_e32 v213, v114, v114
	v_fmac_f32_e32 v213, v115, v115
	global_store_dwordx4 v212, v[116:119], s[90:91] offset:512
	global_store_dwordx4 v212, v[112:115], s[90:91] offset:528
	ds_bpermute_b32 v214, v215, v213
	s_waitcnt lgkmcnt(0)
	v_add_f32_e32 v213, v213, v214
	ds_bpermute_b32 v214, v216, v213
	s_waitcnt lgkmcnt(0)
	v_add_f32_e32 v213, v213, v214
	s_mov_b64 exec, 0xffff
	global_atomic_add_f32 v208, v213, s[10:11]
	s_mov_b64 exec, -1
	v_add_u32_e32 v211, 0x20000, v209
	global_load_dwordx4 v[176:179], v211, s[80:81]
	global_load_dwordx4 v[180:183], v211, s[80:81] offset:256
	s_waitcnt vmcnt(7)
	v_lshlrev_b32_e32 v200, 16, v192
	v_and_b32_e32 v201, 0xffff0000, v192
	v_lshlrev_b32_e32 v202, 16, v193
	v_and_b32_e32 v203, 0xffff0000, v193
	v_lshlrev_b32_e32 v204, 16, v194
	v_and_b32_e32 v205, 0xffff0000, v194
	v_lshlrev_b32_e32 v206, 16, v195
	v_and_b32_e32 v207, 0xffff0000, v195
	v_pk_add_f32 v[108:109], v[108:109], v[200:201]
	v_pk_add_f32 v[110:111], v[110:111], v[202:203]
	v_pk_add_f32 v[104:105], v[104:105], v[204:205]
	v_pk_add_f32 v[106:107], v[106:107], v[206:207]
	v_mul_f32_e32 v213, v108, v108
	v_fmac_f32_e32 v213, v109, v109
	v_fmac_f32_e32 v213, v110, v110
	v_fmac_f32_e32 v213, v111, v111
	v_fmac_f32_e32 v213, v104, v104
	v_fmac_f32_e32 v213, v105, v105
	v_fmac_f32_e32 v213, v106, v106
	v_fmac_f32_e32 v213, v107, v107
	v_add_u32_e32 v212, 0x20000, v210
	global_store_dwordx4 v212, v[108:111], s[90:91]
	global_store_dwordx4 v212, v[104:107], s[90:91] offset:16
	v_lshlrev_b32_e32 v200, 16, v196
	v_and_b32_e32 v201, 0xffff0000, v196
	v_lshlrev_b32_e32 v202, 16, v197
	v_and_b32_e32 v203, 0xffff0000, v197
	v_lshlrev_b32_e32 v204, 16, v198
	v_and_b32_e32 v205, 0xffff0000, v198
	v_lshlrev_b32_e32 v206, 16, v199
	v_and_b32_e32 v207, 0xffff0000, v199
	v_pk_add_f32 v[100:101], v[100:101], v[200:201]
	v_pk_add_f32 v[102:103], v[102:103], v[202:203]
	v_pk_add_f32 v[96:97], v[96:97], v[204:205]
	v_pk_add_f32 v[98:99], v[98:99], v[206:207]
	v_fmac_f32_e32 v213, v100, v100
	v_fmac_f32_e32 v213, v101, v101
	v_fmac_f32_e32 v213, v102, v102
	v_fmac_f32_e32 v213, v103, v103
	v_fmac_f32_e32 v213, v96, v96
	v_fmac_f32_e32 v213, v97, v97
	v_fmac_f32_e32 v213, v98, v98
	v_fmac_f32_e32 v213, v99, v99
	global_store_dwordx4 v212, v[100:103], s[90:91] offset:512
	global_store_dwordx4 v212, v[96:99], s[90:91] offset:528
	ds_bpermute_b32 v214, v215, v213
	s_waitcnt lgkmcnt(0)
	v_add_f32_e32 v213, v213, v214
	ds_bpermute_b32 v214, v216, v213
	s_waitcnt lgkmcnt(0)
	v_add_f32_e32 v213, v213, v214
	s_mov_b64 exec, 0xffff
	global_atomic_add_f32 v208, v213, s[10:11] offset:64
	s_mov_b64 exec, -1
	v_add_u32_e32 v211, 0x30000, v209
	global_load_dwordx4 v[192:195], v211, s[80:81]
	global_load_dwordx4 v[196:199], v211, s[80:81] offset:256
	s_waitcnt vmcnt(7)
	v_lshlrev_b32_e32 v184, 16, v176
	v_and_b32_e32 v185, 0xffff0000, v176
	v_lshlrev_b32_e32 v186, 16, v177
	v_and_b32_e32 v187, 0xffff0000, v177
	v_lshlrev_b32_e32 v188, 16, v178
	v_and_b32_e32 v189, 0xffff0000, v178
	v_lshlrev_b32_e32 v190, 16, v179
	v_and_b32_e32 v191, 0xffff0000, v179
	v_pk_add_f32 v[92:93], v[92:93], v[184:185]
	v_pk_add_f32 v[94:95], v[94:95], v[186:187]
	v_pk_add_f32 v[88:89], v[88:89], v[188:189]
	v_pk_add_f32 v[90:91], v[90:91], v[190:191]
	v_mul_f32_e32 v213, v92, v92
	v_fmac_f32_e32 v213, v93, v93
	v_fmac_f32_e32 v213, v94, v94
	v_fmac_f32_e32 v213, v95, v95
	v_fmac_f32_e32 v213, v88, v88
	v_fmac_f32_e32 v213, v89, v89
	v_fmac_f32_e32 v213, v90, v90
	v_fmac_f32_e32 v213, v91, v91
	v_add_u32_e32 v212, 0x40000, v210
	global_store_dwordx4 v212, v[92:95], s[90:91]
	global_store_dwordx4 v212, v[88:91], s[90:91] offset:16
	v_lshlrev_b32_e32 v184, 16, v180
	v_and_b32_e32 v185, 0xffff0000, v180
	v_lshlrev_b32_e32 v186, 16, v181
	v_and_b32_e32 v187, 0xffff0000, v181
	v_lshlrev_b32_e32 v188, 16, v182
	v_and_b32_e32 v189, 0xffff0000, v182
	v_lshlrev_b32_e32 v190, 16, v183
	v_and_b32_e32 v191, 0xffff0000, v183
	v_pk_add_f32 v[84:85], v[84:85], v[184:185]
	v_pk_add_f32 v[86:87], v[86:87], v[186:187]
	v_pk_add_f32 v[80:81], v[80:81], v[188:189]
	v_pk_add_f32 v[82:83], v[82:83], v[190:191]
	v_fmac_f32_e32 v213, v84, v84
	v_fmac_f32_e32 v213, v85, v85
	v_fmac_f32_e32 v213, v86, v86
	v_fmac_f32_e32 v213, v87, v87
	v_fmac_f32_e32 v213, v80, v80
	v_fmac_f32_e32 v213, v81, v81
	v_fmac_f32_e32 v213, v82, v82
	v_fmac_f32_e32 v213, v83, v83
	global_store_dwordx4 v212, v[84:87], s[90:91] offset:512
	global_store_dwordx4 v212, v[80:83], s[90:91] offset:528
	ds_bpermute_b32 v214, v215, v213
	s_waitcnt lgkmcnt(0)
	v_add_f32_e32 v213, v213, v214
	ds_bpermute_b32 v214, v216, v213
	s_waitcnt lgkmcnt(0)
	v_add_f32_e32 v213, v213, v214
	s_mov_b64 exec, 0xffff
	global_atomic_add_f32 v208, v213, s[10:11] offset:128
	s_mov_b64 exec, -1
	v_add_u32_e32 v211, 0x80000, v209
	global_load_dwordx4 v[176:179], v211, s[80:81]
	global_load_dwordx4 v[180:183], v211, s[80:81] offset:256
	s_waitcnt vmcnt(7)
	v_lshlrev_b32_e32 v200, 16, v192
	v_and_b32_e32 v201, 0xffff0000, v192
	v_lshlrev_b32_e32 v202, 16, v193
	v_and_b32_e32 v203, 0xffff0000, v193
	v_lshlrev_b32_e32 v204, 16, v194
	v_and_b32_e32 v205, 0xffff0000, v194
	v_lshlrev_b32_e32 v206, 16, v195
	v_and_b32_e32 v207, 0xffff0000, v195
	v_pk_add_f32 v[76:77], v[76:77], v[200:201]
	v_pk_add_f32 v[78:79], v[78:79], v[202:203]
	v_pk_add_f32 v[72:73], v[72:73], v[204:205]
	v_pk_add_f32 v[74:75], v[74:75], v[206:207]
	v_mul_f32_e32 v213, v76, v76
	v_fmac_f32_e32 v213, v77, v77
	v_fmac_f32_e32 v213, v78, v78
	v_fmac_f32_e32 v213, v79, v79
	v_fmac_f32_e32 v213, v72, v72
	v_fmac_f32_e32 v213, v73, v73
	v_fmac_f32_e32 v213, v74, v74
	v_fmac_f32_e32 v213, v75, v75
	v_add_u32_e32 v212, 0x60000, v210
	global_store_dwordx4 v212, v[76:79], s[90:91]
	global_store_dwordx4 v212, v[72:75], s[90:91] offset:16
	v_lshlrev_b32_e32 v200, 16, v196
	v_and_b32_e32 v201, 0xffff0000, v196
	v_lshlrev_b32_e32 v202, 16, v197
	v_and_b32_e32 v203, 0xffff0000, v197
	v_lshlrev_b32_e32 v204, 16, v198
	v_and_b32_e32 v205, 0xffff0000, v198
	v_lshlrev_b32_e32 v206, 16, v199
	v_and_b32_e32 v207, 0xffff0000, v199
	v_pk_add_f32 v[68:69], v[68:69], v[200:201]
	v_pk_add_f32 v[70:71], v[70:71], v[202:203]
	v_pk_add_f32 v[64:65], v[64:65], v[204:205]
	v_pk_add_f32 v[66:67], v[66:67], v[206:207]
	v_fmac_f32_e32 v213, v68, v68
	v_fmac_f32_e32 v213, v69, v69
	v_fmac_f32_e32 v213, v70, v70
	v_fmac_f32_e32 v213, v71, v71
	v_fmac_f32_e32 v213, v64, v64
	v_fmac_f32_e32 v213, v65, v65
	v_fmac_f32_e32 v213, v66, v66
	v_fmac_f32_e32 v213, v67, v67
	global_store_dwordx4 v212, v[68:71], s[90:91] offset:512
	global_store_dwordx4 v212, v[64:67], s[90:91] offset:528
	ds_bpermute_b32 v214, v215, v213
	s_waitcnt lgkmcnt(0)
	v_add_f32_e32 v213, v213, v214
	ds_bpermute_b32 v214, v216, v213
	s_waitcnt lgkmcnt(0)
	v_add_f32_e32 v213, v213, v214
	s_mov_b64 exec, 0xffff
	global_atomic_add_f32 v208, v213, s[10:11] offset:192
	s_mov_b64 exec, -1
	v_add_u32_e32 v211, 0x90000, v209
	global_load_dwordx4 v[192:195], v211, s[80:81]
	global_load_dwordx4 v[196:199], v211, s[80:81] offset:256
	s_waitcnt vmcnt(7)
	v_lshlrev_b32_e32 v184, 16, v176
	v_and_b32_e32 v185, 0xffff0000, v176
	v_lshlrev_b32_e32 v186, 16, v177
	v_and_b32_e32 v187, 0xffff0000, v177
	v_lshlrev_b32_e32 v188, 16, v178
	v_and_b32_e32 v189, 0xffff0000, v178
	v_lshlrev_b32_e32 v190, 16, v179
	v_and_b32_e32 v191, 0xffff0000, v179
	v_pk_add_f32 v[60:61], v[60:61], v[184:185]
	v_pk_add_f32 v[62:63], v[62:63], v[186:187]
	v_pk_add_f32 v[56:57], v[56:57], v[188:189]
	v_pk_add_f32 v[58:59], v[58:59], v[190:191]
	v_mul_f32_e32 v213, v60, v60
	v_fmac_f32_e32 v213, v61, v61
	v_fmac_f32_e32 v213, v62, v62
	v_fmac_f32_e32 v213, v63, v63
	v_fmac_f32_e32 v213, v56, v56
	v_fmac_f32_e32 v213, v57, v57
	v_fmac_f32_e32 v213, v58, v58
	v_fmac_f32_e32 v213, v59, v59
	v_add_u32_e32 v212, 0x100000, v210
	global_store_dwordx4 v212, v[60:63], s[90:91]
	global_store_dwordx4 v212, v[56:59], s[90:91] offset:16
	v_lshlrev_b32_e32 v184, 16, v180
	v_and_b32_e32 v185, 0xffff0000, v180
	v_lshlrev_b32_e32 v186, 16, v181
	v_and_b32_e32 v187, 0xffff0000, v181
	v_lshlrev_b32_e32 v188, 16, v182
	v_and_b32_e32 v189, 0xffff0000, v182
	v_lshlrev_b32_e32 v190, 16, v183
	v_and_b32_e32 v191, 0xffff0000, v183
	v_pk_add_f32 v[52:53], v[52:53], v[184:185]
	v_pk_add_f32 v[54:55], v[54:55], v[186:187]
	v_pk_add_f32 v[48:49], v[48:49], v[188:189]
	v_pk_add_f32 v[50:51], v[50:51], v[190:191]
	v_fmac_f32_e32 v213, v52, v52
	v_fmac_f32_e32 v213, v53, v53
	v_fmac_f32_e32 v213, v54, v54
	v_fmac_f32_e32 v213, v55, v55
	v_fmac_f32_e32 v213, v48, v48
	v_fmac_f32_e32 v213, v49, v49
	v_fmac_f32_e32 v213, v50, v50
	v_fmac_f32_e32 v213, v51, v51
	global_store_dwordx4 v212, v[52:55], s[90:91] offset:512
	global_store_dwordx4 v212, v[48:51], s[90:91] offset:528
	ds_bpermute_b32 v214, v215, v213
	s_waitcnt lgkmcnt(0)
	v_add_f32_e32 v213, v213, v214
	ds_bpermute_b32 v214, v216, v213
	s_waitcnt lgkmcnt(0)
	v_add_f32_e32 v213, v213, v214
	s_mov_b64 exec, 0xffff
	global_atomic_add_f32 v208, v213, s[10:11] offset:512
	s_mov_b64 exec, -1
	v_add_u32_e32 v211, 0xa0000, v209
	global_load_dwordx4 v[176:179], v211, s[80:81]
	global_load_dwordx4 v[180:183], v211, s[80:81] offset:256
	s_waitcnt vmcnt(7)
	v_lshlrev_b32_e32 v200, 16, v192
	v_and_b32_e32 v201, 0xffff0000, v192
	v_lshlrev_b32_e32 v202, 16, v193
	v_and_b32_e32 v203, 0xffff0000, v193
	v_lshlrev_b32_e32 v204, 16, v194
	v_and_b32_e32 v205, 0xffff0000, v194
	v_lshlrev_b32_e32 v206, 16, v195
	v_and_b32_e32 v207, 0xffff0000, v195
	v_pk_add_f32 v[44:45], v[44:45], v[200:201]
	v_pk_add_f32 v[46:47], v[46:47], v[202:203]
	v_pk_add_f32 v[40:41], v[40:41], v[204:205]
	v_pk_add_f32 v[42:43], v[42:43], v[206:207]
	v_mul_f32_e32 v213, v44, v44
	v_fmac_f32_e32 v213, v45, v45
	v_fmac_f32_e32 v213, v46, v46
	v_fmac_f32_e32 v213, v47, v47
	v_fmac_f32_e32 v213, v40, v40
	v_fmac_f32_e32 v213, v41, v41
	v_fmac_f32_e32 v213, v42, v42
	v_fmac_f32_e32 v213, v43, v43
	v_add_u32_e32 v212, 0x120000, v210
	global_store_dwordx4 v212, v[44:47], s[90:91]
	global_store_dwordx4 v212, v[40:43], s[90:91] offset:16
	v_lshlrev_b32_e32 v200, 16, v196
	v_and_b32_e32 v201, 0xffff0000, v196
	v_lshlrev_b32_e32 v202, 16, v197
	v_and_b32_e32 v203, 0xffff0000, v197
	v_lshlrev_b32_e32 v204, 16, v198
	v_and_b32_e32 v205, 0xffff0000, v198
	v_lshlrev_b32_e32 v206, 16, v199
	v_and_b32_e32 v207, 0xffff0000, v199
	v_pk_add_f32 v[36:37], v[36:37], v[200:201]
	v_pk_add_f32 v[38:39], v[38:39], v[202:203]
	v_pk_add_f32 v[32:33], v[32:33], v[204:205]
	v_pk_add_f32 v[34:35], v[34:35], v[206:207]
	v_fmac_f32_e32 v213, v36, v36
	v_fmac_f32_e32 v213, v37, v37
	v_fmac_f32_e32 v213, v38, v38
	v_fmac_f32_e32 v213, v39, v39
	v_fmac_f32_e32 v213, v32, v32
	v_fmac_f32_e32 v213, v33, v33
	v_fmac_f32_e32 v213, v34, v34
	v_fmac_f32_e32 v213, v35, v35
	global_store_dwordx4 v212, v[36:39], s[90:91] offset:512
	global_store_dwordx4 v212, v[32:35], s[90:91] offset:528
	ds_bpermute_b32 v214, v215, v213
	s_waitcnt lgkmcnt(0)
	v_add_f32_e32 v213, v213, v214
	ds_bpermute_b32 v214, v216, v213
	s_waitcnt lgkmcnt(0)
	v_add_f32_e32 v213, v213, v214
	s_mov_b64 exec, 0xffff
	global_atomic_add_f32 v208, v213, s[10:11] offset:576
	s_mov_b64 exec, -1
	v_add_u32_e32 v211, 0xb0000, v209
	global_load_dwordx4 v[192:195], v211, s[80:81]
	global_load_dwordx4 v[196:199], v211, s[80:81] offset:256
	s_waitcnt vmcnt(7)
	v_lshlrev_b32_e32 v184, 16, v176
	v_and_b32_e32 v185, 0xffff0000, v176
	v_lshlrev_b32_e32 v186, 16, v177
	v_and_b32_e32 v187, 0xffff0000, v177
	v_lshlrev_b32_e32 v188, 16, v178
	v_and_b32_e32 v189, 0xffff0000, v178
	v_lshlrev_b32_e32 v190, 16, v179
	v_and_b32_e32 v191, 0xffff0000, v179
	v_pk_add_f32 v[28:29], v[28:29], v[184:185]
	v_pk_add_f32 v[30:31], v[30:31], v[186:187]
	v_pk_add_f32 v[24:25], v[24:25], v[188:189]
	v_pk_add_f32 v[26:27], v[26:27], v[190:191]
	v_mul_f32_e32 v213, v28, v28
	v_fmac_f32_e32 v213, v29, v29
	v_fmac_f32_e32 v213, v30, v30
	v_fmac_f32_e32 v213, v31, v31
	v_fmac_f32_e32 v213, v24, v24
	v_fmac_f32_e32 v213, v25, v25
	v_fmac_f32_e32 v213, v26, v26
	v_fmac_f32_e32 v213, v27, v27
	v_add_u32_e32 v212, 0x140000, v210
	global_store_dwordx4 v212, v[28:31], s[90:91]
	global_store_dwordx4 v212, v[24:27], s[90:91] offset:16
	v_lshlrev_b32_e32 v184, 16, v180
	v_and_b32_e32 v185, 0xffff0000, v180
	v_lshlrev_b32_e32 v186, 16, v181
	v_and_b32_e32 v187, 0xffff0000, v181
	v_lshlrev_b32_e32 v188, 16, v182
	v_and_b32_e32 v189, 0xffff0000, v182
	v_lshlrev_b32_e32 v190, 16, v183
	v_and_b32_e32 v191, 0xffff0000, v183
	v_pk_add_f32 v[20:21], v[20:21], v[184:185]
	v_pk_add_f32 v[22:23], v[22:23], v[186:187]
	v_pk_add_f32 v[16:17], v[16:17], v[188:189]
	v_pk_add_f32 v[18:19], v[18:19], v[190:191]
	v_fmac_f32_e32 v213, v20, v20
	v_fmac_f32_e32 v213, v21, v21
	v_fmac_f32_e32 v213, v22, v22
	v_fmac_f32_e32 v213, v23, v23
	v_fmac_f32_e32 v213, v16, v16
	v_fmac_f32_e32 v213, v17, v17
	v_fmac_f32_e32 v213, v18, v18
	v_fmac_f32_e32 v213, v19, v19
	global_store_dwordx4 v212, v[20:23], s[90:91] offset:512
	global_store_dwordx4 v212, v[16:19], s[90:91] offset:528
	ds_bpermute_b32 v214, v215, v213
	s_waitcnt lgkmcnt(0)
	v_add_f32_e32 v213, v213, v214
	ds_bpermute_b32 v214, v216, v213
	s_waitcnt lgkmcnt(0)
	v_add_f32_e32 v213, v213, v214
	s_mov_b64 exec, 0xffff
	global_atomic_add_f32 v208, v213, s[10:11] offset:640
	s_mov_b64 exec, -1
	s_waitcnt vmcnt(5)
	v_lshlrev_b32_e32 v200, 16, v192
	v_and_b32_e32 v201, 0xffff0000, v192
	v_lshlrev_b32_e32 v202, 16, v193
	v_and_b32_e32 v203, 0xffff0000, v193
	v_lshlrev_b32_e32 v204, 16, v194
	v_and_b32_e32 v205, 0xffff0000, v194
	v_lshlrev_b32_e32 v206, 16, v195
	v_and_b32_e32 v207, 0xffff0000, v195
	v_pk_add_f32 v[12:13], v[12:13], v[200:201]
	v_pk_add_f32 v[14:15], v[14:15], v[202:203]
	v_pk_add_f32 v[8:9], v[8:9], v[204:205]
	v_pk_add_f32 v[10:11], v[10:11], v[206:207]
	v_mul_f32_e32 v213, v12, v12
	v_fmac_f32_e32 v213, v13, v13
	v_fmac_f32_e32 v213, v14, v14
	v_fmac_f32_e32 v213, v15, v15
	v_fmac_f32_e32 v213, v8, v8
	v_fmac_f32_e32 v213, v9, v9
	v_fmac_f32_e32 v213, v10, v10
	v_fmac_f32_e32 v213, v11, v11
	v_add_u32_e32 v212, 0x160000, v210
	global_store_dwordx4 v212, v[12:15], s[90:91]
	global_store_dwordx4 v212, v[8:11], s[90:91] offset:16
	v_lshlrev_b32_e32 v200, 16, v196
	v_and_b32_e32 v201, 0xffff0000, v196
	v_lshlrev_b32_e32 v202, 16, v197
	v_and_b32_e32 v203, 0xffff0000, v197
	v_lshlrev_b32_e32 v204, 16, v198
	v_and_b32_e32 v205, 0xffff0000, v198
	v_lshlrev_b32_e32 v206, 16, v199
	v_and_b32_e32 v207, 0xffff0000, v199
	v_pk_add_f32 v[4:5], v[4:5], v[200:201]
	v_pk_add_f32 v[6:7], v[6:7], v[202:203]
	v_pk_add_f32 v[0:1], v[0:1], v[204:205]
	v_pk_add_f32 v[2:3], v[2:3], v[206:207]
	v_fmac_f32_e32 v213, v4, v4
	v_fmac_f32_e32 v213, v5, v5
	v_fmac_f32_e32 v213, v6, v6
	v_fmac_f32_e32 v213, v7, v7
	v_fmac_f32_e32 v213, v0, v0
	v_fmac_f32_e32 v213, v1, v1
	v_fmac_f32_e32 v213, v2, v2
	v_fmac_f32_e32 v213, v3, v3
	global_store_dwordx4 v212, v[4:7], s[90:91] offset:512
	global_store_dwordx4 v212, v[0:3], s[90:91] offset:528
	ds_bpermute_b32 v214, v215, v213
	s_waitcnt lgkmcnt(0)
	v_add_f32_e32 v213, v213, v214
	ds_bpermute_b32 v214, v216, v213
	s_waitcnt lgkmcnt(0)
	v_add_f32_e32 v213, v213, v214
	s_mov_b64 exec, 0xffff
	global_atomic_add_f32 v208, v213, s[10:11] offset:704
	s_mov_b64 exec, -1
	s_branch .LBB0_973
